# K-loop phase rebalancing applied to all seven GEMM K-loops (B fragment reads moved into the DMA-only phase, earlier counted vmcnt publish)
# speedup vs baseline: 1.0177x; 1.0043x over previous
; #define STAGE(P, BASE, LD, br, kt) do { const bf16* _gb = BASE + ((long)(br) * (LD) + (long)(kt) * BK); \
;     _Pragma("unroll") for (int _i = 0; _i < 2; ++_i) { \
;       __builtin_amdgcn_global_load_lds((const unsigned*)(_gb + ((&LD == &lda) ? offA[_i] : offB[_i])), \
;         (unsigned*)((char*)(P) + tidx_ * 16 + _i * 8192), 16, 0, 0); } } while (0)
; #define LDA(dst, b, h) _Pragma("unroll") for (int m = 0; m < 4; ++m) _Pragma("unroll") for (int k = 0; k < 2; ++k) \
;     dst[m][k] = *reinterpret_cast<const bf16x8*>(smem + (((b) * 2 + (h)) * 16384 + m * 2048 + k * 1024) + aoff)
; #define LDB(dst, b, h) _Pragma("unroll") for (int n = 0; n < 2; ++n) _Pragma("unroll") for (int k = 0; k < 2; ++k) \
;     dst[n][k] = *reinterpret_cast<const bf16x8*>(smem + (((b) * 2 + (h)) * 16384 + n * 2048 + k * 1024) + boff)
; #define WAIT_V(n) asm volatile("s_waitcnt vmcnt(" #n ")" ::: "memory")
; #define BAR __builtin_amdgcn_s_barrier()
; #define SCHED __builtin_amdgcn_sched_barrier(0)
; template <class Epi, int NB>
; DEV void gemm_tile_nb(const bf16* __restrict__ A, int lda, long strideA, const bf16* __restrict__ Bt, int ldb, long strideB, int K, int brow, int bcol, Epi& epi) {
;     ...
;   const int wid = __builtin_amdgcn_readfirstlane(tidx_ >> 6), lane = tidx_ & 63, wr = wid >> 2, wc = wid & 3, fr = lane & 15, fq = lane >> 4;
;   f32x4 acc[2][2][4][2] = {};
;   bf16x8 At[4][2], B0[2][2], B1[2][2];
;   const int nt = K / BK;
;   const int lane_off_ = (fr * 64 + fq * 16) ^ ((fr >> 3) << 5);
;   const int aoff = wr * 8192 + lane_off_, boff = 65536 + wc * 4096 + lane_off_;
;   unsigned offA[2], offB[2];
; #pragma unroll
;   for (int _i = 0; _i < 2; ++_i) { int _r, _c; stage_rc(tidx_ * 16 + _i * 8192, _r, _c); offA[_i] = (unsigned)(_r * lda + _c); offB[_i] = (unsigned)(_r * ldb + _c); }
; #pragma unroll 1
;   for (int br = 0; br < NB; ++br) {
;   STAGE(SB(0, 0), Bt, ldb, bcol, 0); STAGE(SA(0, 0), A, lda, brow, 0);
;   STAGE(SB(0, 1), Bt, ldb, bcol + HALF, 0); STAGE(SA(0, 1), A, lda, brow + HALF, 0);
;   if (wr == 1) BAR;
;   WAIT_V(4); BAR;
;   STAGE(SB(1, 0), Bt, ldb, bcol, 1); STAGE(SA(1, 0), A, lda, brow, 1); STAGE(SB(1, 1), Bt, ldb, bcol + HALF, 1);
;   WAIT_V(6); BAR;
;   for (int t = 0; t < nt - 2; t += 2) {
;     LDB(B0, 0, 0); SCHED; LDA(At, 0, 0); STAGE(SA(1, 1), A, lda, brow + HALF, t + 1);
.LBB0_137:
	v_and_b32_e32 v143, 15, v23
	s_bfe_u32 s43, s55, 0x20006
	v_bfe_u32 v142, v23, 4, 2
	v_lshlrev_b32_e32 v0, 6, v143
	v_lshlrev_b32_e32 v23, 2, v23
	v_lshl_or_b32 v0, v142, 4, v0
	v_and_b32_e32 v23, 32, v23
	s_lshl_b32 s45, s54, 13
	s_lshl_b32 s56, s43, 12
	v_add_u32_e32 v153, s13, v16
	v_bitop3_b32 v24, v0, s56, v23 bitop3:0xde
	v_bitop3_b32 v23, v0, s45, v23 bitop3:0xde
	s_mov_b64 s[38:39], 0x80
	v_readfirstlane_b32 s45, v153
	v_add_u32_e32 v154, 0x2000, v153
	v_lshl_add_u64 v[2:3], v[2:3], 0, s[38:39]
	s_mov_b32 m0, s45
	v_readfirstlane_b32 s45, v154
	v_add_u32_e32 v155, 0x8000, v146
	s_waitcnt vmcnt(4)
	s_barrier
	global_load_lds_dwordx4 v[2:3], off
	v_lshl_add_u64 v[2:3], v[6:7], 0, s[38:39]
	s_mov_b32 m0, s45
	v_readfirstlane_b32 s45, v155
	v_add_u32_e32 v156, 0xa000, v146
	global_load_lds_dwordx4 v[2:3], off
	v_lshl_add_u64 v[2:3], v[12:13], 0, s[38:39]
	s_mov_b32 m0, s45
	v_readfirstlane_b32 s45, v156
	v_add_u32_e32 v157, s14, v16
	global_load_lds_dwordx4 v[2:3], off
	v_lshl_add_u64 v[2:3], v[8:9], 0, s[38:39]
	s_mov_b32 m0, s45
	v_readfirstlane_b32 s45, v157
	v_add_u32_e32 v158, 0x2000, v157
	global_load_lds_dwordx4 v[2:3], off
	v_lshl_add_u64 v[2:3], v[10:11], 0, s[38:39]
	s_mov_b32 m0, s45
	v_readfirstlane_b32 s45, v158
	global_load_lds_dwordx4 v[2:3], off
	v_lshl_add_u64 v[2:3], v[4:5], 0, s[38:39]
	s_mov_b32 m0, s45
	v_lshlrev_b32_e32 v0, 13, v14
	global_load_lds_dwordx4 v[2:3], off
	v_and_b32_e32 v0, 0xffffc000, v0
	v_lshl_add_u32 v0, v15, 10, v0
	v_or_b32_e32 v0, v0, v17
	v_add_u32_sdwa v0, v0, sext(v18) dst_sel:DWORD dst_unused:UNUSED_PAD src0_sel:DWORD src1_sel:WORD_0
	v_lshlrev_b64 v[2:3], 1, v[0:1]
	v_lshlrev_b32_e32 v0, 13, v19
	v_and_b32_e32 v0, 0xffffc000, v0
	v_readlane_b32 s8, v254, 63
	v_lshl_add_u32 v0, v20, 10, v0
	s_add_u32 s50, s8, s50
	v_or_b32_e32 v0, v0, v21
	s_waitcnt vmcnt(6)
	s_addc_u32 s51, 0, s51
	v_add_u32_sdwa v0, v0, sext(v22) dst_sel:DWORD dst_unused:UNUSED_PAD src0_sel:DWORD src1_sel:WORD_0
	v_or_b32_e32 v24, 0x10000, v24
	v_lshl_add_u64 v[134:135], s[50:51], 0, v[2:3]
	v_lshlrev_b64 v[4:5], 1, v[0:1]
	v_lshl_add_u64 v[138:139], s[48:49], 0, v[2:3]
	v_mov_b32_e32 v2, 0
	v_lshl_add_u64 v[136:137], s[50:51], 0, v[4:5]
	v_lshl_add_u64 v[140:141], s[48:49], 0, v[4:5]
	s_mov_b32 s45, -2
	v_add_u32_e32 v144, 0, v24
	v_add_u32_e32 v0, 0, v23
	v_mov_b32_e32 v3, v2
	v_mov_b32_e32 v4, v2
	v_mov_b32_e32 v5, v2
	v_mov_b32_e32 v6, v2
	v_mov_b32_e32 v7, v2
	v_mov_b32_e32 v8, v2
	v_mov_b32_e32 v9, v2
	v_mov_b32_e32 v10, v2
	v_mov_b32_e32 v11, v2
	v_mov_b32_e32 v12, v2
	v_mov_b32_e32 v13, v2
	v_mov_b32_e32 v14, v2
	v_mov_b32_e32 v15, v2
	v_mov_b32_e32 v16, v2
	v_mov_b32_e32 v17, v2
	v_mov_b32_e32 v18, v2
	v_mov_b32_e32 v19, v2
	v_mov_b32_e32 v20, v2
	v_mov_b32_e32 v21, v2
	v_mov_b32_e32 v22, v2
	v_mov_b32_e32 v23, v2
	v_mov_b32_e32 v24, v2
	v_mov_b32_e32 v25, v2
	v_mov_b32_e32 v26, v2
	v_mov_b32_e32 v27, v2
	v_mov_b32_e32 v28, v2
	v_mov_b32_e32 v29, v2
	v_mov_b32_e32 v30, v2
	v_mov_b32_e32 v31, v2
	v_mov_b32_e32 v32, v2
	v_mov_b32_e32 v33, v2
	v_mov_b32_e32 v34, v2
	v_mov_b32_e32 v35, v2
	v_mov_b32_e32 v36, v2
	v_mov_b32_e32 v37, v2
	v_mov_b32_e32 v38, v2
	v_mov_b32_e32 v39, v2
	v_mov_b32_e32 v40, v2
	v_mov_b32_e32 v41, v2
	v_mov_b32_e32 v42, v2
	v_mov_b32_e32 v43, v2
	v_mov_b32_e32 v44, v2
	v_mov_b32_e32 v45, v2
	v_mov_b32_e32 v46, v2
	v_mov_b32_e32 v47, v2
	v_mov_b32_e32 v48, v2
	v_mov_b32_e32 v49, v2
	v_mov_b32_e32 v50, v2
	v_mov_b32_e32 v51, v2
	v_mov_b32_e32 v52, v2
	v_mov_b32_e32 v53, v2
	v_mov_b32_e32 v54, v2
	v_mov_b32_e32 v55, v2
	v_mov_b32_e32 v56, v2
	v_mov_b32_e32 v57, v2
	v_mov_b32_e32 v58, v2
	v_mov_b32_e32 v59, v2
	v_mov_b32_e32 v60, v2
	v_mov_b32_e32 v61, v2
	v_mov_b32_e32 v62, v2
	v_mov_b32_e32 v63, v2
	v_mov_b32_e32 v64, v2
	v_mov_b32_e32 v65, v2
	v_mov_b32_e32 v70, v2
	v_mov_b32_e32 v71, v2
	v_mov_b32_e32 v72, v2
	v_mov_b32_e32 v73, v2
	v_mov_b32_e32 v86, v2
	v_mov_b32_e32 v87, v2
	v_mov_b32_e32 v88, v2
	v_mov_b32_e32 v89, v2
	v_mov_b32_e32 v90, v2
	v_mov_b32_e32 v91, v2
	v_mov_b32_e32 v92, v2
	v_mov_b32_e32 v93, v2
	v_mov_b32_e32 v94, v2
	v_mov_b32_e32 v95, v2
	v_mov_b32_e32 v96, v2
	v_mov_b32_e32 v97, v2
	v_mov_b32_e32 v98, v2
	v_mov_b32_e32 v99, v2
	v_mov_b32_e32 v100, v2
	v_mov_b32_e32 v101, v2
	v_mov_b32_e32 v102, v2
	v_mov_b32_e32 v103, v2
	v_mov_b32_e32 v104, v2
	v_mov_b32_e32 v105, v2
	v_mov_b32_e32 v106, v2
	v_mov_b32_e32 v107, v2
	v_mov_b32_e32 v108, v2
	v_mov_b32_e32 v109, v2
	v_mov_b32_e32 v110, v2
	v_mov_b32_e32 v111, v2
	v_mov_b32_e32 v112, v2
	v_mov_b32_e32 v113, v2
	v_mov_b32_e32 v114, v2
	v_mov_b32_e32 v115, v2
	v_mov_b32_e32 v116, v2
	v_mov_b32_e32 v117, v2
	v_mov_b32_e32 v118, v2
	v_mov_b32_e32 v119, v2
	v_mov_b32_e32 v120, v2
	v_mov_b32_e32 v121, v2
	v_mov_b32_e32 v122, v2
	v_mov_b32_e32 v123, v2
	v_mov_b32_e32 v124, v2
	v_mov_b32_e32 v125, v2
	v_mov_b32_e32 v126, v2
	v_mov_b32_e32 v127, v2
	v_mov_b32_e32 v128, v2
	v_mov_b32_e32 v129, v2
	v_mov_b32_e32 v66, v2
	v_mov_b32_e32 v67, v2
	v_mov_b32_e32 v68, v2
	v_mov_b32_e32 v69, v2
	v_mov_b32_e32 v74, v2
	v_mov_b32_e32 v75, v2
	v_mov_b32_e32 v76, v2
	v_mov_b32_e32 v77, v2
	v_mov_b32_e32 v78, v2
	v_mov_b32_e32 v79, v2
	v_mov_b32_e32 v80, v2
	v_mov_b32_e32 v81, v2
	v_mov_b32_e32 v82, v2
	v_mov_b32_e32 v83, v2
	v_mov_b32_e32 v84, v2
	v_mov_b32_e32 v85, v2
	s_mov_b64 s[38:39], 0x1e6e4080
	s_mov_b64 s[50:51], 0x2e80100
	s_mov_b64 s[56:57], 0x1e6a4100
	s_mov_b64 s[58:59], 0x2ec0100
	s_barrier
	ds_read_b128 v[162:165], v144
	ds_read_b128 v[166:169], v144 offset:1024
	ds_read_b128 v[170:173], v144 offset:2048
	ds_read_b128 v[174:177], v144 offset:3072
; #define STAGE(P, BASE, LD, br, kt) do { const bf16* _gb = BASE + ((long)(br) * (LD) + (long)(kt) * BK); \
;     _Pragma("unroll") for (int _i = 0; _i < 2; ++_i) { \
;       __builtin_amdgcn_global_load_lds((const unsigned*)(_gb + ((&LD == &lda) ? offA[_i] : offB[_i])), \
;         (unsigned*)((char*)(P) + tidx_ * 16 + _i * 8192), 16, 0, 0); } } while (0)
; #define LDA(dst, b, h) _Pragma("unroll") for (int m = 0; m < 4; ++m) _Pragma("unroll") for (int k = 0; k < 2; ++k) \
;     dst[m][k] = *reinterpret_cast<const bf16x8*>(smem + (((b) * 2 + (h)) * 16384 + m * 2048 + k * 1024) + aoff)
; #define LDB(dst, b, h) _Pragma("unroll") for (int n = 0; n < 2; ++n) _Pragma("unroll") for (int k = 0; k < 2; ++k) \
;     dst[n][k] = *reinterpret_cast<const bf16x8*>(smem + (((b) * 2 + (h)) * 16384 + n * 2048 + k * 1024) + boff)
; #define MMA(ai, bj, At_, Bt_) do { __builtin_amdgcn_s_setprio(1); \
;     _Pragma("unroll") for (int m = 0; m < 4; ++m) _Pragma("unroll") for (int n = 0; n < 2; ++n) _Pragma("unroll") for (int k = 0; k < 2; ++k) \
;       acc[ai][bj][m][n] = __builtin_amdgcn_mfma_f32_16x16x32_bf16(Bt_[n][k], At_[m][k], acc[ai][bj][m][n], 0, 0, 0); \
;     __builtin_amdgcn_s_setprio(0); } while (0)
; #define WAIT_V(n) asm volatile("s_waitcnt vmcnt(" #n ")" ::: "memory")
; #define WAIT_L(n) asm volatile("s_waitcnt lgkmcnt(" #n ")" ::: "memory")
; #define BAR __builtin_amdgcn_s_barrier()
; #define SCHED __builtin_amdgcn_sched_barrier(0)
; template <class Epi, int NB>
; DEV void gemm_tile_nb(const bf16* __restrict__ A, int lda, long strideA, const bf16* __restrict__ Bt, int ldb, long strideB, int K, int brow, int bcol, Epi& epi) {
;     ...
;   for (int t = 0; t < nt - 2; t += 2) {
;     LDB(B0, 0, 0); SCHED; LDA(At, 0, 0); STAGE(SA(1, 1), A, lda, brow + HALF, t + 1);
;     WAIT_L(8); BAR; WAIT_L(0); MMA(0, 0, At, B0); BAR; SCHED;
;     LDB(B1, 0, 1); STAGE(SB(0, 0), Bt, ldb, bcol, t + 2);
;     BAR; WAIT_L(0); MMA(0, 1, At, B1); BAR;
;     LDA(At, 0, 1); STAGE(SA(0, 0), A, lda, brow, t + 2);
;     BAR; WAIT_L(0); MMA(1, 0, At, B0); BAR; SCHED;
;     STAGE(SB(0, 1), Bt, ldb, bcol + HALF, t + 2);
;     WAIT_V(6); BAR; MMA(1, 1, At, B1); BAR;
.LBB0_138:
	v_add_u32_e32 v159, 0xc000, v146
	v_lshl_add_u64 v[204:205], s[88:89], 0, v[138:139]
	v_readfirstlane_b32 s48, v159
	v_lshl_add_u64 v[160:161], v[204:205], 0, s[38:39]
	s_mov_b32 m0, s48
	ds_read_b128 v[184:187], v0
	ds_read_b128 v[188:191], v0 offset:1024
	ds_read_b128 v[192:195], v0 offset:2048
	ds_read_b128 v[196:199], v0 offset:3072
	ds_read_b128 v[200:203], v0 offset:4096
	ds_read_b128 v[218:221], v0 offset:5120
	ds_read_b128 v[222:225], v0 offset:6144
	ds_read_b128 v[226:229], v0 offset:7168
	global_load_lds_dwordx4 v[160:161], off
	v_add_u32_e32 v160, 0xe000, v146
	v_lshl_add_u64 v[208:209], s[88:89], 0, v[140:141]
	v_readfirstlane_b32 s48, v160
	v_lshl_add_u64 v[214:215], v[208:209], 0, s[38:39]
	s_mov_b32 m0, s48
	s_nop 0
	global_load_lds_dwordx4 v[214:215], off
	s_waitcnt lgkmcnt(8)
	s_barrier
	s_waitcnt lgkmcnt(0)
	s_setprio 1
	s_waitcnt lgkmcnt(0)
	v_mfma_f32_16x16x32_bf16 v[126:129], v[162:165], v[184:187], v[126:129]
	v_mfma_f32_16x16x32_bf16 v[122:125], v[170:173], v[184:187], v[122:125]
	v_mfma_f32_16x16x32_bf16 v[118:121], v[162:165], v[192:195], v[118:121]
	v_mfma_f32_16x16x32_bf16 v[114:117], v[170:173], v[192:195], v[114:117]
	v_mfma_f32_16x16x32_bf16 v[110:113], v[162:165], v[200:203], v[110:113]
	v_mfma_f32_16x16x32_bf16 v[106:109], v[170:173], v[200:203], v[106:109]
	v_mfma_f32_16x16x32_bf16 v[102:105], v[162:165], v[222:225], v[102:105]
	v_mfma_f32_16x16x32_bf16 v[98:101], v[170:173], v[222:225], v[98:101]
	v_mfma_f32_16x16x32_bf16 v[126:129], v[166:169], v[188:191], v[126:129]
	v_mfma_f32_16x16x32_bf16 v[122:125], v[174:177], v[188:191], v[122:125]
	v_mfma_f32_16x16x32_bf16 v[118:121], v[166:169], v[196:199], v[118:121]
	v_mfma_f32_16x16x32_bf16 v[114:117], v[174:177], v[196:199], v[114:117]
	v_mfma_f32_16x16x32_bf16 v[110:113], v[166:169], v[218:221], v[110:113]
	v_mfma_f32_16x16x32_bf16 v[106:109], v[174:177], v[218:221], v[106:109]
	v_mfma_f32_16x16x32_bf16 v[102:105], v[166:169], v[226:229], v[102:105]
	v_mfma_f32_16x16x32_bf16 v[98:101], v[174:177], v[226:229], v[98:101]
	s_setprio 0
	s_barrier
	v_lshl_add_u64 v[214:215], s[88:89], 0, v[134:135]
	v_readfirstlane_b32 s48, v145
	v_lshl_add_u64 v[246:247], v[214:215], 0, s[50:51]
	s_mov_b32 m0, s48
	ds_read_b128 v[230:233], v144 offset:16384
	ds_read_b128 v[234:237], v144 offset:17408
	ds_read_b128 v[238:241], v144 offset:18432
	ds_read_b128 v[242:245], v144 offset:19456
	global_load_lds_dwordx4 v[246:247], off
	v_lshl_add_u64 v[246:247], s[88:89], 0, v[136:137]
	v_readfirstlane_b32 s48, v148
	v_lshl_add_u64 v[248:249], v[246:247], 0, s[50:51]
	s_mov_b32 m0, s48
	s_nop 0
	global_load_lds_dwordx4 v[248:249], off
	s_barrier
	s_waitcnt lgkmcnt(0)
	s_setprio 1
	s_waitcnt lgkmcnt(0)
	v_mfma_f32_16x16x32_bf16 v[94:97], v[230:233], v[184:187], v[94:97]
	v_mfma_f32_16x16x32_bf16 v[90:93], v[238:241], v[184:187], v[90:93]
	v_mfma_f32_16x16x32_bf16 v[86:89], v[230:233], v[192:195], v[86:89]
	v_mfma_f32_16x16x32_bf16 v[70:73], v[238:241], v[192:195], v[70:73]
	v_mfma_f32_16x16x32_bf16 v[62:65], v[230:233], v[200:203], v[62:65]
	v_mfma_f32_16x16x32_bf16 v[58:61], v[238:241], v[200:203], v[58:61]
	v_mfma_f32_16x16x32_bf16 v[54:57], v[230:233], v[222:225], v[54:57]
	v_mfma_f32_16x16x32_bf16 v[50:53], v[238:241], v[222:225], v[50:53]
	v_mfma_f32_16x16x32_bf16 v[94:97], v[234:237], v[188:191], v[94:97]
	v_mfma_f32_16x16x32_bf16 v[90:93], v[242:245], v[188:191], v[90:93]
	v_mfma_f32_16x16x32_bf16 v[86:89], v[234:237], v[196:199], v[86:89]
	v_mfma_f32_16x16x32_bf16 v[70:73], v[242:245], v[196:199], v[70:73]
	v_mfma_f32_16x16x32_bf16 v[62:65], v[234:237], v[218:221], v[62:65]
	v_mfma_f32_16x16x32_bf16 v[58:61], v[242:245], v[218:221], v[58:61]
	v_mfma_f32_16x16x32_bf16 v[54:57], v[234:237], v[226:229], v[54:57]
	v_mfma_f32_16x16x32_bf16 v[50:53], v[242:245], v[226:229], v[50:53]
	s_setprio 0
	v_readfirstlane_b32 s48, v146
	v_lshl_add_u64 v[248:249], v[204:205], 0, s[56:57]
	s_mov_b32 m0, s48
	v_readfirstlane_b32 s48, v150
	s_barrier
	ds_read_b128 v[184:187], v0 offset:16384
	ds_read_b128 v[188:191], v0 offset:17408
	ds_read_b128 v[192:195], v0 offset:18432
	ds_read_b128 v[196:199], v0 offset:19456
	ds_read_b128 v[200:203], v0 offset:20480
	ds_read_b128 v[218:221], v0 offset:21504
	ds_read_b128 v[222:225], v0 offset:22528
	ds_read_b128 v[226:229], v0 offset:23552
	global_load_lds_dwordx4 v[248:249], off
	v_lshl_add_u64 v[248:249], v[208:209], 0, s[56:57]
	s_mov_b32 m0, s48
	s_nop 0
	global_load_lds_dwordx4 v[248:249], off
	s_waitcnt vmcnt(10)
	s_barrier
	s_waitcnt lgkmcnt(0)
	s_setprio 1
	s_waitcnt lgkmcnt(0)
	v_mfma_f32_16x16x32_bf16 v[46:49], v[162:165], v[184:187], v[46:49]
	v_mfma_f32_16x16x32_bf16 v[42:45], v[170:173], v[184:187], v[42:45]
	v_mfma_f32_16x16x32_bf16 v[38:41], v[162:165], v[192:195], v[38:41]
	v_mfma_f32_16x16x32_bf16 v[34:37], v[170:173], v[192:195], v[34:37]
	v_mfma_f32_16x16x32_bf16 v[30:33], v[162:165], v[200:203], v[30:33]
	v_mfma_f32_16x16x32_bf16 v[26:29], v[170:173], v[200:203], v[26:29]
	v_mfma_f32_16x16x32_bf16 v[22:25], v[162:165], v[222:225], v[22:25]
	v_mfma_f32_16x16x32_bf16 v[18:21], v[170:173], v[222:225], v[18:21]
	v_mfma_f32_16x16x32_bf16 v[46:49], v[166:169], v[188:191], v[46:49]
	v_mfma_f32_16x16x32_bf16 v[42:45], v[174:177], v[188:191], v[42:45]
	v_mfma_f32_16x16x32_bf16 v[38:41], v[166:169], v[196:199], v[38:41]
	v_mfma_f32_16x16x32_bf16 v[34:37], v[174:177], v[196:199], v[34:37]
	v_mfma_f32_16x16x32_bf16 v[30:33], v[166:169], v[218:221], v[30:33]
	v_mfma_f32_16x16x32_bf16 v[26:29], v[174:177], v[218:221], v[26:29]
	v_mfma_f32_16x16x32_bf16 v[22:25], v[166:169], v[226:229], v[22:25]
	v_mfma_f32_16x16x32_bf16 v[18:21], v[174:177], v[226:229], v[18:21]
	s_setprio 0
	s_barrier
; #define STAGE(P, BASE, LD, br, kt) do { const bf16* _gb = BASE + ((long)(br) * (LD) + (long)(kt) * BK); \
;     _Pragma("unroll") for (int _i = 0; _i < 2; ++_i) { \
;       __builtin_amdgcn_global_load_lds((const unsigned*)(_gb + ((&LD == &lda) ? offA[_i] : offB[_i])), \
;         (unsigned*)((char*)(P) + tidx_ * 16 + _i * 8192), 16, 0, 0); } } while (0)
; #define LDA(dst, b, h) _Pragma("unroll") for (int m = 0; m < 4; ++m) _Pragma("unroll") for (int k = 0; k < 2; ++k) \
;     dst[m][k] = *reinterpret_cast<const bf16x8*>(smem + (((b) * 2 + (h)) * 16384 + m * 2048 + k * 1024) + aoff)
; #define LDB(dst, b, h) _Pragma("unroll") for (int n = 0; n < 2; ++n) _Pragma("unroll") for (int k = 0; k < 2; ++k) \
;     dst[n][k] = *reinterpret_cast<const bf16x8*>(smem + (((b) * 2 + (h)) * 16384 + n * 2048 + k * 1024) + boff)
; #define MMA(ai, bj, At_, Bt_) do { __builtin_amdgcn_s_setprio(1); \
;     _Pragma("unroll") for (int m = 0; m < 4; ++m) _Pragma("unroll") for (int n = 0; n < 2; ++n) _Pragma("unroll") for (int k = 0; k < 2; ++k) \
;       acc[ai][bj][m][n] = __builtin_amdgcn_mfma_f32_16x16x32_bf16(Bt_[n][k], At_[m][k], acc[ai][bj][m][n], 0, 0, 0); \
;     __builtin_amdgcn_s_setprio(0); } while (0)
; #define WAIT_V(n) asm volatile("s_waitcnt vmcnt(" #n ")" ::: "memory")
; #define WAIT_L(n) asm volatile("s_waitcnt lgkmcnt(" #n ")" ::: "memory")
; #define BAR __builtin_amdgcn_s_barrier()
; #define SCHED __builtin_amdgcn_sched_barrier(0)
; template <class Epi, int NB>
; DEV void gemm_tile_nb(const bf16* __restrict__ A, int lda, long strideA, const bf16* __restrict__ Bt, int ldb, long strideB, int K, int brow, int bcol, Epi& epi) {
;     ...
;     STAGE(SB(0, 1), Bt, ldb, bcol + HALF, t + 2);
;     WAIT_V(6); BAR; MMA(1, 1, At, B1); BAR;
;     LDB(B0, 1, 0); SCHED; LDA(At, 1, 0); STAGE(SA(0, 1), A, lda, brow + HALF, t + 2);
;     WAIT_L(8); BAR; WAIT_L(0); MMA(0, 0, At, B0); BAR; SCHED;
;     LDB(B1, 1, 1); STAGE(SB(1, 0), Bt, ldb, bcol, t + 3);
;     BAR; WAIT_L(0); MMA(0, 1, At, B1); BAR;
;     LDA(At, 1, 1); STAGE(SA(1, 0), A, lda, brow, t + 3);
;     BAR; WAIT_L(0); MMA(1, 0, At, B0); BAR; SCHED;
	v_readfirstlane_b32 s48, v147
	v_lshl_add_u64 v[162:163], v[214:215], 0, s[58:59]
	s_mov_b32 m0, s48
	v_readfirstlane_b32 s48, v151
	global_load_lds_dwordx4 v[162:163], off
	v_lshl_add_u64 v[162:163], v[246:247], 0, s[58:59]
	s_mov_b32 m0, s48
	s_nop 0
	global_load_lds_dwordx4 v[162:163], off
	ds_read_b128 v[162:165], v144 offset:32768
	ds_read_b128 v[166:169], v144 offset:33792
	ds_read_b128 v[170:173], v144 offset:34816
	ds_read_b128 v[174:177], v144 offset:35840
	s_waitcnt vmcnt(6)
	s_barrier
	s_setprio 1
	v_mfma_f32_16x16x32_bf16 v[14:17], v[230:233], v[184:187], v[14:17]
	v_mfma_f32_16x16x32_bf16 v[10:13], v[238:241], v[184:187], v[10:13]
	v_mfma_f32_16x16x32_bf16 v[6:9], v[230:233], v[192:195], v[6:9]
	v_mfma_f32_16x16x32_bf16 v[2:5], v[238:241], v[192:195], v[2:5]
	v_mfma_f32_16x16x32_bf16 v[66:69], v[230:233], v[200:203], v[66:69]
	v_mfma_f32_16x16x32_bf16 v[74:77], v[238:241], v[200:203], v[74:77]
	v_mfma_f32_16x16x32_bf16 v[78:81], v[230:233], v[222:225], v[78:81]
	v_mfma_f32_16x16x32_bf16 v[82:85], v[238:241], v[222:225], v[82:85]
	v_mfma_f32_16x16x32_bf16 v[14:17], v[234:237], v[188:191], v[14:17]
	v_mfma_f32_16x16x32_bf16 v[10:13], v[242:245], v[188:191], v[10:13]
	v_mfma_f32_16x16x32_bf16 v[6:9], v[234:237], v[196:199], v[6:9]
	v_mfma_f32_16x16x32_bf16 v[2:5], v[242:245], v[196:199], v[2:5]
	v_mfma_f32_16x16x32_bf16 v[66:69], v[234:237], v[218:221], v[66:69]
	v_mfma_f32_16x16x32_bf16 v[74:77], v[242:245], v[218:221], v[74:77]
	v_mfma_f32_16x16x32_bf16 v[78:81], v[234:237], v[226:229], v[78:81]
	v_mfma_f32_16x16x32_bf16 v[82:85], v[242:245], v[226:229], v[82:85]
	s_setprio 0
	s_barrier
	v_readfirstlane_b32 s48, v149
	v_lshl_add_u64 v[230:231], v[204:205], 0, s[16:17]
	s_mov_b32 m0, s48
	v_readfirstlane_b32 s48, v152
	ds_read_b128 v[184:187], v0 offset:32768
	ds_read_b128 v[188:191], v0 offset:33792
	ds_read_b128 v[192:195], v0 offset:34816
	ds_read_b128 v[196:199], v0 offset:35840
	ds_read_b128 v[200:203], v0 offset:36864
	ds_read_b128 v[218:221], v0 offset:37888
	ds_read_b128 v[222:225], v0 offset:38912
	ds_read_b128 v[226:229], v0 offset:39936
	global_load_lds_dwordx4 v[230:231], off
	v_lshl_add_u64 v[230:231], v[208:209], 0, s[16:17]
	s_mov_b32 m0, s48
	s_nop 0
	global_load_lds_dwordx4 v[230:231], off
	s_waitcnt lgkmcnt(8)
	s_barrier
	s_waitcnt lgkmcnt(0)
	s_setprio 1
	s_waitcnt lgkmcnt(0)
	v_mfma_f32_16x16x32_bf16 v[126:129], v[162:165], v[184:187], v[126:129]
	v_mfma_f32_16x16x32_bf16 v[122:125], v[170:173], v[184:187], v[122:125]
	v_mfma_f32_16x16x32_bf16 v[118:121], v[162:165], v[192:195], v[118:121]
	v_mfma_f32_16x16x32_bf16 v[114:117], v[170:173], v[192:195], v[114:117]
	v_mfma_f32_16x16x32_bf16 v[110:113], v[162:165], v[200:203], v[110:113]
	v_mfma_f32_16x16x32_bf16 v[106:109], v[170:173], v[200:203], v[106:109]
	v_mfma_f32_16x16x32_bf16 v[102:105], v[162:165], v[222:225], v[102:105]
	v_mfma_f32_16x16x32_bf16 v[98:101], v[170:173], v[222:225], v[98:101]
	v_mfma_f32_16x16x32_bf16 v[126:129], v[166:169], v[188:191], v[126:129]
	v_mfma_f32_16x16x32_bf16 v[122:125], v[174:177], v[188:191], v[122:125]
	v_mfma_f32_16x16x32_bf16 v[118:121], v[166:169], v[196:199], v[118:121]
	v_mfma_f32_16x16x32_bf16 v[114:117], v[174:177], v[196:199], v[114:117]
	v_mfma_f32_16x16x32_bf16 v[110:113], v[166:169], v[218:221], v[110:113]
	v_mfma_f32_16x16x32_bf16 v[106:109], v[174:177], v[218:221], v[106:109]
	v_mfma_f32_16x16x32_bf16 v[102:105], v[166:169], v[226:229], v[102:105]
	v_mfma_f32_16x16x32_bf16 v[98:101], v[174:177], v[226:229], v[98:101]
	s_setprio 0
	s_barrier
	v_readfirstlane_b32 s48, v153
	v_lshl_add_u64 v[248:249], v[214:215], 0, s[36:37]
	s_mov_b32 m0, s48
	v_readfirstlane_b32 s48, v154
	ds_read_b128 v[230:233], v144 offset:49152
	ds_read_b128 v[234:237], v144 offset:50176
	ds_read_b128 v[238:241], v144 offset:51200
	ds_read_b128 v[242:245], v144 offset:52224
	global_load_lds_dwordx4 v[248:249], off
	v_lshl_add_u64 v[248:249], v[246:247], 0, s[36:37]
	s_mov_b32 m0, s48
	s_nop 0
	global_load_lds_dwordx4 v[248:249], off
	s_barrier
	s_waitcnt lgkmcnt(0)
	s_setprio 1
	s_waitcnt lgkmcnt(0)
	v_mfma_f32_16x16x32_bf16 v[94:97], v[230:233], v[184:187], v[94:97]
	v_mfma_f32_16x16x32_bf16 v[90:93], v[238:241], v[184:187], v[90:93]
	v_mfma_f32_16x16x32_bf16 v[86:89], v[230:233], v[192:195], v[86:89]
	v_mfma_f32_16x16x32_bf16 v[70:73], v[238:241], v[192:195], v[70:73]
	v_mfma_f32_16x16x32_bf16 v[62:65], v[230:233], v[200:203], v[62:65]
	v_mfma_f32_16x16x32_bf16 v[58:61], v[238:241], v[200:203], v[58:61]
	v_mfma_f32_16x16x32_bf16 v[54:57], v[230:233], v[222:225], v[54:57]
	v_mfma_f32_16x16x32_bf16 v[50:53], v[238:241], v[222:225], v[50:53]
	v_mfma_f32_16x16x32_bf16 v[94:97], v[234:237], v[188:191], v[94:97]
	v_mfma_f32_16x16x32_bf16 v[90:93], v[242:245], v[188:191], v[90:93]
	v_mfma_f32_16x16x32_bf16 v[86:89], v[234:237], v[196:199], v[86:89]
	v_mfma_f32_16x16x32_bf16 v[70:73], v[242:245], v[196:199], v[70:73]
	v_mfma_f32_16x16x32_bf16 v[62:65], v[234:237], v[218:221], v[62:65]
	v_mfma_f32_16x16x32_bf16 v[58:61], v[242:245], v[218:221], v[58:61]
	v_mfma_f32_16x16x32_bf16 v[54:57], v[234:237], v[226:229], v[54:57]
	v_mfma_f32_16x16x32_bf16 v[50:53], v[242:245], v[226:229], v[50:53]
	s_setprio 0
	v_readfirstlane_b32 s48, v155
	v_lshl_add_u64 v[204:205], v[204:205], 0, s[18:19]
	s_mov_b32 m0, s48
	v_readfirstlane_b32 s48, v156
	s_barrier
	ds_read_b128 v[184:187], v0 offset:49152
	ds_read_b128 v[188:191], v0 offset:50176
	ds_read_b128 v[192:195], v0 offset:51200
	ds_read_b128 v[196:199], v0 offset:52224
	ds_read_b128 v[200:203], v0 offset:53248
	ds_read_b128 v[218:221], v0 offset:54272
	ds_read_b128 v[222:225], v0 offset:55296
	ds_read_b128 v[226:229], v0 offset:56320
	global_load_lds_dwordx4 v[204:205], off
	v_lshl_add_u64 v[204:205], v[208:209], 0, s[18:19]
	s_mov_b32 m0, s48
	s_nop 0
	global_load_lds_dwordx4 v[204:205], off
	s_waitcnt vmcnt(10)
	s_barrier
; #define STAGE(P, BASE, LD, br, kt) do { const bf16* _gb = BASE + ((long)(br) * (LD) + (long)(kt) * BK); \
;     _Pragma("unroll") for (int _i = 0; _i < 2; ++_i) { \
;       __builtin_amdgcn_global_load_lds((const unsigned*)(_gb + ((&LD == &lda) ? offA[_i] : offB[_i])), \
;         (unsigned*)((char*)(P) + tidx_ * 16 + _i * 8192), 16, 0, 0); } } while (0)
; #define LDA(dst, b, h) _Pragma("unroll") for (int m = 0; m < 4; ++m) _Pragma("unroll") for (int k = 0; k < 2; ++k) \
;     dst[m][k] = *reinterpret_cast<const bf16x8*>(smem + (((b) * 2 + (h)) * 16384 + m * 2048 + k * 1024) + aoff)
; #define LDB(dst, b, h) _Pragma("unroll") for (int n = 0; n < 2; ++n) _Pragma("unroll") for (int k = 0; k < 2; ++k) \
;     dst[n][k] = *reinterpret_cast<const bf16x8*>(smem + (((b) * 2 + (h)) * 16384 + n * 2048 + k * 1024) + boff)
; #define MMA(ai, bj, At_, Bt_) do { __builtin_amdgcn_s_setprio(1); \
;     _Pragma("unroll") for (int m = 0; m < 4; ++m) _Pragma("unroll") for (int n = 0; n < 2; ++n) _Pragma("unroll") for (int k = 0; k < 2; ++k) \
;       acc[ai][bj][m][n] = __builtin_amdgcn_mfma_f32_16x16x32_bf16(Bt_[n][k], At_[m][k], acc[ai][bj][m][n], 0, 0, 0); \
;     __builtin_amdgcn_s_setprio(0); } while (0)
; #define WAIT_V(n) asm volatile("s_waitcnt vmcnt(" #n ")" ::: "memory")
; #define WAIT_L(n) asm volatile("s_waitcnt lgkmcnt(" #n ")" ::: "memory")
; #define BAR __builtin_amdgcn_s_barrier()
; template <class Epi, int NB>
; DEV void gemm_tile_nb(const bf16* __restrict__ A, int lda, long strideA, const bf16* __restrict__ Bt, int ldb, long strideB, int K, int brow, int bcol, Epi& epi) {
;     ...
;     STAGE(SB(1, 1), Bt, ldb, bcol + HALF, t + 3);
;     WAIT_V(6); BAR; MMA(1, 1, At, B1); BAR;
;   }
;   { LDB(B0, 0, 0); LDA(At, 0, 0); STAGE(SA(1, 1), A, lda, brow + HALF, nt - 1);
;     BAR; WAIT_L(0); MMA(0, 0, At, B0); BAR;
;     LDB(B1, 0, 1); BAR; WAIT_L(0); MMA(0, 1, At, B1); BAR;
;     LDA(At, 0, 1); WAIT_V(4); BAR; WAIT_L(0); MMA(1, 0, At, B0); MMA(1, 1, At, B1); BAR; }
;   { LDB(B0, 1, 0); LDA(At, 1, 0); WAIT_V(2); BAR; WAIT_L(0); MMA(0, 0, At, B0); BAR;
	s_waitcnt lgkmcnt(0)
	s_setprio 1
	s_waitcnt lgkmcnt(0)
	v_mfma_f32_16x16x32_bf16 v[46:49], v[162:165], v[184:187], v[46:49]
	v_mfma_f32_16x16x32_bf16 v[42:45], v[170:173], v[184:187], v[42:45]
	v_mfma_f32_16x16x32_bf16 v[38:41], v[162:165], v[192:195], v[38:41]
	v_mfma_f32_16x16x32_bf16 v[34:37], v[170:173], v[192:195], v[34:37]
	v_mfma_f32_16x16x32_bf16 v[30:33], v[162:165], v[200:203], v[30:33]
	v_mfma_f32_16x16x32_bf16 v[26:29], v[170:173], v[200:203], v[26:29]
	v_mfma_f32_16x16x32_bf16 v[22:25], v[162:165], v[222:225], v[22:25]
	v_mfma_f32_16x16x32_bf16 v[18:21], v[170:173], v[222:225], v[18:21]
	v_mfma_f32_16x16x32_bf16 v[46:49], v[166:169], v[188:191], v[46:49]
	v_mfma_f32_16x16x32_bf16 v[42:45], v[174:177], v[188:191], v[42:45]
	v_mfma_f32_16x16x32_bf16 v[38:41], v[166:169], v[196:199], v[38:41]
	v_mfma_f32_16x16x32_bf16 v[34:37], v[174:177], v[196:199], v[34:37]
	v_mfma_f32_16x16x32_bf16 v[30:33], v[166:169], v[218:221], v[30:33]
	v_mfma_f32_16x16x32_bf16 v[26:29], v[174:177], v[218:221], v[26:29]
	v_mfma_f32_16x16x32_bf16 v[22:25], v[166:169], v[226:229], v[22:25]
	v_mfma_f32_16x16x32_bf16 v[18:21], v[174:177], v[226:229], v[18:21]
	s_setprio 0
	s_barrier
	v_readfirstlane_b32 s48, v157
	v_lshl_add_u64 v[162:163], v[214:215], 0, s[22:23]
	s_mov_b32 m0, s48
	v_readfirstlane_b32 s48, v158
	global_load_lds_dwordx4 v[162:163], off
	v_lshl_add_u64 v[162:163], v[246:247], 0, s[22:23]
	s_mov_b32 m0, s48
	s_nop 0
	global_load_lds_dwordx4 v[162:163], off
	ds_read_b128 v[162:165], v144
	ds_read_b128 v[166:169], v144 offset:1024
	ds_read_b128 v[170:173], v144 offset:2048
	ds_read_b128 v[174:177], v144 offset:3072
	s_waitcnt vmcnt(6)
	s_barrier
	s_setprio 1
	v_mfma_f32_16x16x32_bf16 v[14:17], v[230:233], v[184:187], v[14:17]
	v_mfma_f32_16x16x32_bf16 v[10:13], v[238:241], v[184:187], v[10:13]
	v_mfma_f32_16x16x32_bf16 v[6:9], v[230:233], v[192:195], v[6:9]
	v_mfma_f32_16x16x32_bf16 v[2:5], v[238:241], v[192:195], v[2:5]
	v_mfma_f32_16x16x32_bf16 v[66:69], v[230:233], v[200:203], v[66:69]
	v_mfma_f32_16x16x32_bf16 v[74:77], v[238:241], v[200:203], v[74:77]
	v_mfma_f32_16x16x32_bf16 v[78:81], v[230:233], v[222:225], v[78:81]
	v_mfma_f32_16x16x32_bf16 v[82:85], v[238:241], v[222:225], v[82:85]
	v_mfma_f32_16x16x32_bf16 v[14:17], v[234:237], v[188:191], v[14:17]
	v_mfma_f32_16x16x32_bf16 v[10:13], v[242:245], v[188:191], v[10:13]
	v_mfma_f32_16x16x32_bf16 v[6:9], v[234:237], v[196:199], v[6:9]
	v_mfma_f32_16x16x32_bf16 v[2:5], v[242:245], v[196:199], v[2:5]
	v_mfma_f32_16x16x32_bf16 v[66:69], v[234:237], v[218:221], v[66:69]
	v_mfma_f32_16x16x32_bf16 v[74:77], v[242:245], v[218:221], v[74:77]
	v_mfma_f32_16x16x32_bf16 v[78:81], v[234:237], v[226:229], v[78:81]
	v_mfma_f32_16x16x32_bf16 v[82:85], v[242:245], v[226:229], v[82:85]
	s_setprio 0
	s_add_i32 s45, s45, 2
	v_lshl_add_u64 v[134:135], v[134:135], 0, s[72:73]
	v_lshl_add_u64 v[136:137], v[136:137], 0, s[72:73]
	v_lshl_add_u64 v[138:139], v[138:139], 0, s[72:73]
	s_cmp_gt_u32 s45, 11
	v_lshl_add_u64 v[140:141], v[140:141], 0, s[72:73]
	s_barrier
	s_cbranch_scc0 .LBB0_138
	s_mov_b64 s[38:39], 0x780
	v_readfirstlane_b32 s45, v159
	v_lshl_add_u64 v[132:133], v[132:133], 0, s[38:39]
	s_mov_b32 m0, s45
	v_readfirstlane_b32 s45, v160
	ds_read_b128 v[134:137], v144
	ds_read_b128 v[138:141], v144 offset:1024
	ds_read_b128 v[146:149], v144 offset:2048
	ds_read_b128 v[150:153], v144 offset:3072
	ds_read_b128 v[154:157], v0
	ds_read_b128 v[162:165], v0 offset:1024
	ds_read_b128 v[166:169], v0 offset:2048
	ds_read_b128 v[170:173], v0 offset:3072
	ds_read_b128 v[174:177], v0 offset:4096
	ds_read_b128 v[184:187], v0 offset:5120
	ds_read_b128 v[188:191], v0 offset:6144
	ds_read_b128 v[192:195], v0 offset:7168
	global_load_lds_dwordx4 v[132:133], off
	v_lshl_add_u64 v[130:131], v[130:131], 0, s[38:39]
	s_mov_b32 m0, s45
	s_cmpk_lt_u32 s55, 0x100
	global_load_lds_dwordx4 v[130:131], off
	s_barrier
	s_waitcnt lgkmcnt(0)
	s_setprio 1
	s_waitcnt lgkmcnt(0)
	v_mfma_f32_16x16x32_bf16 v[126:129], v[134:137], v[154:157], v[126:129]
	v_mfma_f32_16x16x32_bf16 v[118:121], v[134:137], v[166:169], v[118:121]
	v_mfma_f32_16x16x32_bf16 v[110:113], v[134:137], v[174:177], v[110:113]
	v_mfma_f32_16x16x32_bf16 v[102:105], v[134:137], v[188:191], v[102:105]
	v_mfma_f32_16x16x32_bf16 v[98:101], v[146:149], v[188:191], v[98:101]
	v_mfma_f32_16x16x32_bf16 v[126:129], v[138:141], v[162:165], v[126:129]
	v_mfma_f32_16x16x32_bf16 v[122:125], v[146:149], v[154:157], v[122:125]
	v_mfma_f32_16x16x32_bf16 v[118:121], v[138:141], v[170:173], v[118:121]
	v_mfma_f32_16x16x32_bf16 v[114:117], v[146:149], v[166:169], v[114:117]
	v_mfma_f32_16x16x32_bf16 v[110:113], v[138:141], v[184:187], v[110:113]
	v_mfma_f32_16x16x32_bf16 v[106:109], v[146:149], v[174:177], v[106:109]
	v_mfma_f32_16x16x32_bf16 v[102:105], v[138:141], v[192:195], v[102:105]
	v_mfma_f32_16x16x32_bf16 v[98:101], v[150:153], v[192:195], v[98:101]
	v_mfma_f32_16x16x32_bf16 v[130:133], v[150:153], v[162:165], v[122:125]
	v_mfma_f32_16x16x32_bf16 v[158:161], v[150:153], v[170:173], v[114:117]
	v_mfma_f32_16x16x32_bf16 v[196:199], v[150:153], v[184:187], v[106:109]
	s_setprio 0
	s_barrier
	s_nop 0
	ds_read_b128 v[106:109], v144 offset:16384
	ds_read_b128 v[114:117], v144 offset:17408
	ds_read_b128 v[122:125], v144 offset:18432
	ds_read_b128 v[200:203], v144 offset:19456
	s_barrier
; #define LDA(dst, b, h) _Pragma("unroll") for (int m = 0; m < 4; ++m) _Pragma("unroll") for (int k = 0; k < 2; ++k) \
;     dst[m][k] = *reinterpret_cast<const bf16x8*>(smem + (((b) * 2 + (h)) * 16384 + m * 2048 + k * 1024) + aoff)
; #define LDB(dst, b, h) _Pragma("unroll") for (int n = 0; n < 2; ++n) _Pragma("unroll") for (int k = 0; k < 2; ++k) \
;     dst[n][k] = *reinterpret_cast<const bf16x8*>(smem + (((b) * 2 + (h)) * 16384 + n * 2048 + k * 1024) + boff)
; #define MMA(ai, bj, At_, Bt_) do { __builtin_amdgcn_s_setprio(1); \
;     _Pragma("unroll") for (int m = 0; m < 4; ++m) _Pragma("unroll") for (int n = 0; n < 2; ++n) _Pragma("unroll") for (int k = 0; k < 2; ++k) \
;       acc[ai][bj][m][n] = __builtin_amdgcn_mfma_f32_16x16x32_bf16(Bt_[n][k], At_[m][k], acc[ai][bj][m][n], 0, 0, 0); \
;     __builtin_amdgcn_s_setprio(0); } while (0)
; #define WAIT_V(n) asm volatile("s_waitcnt vmcnt(" #n ")" ::: "memory")
; #define WAIT_L(n) asm volatile("s_waitcnt lgkmcnt(" #n ")" ::: "memory")
; #define BAR __builtin_amdgcn_s_barrier()
; template <class Epi, int NB>
; DEV void gemm_tile_nb(const bf16* __restrict__ A, int lda, long strideA, const bf16* __restrict__ Bt, int ldb, long strideB, int K, int brow, int bcol, Epi& epi) {
;     ...
;     LDB(B1, 0, 1); BAR; WAIT_L(0); MMA(0, 1, At, B1); BAR;
;     LDA(At, 0, 1); WAIT_V(4); BAR; WAIT_L(0); MMA(1, 0, At, B0); MMA(1, 1, At, B1); BAR; }
;   { LDB(B0, 1, 0); LDA(At, 1, 0); WAIT_V(2); BAR; WAIT_L(0); MMA(0, 0, At, B0); BAR;
	s_waitcnt lgkmcnt(0)
	s_setprio 1
	s_waitcnt lgkmcnt(0)
	v_mfma_f32_16x16x32_bf16 v[86:89], v[106:109], v[166:169], v[86:89]
	v_mfma_f32_16x16x32_bf16 v[70:73], v[122:125], v[166:169], v[70:73]
	v_mfma_f32_16x16x32_bf16 v[62:65], v[106:109], v[174:177], v[62:65]
	v_mfma_f32_16x16x32_bf16 v[58:61], v[122:125], v[174:177], v[58:61]
	v_mfma_f32_16x16x32_bf16 v[54:57], v[106:109], v[188:191], v[54:57]
	v_mfma_f32_16x16x32_bf16 v[50:53], v[122:125], v[188:191], v[50:53]
	v_mfma_f32_16x16x32_bf16 v[94:97], v[106:109], v[154:157], v[94:97]
	v_mfma_f32_16x16x32_bf16 v[90:93], v[122:125], v[154:157], v[90:93]
	v_mfma_f32_16x16x32_bf16 v[86:89], v[114:117], v[170:173], v[86:89]
	v_mfma_f32_16x16x32_bf16 v[70:73], v[200:203], v[170:173], v[70:73]
	v_mfma_f32_16x16x32_bf16 v[62:65], v[114:117], v[184:187], v[62:65]
	v_mfma_f32_16x16x32_bf16 v[58:61], v[200:203], v[184:187], v[58:61]
	v_mfma_f32_16x16x32_bf16 v[54:57], v[114:117], v[192:195], v[54:57]
	v_mfma_f32_16x16x32_bf16 v[50:53], v[200:203], v[192:195], v[50:53]
	v_mfma_f32_16x16x32_bf16 v[218:221], v[114:117], v[162:165], v[94:97]
	v_mfma_f32_16x16x32_bf16 v[154:157], v[200:203], v[162:165], v[90:93]
	s_setprio 0
	s_barrier
	s_nop 0
	ds_read_b128 v[90:93], v0 offset:16384
	ds_read_b128 v[94:97], v0 offset:17408
	ds_read_b128 v[162:165], v0 offset:18432
	ds_read_b128 v[166:169], v0 offset:19456
	ds_read_b128 v[170:173], v0 offset:20480
	ds_read_b128 v[174:177], v0 offset:21504
	ds_read_b128 v[184:187], v0 offset:22528
	ds_read_b128 v[188:191], v0 offset:23552
	s_waitcnt vmcnt(4)
	s_barrier
	s_waitcnt lgkmcnt(0)
	s_setprio 1
	s_waitcnt lgkmcnt(0)
	v_mfma_f32_16x16x32_bf16 v[46:49], v[134:137], v[90:93], v[46:49]
	v_mfma_f32_16x16x32_bf16 v[42:45], v[146:149], v[90:93], v[42:45]
	v_mfma_f32_16x16x32_bf16 v[38:41], v[134:137], v[162:165], v[38:41]
	v_mfma_f32_16x16x32_bf16 v[34:37], v[146:149], v[162:165], v[34:37]
	v_mfma_f32_16x16x32_bf16 v[30:33], v[134:137], v[170:173], v[30:33]
	v_mfma_f32_16x16x32_bf16 v[26:29], v[146:149], v[170:173], v[26:29]
	v_mfma_f32_16x16x32_bf16 v[22:25], v[134:137], v[184:187], v[22:25]
	v_mfma_f32_16x16x32_bf16 v[18:21], v[146:149], v[184:187], v[18:21]
	v_mfma_f32_16x16x32_bf16 v[46:49], v[138:141], v[94:97], v[46:49]
	v_mfma_f32_16x16x32_bf16 v[42:45], v[150:153], v[94:97], v[42:45]
	v_mfma_f32_16x16x32_bf16 v[38:41], v[138:141], v[166:169], v[38:41]
	v_mfma_f32_16x16x32_bf16 v[34:37], v[150:153], v[166:169], v[34:37]
	v_mfma_f32_16x16x32_bf16 v[30:33], v[138:141], v[174:177], v[30:33]
	v_mfma_f32_16x16x32_bf16 v[26:29], v[150:153], v[174:177], v[26:29]
	v_mfma_f32_16x16x32_bf16 v[22:25], v[138:141], v[188:191], v[22:25]
	v_mfma_f32_16x16x32_bf16 v[18:21], v[150:153], v[188:191], v[18:21]
	s_setprio 0
	s_setprio 1
	v_mfma_f32_16x16x32_bf16 v[66:69], v[106:109], v[170:173], v[66:69]
	v_mfma_f32_16x16x32_bf16 v[134:137], v[114:117], v[174:177], v[66:69]
	v_mfma_f32_16x16x32_bf16 v[66:69], v[122:125], v[170:173], v[74:77]
	v_mfma_f32_16x16x32_bf16 v[14:17], v[106:109], v[90:93], v[14:17]
	v_mfma_f32_16x16x32_bf16 v[10:13], v[122:125], v[90:93], v[10:13]
	v_mfma_f32_16x16x32_bf16 v[6:9], v[106:109], v[162:165], v[6:9]
	v_mfma_f32_16x16x32_bf16 v[2:5], v[122:125], v[162:165], v[2:5]
	v_mfma_f32_16x16x32_bf16 v[138:141], v[200:203], v[174:177], v[66:69]
	v_mfma_f32_16x16x32_bf16 v[66:69], v[106:109], v[184:187], v[78:81]
	v_mfma_f32_16x16x32_bf16 v[14:17], v[114:117], v[94:97], v[14:17]
	v_mfma_f32_16x16x32_bf16 v[10:13], v[200:203], v[94:97], v[10:13]
	v_mfma_f32_16x16x32_bf16 v[6:9], v[114:117], v[166:169], v[6:9]
	v_mfma_f32_16x16x32_bf16 v[2:5], v[200:203], v[166:169], v[2:5]
	v_mfma_f32_16x16x32_bf16 v[146:149], v[114:117], v[188:191], v[66:69]
	v_mfma_f32_16x16x32_bf16 v[66:69], v[122:125], v[184:187], v[82:85]
	v_mfma_f32_16x16x32_bf16 v[150:153], v[200:203], v[188:191], v[66:69]
	s_setprio 0
	s_barrier
	ds_read_b128 v[162:165], v144 offset:32768
	ds_read_b128 v[166:169], v144 offset:33792
	ds_read_b128 v[170:173], v144 offset:34816
	ds_read_b128 v[174:177], v144 offset:35840
	s_nop 0
	ds_read_b128 v[66:69], v0 offset:32768
	ds_read_b128 v[74:77], v0 offset:33792
	ds_read_b128 v[78:81], v0 offset:34816
	ds_read_b128 v[184:187], v0 offset:35840
	ds_read_b128 v[188:191], v0 offset:36864
	ds_read_b128 v[192:195], v0 offset:37888
	ds_read_b128 v[200:203], v0 offset:38912
	ds_read_b128 v[222:225], v0 offset:39936
	s_waitcnt vmcnt(2)
	s_barrier
; #define LDA(dst, b, h) _Pragma("unroll") for (int m = 0; m < 4; ++m) _Pragma("unroll") for (int k = 0; k < 2; ++k) \
;     dst[m][k] = *reinterpret_cast<const bf16x8*>(smem + (((b) * 2 + (h)) * 16384 + m * 2048 + k * 1024) + aoff)
; #define LDB(dst, b, h) _Pragma("unroll") for (int n = 0; n < 2; ++n) _Pragma("unroll") for (int k = 0; k < 2; ++k) \
;     dst[n][k] = *reinterpret_cast<const bf16x8*>(smem + (((b) * 2 + (h)) * 16384 + n * 2048 + k * 1024) + boff)
; #define MMA(ai, bj, At_, Bt_) do { __builtin_amdgcn_s_setprio(1); \
;     _Pragma("unroll") for (int m = 0; m < 4; ++m) _Pragma("unroll") for (int n = 0; n < 2; ++n) _Pragma("unroll") for (int k = 0; k < 2; ++k) \
;       acc[ai][bj][m][n] = __builtin_amdgcn_mfma_f32_16x16x32_bf16(Bt_[n][k], At_[m][k], acc[ai][bj][m][n], 0, 0, 0); \
;     __builtin_amdgcn_s_setprio(0); } while (0)
; #define WAIT_V(n) asm volatile("s_waitcnt vmcnt(" #n ")" ::: "memory")
; #define WAIT_L(n) asm volatile("s_waitcnt lgkmcnt(" #n ")" ::: "memory")
; #define BAR __builtin_amdgcn_s_barrier()
; template <class Epi, int NB>
; DEV void gemm_tile_nb(const bf16* __restrict__ A, int lda, long strideA, const bf16* __restrict__ Bt, int ldb, long strideB, int K, int brow, int bcol, Epi& epi) {
;     ...
;   { LDB(B0, 1, 0); LDA(At, 1, 0); WAIT_V(2); BAR; WAIT_L(0); MMA(0, 0, At, B0); BAR;
;     LDB(B1, 1, 1); WAIT_V(0); BAR; WAIT_L(0); MMA(0, 1, At, B1); BAR;
;     LDA(At, 1, 1); BAR; WAIT_L(0); MMA(1, 0, At, B0); MMA(1, 1, At, B1); BAR; }
;   if (wr == 0) BAR;
	s_waitcnt lgkmcnt(0)
	s_setprio 1
	s_waitcnt lgkmcnt(0)
	v_mfma_f32_16x16x32_bf16 v[82:85], v[162:165], v[66:69], v[126:129]
	v_mfma_f32_16x16x32_bf16 v[122:125], v[166:169], v[74:77], v[82:85]
	v_mfma_f32_16x16x32_bf16 v[82:85], v[170:173], v[66:69], v[130:133]
	v_mfma_f32_16x16x32_bf16 v[126:129], v[174:177], v[74:77], v[82:85]
	v_mfma_f32_16x16x32_bf16 v[82:85], v[162:165], v[78:81], v[118:121]
	v_mfma_f32_16x16x32_bf16 v[114:117], v[166:169], v[184:187], v[82:85]
	v_mfma_f32_16x16x32_bf16 v[82:85], v[170:173], v[78:81], v[158:161]
	v_mfma_f32_16x16x32_bf16 v[118:121], v[174:177], v[184:187], v[82:85]
	v_mfma_f32_16x16x32_bf16 v[82:85], v[162:165], v[188:191], v[110:113]
	v_mfma_f32_16x16x32_bf16 v[106:109], v[166:169], v[192:195], v[82:85]
	v_mfma_f32_16x16x32_bf16 v[82:85], v[170:173], v[188:191], v[196:199]
	v_mfma_f32_16x16x32_bf16 v[110:113], v[174:177], v[192:195], v[82:85]
	v_mfma_f32_16x16x32_bf16 v[82:85], v[162:165], v[200:203], v[102:105]
	v_mfma_f32_16x16x32_bf16 v[90:93], v[166:169], v[222:225], v[82:85]
	v_mfma_f32_16x16x32_bf16 v[82:85], v[170:173], v[200:203], v[98:101]
	v_mfma_f32_16x16x32_bf16 v[94:97], v[174:177], v[222:225], v[82:85]
	s_setprio 0
	s_barrier
	ds_read_b128 v[130:133], v144 offset:49152
	ds_read_b128 v[158:161], v144 offset:50176
	ds_read_b128 v[196:199], v144 offset:51200
	ds_read_b128 v[226:229], v144 offset:52224
	s_waitcnt vmcnt(0)
	s_barrier
	s_waitcnt lgkmcnt(0)
	s_setprio 1
	s_waitcnt lgkmcnt(0)
	v_mfma_f32_16x16x32_bf16 v[82:85], v[130:133], v[66:69], v[218:221]
	v_mfma_f32_16x16x32_bf16 v[66:69], v[196:199], v[66:69], v[154:157]
	v_mfma_f32_16x16x32_bf16 v[102:105], v[226:229], v[74:77], v[66:69]
	v_mfma_f32_16x16x32_bf16 v[66:69], v[130:133], v[78:81], v[86:89]
	v_mfma_f32_16x16x32_bf16 v[98:101], v[158:161], v[74:77], v[82:85]
	v_mfma_f32_16x16x32_bf16 v[82:85], v[158:161], v[184:187], v[66:69]
	v_mfma_f32_16x16x32_bf16 v[66:69], v[196:199], v[78:81], v[70:73]
	v_mfma_f32_16x16x32_bf16 v[62:65], v[130:133], v[188:191], v[62:65]
	v_mfma_f32_16x16x32_bf16 v[58:61], v[196:199], v[188:191], v[58:61]
	v_mfma_f32_16x16x32_bf16 v[54:57], v[130:133], v[200:203], v[54:57]
	v_mfma_f32_16x16x32_bf16 v[50:53], v[196:199], v[200:203], v[50:53]
	v_mfma_f32_16x16x32_bf16 v[86:89], v[226:229], v[184:187], v[66:69]
	v_mfma_f32_16x16x32_bf16 v[74:77], v[158:161], v[192:195], v[62:65]
	v_mfma_f32_16x16x32_bf16 v[78:81], v[226:229], v[192:195], v[58:61]
	v_mfma_f32_16x16x32_bf16 v[66:69], v[158:161], v[222:225], v[54:57]
	v_mfma_f32_16x16x32_bf16 v[70:73], v[226:229], v[222:225], v[50:53]
	s_setprio 0
	s_barrier
	ds_read_b128 v[154:157], v0 offset:49152
	ds_read_b128 v[184:187], v0 offset:50176
	ds_read_b128 v[188:191], v0 offset:51200
	ds_read_b128 v[192:195], v0 offset:52224
	ds_read_b128 v[200:203], v0 offset:53248
	ds_read_b128 v[218:221], v0 offset:54272
	ds_read_b128 v[222:225], v0 offset:55296
	ds_read_b128 v[230:233], v0 offset:56320
	s_barrier
	s_waitcnt lgkmcnt(0)
	s_setprio 1
	s_waitcnt lgkmcnt(0)
	v_mfma_f32_16x16x32_bf16 v[46:49], v[162:165], v[154:157], v[46:49]
	v_mfma_f32_16x16x32_bf16 v[42:45], v[170:173], v[154:157], v[42:45]
	v_mfma_f32_16x16x32_bf16 v[38:41], v[162:165], v[188:191], v[38:41]
	v_mfma_f32_16x16x32_bf16 v[34:37], v[170:173], v[188:191], v[34:37]
	v_mfma_f32_16x16x32_bf16 v[30:33], v[162:165], v[200:203], v[30:33]
	v_mfma_f32_16x16x32_bf16 v[26:29], v[170:173], v[200:203], v[26:29]
	v_mfma_f32_16x16x32_bf16 v[22:25], v[162:165], v[222:225], v[22:25]
	v_mfma_f32_16x16x32_bf16 v[18:21], v[170:173], v[222:225], v[18:21]
	v_mfma_f32_16x16x32_bf16 v[58:61], v[166:169], v[184:187], v[46:49]
	v_mfma_f32_16x16x32_bf16 v[62:65], v[174:177], v[184:187], v[42:45]
	v_mfma_f32_16x16x32_bf16 v[50:53], v[166:169], v[192:195], v[38:41]
	v_mfma_f32_16x16x32_bf16 v[54:57], v[174:177], v[192:195], v[34:37]
	v_mfma_f32_16x16x32_bf16 v[42:45], v[166:169], v[218:221], v[30:33]
	v_mfma_f32_16x16x32_bf16 v[46:49], v[174:177], v[218:221], v[26:29]
	v_mfma_f32_16x16x32_bf16 v[34:37], v[166:169], v[230:233], v[22:25]
	v_mfma_f32_16x16x32_bf16 v[38:41], v[174:177], v[230:233], v[18:21]
	s_setprio 0
	s_setprio 1
	v_mfma_f32_16x16x32_bf16 v[2:5], v[196:199], v[188:191], v[2:5]
	v_mfma_f32_16x16x32_bf16 v[10:13], v[196:199], v[154:157], v[10:13]
	v_mfma_f32_16x16x32_bf16 v[22:25], v[226:229], v[192:195], v[2:5]
	v_mfma_f32_16x16x32_bf16 v[2:5], v[130:133], v[200:203], v[134:137]
	v_mfma_f32_16x16x32_bf16 v[14:17], v[130:133], v[154:157], v[14:17]
	v_mfma_f32_16x16x32_bf16 v[30:33], v[226:229], v[184:187], v[10:13]
	v_mfma_f32_16x16x32_bf16 v[6:9], v[130:133], v[188:191], v[6:9]
	v_mfma_f32_16x16x32_bf16 v[10:13], v[158:161], v[218:221], v[2:5]
	v_mfma_f32_16x16x32_bf16 v[2:5], v[196:199], v[200:203], v[138:141]
	v_mfma_f32_16x16x32_bf16 v[26:29], v[158:161], v[184:187], v[14:17]
	v_mfma_f32_16x16x32_bf16 v[18:21], v[158:161], v[192:195], v[6:9]
	v_mfma_f32_16x16x32_bf16 v[14:17], v[226:229], v[218:221], v[2:5]
	v_mfma_f32_16x16x32_bf16 v[2:5], v[130:133], v[222:225], v[146:149]
	v_mfma_f32_16x16x32_bf16 v[6:9], v[196:199], v[222:225], v[150:153]
	v_mfma_f32_16x16x32_bf16 v[2:5], v[158:161], v[230:233], v[2:5]
	v_mfma_f32_16x16x32_bf16 v[6:9], v[226:229], v[230:233], v[6:9]
	s_setprio 0
	v_readlane_b32 s48, v250, 5
	v_readlane_b32 s49, v250, 6
	s_barrier
	s_cbranch_scc0 .LBB0_133
	s_barrier
	s_branch .LBB0_133

; #define STAGE(P, BASE, LD, br, kt) do { const bf16* _gb = BASE + ((long)(br) * (LD) + (long)(kt) * BK); \
;     _Pragma("unroll") for (int _i = 0; _i < 2; ++_i) { \
;       __builtin_amdgcn_global_load_lds((const unsigned*)(_gb + ((&LD == &lda) ? offA[_i] : offB[_i])), \
;         (unsigned*)((char*)(P) + tidx_ * 16 + _i * 8192), 16, 0, 0); } } while (0)
; #define LDA(dst, b, h) _Pragma("unroll") for (int m = 0; m < 4; ++m) _Pragma("unroll") for (int k = 0; k < 2; ++k) \
;     dst[m][k] = *reinterpret_cast<const bf16x8*>(smem + (((b) * 2 + (h)) * 16384 + m * 2048 + k * 1024) + aoff)
; #define LDB(dst, b, h) _Pragma("unroll") for (int n = 0; n < 2; ++n) _Pragma("unroll") for (int k = 0; k < 2; ++k) \
;     dst[n][k] = *reinterpret_cast<const bf16x8*>(smem + (((b) * 2 + (h)) * 16384 + n * 2048 + k * 1024) + boff)
; #define WAIT_V(n) asm volatile("s_waitcnt vmcnt(" #n ")" ::: "memory")
; #define WAIT_L(n) asm volatile("s_waitcnt lgkmcnt(" #n ")" ::: "memory")
; #define BAR __builtin_amdgcn_s_barrier()
; #define SCHED __builtin_amdgcn_sched_barrier(0)
; template <class Epi, int NB>
; DEV void gemm_tile_nb(const bf16* __restrict__ A, int lda, long strideA, const bf16* __restrict__ Bt, int ldb, long strideB, int K, int brow, int bcol, Epi& epi) {
;     ...
;   f32x4 acc[2][2][4][2] = {};
;   bf16x8 At[4][2], B0[2][2], B1[2][2];
;   const int nt = K / BK;
;   const int lane_off_ = (fr * 64 + fq * 16) ^ ((fr >> 3) << 5);
;   const int aoff = wr * 8192 + lane_off_, boff = 65536 + wc * 4096 + lane_off_;
;   unsigned offA[2], offB[2];
; #pragma unroll
;   for (int _i = 0; _i < 2; ++_i) { int _r, _c; stage_rc(tidx_ * 16 + _i * 8192, _r, _c); offA[_i] = (unsigned)(_r * lda + _c); offB[_i] = (unsigned)(_r * ldb + _c); }
; #pragma unroll 1
;   for (int br = 0; br < NB; ++br) {
;   STAGE(SB(0, 0), Bt, ldb, bcol, 0); STAGE(SA(0, 0), A, lda, brow, 0);
;   STAGE(SB(0, 1), Bt, ldb, bcol + HALF, 0); STAGE(SA(0, 1), A, lda, brow + HALF, 0);
;   if (wr == 1) BAR;
;   WAIT_V(4); BAR;
;   STAGE(SB(1, 0), Bt, ldb, bcol, 1); STAGE(SA(1, 0), A, lda, brow, 1); STAGE(SB(1, 1), Bt, ldb, bcol + HALF, 1);
;   WAIT_V(6); BAR;
;   for (int t = 0; t < nt - 2; t += 2) {
;     LDB(B0, 0, 0); SCHED; LDA(At, 0, 0); STAGE(SA(1, 1), A, lda, brow + HALF, t + 1);
;     WAIT_L(8); BAR; WAIT_L(0); MMA(0, 0, At, B0); BAR; SCHED;
.Lwin_w6b:
	v_add_u32_sdwa v0, v0, sext(v22) dst_sel:DWORD dst_unused:UNUSED_PAD src0_sel:DWORD src1_sel:WORD_0
	v_or_b32_e32 v24, 0x10000, v24
	v_lshl_add_u64 v[134:135], s[44:45], 0, v[2:3]
	v_lshlrev_b64 v[4:5], 1, v[0:1]
	v_lshl_add_u64 v[138:139], s[42:43], 0, v[2:3]
	v_mov_b32_e32 v2, 0
	v_lshl_add_u64 v[136:137], s[44:45], 0, v[4:5]
	v_lshl_add_u64 v[140:141], s[42:43], 0, v[4:5]
	s_mov_b32 s41, -2
	v_add_u32_e32 v144, 0, v24
	v_add_u32_e32 v0, 0, v23
	v_mov_b32_e32 v3, v2
	v_mov_b32_e32 v4, v2
	v_mov_b32_e32 v5, v2
	v_mov_b32_e32 v6, v2
	v_mov_b32_e32 v7, v2
	v_mov_b32_e32 v8, v2
	v_mov_b32_e32 v9, v2
	v_mov_b32_e32 v10, v2
	v_mov_b32_e32 v11, v2
	v_mov_b32_e32 v12, v2
	v_mov_b32_e32 v13, v2
	v_mov_b32_e32 v14, v2
	v_mov_b32_e32 v15, v2
	v_mov_b32_e32 v16, v2
	v_mov_b32_e32 v17, v2
	v_mov_b32_e32 v18, v2
	v_mov_b32_e32 v19, v2
	v_mov_b32_e32 v20, v2
	v_mov_b32_e32 v21, v2
	v_mov_b32_e32 v22, v2
	v_mov_b32_e32 v23, v2
	v_mov_b32_e32 v24, v2
	v_mov_b32_e32 v25, v2
	v_mov_b32_e32 v26, v2
	v_mov_b32_e32 v27, v2
	s_waitcnt vmcnt(0)
	v_mov_b32_e32 v28, v2
	v_mov_b32_e32 v29, v2
	v_mov_b32_e32 v30, v2
	v_mov_b32_e32 v31, v2
	v_mov_b32_e32 v32, v2
	v_mov_b32_e32 v33, v2
	v_mov_b32_e32 v34, v2
	v_mov_b32_e32 v35, v2
	v_mov_b32_e32 v36, v2
	v_mov_b32_e32 v37, v2
	v_mov_b32_e32 v38, v2
	v_mov_b32_e32 v39, v2
	v_mov_b32_e32 v40, v2
	v_mov_b32_e32 v41, v2
	v_mov_b32_e32 v42, v2
	v_mov_b32_e32 v43, v2
	v_mov_b32_e32 v44, v2
	v_mov_b32_e32 v45, v2
	v_mov_b32_e32 v46, v2
	v_mov_b32_e32 v47, v2
	v_mov_b32_e32 v48, v2
	v_mov_b32_e32 v49, v2
	v_mov_b32_e32 v50, v2
	v_mov_b32_e32 v51, v2
	v_mov_b32_e32 v52, v2
	v_mov_b32_e32 v53, v2
	v_mov_b32_e32 v54, v2
	v_mov_b32_e32 v55, v2
	v_mov_b32_e32 v56, v2
	v_mov_b32_e32 v57, v2
	v_mov_b32_e32 v58, v2
	v_mov_b32_e32 v59, v2
	v_mov_b32_e32 v60, v2
	v_mov_b32_e32 v61, v2
	v_mov_b32_e32 v62, v2
	v_mov_b32_e32 v63, v2
	v_mov_b32_e32 v64, v2
	v_mov_b32_e32 v65, v2
	v_mov_b32_e32 v70, v2
	v_mov_b32_e32 v71, v2
	v_mov_b32_e32 v72, v2
	v_mov_b32_e32 v73, v2
	v_mov_b32_e32 v86, v2
	v_mov_b32_e32 v87, v2
	v_mov_b32_e32 v88, v2
	v_mov_b32_e32 v89, v2
	v_mov_b32_e32 v90, v2
	v_mov_b32_e32 v91, v2
	v_mov_b32_e32 v92, v2
	v_mov_b32_e32 v93, v2
	v_mov_b32_e32 v94, v2
	v_mov_b32_e32 v95, v2
	v_mov_b32_e32 v96, v2
	v_mov_b32_e32 v97, v2
	v_mov_b32_e32 v98, v2
	v_mov_b32_e32 v99, v2
	v_mov_b32_e32 v100, v2
	v_mov_b32_e32 v101, v2
	v_mov_b32_e32 v102, v2
	v_mov_b32_e32 v103, v2
	v_mov_b32_e32 v104, v2
	v_mov_b32_e32 v105, v2
	v_mov_b32_e32 v106, v2
	v_mov_b32_e32 v107, v2
	v_mov_b32_e32 v108, v2
	v_mov_b32_e32 v109, v2
	v_mov_b32_e32 v110, v2
	v_mov_b32_e32 v111, v2
	v_mov_b32_e32 v112, v2
	v_mov_b32_e32 v113, v2
	v_mov_b32_e32 v114, v2
	v_mov_b32_e32 v115, v2
	v_mov_b32_e32 v116, v2
	v_mov_b32_e32 v117, v2
	v_mov_b32_e32 v118, v2
	v_mov_b32_e32 v119, v2
	v_mov_b32_e32 v120, v2
	v_mov_b32_e32 v121, v2
	v_mov_b32_e32 v122, v2
	v_mov_b32_e32 v123, v2
	v_mov_b32_e32 v124, v2
	v_mov_b32_e32 v125, v2
	v_mov_b32_e32 v126, v2
	v_mov_b32_e32 v127, v2
	v_mov_b32_e32 v128, v2
	v_mov_b32_e32 v129, v2
	v_mov_b32_e32 v66, v2
	v_mov_b32_e32 v67, v2
	v_mov_b32_e32 v68, v2
	v_mov_b32_e32 v69, v2
	v_mov_b32_e32 v74, v2
	v_mov_b32_e32 v75, v2
	v_mov_b32_e32 v76, v2
	v_mov_b32_e32 v77, v2
	v_mov_b32_e32 v78, v2
	v_mov_b32_e32 v79, v2
	v_mov_b32_e32 v80, v2
	v_mov_b32_e32 v81, v2
	v_mov_b32_e32 v82, v2
	v_mov_b32_e32 v83, v2
	v_mov_b32_e32 v84, v2
	v_mov_b32_e32 v85, v2
	s_mov_b64 s[44:45], 0xabe4080
	s_mov_b64 s[54:55], 0x2100100
	s_mov_b64 s[56:57], 0x2140100
	s_mov_b64 s[58:59], 0xabe4100
	s_mov_b64 s[60:61], 0x2100180
	s_mov_b64 s[62:63], 0x2140180
	s_barrier
	ds_read_b128 v[162:165], v144
	ds_read_b128 v[166:169], v144 offset:1024
	ds_read_b128 v[170:173], v144 offset:2048
	ds_read_b128 v[174:177], v144 offset:3072
.LBB0_768:
	v_add_u32_e32 v159, 0xc000, v146
	v_lshl_add_u64 v[204:205], s[88:89], 0, v[138:139]
	v_readfirstlane_b32 s42, v159
	v_lshl_add_u64 v[160:161], v[204:205], 0, s[44:45]
	s_mov_b32 m0, s42
	ds_read_b128 v[184:187], v0
	ds_read_b128 v[188:191], v0 offset:1024
	ds_read_b128 v[192:195], v0 offset:2048
	ds_read_b128 v[196:199], v0 offset:3072
	ds_read_b128 v[200:203], v0 offset:4096
	ds_read_b128 v[218:221], v0 offset:5120
	ds_read_b128 v[222:225], v0 offset:6144
	ds_read_b128 v[226:229], v0 offset:7168
	global_load_lds_dwordx4 v[160:161], off
	v_add_u32_e32 v160, 0xe000, v146
	v_lshl_add_u64 v[208:209], s[88:89], 0, v[140:141]
	v_readfirstlane_b32 s42, v160
	v_lshl_add_u64 v[214:215], v[208:209], 0, s[44:45]
	s_mov_b32 m0, s42
	s_nop 0
	global_load_lds_dwordx4 v[214:215], off
	s_waitcnt lgkmcnt(8)
	s_barrier
	s_waitcnt lgkmcnt(0)
	s_setprio 1
	s_waitcnt lgkmcnt(0)
	v_mfma_f32_16x16x32_bf16 v[126:129], v[162:165], v[184:187], v[126:129]
	v_mfma_f32_16x16x32_bf16 v[122:125], v[170:173], v[184:187], v[122:125]
	v_mfma_f32_16x16x32_bf16 v[118:121], v[162:165], v[192:195], v[118:121]
	v_mfma_f32_16x16x32_bf16 v[114:117], v[170:173], v[192:195], v[114:117]
	v_mfma_f32_16x16x32_bf16 v[110:113], v[162:165], v[200:203], v[110:113]
	v_mfma_f32_16x16x32_bf16 v[106:109], v[170:173], v[200:203], v[106:109]
	v_mfma_f32_16x16x32_bf16 v[102:105], v[162:165], v[222:225], v[102:105]
	v_mfma_f32_16x16x32_bf16 v[98:101], v[170:173], v[222:225], v[98:101]
	v_mfma_f32_16x16x32_bf16 v[126:129], v[166:169], v[188:191], v[126:129]
	v_mfma_f32_16x16x32_bf16 v[122:125], v[174:177], v[188:191], v[122:125]
	v_mfma_f32_16x16x32_bf16 v[118:121], v[166:169], v[196:199], v[118:121]
	v_mfma_f32_16x16x32_bf16 v[114:117], v[174:177], v[196:199], v[114:117]
	v_mfma_f32_16x16x32_bf16 v[110:113], v[166:169], v[218:221], v[110:113]
	v_mfma_f32_16x16x32_bf16 v[106:109], v[174:177], v[218:221], v[106:109]
	v_mfma_f32_16x16x32_bf16 v[102:105], v[166:169], v[226:229], v[102:105]
	v_mfma_f32_16x16x32_bf16 v[98:101], v[174:177], v[226:229], v[98:101]
	s_setprio 0
	s_barrier
; #define STAGE(P, BASE, LD, br, kt) do { const bf16* _gb = BASE + ((long)(br) * (LD) + (long)(kt) * BK); \
;     _Pragma("unroll") for (int _i = 0; _i < 2; ++_i) { \
;       __builtin_amdgcn_global_load_lds((const unsigned*)(_gb + ((&LD == &lda) ? offA[_i] : offB[_i])), \
;         (unsigned*)((char*)(P) + tidx_ * 16 + _i * 8192), 16, 0, 0); } } while (0)
; #define LDA(dst, b, h) _Pragma("unroll") for (int m = 0; m < 4; ++m) _Pragma("unroll") for (int k = 0; k < 2; ++k) \
;     dst[m][k] = *reinterpret_cast<const bf16x8*>(smem + (((b) * 2 + (h)) * 16384 + m * 2048 + k * 1024) + aoff)
; #define LDB(dst, b, h) _Pragma("unroll") for (int n = 0; n < 2; ++n) _Pragma("unroll") for (int k = 0; k < 2; ++k) \
;     dst[n][k] = *reinterpret_cast<const bf16x8*>(smem + (((b) * 2 + (h)) * 16384 + n * 2048 + k * 1024) + boff)
; #define MMA(ai, bj, At_, Bt_) do { __builtin_amdgcn_s_setprio(1); \
;     _Pragma("unroll") for (int m = 0; m < 4; ++m) _Pragma("unroll") for (int n = 0; n < 2; ++n) _Pragma("unroll") for (int k = 0; k < 2; ++k) \
;       acc[ai][bj][m][n] = __builtin_amdgcn_mfma_f32_16x16x32_bf16(Bt_[n][k], At_[m][k], acc[ai][bj][m][n], 0, 0, 0); \
;     __builtin_amdgcn_s_setprio(0); } while (0)
; #define WAIT_V(n) asm volatile("s_waitcnt vmcnt(" #n ")" ::: "memory")
; #define WAIT_L(n) asm volatile("s_waitcnt lgkmcnt(" #n ")" ::: "memory")
; #define BAR __builtin_amdgcn_s_barrier()
; #define SCHED __builtin_amdgcn_sched_barrier(0)
; template <class Epi, int NB>
; DEV void gemm_tile_nb(const bf16* __restrict__ A, int lda, long strideA, const bf16* __restrict__ Bt, int ldb, long strideB, int K, int brow, int bcol, Epi& epi) {
;     ...
;     LDB(B1, 0, 1); STAGE(SB(0, 0), Bt, ldb, bcol, t + 2);
;     BAR; WAIT_L(0); MMA(0, 1, At, B1); BAR;
;     LDA(At, 0, 1); STAGE(SA(0, 0), A, lda, brow, t + 2);
;     BAR; WAIT_L(0); MMA(1, 0, At, B0); BAR; SCHED;
;     STAGE(SB(0, 1), Bt, ldb, bcol + HALF, t + 2);
;     WAIT_V(6); BAR; MMA(1, 1, At, B1); BAR;
;     LDB(B0, 1, 0); SCHED; LDA(At, 1, 0); STAGE(SA(0, 1), A, lda, brow + HALF, t + 2);
;     WAIT_L(8); BAR; WAIT_L(0); MMA(0, 0, At, B0); BAR; SCHED;
	v_lshl_add_u64 v[214:215], s[88:89], 0, v[134:135]
	v_readfirstlane_b32 s42, v145
	v_lshl_add_u64 v[246:247], v[214:215], 0, s[54:55]
	s_mov_b32 m0, s42
	ds_read_b128 v[230:233], v144 offset:16384
	ds_read_b128 v[234:237], v144 offset:17408
	ds_read_b128 v[238:241], v144 offset:18432
	ds_read_b128 v[242:245], v144 offset:19456
	global_load_lds_dwordx4 v[246:247], off
	v_lshl_add_u64 v[246:247], s[88:89], 0, v[136:137]
	v_readfirstlane_b32 s42, v148
	v_lshl_add_u64 v[248:249], v[246:247], 0, s[54:55]
	s_mov_b32 m0, s42
	s_nop 0
	global_load_lds_dwordx4 v[248:249], off
	s_barrier
	s_waitcnt lgkmcnt(0)
	s_setprio 1
	s_waitcnt lgkmcnt(0)
	v_mfma_f32_16x16x32_bf16 v[94:97], v[230:233], v[184:187], v[94:97]
	v_mfma_f32_16x16x32_bf16 v[90:93], v[238:241], v[184:187], v[90:93]
	v_mfma_f32_16x16x32_bf16 v[86:89], v[230:233], v[192:195], v[86:89]
	v_mfma_f32_16x16x32_bf16 v[70:73], v[238:241], v[192:195], v[70:73]
	v_mfma_f32_16x16x32_bf16 v[62:65], v[230:233], v[200:203], v[62:65]
	v_mfma_f32_16x16x32_bf16 v[58:61], v[238:241], v[200:203], v[58:61]
	v_mfma_f32_16x16x32_bf16 v[54:57], v[230:233], v[222:225], v[54:57]
	v_mfma_f32_16x16x32_bf16 v[50:53], v[238:241], v[222:225], v[50:53]
	v_mfma_f32_16x16x32_bf16 v[94:97], v[234:237], v[188:191], v[94:97]
	v_mfma_f32_16x16x32_bf16 v[90:93], v[242:245], v[188:191], v[90:93]
	v_mfma_f32_16x16x32_bf16 v[86:89], v[234:237], v[196:199], v[86:89]
	v_mfma_f32_16x16x32_bf16 v[70:73], v[242:245], v[196:199], v[70:73]
	v_mfma_f32_16x16x32_bf16 v[62:65], v[234:237], v[218:221], v[62:65]
	v_mfma_f32_16x16x32_bf16 v[58:61], v[242:245], v[218:221], v[58:61]
	v_mfma_f32_16x16x32_bf16 v[54:57], v[234:237], v[226:229], v[54:57]
	v_mfma_f32_16x16x32_bf16 v[50:53], v[242:245], v[226:229], v[50:53]
	s_setprio 0
	v_readfirstlane_b32 s42, v146
	v_lshl_add_u64 v[248:249], v[204:205], 0, s[28:29]
	s_mov_b32 m0, s42
	v_readfirstlane_b32 s42, v150
	s_barrier
	ds_read_b128 v[184:187], v0 offset:16384
	ds_read_b128 v[188:191], v0 offset:17408
	ds_read_b128 v[192:195], v0 offset:18432
	ds_read_b128 v[196:199], v0 offset:19456
	ds_read_b128 v[200:203], v0 offset:20480
	ds_read_b128 v[218:221], v0 offset:21504
	ds_read_b128 v[222:225], v0 offset:22528
	ds_read_b128 v[226:229], v0 offset:23552
	global_load_lds_dwordx4 v[248:249], off
	v_lshl_add_u64 v[248:249], v[208:209], 0, s[28:29]
	s_mov_b32 m0, s42
	s_nop 0
	global_load_lds_dwordx4 v[248:249], off
	s_waitcnt vmcnt(10)
	s_barrier
	s_waitcnt lgkmcnt(0)
	s_setprio 1
	s_waitcnt lgkmcnt(0)
	v_mfma_f32_16x16x32_bf16 v[46:49], v[162:165], v[184:187], v[46:49]
	v_mfma_f32_16x16x32_bf16 v[42:45], v[170:173], v[184:187], v[42:45]
	v_mfma_f32_16x16x32_bf16 v[38:41], v[162:165], v[192:195], v[38:41]
	v_mfma_f32_16x16x32_bf16 v[34:37], v[170:173], v[192:195], v[34:37]
	v_mfma_f32_16x16x32_bf16 v[30:33], v[162:165], v[200:203], v[30:33]
	v_mfma_f32_16x16x32_bf16 v[26:29], v[170:173], v[200:203], v[26:29]
	v_mfma_f32_16x16x32_bf16 v[22:25], v[162:165], v[222:225], v[22:25]
	v_mfma_f32_16x16x32_bf16 v[18:21], v[170:173], v[222:225], v[18:21]
	v_mfma_f32_16x16x32_bf16 v[46:49], v[166:169], v[188:191], v[46:49]
	v_mfma_f32_16x16x32_bf16 v[42:45], v[174:177], v[188:191], v[42:45]
	v_mfma_f32_16x16x32_bf16 v[38:41], v[166:169], v[196:199], v[38:41]
	v_mfma_f32_16x16x32_bf16 v[34:37], v[174:177], v[196:199], v[34:37]
	v_mfma_f32_16x16x32_bf16 v[30:33], v[166:169], v[218:221], v[30:33]
	v_mfma_f32_16x16x32_bf16 v[26:29], v[174:177], v[218:221], v[26:29]
	v_mfma_f32_16x16x32_bf16 v[22:25], v[166:169], v[226:229], v[22:25]
	v_mfma_f32_16x16x32_bf16 v[18:21], v[174:177], v[226:229], v[18:21]
	s_setprio 0
	s_barrier
	v_readfirstlane_b32 s42, v147
	v_lshl_add_u64 v[162:163], v[214:215], 0, s[56:57]
	s_mov_b32 m0, s42
	v_readfirstlane_b32 s42, v151
	global_load_lds_dwordx4 v[162:163], off
	v_lshl_add_u64 v[162:163], v[246:247], 0, s[56:57]
	s_mov_b32 m0, s42
	s_nop 0
	global_load_lds_dwordx4 v[162:163], off
	ds_read_b128 v[162:165], v144 offset:32768
	ds_read_b128 v[166:169], v144 offset:33792
	ds_read_b128 v[170:173], v144 offset:34816
	ds_read_b128 v[174:177], v144 offset:35840
	s_waitcnt vmcnt(6)
	s_barrier
	s_setprio 1
	v_mfma_f32_16x16x32_bf16 v[14:17], v[230:233], v[184:187], v[14:17]
	v_mfma_f32_16x16x32_bf16 v[10:13], v[238:241], v[184:187], v[10:13]
	v_mfma_f32_16x16x32_bf16 v[6:9], v[230:233], v[192:195], v[6:9]
	v_mfma_f32_16x16x32_bf16 v[2:5], v[238:241], v[192:195], v[2:5]
	v_mfma_f32_16x16x32_bf16 v[66:69], v[230:233], v[200:203], v[66:69]
	v_mfma_f32_16x16x32_bf16 v[74:77], v[238:241], v[200:203], v[74:77]
	v_mfma_f32_16x16x32_bf16 v[78:81], v[230:233], v[222:225], v[78:81]
	v_mfma_f32_16x16x32_bf16 v[82:85], v[238:241], v[222:225], v[82:85]
	v_mfma_f32_16x16x32_bf16 v[14:17], v[234:237], v[188:191], v[14:17]
	v_mfma_f32_16x16x32_bf16 v[10:13], v[242:245], v[188:191], v[10:13]
	v_mfma_f32_16x16x32_bf16 v[6:9], v[234:237], v[196:199], v[6:9]
	v_mfma_f32_16x16x32_bf16 v[2:5], v[242:245], v[196:199], v[2:5]
	v_mfma_f32_16x16x32_bf16 v[66:69], v[234:237], v[218:221], v[66:69]
	v_mfma_f32_16x16x32_bf16 v[74:77], v[242:245], v[218:221], v[74:77]
	v_mfma_f32_16x16x32_bf16 v[78:81], v[234:237], v[226:229], v[78:81]
	v_mfma_f32_16x16x32_bf16 v[82:85], v[242:245], v[226:229], v[82:85]
	s_setprio 0
	s_barrier
	v_readfirstlane_b32 s42, v149
	v_lshl_add_u64 v[230:231], v[204:205], 0, s[58:59]
	s_mov_b32 m0, s42
	v_readfirstlane_b32 s42, v152
	ds_read_b128 v[184:187], v0 offset:32768
	ds_read_b128 v[188:191], v0 offset:33792
	ds_read_b128 v[192:195], v0 offset:34816
	ds_read_b128 v[196:199], v0 offset:35840
	ds_read_b128 v[200:203], v0 offset:36864
	ds_read_b128 v[218:221], v0 offset:37888
	ds_read_b128 v[222:225], v0 offset:38912
	ds_read_b128 v[226:229], v0 offset:39936
	global_load_lds_dwordx4 v[230:231], off
	v_lshl_add_u64 v[230:231], v[208:209], 0, s[58:59]
	s_mov_b32 m0, s42
	s_nop 0
	global_load_lds_dwordx4 v[230:231], off
	s_waitcnt lgkmcnt(8)
	s_barrier
; #define STAGE(P, BASE, LD, br, kt) do { const bf16* _gb = BASE + ((long)(br) * (LD) + (long)(kt) * BK); \
;     _Pragma("unroll") for (int _i = 0; _i < 2; ++_i) { \
;       __builtin_amdgcn_global_load_lds((const unsigned*)(_gb + ((&LD == &lda) ? offA[_i] : offB[_i])), \
;         (unsigned*)((char*)(P) + tidx_ * 16 + _i * 8192), 16, 0, 0); } } while (0)
; #define LDA(dst, b, h) _Pragma("unroll") for (int m = 0; m < 4; ++m) _Pragma("unroll") for (int k = 0; k < 2; ++k) \
;     dst[m][k] = *reinterpret_cast<const bf16x8*>(smem + (((b) * 2 + (h)) * 16384 + m * 2048 + k * 1024) + aoff)
; #define LDB(dst, b, h) _Pragma("unroll") for (int n = 0; n < 2; ++n) _Pragma("unroll") for (int k = 0; k < 2; ++k) \
;     dst[n][k] = *reinterpret_cast<const bf16x8*>(smem + (((b) * 2 + (h)) * 16384 + n * 2048 + k * 1024) + boff)
; #define MMA(ai, bj, At_, Bt_) do { __builtin_amdgcn_s_setprio(1); \
;     _Pragma("unroll") for (int m = 0; m < 4; ++m) _Pragma("unroll") for (int n = 0; n < 2; ++n) _Pragma("unroll") for (int k = 0; k < 2; ++k) \
;       acc[ai][bj][m][n] = __builtin_amdgcn_mfma_f32_16x16x32_bf16(Bt_[n][k], At_[m][k], acc[ai][bj][m][n], 0, 0, 0); \
;     __builtin_amdgcn_s_setprio(0); } while (0)
; #define WAIT_V(n) asm volatile("s_waitcnt vmcnt(" #n ")" ::: "memory")
; #define WAIT_L(n) asm volatile("s_waitcnt lgkmcnt(" #n ")" ::: "memory")
; #define BAR __builtin_amdgcn_s_barrier()
; #define SCHED __builtin_amdgcn_sched_barrier(0)
; template <class Epi, int NB>
; DEV void gemm_tile_nb(const bf16* __restrict__ A, int lda, long strideA, const bf16* __restrict__ Bt, int ldb, long strideB, int K, int brow, int bcol, Epi& epi) {
;     ...
;     WAIT_L(8); BAR; WAIT_L(0); MMA(0, 0, At, B0); BAR; SCHED;
;     LDB(B1, 1, 1); STAGE(SB(1, 0), Bt, ldb, bcol, t + 3);
;     BAR; WAIT_L(0); MMA(0, 1, At, B1); BAR;
;     LDA(At, 1, 1); STAGE(SA(1, 0), A, lda, brow, t + 3);
;     BAR; WAIT_L(0); MMA(1, 0, At, B0); BAR; SCHED;
;     STAGE(SB(1, 1), Bt, ldb, bcol + HALF, t + 3);
;     WAIT_V(6); BAR; MMA(1, 1, At, B1); BAR;
	s_waitcnt lgkmcnt(0)
	s_setprio 1
	s_waitcnt lgkmcnt(0)
	v_mfma_f32_16x16x32_bf16 v[126:129], v[162:165], v[184:187], v[126:129]
	v_mfma_f32_16x16x32_bf16 v[122:125], v[170:173], v[184:187], v[122:125]
	v_mfma_f32_16x16x32_bf16 v[118:121], v[162:165], v[192:195], v[118:121]
	v_mfma_f32_16x16x32_bf16 v[114:117], v[170:173], v[192:195], v[114:117]
	v_mfma_f32_16x16x32_bf16 v[110:113], v[162:165], v[200:203], v[110:113]
	v_mfma_f32_16x16x32_bf16 v[106:109], v[170:173], v[200:203], v[106:109]
	v_mfma_f32_16x16x32_bf16 v[102:105], v[162:165], v[222:225], v[102:105]
	v_mfma_f32_16x16x32_bf16 v[98:101], v[170:173], v[222:225], v[98:101]
	v_mfma_f32_16x16x32_bf16 v[126:129], v[166:169], v[188:191], v[126:129]
	v_mfma_f32_16x16x32_bf16 v[122:125], v[174:177], v[188:191], v[122:125]
	v_mfma_f32_16x16x32_bf16 v[118:121], v[166:169], v[196:199], v[118:121]
	v_mfma_f32_16x16x32_bf16 v[114:117], v[174:177], v[196:199], v[114:117]
	v_mfma_f32_16x16x32_bf16 v[110:113], v[166:169], v[218:221], v[110:113]
	v_mfma_f32_16x16x32_bf16 v[106:109], v[174:177], v[218:221], v[106:109]
	v_mfma_f32_16x16x32_bf16 v[102:105], v[166:169], v[226:229], v[102:105]
	v_mfma_f32_16x16x32_bf16 v[98:101], v[174:177], v[226:229], v[98:101]
	s_setprio 0
	s_barrier
	v_readfirstlane_b32 s42, v153
	v_lshl_add_u64 v[248:249], v[214:215], 0, s[60:61]
	s_mov_b32 m0, s42
	v_readfirstlane_b32 s42, v154
	ds_read_b128 v[230:233], v144 offset:49152
	ds_read_b128 v[234:237], v144 offset:50176
	ds_read_b128 v[238:241], v144 offset:51200
	ds_read_b128 v[242:245], v144 offset:52224
	global_load_lds_dwordx4 v[248:249], off
	v_lshl_add_u64 v[248:249], v[246:247], 0, s[60:61]
	s_mov_b32 m0, s42
	s_nop 0
	global_load_lds_dwordx4 v[248:249], off
	s_barrier
	s_waitcnt lgkmcnt(0)
	s_setprio 1
	s_waitcnt lgkmcnt(0)
	v_mfma_f32_16x16x32_bf16 v[94:97], v[230:233], v[184:187], v[94:97]
	v_mfma_f32_16x16x32_bf16 v[90:93], v[238:241], v[184:187], v[90:93]
	v_mfma_f32_16x16x32_bf16 v[86:89], v[230:233], v[192:195], v[86:89]
	v_mfma_f32_16x16x32_bf16 v[70:73], v[238:241], v[192:195], v[70:73]
	v_mfma_f32_16x16x32_bf16 v[62:65], v[230:233], v[200:203], v[62:65]
	v_mfma_f32_16x16x32_bf16 v[58:61], v[238:241], v[200:203], v[58:61]
	v_mfma_f32_16x16x32_bf16 v[54:57], v[230:233], v[222:225], v[54:57]
	v_mfma_f32_16x16x32_bf16 v[50:53], v[238:241], v[222:225], v[50:53]
	v_mfma_f32_16x16x32_bf16 v[94:97], v[234:237], v[188:191], v[94:97]
	v_mfma_f32_16x16x32_bf16 v[90:93], v[242:245], v[188:191], v[90:93]
	v_mfma_f32_16x16x32_bf16 v[86:89], v[234:237], v[196:199], v[86:89]
	v_mfma_f32_16x16x32_bf16 v[70:73], v[242:245], v[196:199], v[70:73]
	v_mfma_f32_16x16x32_bf16 v[62:65], v[234:237], v[218:221], v[62:65]
	v_mfma_f32_16x16x32_bf16 v[58:61], v[242:245], v[218:221], v[58:61]
	v_mfma_f32_16x16x32_bf16 v[54:57], v[234:237], v[226:229], v[54:57]
	v_mfma_f32_16x16x32_bf16 v[50:53], v[242:245], v[226:229], v[50:53]
	s_setprio 0
	v_readfirstlane_b32 s42, v155
	v_lshl_add_u64 v[204:205], v[204:205], 0, s[20:21]
	s_mov_b32 m0, s42
	v_readfirstlane_b32 s42, v156
	s_barrier
	ds_read_b128 v[184:187], v0 offset:49152
	ds_read_b128 v[188:191], v0 offset:50176
	ds_read_b128 v[192:195], v0 offset:51200
	ds_read_b128 v[196:199], v0 offset:52224
	ds_read_b128 v[200:203], v0 offset:53248
	ds_read_b128 v[218:221], v0 offset:54272
	ds_read_b128 v[222:225], v0 offset:55296
	ds_read_b128 v[226:229], v0 offset:56320
	global_load_lds_dwordx4 v[204:205], off
	v_lshl_add_u64 v[204:205], v[208:209], 0, s[20:21]
	s_mov_b32 m0, s42
	s_nop 0
	global_load_lds_dwordx4 v[204:205], off
	s_waitcnt vmcnt(10)
	s_barrier
	s_waitcnt lgkmcnt(0)
	s_setprio 1
	s_waitcnt lgkmcnt(0)
	v_mfma_f32_16x16x32_bf16 v[46:49], v[162:165], v[184:187], v[46:49]
	v_mfma_f32_16x16x32_bf16 v[42:45], v[170:173], v[184:187], v[42:45]
	v_mfma_f32_16x16x32_bf16 v[38:41], v[162:165], v[192:195], v[38:41]
	v_mfma_f32_16x16x32_bf16 v[34:37], v[170:173], v[192:195], v[34:37]
	v_mfma_f32_16x16x32_bf16 v[30:33], v[162:165], v[200:203], v[30:33]
	v_mfma_f32_16x16x32_bf16 v[26:29], v[170:173], v[200:203], v[26:29]
	v_mfma_f32_16x16x32_bf16 v[22:25], v[162:165], v[222:225], v[22:25]
	v_mfma_f32_16x16x32_bf16 v[18:21], v[170:173], v[222:225], v[18:21]
	v_mfma_f32_16x16x32_bf16 v[46:49], v[166:169], v[188:191], v[46:49]
	v_mfma_f32_16x16x32_bf16 v[42:45], v[174:177], v[188:191], v[42:45]
	v_mfma_f32_16x16x32_bf16 v[38:41], v[166:169], v[196:199], v[38:41]
	v_mfma_f32_16x16x32_bf16 v[34:37], v[174:177], v[196:199], v[34:37]
	v_mfma_f32_16x16x32_bf16 v[30:33], v[166:169], v[218:221], v[30:33]
	v_mfma_f32_16x16x32_bf16 v[26:29], v[174:177], v[218:221], v[26:29]
	v_mfma_f32_16x16x32_bf16 v[22:25], v[166:169], v[226:229], v[22:25]
	v_mfma_f32_16x16x32_bf16 v[18:21], v[174:177], v[226:229], v[18:21]
	s_setprio 0
	s_barrier
	v_readfirstlane_b32 s42, v157
	v_lshl_add_u64 v[162:163], v[214:215], 0, s[62:63]
	s_mov_b32 m0, s42
	v_readfirstlane_b32 s42, v158
	global_load_lds_dwordx4 v[162:163], off
	v_lshl_add_u64 v[162:163], v[246:247], 0, s[62:63]
	s_mov_b32 m0, s42
	s_nop 0
	global_load_lds_dwordx4 v[162:163], off
	ds_read_b128 v[162:165], v144
	ds_read_b128 v[166:169], v144 offset:1024
	ds_read_b128 v[170:173], v144 offset:2048
	ds_read_b128 v[174:177], v144 offset:3072
	s_waitcnt vmcnt(6)
	s_barrier
; #define STAGE(P, BASE, LD, br, kt) do { const bf16* _gb = BASE + ((long)(br) * (LD) + (long)(kt) * BK); \
;     _Pragma("unroll") for (int _i = 0; _i < 2; ++_i) { \
;       __builtin_amdgcn_global_load_lds((const unsigned*)(_gb + ((&LD == &lda) ? offA[_i] : offB[_i])), \
;         (unsigned*)((char*)(P) + tidx_ * 16 + _i * 8192), 16, 0, 0); } } while (0)
; #define LDA(dst, b, h) _Pragma("unroll") for (int m = 0; m < 4; ++m) _Pragma("unroll") for (int k = 0; k < 2; ++k) \
;     dst[m][k] = *reinterpret_cast<const bf16x8*>(smem + (((b) * 2 + (h)) * 16384 + m * 2048 + k * 1024) + aoff)
; #define LDB(dst, b, h) _Pragma("unroll") for (int n = 0; n < 2; ++n) _Pragma("unroll") for (int k = 0; k < 2; ++k) \
;     dst[n][k] = *reinterpret_cast<const bf16x8*>(smem + (((b) * 2 + (h)) * 16384 + n * 2048 + k * 1024) + boff)
; #define MMA(ai, bj, At_, Bt_) do { __builtin_amdgcn_s_setprio(1); \
;     _Pragma("unroll") for (int m = 0; m < 4; ++m) _Pragma("unroll") for (int n = 0; n < 2; ++n) _Pragma("unroll") for (int k = 0; k < 2; ++k) \
;       acc[ai][bj][m][n] = __builtin_amdgcn_mfma_f32_16x16x32_bf16(Bt_[n][k], At_[m][k], acc[ai][bj][m][n], 0, 0, 0); \
;     __builtin_amdgcn_s_setprio(0); } while (0)
; #define WAIT_V(n) asm volatile("s_waitcnt vmcnt(" #n ")" ::: "memory")
; #define WAIT_L(n) asm volatile("s_waitcnt lgkmcnt(" #n ")" ::: "memory")
; #define BAR __builtin_amdgcn_s_barrier()
; template <class Epi, int NB>
; DEV void gemm_tile_nb(const bf16* __restrict__ A, int lda, long strideA, const bf16* __restrict__ Bt, int ldb, long strideB, int K, int brow, int bcol, Epi& epi) {
;     ...
;     WAIT_V(6); BAR; MMA(1, 1, At, B1); BAR;
;   }
;   { LDB(B0, 0, 0); LDA(At, 0, 0); STAGE(SA(1, 1), A, lda, brow + HALF, nt - 1);
;     BAR; WAIT_L(0); MMA(0, 0, At, B0); BAR;
;     LDB(B1, 0, 1); BAR; WAIT_L(0); MMA(0, 1, At, B1); BAR;
;     LDA(At, 0, 1); WAIT_V(4); BAR; WAIT_L(0); MMA(1, 0, At, B0); MMA(1, 1, At, B1); BAR; }
	s_setprio 1
	v_mfma_f32_16x16x32_bf16 v[14:17], v[230:233], v[184:187], v[14:17]
	v_mfma_f32_16x16x32_bf16 v[10:13], v[238:241], v[184:187], v[10:13]
	v_mfma_f32_16x16x32_bf16 v[6:9], v[230:233], v[192:195], v[6:9]
	v_mfma_f32_16x16x32_bf16 v[2:5], v[238:241], v[192:195], v[2:5]
	v_mfma_f32_16x16x32_bf16 v[66:69], v[230:233], v[200:203], v[66:69]
	v_mfma_f32_16x16x32_bf16 v[74:77], v[238:241], v[200:203], v[74:77]
	v_mfma_f32_16x16x32_bf16 v[78:81], v[230:233], v[222:225], v[78:81]
	v_mfma_f32_16x16x32_bf16 v[82:85], v[238:241], v[222:225], v[82:85]
	v_mfma_f32_16x16x32_bf16 v[14:17], v[234:237], v[188:191], v[14:17]
	v_mfma_f32_16x16x32_bf16 v[10:13], v[242:245], v[188:191], v[10:13]
	v_mfma_f32_16x16x32_bf16 v[6:9], v[234:237], v[196:199], v[6:9]
	v_mfma_f32_16x16x32_bf16 v[2:5], v[242:245], v[196:199], v[2:5]
	v_mfma_f32_16x16x32_bf16 v[66:69], v[234:237], v[218:221], v[66:69]
	v_mfma_f32_16x16x32_bf16 v[74:77], v[242:245], v[218:221], v[74:77]
	v_mfma_f32_16x16x32_bf16 v[78:81], v[234:237], v[226:229], v[78:81]
	v_mfma_f32_16x16x32_bf16 v[82:85], v[242:245], v[226:229], v[82:85]
	s_setprio 0
	s_add_i32 s41, s41, 2
	v_lshl_add_u64 v[134:135], v[134:135], 0, s[72:73]
	v_lshl_add_u64 v[136:137], v[136:137], 0, s[72:73]
	v_lshl_add_u64 v[138:139], v[138:139], 0, s[72:73]
	s_cmp_lt_u32 s41, 12
	v_lshl_add_u64 v[140:141], v[140:141], 0, s[72:73]
	s_barrier
	s_cbranch_scc1 .LBB0_768
	s_mov_b64 s[42:43], 0x780
	v_readfirstlane_b32 s41, v159
	v_lshl_add_u64 v[132:133], v[132:133], 0, s[42:43]
	s_mov_b32 m0, s41
	v_readfirstlane_b32 s41, v160
	ds_read_b128 v[134:137], v144
	ds_read_b128 v[138:141], v144 offset:1024
	ds_read_b128 v[146:149], v144 offset:2048
	ds_read_b128 v[150:153], v144 offset:3072
	ds_read_b128 v[154:157], v0
	ds_read_b128 v[162:165], v0 offset:1024
	ds_read_b128 v[166:169], v0 offset:2048
	ds_read_b128 v[170:173], v0 offset:3072
	ds_read_b128 v[174:177], v0 offset:4096
	ds_read_b128 v[184:187], v0 offset:5120
	ds_read_b128 v[188:191], v0 offset:6144
	ds_read_b128 v[192:195], v0 offset:7168
	global_load_lds_dwordx4 v[132:133], off
	v_lshl_add_u64 v[130:131], v[130:131], 0, s[42:43]
	s_mov_b32 m0, s41
	s_cmpk_gt_u32 s52, 0xff
	global_load_lds_dwordx4 v[130:131], off
	s_barrier
	s_waitcnt lgkmcnt(0)
	s_setprio 1
	s_waitcnt lgkmcnt(0)
	v_mfma_f32_16x16x32_bf16 v[126:129], v[134:137], v[154:157], v[126:129]
	v_mfma_f32_16x16x32_bf16 v[118:121], v[134:137], v[166:169], v[118:121]
	v_mfma_f32_16x16x32_bf16 v[110:113], v[134:137], v[174:177], v[110:113]
	v_mfma_f32_16x16x32_bf16 v[102:105], v[134:137], v[188:191], v[102:105]
	v_mfma_f32_16x16x32_bf16 v[98:101], v[146:149], v[188:191], v[98:101]
	v_mfma_f32_16x16x32_bf16 v[126:129], v[138:141], v[162:165], v[126:129]
	v_mfma_f32_16x16x32_bf16 v[122:125], v[146:149], v[154:157], v[122:125]
	v_mfma_f32_16x16x32_bf16 v[118:121], v[138:141], v[170:173], v[118:121]
	v_mfma_f32_16x16x32_bf16 v[114:117], v[146:149], v[166:169], v[114:117]
	v_mfma_f32_16x16x32_bf16 v[110:113], v[138:141], v[184:187], v[110:113]
	v_mfma_f32_16x16x32_bf16 v[106:109], v[146:149], v[174:177], v[106:109]
	v_mfma_f32_16x16x32_bf16 v[102:105], v[138:141], v[192:195], v[102:105]
	v_mfma_f32_16x16x32_bf16 v[98:101], v[150:153], v[192:195], v[98:101]
	v_mfma_f32_16x16x32_bf16 v[130:133], v[150:153], v[162:165], v[122:125]
	v_mfma_f32_16x16x32_bf16 v[158:161], v[150:153], v[170:173], v[114:117]
	v_mfma_f32_16x16x32_bf16 v[196:199], v[150:153], v[184:187], v[106:109]
	s_setprio 0
	s_barrier
	s_nop 0
	ds_read_b128 v[106:109], v144 offset:16384
	ds_read_b128 v[114:117], v144 offset:17408
	ds_read_b128 v[122:125], v144 offset:18432
	ds_read_b128 v[200:203], v144 offset:19456
	s_barrier
	s_waitcnt lgkmcnt(0)
	s_setprio 1
	s_waitcnt lgkmcnt(0)
	v_mfma_f32_16x16x32_bf16 v[86:89], v[106:109], v[166:169], v[86:89]
	v_mfma_f32_16x16x32_bf16 v[70:73], v[122:125], v[166:169], v[70:73]
	v_mfma_f32_16x16x32_bf16 v[62:65], v[106:109], v[174:177], v[62:65]
	v_mfma_f32_16x16x32_bf16 v[58:61], v[122:125], v[174:177], v[58:61]
	v_mfma_f32_16x16x32_bf16 v[54:57], v[106:109], v[188:191], v[54:57]
	v_mfma_f32_16x16x32_bf16 v[50:53], v[122:125], v[188:191], v[50:53]
	v_mfma_f32_16x16x32_bf16 v[94:97], v[106:109], v[154:157], v[94:97]
	v_mfma_f32_16x16x32_bf16 v[90:93], v[122:125], v[154:157], v[90:93]
	v_mfma_f32_16x16x32_bf16 v[86:89], v[114:117], v[170:173], v[86:89]
	v_mfma_f32_16x16x32_bf16 v[70:73], v[200:203], v[170:173], v[70:73]
	v_mfma_f32_16x16x32_bf16 v[62:65], v[114:117], v[184:187], v[62:65]
	v_mfma_f32_16x16x32_bf16 v[58:61], v[200:203], v[184:187], v[58:61]
	v_mfma_f32_16x16x32_bf16 v[54:57], v[114:117], v[192:195], v[54:57]
	v_mfma_f32_16x16x32_bf16 v[50:53], v[200:203], v[192:195], v[50:53]
	v_mfma_f32_16x16x32_bf16 v[218:221], v[114:117], v[162:165], v[94:97]
	v_mfma_f32_16x16x32_bf16 v[154:157], v[200:203], v[162:165], v[90:93]
	s_setprio 0
	s_barrier
	s_nop 0
	ds_read_b128 v[90:93], v0 offset:16384
	ds_read_b128 v[94:97], v0 offset:17408
	ds_read_b128 v[162:165], v0 offset:18432
	ds_read_b128 v[166:169], v0 offset:19456
	ds_read_b128 v[170:173], v0 offset:20480
	ds_read_b128 v[174:177], v0 offset:21504
	ds_read_b128 v[184:187], v0 offset:22528
	ds_read_b128 v[188:191], v0 offset:23552
	s_waitcnt vmcnt(4)
	s_barrier
; #define LDA(dst, b, h) _Pragma("unroll") for (int m = 0; m < 4; ++m) _Pragma("unroll") for (int k = 0; k < 2; ++k) \
;     dst[m][k] = *reinterpret_cast<const bf16x8*>(smem + (((b) * 2 + (h)) * 16384 + m * 2048 + k * 1024) + aoff)
; #define LDB(dst, b, h) _Pragma("unroll") for (int n = 0; n < 2; ++n) _Pragma("unroll") for (int k = 0; k < 2; ++k) \
;     dst[n][k] = *reinterpret_cast<const bf16x8*>(smem + (((b) * 2 + (h)) * 16384 + n * 2048 + k * 1024) + boff)
; #define MMA(ai, bj, At_, Bt_) do { __builtin_amdgcn_s_setprio(1); \
;     _Pragma("unroll") for (int m = 0; m < 4; ++m) _Pragma("unroll") for (int n = 0; n < 2; ++n) _Pragma("unroll") for (int k = 0; k < 2; ++k) \
;       acc[ai][bj][m][n] = __builtin_amdgcn_mfma_f32_16x16x32_bf16(Bt_[n][k], At_[m][k], acc[ai][bj][m][n], 0, 0, 0); \
;     __builtin_amdgcn_s_setprio(0); } while (0)
; #define WAIT_V(n) asm volatile("s_waitcnt vmcnt(" #n ")" ::: "memory")
; #define WAIT_L(n) asm volatile("s_waitcnt lgkmcnt(" #n ")" ::: "memory")
; #define BAR __builtin_amdgcn_s_barrier()
; template <class Epi, int NB>
; DEV void gemm_tile_nb(const bf16* __restrict__ A, int lda, long strideA, const bf16* __restrict__ Bt, int ldb, long strideB, int K, int brow, int bcol, Epi& epi) {
;     ...
;     LDA(At, 0, 1); WAIT_V(4); BAR; WAIT_L(0); MMA(1, 0, At, B0); MMA(1, 1, At, B1); BAR; }
;   { LDB(B0, 1, 0); LDA(At, 1, 0); WAIT_V(2); BAR; WAIT_L(0); MMA(0, 0, At, B0); BAR;
	s_waitcnt lgkmcnt(0)
	s_setprio 1
	s_waitcnt lgkmcnt(0)
	v_mfma_f32_16x16x32_bf16 v[46:49], v[134:137], v[90:93], v[46:49]
	v_mfma_f32_16x16x32_bf16 v[42:45], v[146:149], v[90:93], v[42:45]
	v_mfma_f32_16x16x32_bf16 v[38:41], v[134:137], v[162:165], v[38:41]
	v_mfma_f32_16x16x32_bf16 v[34:37], v[146:149], v[162:165], v[34:37]
	v_mfma_f32_16x16x32_bf16 v[30:33], v[134:137], v[170:173], v[30:33]
	v_mfma_f32_16x16x32_bf16 v[26:29], v[146:149], v[170:173], v[26:29]
	v_mfma_f32_16x16x32_bf16 v[22:25], v[134:137], v[184:187], v[22:25]
	v_mfma_f32_16x16x32_bf16 v[18:21], v[146:149], v[184:187], v[18:21]
	v_mfma_f32_16x16x32_bf16 v[46:49], v[138:141], v[94:97], v[46:49]
	v_mfma_f32_16x16x32_bf16 v[42:45], v[150:153], v[94:97], v[42:45]
	v_mfma_f32_16x16x32_bf16 v[38:41], v[138:141], v[166:169], v[38:41]
	v_mfma_f32_16x16x32_bf16 v[34:37], v[150:153], v[166:169], v[34:37]
	v_mfma_f32_16x16x32_bf16 v[30:33], v[138:141], v[174:177], v[30:33]
	v_mfma_f32_16x16x32_bf16 v[26:29], v[150:153], v[174:177], v[26:29]
	v_mfma_f32_16x16x32_bf16 v[22:25], v[138:141], v[188:191], v[22:25]
	v_mfma_f32_16x16x32_bf16 v[18:21], v[150:153], v[188:191], v[18:21]
	s_setprio 0
	s_setprio 1
	v_mfma_f32_16x16x32_bf16 v[66:69], v[106:109], v[170:173], v[66:69]
	v_mfma_f32_16x16x32_bf16 v[134:137], v[114:117], v[174:177], v[66:69]
	v_mfma_f32_16x16x32_bf16 v[66:69], v[122:125], v[170:173], v[74:77]
	v_mfma_f32_16x16x32_bf16 v[14:17], v[106:109], v[90:93], v[14:17]
	v_mfma_f32_16x16x32_bf16 v[10:13], v[122:125], v[90:93], v[10:13]
	v_mfma_f32_16x16x32_bf16 v[6:9], v[106:109], v[162:165], v[6:9]
	v_mfma_f32_16x16x32_bf16 v[2:5], v[122:125], v[162:165], v[2:5]
	v_mfma_f32_16x16x32_bf16 v[138:141], v[200:203], v[174:177], v[66:69]
	v_mfma_f32_16x16x32_bf16 v[66:69], v[106:109], v[184:187], v[78:81]
	v_mfma_f32_16x16x32_bf16 v[14:17], v[114:117], v[94:97], v[14:17]
	v_mfma_f32_16x16x32_bf16 v[10:13], v[200:203], v[94:97], v[10:13]
	v_mfma_f32_16x16x32_bf16 v[6:9], v[114:117], v[166:169], v[6:9]
	v_mfma_f32_16x16x32_bf16 v[2:5], v[200:203], v[166:169], v[2:5]
	v_mfma_f32_16x16x32_bf16 v[146:149], v[114:117], v[188:191], v[66:69]
	v_mfma_f32_16x16x32_bf16 v[66:69], v[122:125], v[184:187], v[82:85]
	v_mfma_f32_16x16x32_bf16 v[150:153], v[200:203], v[188:191], v[66:69]
	s_setprio 0
	s_barrier
	ds_read_b128 v[162:165], v144 offset:32768
	ds_read_b128 v[166:169], v144 offset:33792
	ds_read_b128 v[170:173], v144 offset:34816
	ds_read_b128 v[174:177], v144 offset:35840
	s_nop 0
	ds_read_b128 v[66:69], v0 offset:32768
	ds_read_b128 v[74:77], v0 offset:33792
	ds_read_b128 v[78:81], v0 offset:34816
	ds_read_b128 v[184:187], v0 offset:35840
	ds_read_b128 v[188:191], v0 offset:36864
	ds_read_b128 v[192:195], v0 offset:37888
	ds_read_b128 v[200:203], v0 offset:38912
	ds_read_b128 v[222:225], v0 offset:39936
	s_waitcnt vmcnt(2)
	s_barrier
	s_waitcnt lgkmcnt(0)
	s_setprio 1
	s_waitcnt lgkmcnt(0)
	v_mfma_f32_16x16x32_bf16 v[82:85], v[162:165], v[66:69], v[126:129]
	v_mfma_f32_16x16x32_bf16 v[122:125], v[166:169], v[74:77], v[82:85]
	v_mfma_f32_16x16x32_bf16 v[82:85], v[170:173], v[66:69], v[130:133]
	v_mfma_f32_16x16x32_bf16 v[126:129], v[174:177], v[74:77], v[82:85]
	v_mfma_f32_16x16x32_bf16 v[82:85], v[162:165], v[78:81], v[118:121]
	v_mfma_f32_16x16x32_bf16 v[114:117], v[166:169], v[184:187], v[82:85]
	v_mfma_f32_16x16x32_bf16 v[82:85], v[170:173], v[78:81], v[158:161]
	v_mfma_f32_16x16x32_bf16 v[118:121], v[174:177], v[184:187], v[82:85]
	v_mfma_f32_16x16x32_bf16 v[82:85], v[162:165], v[188:191], v[110:113]
	v_mfma_f32_16x16x32_bf16 v[106:109], v[166:169], v[192:195], v[82:85]
	v_mfma_f32_16x16x32_bf16 v[82:85], v[170:173], v[188:191], v[196:199]
	v_mfma_f32_16x16x32_bf16 v[110:113], v[174:177], v[192:195], v[82:85]
	v_mfma_f32_16x16x32_bf16 v[82:85], v[162:165], v[200:203], v[102:105]
	v_mfma_f32_16x16x32_bf16 v[90:93], v[166:169], v[222:225], v[82:85]
	v_mfma_f32_16x16x32_bf16 v[82:85], v[170:173], v[200:203], v[98:101]
	v_mfma_f32_16x16x32_bf16 v[94:97], v[174:177], v[222:225], v[82:85]
	s_setprio 0
	s_barrier
; #define LDA(dst, b, h) _Pragma("unroll") for (int m = 0; m < 4; ++m) _Pragma("unroll") for (int k = 0; k < 2; ++k) \
;     dst[m][k] = *reinterpret_cast<const bf16x8*>(smem + (((b) * 2 + (h)) * 16384 + m * 2048 + k * 1024) + aoff)
; #define LDB(dst, b, h) _Pragma("unroll") for (int n = 0; n < 2; ++n) _Pragma("unroll") for (int k = 0; k < 2; ++k) \
;     dst[n][k] = *reinterpret_cast<const bf16x8*>(smem + (((b) * 2 + (h)) * 16384 + n * 2048 + k * 1024) + boff)
; #define MMA(ai, bj, At_, Bt_) do { __builtin_amdgcn_s_setprio(1); \
;     _Pragma("unroll") for (int m = 0; m < 4; ++m) _Pragma("unroll") for (int n = 0; n < 2; ++n) _Pragma("unroll") for (int k = 0; k < 2; ++k) \
;       acc[ai][bj][m][n] = __builtin_amdgcn_mfma_f32_16x16x32_bf16(Bt_[n][k], At_[m][k], acc[ai][bj][m][n], 0, 0, 0); \
;     __builtin_amdgcn_s_setprio(0); } while (0)
; #define WAIT_V(n) asm volatile("s_waitcnt vmcnt(" #n ")" ::: "memory")
; #define WAIT_L(n) asm volatile("s_waitcnt lgkmcnt(" #n ")" ::: "memory")
; #define BAR __builtin_amdgcn_s_barrier()
; template <class Epi, int NB>
; DEV void gemm_tile_nb(const bf16* __restrict__ A, int lda, long strideA, const bf16* __restrict__ Bt, int ldb, long strideB, int K, int brow, int bcol, Epi& epi) {
;     ...
;     LDB(B1, 1, 1); WAIT_V(0); BAR; WAIT_L(0); MMA(0, 1, At, B1); BAR;
;     LDA(At, 1, 1); BAR; WAIT_L(0); MMA(1, 0, At, B0); MMA(1, 1, At, B1); BAR; }
;   if (wr == 0) BAR;
	ds_read_b128 v[130:133], v144 offset:49152
	ds_read_b128 v[158:161], v144 offset:50176
	ds_read_b128 v[196:199], v144 offset:51200
	ds_read_b128 v[226:229], v144 offset:52224
	s_waitcnt vmcnt(0)
	s_barrier
	s_waitcnt lgkmcnt(0)
	s_setprio 1
	s_waitcnt lgkmcnt(0)
	v_mfma_f32_16x16x32_bf16 v[82:85], v[130:133], v[66:69], v[218:221]
	v_mfma_f32_16x16x32_bf16 v[66:69], v[196:199], v[66:69], v[154:157]
	v_mfma_f32_16x16x32_bf16 v[102:105], v[226:229], v[74:77], v[66:69]
	v_mfma_f32_16x16x32_bf16 v[66:69], v[130:133], v[78:81], v[86:89]
	v_mfma_f32_16x16x32_bf16 v[98:101], v[158:161], v[74:77], v[82:85]
	v_mfma_f32_16x16x32_bf16 v[82:85], v[158:161], v[184:187], v[66:69]
	v_mfma_f32_16x16x32_bf16 v[66:69], v[196:199], v[78:81], v[70:73]
	v_mfma_f32_16x16x32_bf16 v[62:65], v[130:133], v[188:191], v[62:65]
	v_mfma_f32_16x16x32_bf16 v[58:61], v[196:199], v[188:191], v[58:61]
	v_mfma_f32_16x16x32_bf16 v[54:57], v[130:133], v[200:203], v[54:57]
	v_mfma_f32_16x16x32_bf16 v[50:53], v[196:199], v[200:203], v[50:53]
	v_mfma_f32_16x16x32_bf16 v[86:89], v[226:229], v[184:187], v[66:69]
	v_mfma_f32_16x16x32_bf16 v[74:77], v[158:161], v[192:195], v[62:65]
	v_mfma_f32_16x16x32_bf16 v[78:81], v[226:229], v[192:195], v[58:61]
	v_mfma_f32_16x16x32_bf16 v[66:69], v[158:161], v[222:225], v[54:57]
	v_mfma_f32_16x16x32_bf16 v[70:73], v[226:229], v[222:225], v[50:53]
	s_setprio 0
	s_barrier
	ds_read_b128 v[154:157], v0 offset:49152
	ds_read_b128 v[184:187], v0 offset:50176
	ds_read_b128 v[188:191], v0 offset:51200
	ds_read_b128 v[192:195], v0 offset:52224
	ds_read_b128 v[200:203], v0 offset:53248
	ds_read_b128 v[218:221], v0 offset:54272
	ds_read_b128 v[222:225], v0 offset:55296
	ds_read_b128 v[230:233], v0 offset:56320
	s_barrier
	s_waitcnt lgkmcnt(0)
	s_setprio 1
	s_waitcnt lgkmcnt(0)
	v_mfma_f32_16x16x32_bf16 v[46:49], v[162:165], v[154:157], v[46:49]
	v_mfma_f32_16x16x32_bf16 v[42:45], v[170:173], v[154:157], v[42:45]
	v_mfma_f32_16x16x32_bf16 v[38:41], v[162:165], v[188:191], v[38:41]
	v_mfma_f32_16x16x32_bf16 v[34:37], v[170:173], v[188:191], v[34:37]
	v_mfma_f32_16x16x32_bf16 v[30:33], v[162:165], v[200:203], v[30:33]
	v_mfma_f32_16x16x32_bf16 v[26:29], v[170:173], v[200:203], v[26:29]
	v_mfma_f32_16x16x32_bf16 v[22:25], v[162:165], v[222:225], v[22:25]
	v_mfma_f32_16x16x32_bf16 v[18:21], v[170:173], v[222:225], v[18:21]
	v_mfma_f32_16x16x32_bf16 v[58:61], v[166:169], v[184:187], v[46:49]
	v_mfma_f32_16x16x32_bf16 v[62:65], v[174:177], v[184:187], v[42:45]
	v_mfma_f32_16x16x32_bf16 v[50:53], v[166:169], v[192:195], v[38:41]
	v_mfma_f32_16x16x32_bf16 v[54:57], v[174:177], v[192:195], v[34:37]
	v_mfma_f32_16x16x32_bf16 v[42:45], v[166:169], v[218:221], v[30:33]
	v_mfma_f32_16x16x32_bf16 v[46:49], v[174:177], v[218:221], v[26:29]
	v_mfma_f32_16x16x32_bf16 v[34:37], v[166:169], v[230:233], v[22:25]
	v_mfma_f32_16x16x32_bf16 v[38:41], v[174:177], v[230:233], v[18:21]
	s_setprio 0
	s_setprio 1
	v_mfma_f32_16x16x32_bf16 v[2:5], v[196:199], v[188:191], v[2:5]
	v_mfma_f32_16x16x32_bf16 v[10:13], v[196:199], v[154:157], v[10:13]
	v_mfma_f32_16x16x32_bf16 v[22:25], v[226:229], v[192:195], v[2:5]
	v_mfma_f32_16x16x32_bf16 v[2:5], v[130:133], v[200:203], v[134:137]
	v_mfma_f32_16x16x32_bf16 v[14:17], v[130:133], v[154:157], v[14:17]
	v_mfma_f32_16x16x32_bf16 v[30:33], v[226:229], v[184:187], v[10:13]
	v_mfma_f32_16x16x32_bf16 v[6:9], v[130:133], v[188:191], v[6:9]
	v_mfma_f32_16x16x32_bf16 v[10:13], v[158:161], v[218:221], v[2:5]
	v_mfma_f32_16x16x32_bf16 v[2:5], v[196:199], v[200:203], v[138:141]
	v_mfma_f32_16x16x32_bf16 v[26:29], v[158:161], v[184:187], v[14:17]
	v_mfma_f32_16x16x32_bf16 v[18:21], v[158:161], v[192:195], v[6:9]
	v_mfma_f32_16x16x32_bf16 v[14:17], v[226:229], v[218:221], v[2:5]
	v_mfma_f32_16x16x32_bf16 v[2:5], v[130:133], v[222:225], v[146:149]
	v_mfma_f32_16x16x32_bf16 v[6:9], v[196:199], v[222:225], v[150:153]
	v_mfma_f32_16x16x32_bf16 v[2:5], v[158:161], v[230:233], v[2:5]
	v_mfma_f32_16x16x32_bf16 v[6:9], v[226:229], v[230:233], v[6:9]
	s_setprio 0
	s_barrier
	s_cbranch_scc1 .LBB0_763
	s_barrier
	s_branch .LBB0_763

; #define STAGE(P, BASE, LD, br, kt) do { const bf16* _gb = BASE + ((long)(br) * (LD) + (long)(kt) * BK); \
;     _Pragma("unroll") for (int _i = 0; _i < 2; ++_i) { \
;       __builtin_amdgcn_global_load_lds((const unsigned*)(_gb + ((&LD == &lda) ? offA[_i] : offB[_i])), \
;         (unsigned*)((char*)(P) + tidx_ * 16 + _i * 8192), 16, 0, 0); } } while (0)
; #define WAIT_V(n) asm volatile("s_waitcnt vmcnt(" #n ")" ::: "memory")
; #define BAR __builtin_amdgcn_s_barrier()
; template <class Epi, int NB>
; DEV void gemm_tile_nb(const bf16* __restrict__ A, int lda, long strideA, const bf16* __restrict__ Bt, int ldb, long strideB, int K, int brow, int bcol, Epi& epi) {
;     ...
;   const int lane_off_ = (fr * 64 + fq * 16) ^ ((fr >> 3) << 5);
;   const int aoff = wr * 8192 + lane_off_, boff = 65536 + wc * 4096 + lane_off_;
;   unsigned offA[2], offB[2];
; #pragma unroll
;   for (int _i = 0; _i < 2; ++_i) { int _r, _c; stage_rc(tidx_ * 16 + _i * 8192, _r, _c); offA[_i] = (unsigned)(_r * lda + _c); offB[_i] = (unsigned)(_r * ldb + _c); }
; #pragma unroll 1
;   for (int br = 0; br < NB; ++br) {
;   STAGE(SB(0, 0), Bt, ldb, bcol, 0); STAGE(SA(0, 0), A, lda, brow, 0);
;   STAGE(SB(0, 1), Bt, ldb, bcol + HALF, 0); STAGE(SA(0, 1), A, lda, brow + HALF, 0);
;   if (wr == 1) BAR;
;   WAIT_V(4); BAR;
;   STAGE(SB(1, 0), Bt, ldb, bcol, 1); STAGE(SA(1, 0), A, lda, brow, 1); STAGE(SB(1, 1), Bt, ldb, bcol + HALF, 1);
;   WAIT_V(6); BAR;
.LBB0_783:
	v_and_b32_e32 v143, 15, v23
	s_bfe_u32 s1, s50, 0x20006
	v_bfe_u32 v142, v23, 4, 2
	v_lshlrev_b32_e32 v0, 6, v143
	v_lshlrev_b32_e32 v23, 2, v23
	v_lshl_or_b32 v0, v142, 4, v0
	v_and_b32_e32 v23, 32, v23
	s_lshl_b32 s39, s45, 13
	s_lshl_b32 s51, s1, 12
	v_add_u32_e32 v153, s13, v16
	v_bitop3_b32 v24, v0, s51, v23 bitop3:0xde
	v_bitop3_b32 v23, v0, s39, v23 bitop3:0xde
	s_mov_b64 s[52:53], 0x80
	v_readfirstlane_b32 s39, v153
	v_add_u32_e32 v154, 0x2000, v153
	v_lshl_add_u64 v[2:3], v[2:3], 0, s[52:53]
	s_mov_b32 m0, s39
	v_readfirstlane_b32 s39, v154
	v_add_u32_e32 v155, 0x8000, v146
	s_waitcnt vmcnt(4)
	s_barrier
	global_load_lds_dwordx4 v[2:3], off
	v_lshl_add_u64 v[2:3], v[6:7], 0, s[52:53]
	s_mov_b32 m0, s39
	v_readfirstlane_b32 s39, v155
	v_add_u32_e32 v156, 0xa000, v146
	global_load_lds_dwordx4 v[2:3], off
	v_lshl_add_u64 v[2:3], v[12:13], 0, s[52:53]
	s_mov_b32 m0, s39
	v_readfirstlane_b32 s39, v156
	v_add_u32_e32 v157, s14, v16
	global_load_lds_dwordx4 v[2:3], off
	v_lshl_add_u64 v[2:3], v[8:9], 0, s[52:53]
	s_mov_b32 m0, s39
	v_readfirstlane_b32 s39, v157
	v_add_u32_e32 v158, 0x2000, v157
	global_load_lds_dwordx4 v[2:3], off
	v_lshl_add_u64 v[2:3], v[10:11], 0, s[52:53]
	s_mov_b32 m0, s39
	v_readfirstlane_b32 s39, v158
	global_load_lds_dwordx4 v[2:3], off
	v_lshl_add_u64 v[2:3], v[4:5], 0, s[52:53]
	s_mov_b32 m0, s39
	v_lshlrev_b32_e32 v0, 13, v14
	global_load_lds_dwordx4 v[2:3], off
	v_and_b32_e32 v0, 0xffffc000, v0
	v_lshl_add_u32 v0, v15, 10, v0
	v_or_b32_e32 v0, v0, v17
	v_add_u32_sdwa v0, v0, sext(v18) dst_sel:DWORD dst_unused:UNUSED_PAD src0_sel:DWORD src1_sel:WORD_0
	v_lshlrev_b64 v[2:3], 1, v[0:1]
	v_lshlrev_b32_e32 v0, 13, v19
	v_and_b32_e32 v0, 0xffffc000, v0
	v_readlane_b32 s8, v254, 63
	v_lshl_add_u32 v0, v20, 10, v0
	s_add_u32 s42, s8, s42
	v_or_b32_e32 v0, v0, v21
	s_waitcnt vmcnt(6)
	s_addc_u32 s43, 0, s43
	v_add_u32_sdwa v0, v0, sext(v22) dst_sel:DWORD dst_unused:UNUSED_PAD src0_sel:DWORD src1_sel:WORD_0
	v_or_b32_e32 v24, 0x10000, v24
	v_lshl_add_u64 v[134:135], s[42:43], 0, v[2:3]
	v_lshlrev_b64 v[4:5], 1, v[0:1]
	v_lshl_add_u64 v[138:139], s[40:41], 0, v[2:3]
	v_mov_b32_e32 v2, 0
	v_lshl_add_u64 v[136:137], s[42:43], 0, v[4:5]
	v_lshl_add_u64 v[140:141], s[40:41], 0, v[4:5]
	s_mov_b32 s39, -2
	v_add_u32_e32 v144, 0, v24
	v_add_u32_e32 v0, 0, v23
	v_mov_b32_e32 v3, v2
	v_mov_b32_e32 v4, v2
	v_mov_b32_e32 v5, v2
	v_mov_b32_e32 v6, v2
	v_mov_b32_e32 v7, v2
	v_mov_b32_e32 v8, v2
	v_mov_b32_e32 v9, v2
	v_mov_b32_e32 v10, v2
	v_mov_b32_e32 v11, v2
	v_mov_b32_e32 v12, v2
	v_mov_b32_e32 v13, v2
	v_mov_b32_e32 v14, v2
	v_mov_b32_e32 v15, v2
	v_mov_b32_e32 v16, v2
	v_mov_b32_e32 v17, v2
	v_mov_b32_e32 v18, v2
	v_mov_b32_e32 v19, v2
	v_mov_b32_e32 v20, v2
	v_mov_b32_e32 v21, v2
	v_mov_b32_e32 v22, v2
	v_mov_b32_e32 v23, v2
	v_mov_b32_e32 v24, v2
	v_mov_b32_e32 v25, v2
	v_mov_b32_e32 v26, v2
	v_mov_b32_e32 v27, v2
	s_waitcnt vmcnt(0)
	v_mov_b32_e32 v28, v2
	v_mov_b32_e32 v29, v2
	v_mov_b32_e32 v30, v2
	v_mov_b32_e32 v31, v2
	v_mov_b32_e32 v32, v2
	v_mov_b32_e32 v33, v2
	v_mov_b32_e32 v34, v2
	v_mov_b32_e32 v35, v2
	v_mov_b32_e32 v36, v2
	v_mov_b32_e32 v37, v2
	v_mov_b32_e32 v38, v2
	v_mov_b32_e32 v39, v2
	v_mov_b32_e32 v40, v2
	v_mov_b32_e32 v41, v2
	v_mov_b32_e32 v42, v2
	v_mov_b32_e32 v43, v2
	v_mov_b32_e32 v44, v2
	v_mov_b32_e32 v45, v2
	v_mov_b32_e32 v46, v2
	v_mov_b32_e32 v47, v2
	v_mov_b32_e32 v48, v2
	v_mov_b32_e32 v49, v2
	v_mov_b32_e32 v50, v2
	v_mov_b32_e32 v51, v2
	v_mov_b32_e32 v52, v2
	v_mov_b32_e32 v53, v2
	v_mov_b32_e32 v54, v2
	v_mov_b32_e32 v55, v2
	v_mov_b32_e32 v56, v2
	v_mov_b32_e32 v57, v2
	v_mov_b32_e32 v58, v2
	v_mov_b32_e32 v59, v2
	v_mov_b32_e32 v60, v2
	v_mov_b32_e32 v61, v2
	v_mov_b32_e32 v62, v2
	v_mov_b32_e32 v63, v2
	v_mov_b32_e32 v64, v2
	v_mov_b32_e32 v65, v2
	v_mov_b32_e32 v70, v2
	v_mov_b32_e32 v71, v2
	v_mov_b32_e32 v72, v2
	v_mov_b32_e32 v73, v2
	v_mov_b32_e32 v86, v2
	v_mov_b32_e32 v87, v2
	v_mov_b32_e32 v88, v2
	v_mov_b32_e32 v89, v2
	v_mov_b32_e32 v90, v2
	v_mov_b32_e32 v91, v2
	v_mov_b32_e32 v92, v2
	v_mov_b32_e32 v93, v2
	v_mov_b32_e32 v94, v2
	v_mov_b32_e32 v95, v2
	v_mov_b32_e32 v96, v2
	v_mov_b32_e32 v97, v2
	v_mov_b32_e32 v98, v2
	v_mov_b32_e32 v99, v2
	v_mov_b32_e32 v100, v2
	v_mov_b32_e32 v101, v2
	v_mov_b32_e32 v102, v2
	v_mov_b32_e32 v103, v2
	v_mov_b32_e32 v104, v2
	v_mov_b32_e32 v105, v2
	v_mov_b32_e32 v106, v2
	v_mov_b32_e32 v107, v2
	v_mov_b32_e32 v108, v2
	v_mov_b32_e32 v109, v2
	v_mov_b32_e32 v110, v2
	v_mov_b32_e32 v111, v2
	v_mov_b32_e32 v112, v2
	v_mov_b32_e32 v113, v2
	v_mov_b32_e32 v114, v2
	v_mov_b32_e32 v115, v2
	v_mov_b32_e32 v116, v2
	v_mov_b32_e32 v117, v2
	v_mov_b32_e32 v118, v2
	v_mov_b32_e32 v119, v2
	v_mov_b32_e32 v120, v2
	v_mov_b32_e32 v121, v2
	v_mov_b32_e32 v122, v2
	v_mov_b32_e32 v123, v2
	v_mov_b32_e32 v124, v2
	v_mov_b32_e32 v125, v2
	v_mov_b32_e32 v126, v2
	v_mov_b32_e32 v127, v2
	v_mov_b32_e32 v128, v2
	v_mov_b32_e32 v129, v2
	v_mov_b32_e32 v66, v2
	v_mov_b32_e32 v67, v2
	v_mov_b32_e32 v68, v2
	v_mov_b32_e32 v69, v2
	v_mov_b32_e32 v74, v2
	v_mov_b32_e32 v75, v2
	v_mov_b32_e32 v76, v2
	v_mov_b32_e32 v77, v2
	v_mov_b32_e32 v78, v2
	v_mov_b32_e32 v79, v2
	v_mov_b32_e32 v80, v2
	v_mov_b32_e32 v81, v2
	v_mov_b32_e32 v82, v2
	v_mov_b32_e32 v83, v2
	v_mov_b32_e32 v84, v2
	v_mov_b32_e32 v85, v2
	s_mov_b64 s[42:43], 0xabe4080
	s_mov_b64 s[52:53], 0x2100100
	s_mov_b64 s[54:55], 0x2140100
	s_mov_b64 s[56:57], 0xabe4100
	s_mov_b64 s[58:59], 0x2100180
	s_mov_b64 s[60:61], 0x2140180
	s_barrier
	ds_read_b128 v[162:165], v144
	ds_read_b128 v[166:169], v144 offset:1024
	ds_read_b128 v[170:173], v144 offset:2048
	ds_read_b128 v[174:177], v144 offset:3072
; #define STAGE(P, BASE, LD, br, kt) do { const bf16* _gb = BASE + ((long)(br) * (LD) + (long)(kt) * BK); \
;     _Pragma("unroll") for (int _i = 0; _i < 2; ++_i) { \
;       __builtin_amdgcn_global_load_lds((const unsigned*)(_gb + ((&LD == &lda) ? offA[_i] : offB[_i])), \
;         (unsigned*)((char*)(P) + tidx_ * 16 + _i * 8192), 16, 0, 0); } } while (0)
; #define LDA(dst, b, h) _Pragma("unroll") for (int m = 0; m < 4; ++m) _Pragma("unroll") for (int k = 0; k < 2; ++k) \
;     dst[m][k] = *reinterpret_cast<const bf16x8*>(smem + (((b) * 2 + (h)) * 16384 + m * 2048 + k * 1024) + aoff)
; #define LDB(dst, b, h) _Pragma("unroll") for (int n = 0; n < 2; ++n) _Pragma("unroll") for (int k = 0; k < 2; ++k) \
;     dst[n][k] = *reinterpret_cast<const bf16x8*>(smem + (((b) * 2 + (h)) * 16384 + n * 2048 + k * 1024) + boff)
; #define MMA(ai, bj, At_, Bt_) do { __builtin_amdgcn_s_setprio(1); \
;     _Pragma("unroll") for (int m = 0; m < 4; ++m) _Pragma("unroll") for (int n = 0; n < 2; ++n) _Pragma("unroll") for (int k = 0; k < 2; ++k) \
;       acc[ai][bj][m][n] = __builtin_amdgcn_mfma_f32_16x16x32_bf16(Bt_[n][k], At_[m][k], acc[ai][bj][m][n], 0, 0, 0); \
;     __builtin_amdgcn_s_setprio(0); } while (0)
; #define WAIT_L(n) asm volatile("s_waitcnt lgkmcnt(" #n ")" ::: "memory")
; #define BAR __builtin_amdgcn_s_barrier()
; #define SCHED __builtin_amdgcn_sched_barrier(0)
; template <class Epi, int NB>
; DEV void gemm_tile_nb(const bf16* __restrict__ A, int lda, long strideA, const bf16* __restrict__ Bt, int ldb, long strideB, int K, int brow, int bcol, Epi& epi) {
;     ...
;     LDB(B0, 0, 0); SCHED; LDA(At, 0, 0); STAGE(SA(1, 1), A, lda, brow + HALF, t + 1);
;     WAIT_L(8); BAR; WAIT_L(0); MMA(0, 0, At, B0); BAR; SCHED;
;     LDB(B1, 0, 1); STAGE(SB(0, 0), Bt, ldb, bcol, t + 2);
;     BAR; WAIT_L(0); MMA(0, 1, At, B1); BAR;
;     LDA(At, 0, 1); STAGE(SA(0, 0), A, lda, brow, t + 2);
;     BAR; WAIT_L(0); MMA(1, 0, At, B0); BAR; SCHED;
.LBB0_784:
	v_add_u32_e32 v159, 0xc000, v146
	v_lshl_add_u64 v[204:205], s[88:89], 0, v[138:139]
	v_readfirstlane_b32 s40, v159
	v_lshl_add_u64 v[160:161], v[204:205], 0, s[42:43]
	s_mov_b32 m0, s40
	ds_read_b128 v[184:187], v0
	ds_read_b128 v[188:191], v0 offset:1024
	ds_read_b128 v[192:195], v0 offset:2048
	ds_read_b128 v[196:199], v0 offset:3072
	ds_read_b128 v[200:203], v0 offset:4096
	ds_read_b128 v[218:221], v0 offset:5120
	ds_read_b128 v[222:225], v0 offset:6144
	ds_read_b128 v[226:229], v0 offset:7168
	global_load_lds_dwordx4 v[160:161], off
	v_add_u32_e32 v160, 0xe000, v146
	v_lshl_add_u64 v[208:209], s[88:89], 0, v[140:141]
	v_readfirstlane_b32 s40, v160
	v_lshl_add_u64 v[214:215], v[208:209], 0, s[42:43]
	s_mov_b32 m0, s40
	s_nop 0
	global_load_lds_dwordx4 v[214:215], off
	s_waitcnt lgkmcnt(8)
	s_barrier
	s_waitcnt lgkmcnt(0)
	s_setprio 1
	s_waitcnt lgkmcnt(0)
	v_mfma_f32_16x16x32_bf16 v[126:129], v[162:165], v[184:187], v[126:129]
	v_mfma_f32_16x16x32_bf16 v[122:125], v[170:173], v[184:187], v[122:125]
	v_mfma_f32_16x16x32_bf16 v[118:121], v[162:165], v[192:195], v[118:121]
	v_mfma_f32_16x16x32_bf16 v[114:117], v[170:173], v[192:195], v[114:117]
	v_mfma_f32_16x16x32_bf16 v[110:113], v[162:165], v[200:203], v[110:113]
	v_mfma_f32_16x16x32_bf16 v[106:109], v[170:173], v[200:203], v[106:109]
	v_mfma_f32_16x16x32_bf16 v[102:105], v[162:165], v[222:225], v[102:105]
	v_mfma_f32_16x16x32_bf16 v[98:101], v[170:173], v[222:225], v[98:101]
	v_mfma_f32_16x16x32_bf16 v[126:129], v[166:169], v[188:191], v[126:129]
	v_mfma_f32_16x16x32_bf16 v[122:125], v[174:177], v[188:191], v[122:125]
	v_mfma_f32_16x16x32_bf16 v[118:121], v[166:169], v[196:199], v[118:121]
	v_mfma_f32_16x16x32_bf16 v[114:117], v[174:177], v[196:199], v[114:117]
	v_mfma_f32_16x16x32_bf16 v[110:113], v[166:169], v[218:221], v[110:113]
	v_mfma_f32_16x16x32_bf16 v[106:109], v[174:177], v[218:221], v[106:109]
	v_mfma_f32_16x16x32_bf16 v[102:105], v[166:169], v[226:229], v[102:105]
	v_mfma_f32_16x16x32_bf16 v[98:101], v[174:177], v[226:229], v[98:101]
	s_setprio 0
	s_barrier
	v_lshl_add_u64 v[214:215], s[88:89], 0, v[134:135]
	v_readfirstlane_b32 s40, v145
	v_lshl_add_u64 v[246:247], v[214:215], 0, s[52:53]
	s_mov_b32 m0, s40
	ds_read_b128 v[230:233], v144 offset:16384
	ds_read_b128 v[234:237], v144 offset:17408
	ds_read_b128 v[238:241], v144 offset:18432
	ds_read_b128 v[242:245], v144 offset:19456
	global_load_lds_dwordx4 v[246:247], off
	v_lshl_add_u64 v[246:247], s[88:89], 0, v[136:137]
	v_readfirstlane_b32 s40, v148
	v_lshl_add_u64 v[248:249], v[246:247], 0, s[52:53]
	s_mov_b32 m0, s40
	s_nop 0
	global_load_lds_dwordx4 v[248:249], off
	s_barrier
	s_waitcnt lgkmcnt(0)
	s_setprio 1
	s_waitcnt lgkmcnt(0)
	v_mfma_f32_16x16x32_bf16 v[94:97], v[230:233], v[184:187], v[94:97]
	v_mfma_f32_16x16x32_bf16 v[90:93], v[238:241], v[184:187], v[90:93]
	v_mfma_f32_16x16x32_bf16 v[86:89], v[230:233], v[192:195], v[86:89]
	v_mfma_f32_16x16x32_bf16 v[70:73], v[238:241], v[192:195], v[70:73]
	v_mfma_f32_16x16x32_bf16 v[62:65], v[230:233], v[200:203], v[62:65]
	v_mfma_f32_16x16x32_bf16 v[58:61], v[238:241], v[200:203], v[58:61]
	v_mfma_f32_16x16x32_bf16 v[54:57], v[230:233], v[222:225], v[54:57]
	v_mfma_f32_16x16x32_bf16 v[50:53], v[238:241], v[222:225], v[50:53]
	v_mfma_f32_16x16x32_bf16 v[94:97], v[234:237], v[188:191], v[94:97]
	v_mfma_f32_16x16x32_bf16 v[90:93], v[242:245], v[188:191], v[90:93]
	v_mfma_f32_16x16x32_bf16 v[86:89], v[234:237], v[196:199], v[86:89]
	v_mfma_f32_16x16x32_bf16 v[70:73], v[242:245], v[196:199], v[70:73]
	v_mfma_f32_16x16x32_bf16 v[62:65], v[234:237], v[218:221], v[62:65]
	v_mfma_f32_16x16x32_bf16 v[58:61], v[242:245], v[218:221], v[58:61]
	v_mfma_f32_16x16x32_bf16 v[54:57], v[234:237], v[226:229], v[54:57]
	v_mfma_f32_16x16x32_bf16 v[50:53], v[242:245], v[226:229], v[50:53]
	s_setprio 0
	v_readfirstlane_b32 s40, v146
	v_lshl_add_u64 v[248:249], v[204:205], 0, s[28:29]
	s_mov_b32 m0, s40
	v_readfirstlane_b32 s40, v150
	s_barrier
	ds_read_b128 v[184:187], v0 offset:16384
	ds_read_b128 v[188:191], v0 offset:17408
	ds_read_b128 v[192:195], v0 offset:18432
	ds_read_b128 v[196:199], v0 offset:19456
	ds_read_b128 v[200:203], v0 offset:20480
	ds_read_b128 v[218:221], v0 offset:21504
	ds_read_b128 v[222:225], v0 offset:22528
	ds_read_b128 v[226:229], v0 offset:23552
	global_load_lds_dwordx4 v[248:249], off
	v_lshl_add_u64 v[248:249], v[208:209], 0, s[28:29]
	s_mov_b32 m0, s40
	s_nop 0
	global_load_lds_dwordx4 v[248:249], off
	s_waitcnt vmcnt(10)
	s_barrier
	s_waitcnt lgkmcnt(0)
	s_setprio 1
	s_waitcnt lgkmcnt(0)
	v_mfma_f32_16x16x32_bf16 v[46:49], v[162:165], v[184:187], v[46:49]
	v_mfma_f32_16x16x32_bf16 v[42:45], v[170:173], v[184:187], v[42:45]
	v_mfma_f32_16x16x32_bf16 v[38:41], v[162:165], v[192:195], v[38:41]
	v_mfma_f32_16x16x32_bf16 v[34:37], v[170:173], v[192:195], v[34:37]
	v_mfma_f32_16x16x32_bf16 v[30:33], v[162:165], v[200:203], v[30:33]
	v_mfma_f32_16x16x32_bf16 v[26:29], v[170:173], v[200:203], v[26:29]
	v_mfma_f32_16x16x32_bf16 v[22:25], v[162:165], v[222:225], v[22:25]
	v_mfma_f32_16x16x32_bf16 v[18:21], v[170:173], v[222:225], v[18:21]
	v_mfma_f32_16x16x32_bf16 v[46:49], v[166:169], v[188:191], v[46:49]
	v_mfma_f32_16x16x32_bf16 v[42:45], v[174:177], v[188:191], v[42:45]
	v_mfma_f32_16x16x32_bf16 v[38:41], v[166:169], v[196:199], v[38:41]
	v_mfma_f32_16x16x32_bf16 v[34:37], v[174:177], v[196:199], v[34:37]
	v_mfma_f32_16x16x32_bf16 v[30:33], v[166:169], v[218:221], v[30:33]
	v_mfma_f32_16x16x32_bf16 v[26:29], v[174:177], v[218:221], v[26:29]
	v_mfma_f32_16x16x32_bf16 v[22:25], v[166:169], v[226:229], v[22:25]
	v_mfma_f32_16x16x32_bf16 v[18:21], v[174:177], v[226:229], v[18:21]
	s_setprio 0
	s_barrier
; #define STAGE(P, BASE, LD, br, kt) do { const bf16* _gb = BASE + ((long)(br) * (LD) + (long)(kt) * BK); \
;     _Pragma("unroll") for (int _i = 0; _i < 2; ++_i) { \
;       __builtin_amdgcn_global_load_lds((const unsigned*)(_gb + ((&LD == &lda) ? offA[_i] : offB[_i])), \
;         (unsigned*)((char*)(P) + tidx_ * 16 + _i * 8192), 16, 0, 0); } } while (0)
; #define LDA(dst, b, h) _Pragma("unroll") for (int m = 0; m < 4; ++m) _Pragma("unroll") for (int k = 0; k < 2; ++k) \
;     dst[m][k] = *reinterpret_cast<const bf16x8*>(smem + (((b) * 2 + (h)) * 16384 + m * 2048 + k * 1024) + aoff)
; #define LDB(dst, b, h) _Pragma("unroll") for (int n = 0; n < 2; ++n) _Pragma("unroll") for (int k = 0; k < 2; ++k) \
;     dst[n][k] = *reinterpret_cast<const bf16x8*>(smem + (((b) * 2 + (h)) * 16384 + n * 2048 + k * 1024) + boff)
; #define MMA(ai, bj, At_, Bt_) do { __builtin_amdgcn_s_setprio(1); \
;     _Pragma("unroll") for (int m = 0; m < 4; ++m) _Pragma("unroll") for (int n = 0; n < 2; ++n) _Pragma("unroll") for (int k = 0; k < 2; ++k) \
;       acc[ai][bj][m][n] = __builtin_amdgcn_mfma_f32_16x16x32_bf16(Bt_[n][k], At_[m][k], acc[ai][bj][m][n], 0, 0, 0); \
;     __builtin_amdgcn_s_setprio(0); } while (0)
; #define WAIT_V(n) asm volatile("s_waitcnt vmcnt(" #n ")" ::: "memory")
; #define WAIT_L(n) asm volatile("s_waitcnt lgkmcnt(" #n ")" ::: "memory")
; #define BAR __builtin_amdgcn_s_barrier()
; #define SCHED __builtin_amdgcn_sched_barrier(0)
; template <class Epi, int NB>
; DEV void gemm_tile_nb(const bf16* __restrict__ A, int lda, long strideA, const bf16* __restrict__ Bt, int ldb, long strideB, int K, int brow, int bcol, Epi& epi) {
;     ...
;     STAGE(SB(0, 1), Bt, ldb, bcol + HALF, t + 2);
;     WAIT_V(6); BAR; MMA(1, 1, At, B1); BAR;
;     LDB(B0, 1, 0); SCHED; LDA(At, 1, 0); STAGE(SA(0, 1), A, lda, brow + HALF, t + 2);
;     WAIT_L(8); BAR; WAIT_L(0); MMA(0, 0, At, B0); BAR; SCHED;
;     LDB(B1, 1, 1); STAGE(SB(1, 0), Bt, ldb, bcol, t + 3);
;     BAR; WAIT_L(0); MMA(0, 1, At, B1); BAR;
;     LDA(At, 1, 1); STAGE(SA(1, 0), A, lda, brow, t + 3);
	v_readfirstlane_b32 s40, v147
	v_lshl_add_u64 v[162:163], v[214:215], 0, s[54:55]
	s_mov_b32 m0, s40
	v_readfirstlane_b32 s40, v151
	global_load_lds_dwordx4 v[162:163], off
	v_lshl_add_u64 v[162:163], v[246:247], 0, s[54:55]
	s_mov_b32 m0, s40
	s_nop 0
	global_load_lds_dwordx4 v[162:163], off
	ds_read_b128 v[162:165], v144 offset:32768
	ds_read_b128 v[166:169], v144 offset:33792
	ds_read_b128 v[170:173], v144 offset:34816
	ds_read_b128 v[174:177], v144 offset:35840
	s_waitcnt vmcnt(6)
	s_barrier
	s_setprio 1
	v_mfma_f32_16x16x32_bf16 v[14:17], v[230:233], v[184:187], v[14:17]
	v_mfma_f32_16x16x32_bf16 v[10:13], v[238:241], v[184:187], v[10:13]
	v_mfma_f32_16x16x32_bf16 v[6:9], v[230:233], v[192:195], v[6:9]
	v_mfma_f32_16x16x32_bf16 v[2:5], v[238:241], v[192:195], v[2:5]
	v_mfma_f32_16x16x32_bf16 v[66:69], v[230:233], v[200:203], v[66:69]
	v_mfma_f32_16x16x32_bf16 v[74:77], v[238:241], v[200:203], v[74:77]
	v_mfma_f32_16x16x32_bf16 v[78:81], v[230:233], v[222:225], v[78:81]
	v_mfma_f32_16x16x32_bf16 v[82:85], v[238:241], v[222:225], v[82:85]
	v_mfma_f32_16x16x32_bf16 v[14:17], v[234:237], v[188:191], v[14:17]
	v_mfma_f32_16x16x32_bf16 v[10:13], v[242:245], v[188:191], v[10:13]
	v_mfma_f32_16x16x32_bf16 v[6:9], v[234:237], v[196:199], v[6:9]
	v_mfma_f32_16x16x32_bf16 v[2:5], v[242:245], v[196:199], v[2:5]
	v_mfma_f32_16x16x32_bf16 v[66:69], v[234:237], v[218:221], v[66:69]
	v_mfma_f32_16x16x32_bf16 v[74:77], v[242:245], v[218:221], v[74:77]
	v_mfma_f32_16x16x32_bf16 v[78:81], v[234:237], v[226:229], v[78:81]
	v_mfma_f32_16x16x32_bf16 v[82:85], v[242:245], v[226:229], v[82:85]
	s_setprio 0
	s_barrier
	v_readfirstlane_b32 s40, v149
	v_lshl_add_u64 v[230:231], v[204:205], 0, s[56:57]
	s_mov_b32 m0, s40
	v_readfirstlane_b32 s40, v152
	ds_read_b128 v[184:187], v0 offset:32768
	ds_read_b128 v[188:191], v0 offset:33792
	ds_read_b128 v[192:195], v0 offset:34816
	ds_read_b128 v[196:199], v0 offset:35840
	ds_read_b128 v[200:203], v0 offset:36864
	ds_read_b128 v[218:221], v0 offset:37888
	ds_read_b128 v[222:225], v0 offset:38912
	ds_read_b128 v[226:229], v0 offset:39936
	global_load_lds_dwordx4 v[230:231], off
	v_lshl_add_u64 v[230:231], v[208:209], 0, s[56:57]
	s_mov_b32 m0, s40
	s_nop 0
	global_load_lds_dwordx4 v[230:231], off
	s_waitcnt lgkmcnt(8)
	s_barrier
	s_waitcnt lgkmcnt(0)
	s_setprio 1
	s_waitcnt lgkmcnt(0)
	v_mfma_f32_16x16x32_bf16 v[126:129], v[162:165], v[184:187], v[126:129]
	v_mfma_f32_16x16x32_bf16 v[122:125], v[170:173], v[184:187], v[122:125]
	v_mfma_f32_16x16x32_bf16 v[118:121], v[162:165], v[192:195], v[118:121]
	v_mfma_f32_16x16x32_bf16 v[114:117], v[170:173], v[192:195], v[114:117]
	v_mfma_f32_16x16x32_bf16 v[110:113], v[162:165], v[200:203], v[110:113]
	v_mfma_f32_16x16x32_bf16 v[106:109], v[170:173], v[200:203], v[106:109]
	v_mfma_f32_16x16x32_bf16 v[102:105], v[162:165], v[222:225], v[102:105]
	v_mfma_f32_16x16x32_bf16 v[98:101], v[170:173], v[222:225], v[98:101]
	v_mfma_f32_16x16x32_bf16 v[126:129], v[166:169], v[188:191], v[126:129]
	v_mfma_f32_16x16x32_bf16 v[122:125], v[174:177], v[188:191], v[122:125]
	v_mfma_f32_16x16x32_bf16 v[118:121], v[166:169], v[196:199], v[118:121]
	v_mfma_f32_16x16x32_bf16 v[114:117], v[174:177], v[196:199], v[114:117]
	v_mfma_f32_16x16x32_bf16 v[110:113], v[166:169], v[218:221], v[110:113]
	v_mfma_f32_16x16x32_bf16 v[106:109], v[174:177], v[218:221], v[106:109]
	v_mfma_f32_16x16x32_bf16 v[102:105], v[166:169], v[226:229], v[102:105]
	v_mfma_f32_16x16x32_bf16 v[98:101], v[174:177], v[226:229], v[98:101]
	s_setprio 0
	s_barrier
	v_readfirstlane_b32 s40, v153
	v_lshl_add_u64 v[248:249], v[214:215], 0, s[58:59]
	s_mov_b32 m0, s40
	v_readfirstlane_b32 s40, v154
	ds_read_b128 v[230:233], v144 offset:49152
	ds_read_b128 v[234:237], v144 offset:50176
	ds_read_b128 v[238:241], v144 offset:51200
	ds_read_b128 v[242:245], v144 offset:52224
	global_load_lds_dwordx4 v[248:249], off
	v_lshl_add_u64 v[248:249], v[246:247], 0, s[58:59]
	s_mov_b32 m0, s40
	s_nop 0
	global_load_lds_dwordx4 v[248:249], off
	s_barrier
	s_waitcnt lgkmcnt(0)
	s_setprio 1
	s_waitcnt lgkmcnt(0)
	v_mfma_f32_16x16x32_bf16 v[94:97], v[230:233], v[184:187], v[94:97]
	v_mfma_f32_16x16x32_bf16 v[90:93], v[238:241], v[184:187], v[90:93]
	v_mfma_f32_16x16x32_bf16 v[86:89], v[230:233], v[192:195], v[86:89]
	v_mfma_f32_16x16x32_bf16 v[70:73], v[238:241], v[192:195], v[70:73]
	v_mfma_f32_16x16x32_bf16 v[62:65], v[230:233], v[200:203], v[62:65]
	v_mfma_f32_16x16x32_bf16 v[58:61], v[238:241], v[200:203], v[58:61]
	v_mfma_f32_16x16x32_bf16 v[54:57], v[230:233], v[222:225], v[54:57]
	v_mfma_f32_16x16x32_bf16 v[50:53], v[238:241], v[222:225], v[50:53]
	v_mfma_f32_16x16x32_bf16 v[94:97], v[234:237], v[188:191], v[94:97]
	v_mfma_f32_16x16x32_bf16 v[90:93], v[242:245], v[188:191], v[90:93]
	v_mfma_f32_16x16x32_bf16 v[86:89], v[234:237], v[196:199], v[86:89]
	v_mfma_f32_16x16x32_bf16 v[70:73], v[242:245], v[196:199], v[70:73]
	v_mfma_f32_16x16x32_bf16 v[62:65], v[234:237], v[218:221], v[62:65]
	v_mfma_f32_16x16x32_bf16 v[58:61], v[242:245], v[218:221], v[58:61]
	v_mfma_f32_16x16x32_bf16 v[54:57], v[234:237], v[226:229], v[54:57]
	v_mfma_f32_16x16x32_bf16 v[50:53], v[242:245], v[226:229], v[50:53]
	s_setprio 0
	v_readfirstlane_b32 s40, v155
	v_lshl_add_u64 v[204:205], v[204:205], 0, s[20:21]
	s_mov_b32 m0, s40
	v_readfirstlane_b32 s40, v156
	s_barrier
	ds_read_b128 v[184:187], v0 offset:49152
	ds_read_b128 v[188:191], v0 offset:50176
	ds_read_b128 v[192:195], v0 offset:51200
	ds_read_b128 v[196:199], v0 offset:52224
	ds_read_b128 v[200:203], v0 offset:53248
	ds_read_b128 v[218:221], v0 offset:54272
	ds_read_b128 v[222:225], v0 offset:55296
	ds_read_b128 v[226:229], v0 offset:56320
	global_load_lds_dwordx4 v[204:205], off
	v_lshl_add_u64 v[204:205], v[208:209], 0, s[20:21]
	s_mov_b32 m0, s40
	s_nop 0
	global_load_lds_dwordx4 v[204:205], off
	s_waitcnt vmcnt(10)
	s_barrier
; #define STAGE(P, BASE, LD, br, kt) do { const bf16* _gb = BASE + ((long)(br) * (LD) + (long)(kt) * BK); \
;     _Pragma("unroll") for (int _i = 0; _i < 2; ++_i) { \
;       __builtin_amdgcn_global_load_lds((const unsigned*)(_gb + ((&LD == &lda) ? offA[_i] : offB[_i])), \
;         (unsigned*)((char*)(P) + tidx_ * 16 + _i * 8192), 16, 0, 0); } } while (0)
; #define LDA(dst, b, h) _Pragma("unroll") for (int m = 0; m < 4; ++m) _Pragma("unroll") for (int k = 0; k < 2; ++k) \
;     dst[m][k] = *reinterpret_cast<const bf16x8*>(smem + (((b) * 2 + (h)) * 16384 + m * 2048 + k * 1024) + aoff)
; #define LDB(dst, b, h) _Pragma("unroll") for (int n = 0; n < 2; ++n) _Pragma("unroll") for (int k = 0; k < 2; ++k) \
;     dst[n][k] = *reinterpret_cast<const bf16x8*>(smem + (((b) * 2 + (h)) * 16384 + n * 2048 + k * 1024) + boff)
; #define MMA(ai, bj, At_, Bt_) do { __builtin_amdgcn_s_setprio(1); \
;     _Pragma("unroll") for (int m = 0; m < 4; ++m) _Pragma("unroll") for (int n = 0; n < 2; ++n) _Pragma("unroll") for (int k = 0; k < 2; ++k) \
;       acc[ai][bj][m][n] = __builtin_amdgcn_mfma_f32_16x16x32_bf16(Bt_[n][k], At_[m][k], acc[ai][bj][m][n], 0, 0, 0); \
;     __builtin_amdgcn_s_setprio(0); } while (0)
; #define WAIT_V(n) asm volatile("s_waitcnt vmcnt(" #n ")" ::: "memory")
; #define WAIT_L(n) asm volatile("s_waitcnt lgkmcnt(" #n ")" ::: "memory")
; #define BAR __builtin_amdgcn_s_barrier()
; #define SCHED __builtin_amdgcn_sched_barrier(0)
; template <class Epi, int NB>
; DEV void gemm_tile_nb(const bf16* __restrict__ A, int lda, long strideA, const bf16* __restrict__ Bt, int ldb, long strideB, int K, int brow, int bcol, Epi& epi) {
;     ...
;     BAR; WAIT_L(0); MMA(1, 0, At, B0); BAR; SCHED;
;     STAGE(SB(1, 1), Bt, ldb, bcol + HALF, t + 3);
;     WAIT_V(6); BAR; MMA(1, 1, At, B1); BAR;
;   }
;   { LDB(B0, 0, 0); LDA(At, 0, 0); STAGE(SA(1, 1), A, lda, brow + HALF, nt - 1);
;     BAR; WAIT_L(0); MMA(0, 0, At, B0); BAR;
;     LDB(B1, 0, 1); BAR; WAIT_L(0); MMA(0, 1, At, B1); BAR;
	s_waitcnt lgkmcnt(0)
	s_setprio 1
	s_waitcnt lgkmcnt(0)
	v_mfma_f32_16x16x32_bf16 v[46:49], v[162:165], v[184:187], v[46:49]
	v_mfma_f32_16x16x32_bf16 v[42:45], v[170:173], v[184:187], v[42:45]
	v_mfma_f32_16x16x32_bf16 v[38:41], v[162:165], v[192:195], v[38:41]
	v_mfma_f32_16x16x32_bf16 v[34:37], v[170:173], v[192:195], v[34:37]
	v_mfma_f32_16x16x32_bf16 v[30:33], v[162:165], v[200:203], v[30:33]
	v_mfma_f32_16x16x32_bf16 v[26:29], v[170:173], v[200:203], v[26:29]
	v_mfma_f32_16x16x32_bf16 v[22:25], v[162:165], v[222:225], v[22:25]
	v_mfma_f32_16x16x32_bf16 v[18:21], v[170:173], v[222:225], v[18:21]
	v_mfma_f32_16x16x32_bf16 v[46:49], v[166:169], v[188:191], v[46:49]
	v_mfma_f32_16x16x32_bf16 v[42:45], v[174:177], v[188:191], v[42:45]
	v_mfma_f32_16x16x32_bf16 v[38:41], v[166:169], v[196:199], v[38:41]
	v_mfma_f32_16x16x32_bf16 v[34:37], v[174:177], v[196:199], v[34:37]
	v_mfma_f32_16x16x32_bf16 v[30:33], v[166:169], v[218:221], v[30:33]
	v_mfma_f32_16x16x32_bf16 v[26:29], v[174:177], v[218:221], v[26:29]
	v_mfma_f32_16x16x32_bf16 v[22:25], v[166:169], v[226:229], v[22:25]
	v_mfma_f32_16x16x32_bf16 v[18:21], v[174:177], v[226:229], v[18:21]
	s_setprio 0
	s_barrier
	v_readfirstlane_b32 s40, v157
	v_lshl_add_u64 v[162:163], v[214:215], 0, s[60:61]
	s_mov_b32 m0, s40
	v_readfirstlane_b32 s40, v158
	global_load_lds_dwordx4 v[162:163], off
	v_lshl_add_u64 v[162:163], v[246:247], 0, s[60:61]
	s_mov_b32 m0, s40
	s_nop 0
	global_load_lds_dwordx4 v[162:163], off
	ds_read_b128 v[162:165], v144
	ds_read_b128 v[166:169], v144 offset:1024
	ds_read_b128 v[170:173], v144 offset:2048
	ds_read_b128 v[174:177], v144 offset:3072
	s_waitcnt vmcnt(6)
	s_barrier
	s_setprio 1
	v_mfma_f32_16x16x32_bf16 v[14:17], v[230:233], v[184:187], v[14:17]
	v_mfma_f32_16x16x32_bf16 v[10:13], v[238:241], v[184:187], v[10:13]
	v_mfma_f32_16x16x32_bf16 v[6:9], v[230:233], v[192:195], v[6:9]
	v_mfma_f32_16x16x32_bf16 v[2:5], v[238:241], v[192:195], v[2:5]
	v_mfma_f32_16x16x32_bf16 v[66:69], v[230:233], v[200:203], v[66:69]
	v_mfma_f32_16x16x32_bf16 v[74:77], v[238:241], v[200:203], v[74:77]
	v_mfma_f32_16x16x32_bf16 v[78:81], v[230:233], v[222:225], v[78:81]
	v_mfma_f32_16x16x32_bf16 v[82:85], v[238:241], v[222:225], v[82:85]
	v_mfma_f32_16x16x32_bf16 v[14:17], v[234:237], v[188:191], v[14:17]
	v_mfma_f32_16x16x32_bf16 v[10:13], v[242:245], v[188:191], v[10:13]
	v_mfma_f32_16x16x32_bf16 v[6:9], v[234:237], v[196:199], v[6:9]
	v_mfma_f32_16x16x32_bf16 v[2:5], v[242:245], v[196:199], v[2:5]
	v_mfma_f32_16x16x32_bf16 v[66:69], v[234:237], v[218:221], v[66:69]
	v_mfma_f32_16x16x32_bf16 v[74:77], v[242:245], v[218:221], v[74:77]
	v_mfma_f32_16x16x32_bf16 v[78:81], v[234:237], v[226:229], v[78:81]
	v_mfma_f32_16x16x32_bf16 v[82:85], v[242:245], v[226:229], v[82:85]
	s_setprio 0
	s_add_i32 s39, s39, 2
	v_lshl_add_u64 v[134:135], v[134:135], 0, s[72:73]
	v_lshl_add_u64 v[136:137], v[136:137], 0, s[72:73]
	v_lshl_add_u64 v[138:139], v[138:139], 0, s[72:73]
	s_cmp_lt_u32 s39, 12
	v_lshl_add_u64 v[140:141], v[140:141], 0, s[72:73]
	s_barrier
	s_cbranch_scc1 .LBB0_784
	s_mov_b64 s[40:41], 0x780
	v_readfirstlane_b32 s39, v159
	v_lshl_add_u64 v[132:133], v[132:133], 0, s[40:41]
	s_mov_b32 m0, s39
	v_readfirstlane_b32 s39, v160
	ds_read_b128 v[134:137], v144
	ds_read_b128 v[138:141], v144 offset:1024
	ds_read_b128 v[146:149], v144 offset:2048
	ds_read_b128 v[150:153], v144 offset:3072
	ds_read_b128 v[154:157], v0
	ds_read_b128 v[162:165], v0 offset:1024
	ds_read_b128 v[166:169], v0 offset:2048
	ds_read_b128 v[170:173], v0 offset:3072
	ds_read_b128 v[174:177], v0 offset:4096
	ds_read_b128 v[184:187], v0 offset:5120
	ds_read_b128 v[188:191], v0 offset:6144
	ds_read_b128 v[192:195], v0 offset:7168
	global_load_lds_dwordx4 v[132:133], off
	v_lshl_add_u64 v[130:131], v[130:131], 0, s[40:41]
	s_mov_b32 m0, s39
	s_cmpk_gt_u32 s50, 0xff
	global_load_lds_dwordx4 v[130:131], off
	s_barrier
	s_waitcnt lgkmcnt(0)
	s_setprio 1
	s_waitcnt lgkmcnt(0)
	v_mfma_f32_16x16x32_bf16 v[126:129], v[134:137], v[154:157], v[126:129]
	v_mfma_f32_16x16x32_bf16 v[118:121], v[134:137], v[166:169], v[118:121]
	v_mfma_f32_16x16x32_bf16 v[110:113], v[134:137], v[174:177], v[110:113]
	v_mfma_f32_16x16x32_bf16 v[102:105], v[134:137], v[188:191], v[102:105]
	v_mfma_f32_16x16x32_bf16 v[98:101], v[146:149], v[188:191], v[98:101]
	v_mfma_f32_16x16x32_bf16 v[126:129], v[138:141], v[162:165], v[126:129]
	v_mfma_f32_16x16x32_bf16 v[122:125], v[146:149], v[154:157], v[122:125]
	v_mfma_f32_16x16x32_bf16 v[118:121], v[138:141], v[170:173], v[118:121]
	v_mfma_f32_16x16x32_bf16 v[114:117], v[146:149], v[166:169], v[114:117]
	v_mfma_f32_16x16x32_bf16 v[110:113], v[138:141], v[184:187], v[110:113]
	v_mfma_f32_16x16x32_bf16 v[106:109], v[146:149], v[174:177], v[106:109]
	v_mfma_f32_16x16x32_bf16 v[102:105], v[138:141], v[192:195], v[102:105]
	v_mfma_f32_16x16x32_bf16 v[98:101], v[150:153], v[192:195], v[98:101]
	v_mfma_f32_16x16x32_bf16 v[130:133], v[150:153], v[162:165], v[122:125]
	v_mfma_f32_16x16x32_bf16 v[158:161], v[150:153], v[170:173], v[114:117]
	v_mfma_f32_16x16x32_bf16 v[196:199], v[150:153], v[184:187], v[106:109]
	s_setprio 0
	s_barrier
	s_nop 0
	ds_read_b128 v[106:109], v144 offset:16384
	ds_read_b128 v[114:117], v144 offset:17408
	ds_read_b128 v[122:125], v144 offset:18432
	ds_read_b128 v[200:203], v144 offset:19456
	s_barrier
; #define LDA(dst, b, h) _Pragma("unroll") for (int m = 0; m < 4; ++m) _Pragma("unroll") for (int k = 0; k < 2; ++k) \
;     dst[m][k] = *reinterpret_cast<const bf16x8*>(smem + (((b) * 2 + (h)) * 16384 + m * 2048 + k * 1024) + aoff)
; #define LDB(dst, b, h) _Pragma("unroll") for (int n = 0; n < 2; ++n) _Pragma("unroll") for (int k = 0; k < 2; ++k) \
;     dst[n][k] = *reinterpret_cast<const bf16x8*>(smem + (((b) * 2 + (h)) * 16384 + n * 2048 + k * 1024) + boff)
; #define MMA(ai, bj, At_, Bt_) do { __builtin_amdgcn_s_setprio(1); \
;     _Pragma("unroll") for (int m = 0; m < 4; ++m) _Pragma("unroll") for (int n = 0; n < 2; ++n) _Pragma("unroll") for (int k = 0; k < 2; ++k) \
;       acc[ai][bj][m][n] = __builtin_amdgcn_mfma_f32_16x16x32_bf16(Bt_[n][k], At_[m][k], acc[ai][bj][m][n], 0, 0, 0); \
;     __builtin_amdgcn_s_setprio(0); } while (0)
; #define WAIT_V(n) asm volatile("s_waitcnt vmcnt(" #n ")" ::: "memory")
; #define WAIT_L(n) asm volatile("s_waitcnt lgkmcnt(" #n ")" ::: "memory")
; #define BAR __builtin_amdgcn_s_barrier()
; template <class Epi, int NB>
; DEV void gemm_tile_nb(const bf16* __restrict__ A, int lda, long strideA, const bf16* __restrict__ Bt, int ldb, long strideB, int K, int brow, int bcol, Epi& epi) {
;     ...
;     LDB(B1, 0, 1); BAR; WAIT_L(0); MMA(0, 1, At, B1); BAR;
;     LDA(At, 0, 1); WAIT_V(4); BAR; WAIT_L(0); MMA(1, 0, At, B0); MMA(1, 1, At, B1); BAR; }
;   { LDB(B0, 1, 0); LDA(At, 1, 0); WAIT_V(2); BAR; WAIT_L(0); MMA(0, 0, At, B0); BAR;
	s_waitcnt lgkmcnt(0)
	s_setprio 1
	s_waitcnt lgkmcnt(0)
	v_mfma_f32_16x16x32_bf16 v[86:89], v[106:109], v[166:169], v[86:89]
	v_mfma_f32_16x16x32_bf16 v[70:73], v[122:125], v[166:169], v[70:73]
	v_mfma_f32_16x16x32_bf16 v[62:65], v[106:109], v[174:177], v[62:65]
	v_mfma_f32_16x16x32_bf16 v[58:61], v[122:125], v[174:177], v[58:61]
	v_mfma_f32_16x16x32_bf16 v[54:57], v[106:109], v[188:191], v[54:57]
	v_mfma_f32_16x16x32_bf16 v[50:53], v[122:125], v[188:191], v[50:53]
	v_mfma_f32_16x16x32_bf16 v[94:97], v[106:109], v[154:157], v[94:97]
	v_mfma_f32_16x16x32_bf16 v[90:93], v[122:125], v[154:157], v[90:93]
	v_mfma_f32_16x16x32_bf16 v[86:89], v[114:117], v[170:173], v[86:89]
	v_mfma_f32_16x16x32_bf16 v[70:73], v[200:203], v[170:173], v[70:73]
	v_mfma_f32_16x16x32_bf16 v[62:65], v[114:117], v[184:187], v[62:65]
	v_mfma_f32_16x16x32_bf16 v[58:61], v[200:203], v[184:187], v[58:61]
	v_mfma_f32_16x16x32_bf16 v[54:57], v[114:117], v[192:195], v[54:57]
	v_mfma_f32_16x16x32_bf16 v[50:53], v[200:203], v[192:195], v[50:53]
	v_mfma_f32_16x16x32_bf16 v[218:221], v[114:117], v[162:165], v[94:97]
	v_mfma_f32_16x16x32_bf16 v[154:157], v[200:203], v[162:165], v[90:93]
	s_setprio 0
	s_barrier
	s_nop 0
	ds_read_b128 v[90:93], v0 offset:16384
	ds_read_b128 v[94:97], v0 offset:17408
	ds_read_b128 v[162:165], v0 offset:18432
	ds_read_b128 v[166:169], v0 offset:19456
	ds_read_b128 v[170:173], v0 offset:20480
	ds_read_b128 v[174:177], v0 offset:21504
	ds_read_b128 v[184:187], v0 offset:22528
	ds_read_b128 v[188:191], v0 offset:23552
	s_waitcnt vmcnt(4)
	s_barrier
	s_waitcnt lgkmcnt(0)
	s_setprio 1
	s_waitcnt lgkmcnt(0)
	v_mfma_f32_16x16x32_bf16 v[46:49], v[134:137], v[90:93], v[46:49]
	v_mfma_f32_16x16x32_bf16 v[42:45], v[146:149], v[90:93], v[42:45]
	v_mfma_f32_16x16x32_bf16 v[38:41], v[134:137], v[162:165], v[38:41]
	v_mfma_f32_16x16x32_bf16 v[34:37], v[146:149], v[162:165], v[34:37]
	v_mfma_f32_16x16x32_bf16 v[30:33], v[134:137], v[170:173], v[30:33]
	v_mfma_f32_16x16x32_bf16 v[26:29], v[146:149], v[170:173], v[26:29]
	v_mfma_f32_16x16x32_bf16 v[22:25], v[134:137], v[184:187], v[22:25]
	v_mfma_f32_16x16x32_bf16 v[18:21], v[146:149], v[184:187], v[18:21]
	v_mfma_f32_16x16x32_bf16 v[46:49], v[138:141], v[94:97], v[46:49]
	v_mfma_f32_16x16x32_bf16 v[42:45], v[150:153], v[94:97], v[42:45]
	v_mfma_f32_16x16x32_bf16 v[38:41], v[138:141], v[166:169], v[38:41]
	v_mfma_f32_16x16x32_bf16 v[34:37], v[150:153], v[166:169], v[34:37]
	v_mfma_f32_16x16x32_bf16 v[30:33], v[138:141], v[174:177], v[30:33]
	v_mfma_f32_16x16x32_bf16 v[26:29], v[150:153], v[174:177], v[26:29]
	v_mfma_f32_16x16x32_bf16 v[22:25], v[138:141], v[188:191], v[22:25]
	v_mfma_f32_16x16x32_bf16 v[18:21], v[150:153], v[188:191], v[18:21]
	s_setprio 0
	s_setprio 1
	v_mfma_f32_16x16x32_bf16 v[66:69], v[106:109], v[170:173], v[66:69]
	v_mfma_f32_16x16x32_bf16 v[134:137], v[114:117], v[174:177], v[66:69]
	v_mfma_f32_16x16x32_bf16 v[66:69], v[122:125], v[170:173], v[74:77]
	v_mfma_f32_16x16x32_bf16 v[14:17], v[106:109], v[90:93], v[14:17]
	v_mfma_f32_16x16x32_bf16 v[10:13], v[122:125], v[90:93], v[10:13]
	v_mfma_f32_16x16x32_bf16 v[6:9], v[106:109], v[162:165], v[6:9]
	v_mfma_f32_16x16x32_bf16 v[2:5], v[122:125], v[162:165], v[2:5]
	v_mfma_f32_16x16x32_bf16 v[138:141], v[200:203], v[174:177], v[66:69]
	v_mfma_f32_16x16x32_bf16 v[66:69], v[106:109], v[184:187], v[78:81]
	v_mfma_f32_16x16x32_bf16 v[14:17], v[114:117], v[94:97], v[14:17]
	v_mfma_f32_16x16x32_bf16 v[10:13], v[200:203], v[94:97], v[10:13]
	v_mfma_f32_16x16x32_bf16 v[6:9], v[114:117], v[166:169], v[6:9]
	v_mfma_f32_16x16x32_bf16 v[2:5], v[200:203], v[166:169], v[2:5]
	v_mfma_f32_16x16x32_bf16 v[146:149], v[114:117], v[188:191], v[66:69]
	v_mfma_f32_16x16x32_bf16 v[66:69], v[122:125], v[184:187], v[82:85]
	v_mfma_f32_16x16x32_bf16 v[150:153], v[200:203], v[188:191], v[66:69]
	s_setprio 0
	s_barrier
	ds_read_b128 v[162:165], v144 offset:32768
	ds_read_b128 v[166:169], v144 offset:33792
	ds_read_b128 v[170:173], v144 offset:34816
	ds_read_b128 v[174:177], v144 offset:35840
	s_nop 0
	ds_read_b128 v[66:69], v0 offset:32768
	ds_read_b128 v[74:77], v0 offset:33792
	ds_read_b128 v[78:81], v0 offset:34816
	ds_read_b128 v[184:187], v0 offset:35840
	ds_read_b128 v[188:191], v0 offset:36864
	ds_read_b128 v[192:195], v0 offset:37888
	ds_read_b128 v[200:203], v0 offset:38912
	ds_read_b128 v[222:225], v0 offset:39936
	s_waitcnt vmcnt(2)
	s_barrier
; #define LDA(dst, b, h) _Pragma("unroll") for (int m = 0; m < 4; ++m) _Pragma("unroll") for (int k = 0; k < 2; ++k) \
;     dst[m][k] = *reinterpret_cast<const bf16x8*>(smem + (((b) * 2 + (h)) * 16384 + m * 2048 + k * 1024) + aoff)
; #define LDB(dst, b, h) _Pragma("unroll") for (int n = 0; n < 2; ++n) _Pragma("unroll") for (int k = 0; k < 2; ++k) \
;     dst[n][k] = *reinterpret_cast<const bf16x8*>(smem + (((b) * 2 + (h)) * 16384 + n * 2048 + k * 1024) + boff)
; #define MMA(ai, bj, At_, Bt_) do { __builtin_amdgcn_s_setprio(1); \
;     _Pragma("unroll") for (int m = 0; m < 4; ++m) _Pragma("unroll") for (int n = 0; n < 2; ++n) _Pragma("unroll") for (int k = 0; k < 2; ++k) \
;       acc[ai][bj][m][n] = __builtin_amdgcn_mfma_f32_16x16x32_bf16(Bt_[n][k], At_[m][k], acc[ai][bj][m][n], 0, 0, 0); \
;     __builtin_amdgcn_s_setprio(0); } while (0)
; #define WAIT_V(n) asm volatile("s_waitcnt vmcnt(" #n ")" ::: "memory")
; #define WAIT_L(n) asm volatile("s_waitcnt lgkmcnt(" #n ")" ::: "memory")
; #define BAR __builtin_amdgcn_s_barrier()
; template <class Epi, int NB>
; DEV void gemm_tile_nb(const bf16* __restrict__ A, int lda, long strideA, const bf16* __restrict__ Bt, int ldb, long strideB, int K, int brow, int bcol, Epi& epi) {
;     ...
;   { LDB(B0, 1, 0); LDA(At, 1, 0); WAIT_V(2); BAR; WAIT_L(0); MMA(0, 0, At, B0); BAR;
;     LDB(B1, 1, 1); WAIT_V(0); BAR; WAIT_L(0); MMA(0, 1, At, B1); BAR;
;     LDA(At, 1, 1); BAR; WAIT_L(0); MMA(1, 0, At, B0); MMA(1, 1, At, B1); BAR; }
;   if (wr == 0) BAR;
	s_waitcnt lgkmcnt(0)
	s_setprio 1
	s_waitcnt lgkmcnt(0)
	v_mfma_f32_16x16x32_bf16 v[82:85], v[162:165], v[66:69], v[126:129]
	v_mfma_f32_16x16x32_bf16 v[122:125], v[166:169], v[74:77], v[82:85]
	v_mfma_f32_16x16x32_bf16 v[82:85], v[170:173], v[66:69], v[130:133]
	v_mfma_f32_16x16x32_bf16 v[126:129], v[174:177], v[74:77], v[82:85]
	v_mfma_f32_16x16x32_bf16 v[82:85], v[162:165], v[78:81], v[118:121]
	v_mfma_f32_16x16x32_bf16 v[114:117], v[166:169], v[184:187], v[82:85]
	v_mfma_f32_16x16x32_bf16 v[82:85], v[170:173], v[78:81], v[158:161]
	v_mfma_f32_16x16x32_bf16 v[118:121], v[174:177], v[184:187], v[82:85]
	v_mfma_f32_16x16x32_bf16 v[82:85], v[162:165], v[188:191], v[110:113]
	v_mfma_f32_16x16x32_bf16 v[106:109], v[166:169], v[192:195], v[82:85]
	v_mfma_f32_16x16x32_bf16 v[82:85], v[170:173], v[188:191], v[196:199]
	v_mfma_f32_16x16x32_bf16 v[110:113], v[174:177], v[192:195], v[82:85]
	v_mfma_f32_16x16x32_bf16 v[82:85], v[162:165], v[200:203], v[102:105]
	v_mfma_f32_16x16x32_bf16 v[90:93], v[166:169], v[222:225], v[82:85]
	v_mfma_f32_16x16x32_bf16 v[82:85], v[170:173], v[200:203], v[98:101]
	v_mfma_f32_16x16x32_bf16 v[94:97], v[174:177], v[222:225], v[82:85]
	s_setprio 0
	s_barrier
	ds_read_b128 v[130:133], v144 offset:49152
	ds_read_b128 v[158:161], v144 offset:50176
	ds_read_b128 v[196:199], v144 offset:51200
	ds_read_b128 v[226:229], v144 offset:52224
	s_waitcnt vmcnt(0)
	s_barrier
	s_waitcnt lgkmcnt(0)
	s_setprio 1
	s_waitcnt lgkmcnt(0)
	v_mfma_f32_16x16x32_bf16 v[82:85], v[130:133], v[66:69], v[218:221]
	v_mfma_f32_16x16x32_bf16 v[66:69], v[196:199], v[66:69], v[154:157]
	v_mfma_f32_16x16x32_bf16 v[102:105], v[226:229], v[74:77], v[66:69]
	v_mfma_f32_16x16x32_bf16 v[66:69], v[130:133], v[78:81], v[86:89]
	v_mfma_f32_16x16x32_bf16 v[98:101], v[158:161], v[74:77], v[82:85]
	v_mfma_f32_16x16x32_bf16 v[82:85], v[158:161], v[184:187], v[66:69]
	v_mfma_f32_16x16x32_bf16 v[66:69], v[196:199], v[78:81], v[70:73]
	v_mfma_f32_16x16x32_bf16 v[62:65], v[130:133], v[188:191], v[62:65]
	v_mfma_f32_16x16x32_bf16 v[58:61], v[196:199], v[188:191], v[58:61]
	v_mfma_f32_16x16x32_bf16 v[54:57], v[130:133], v[200:203], v[54:57]
	v_mfma_f32_16x16x32_bf16 v[50:53], v[196:199], v[200:203], v[50:53]
	v_mfma_f32_16x16x32_bf16 v[86:89], v[226:229], v[184:187], v[66:69]
	v_mfma_f32_16x16x32_bf16 v[74:77], v[158:161], v[192:195], v[62:65]
	v_mfma_f32_16x16x32_bf16 v[78:81], v[226:229], v[192:195], v[58:61]
	v_mfma_f32_16x16x32_bf16 v[66:69], v[158:161], v[222:225], v[54:57]
	v_mfma_f32_16x16x32_bf16 v[70:73], v[226:229], v[222:225], v[50:53]
	s_setprio 0
	s_barrier
	ds_read_b128 v[154:157], v0 offset:49152
	ds_read_b128 v[184:187], v0 offset:50176
	ds_read_b128 v[188:191], v0 offset:51200
	ds_read_b128 v[192:195], v0 offset:52224
	ds_read_b128 v[200:203], v0 offset:53248
	ds_read_b128 v[218:221], v0 offset:54272
	ds_read_b128 v[222:225], v0 offset:55296
	ds_read_b128 v[230:233], v0 offset:56320
	s_barrier
	s_waitcnt lgkmcnt(0)
	s_setprio 1
	s_waitcnt lgkmcnt(0)
	v_mfma_f32_16x16x32_bf16 v[46:49], v[162:165], v[154:157], v[46:49]
	v_mfma_f32_16x16x32_bf16 v[42:45], v[170:173], v[154:157], v[42:45]
	v_mfma_f32_16x16x32_bf16 v[38:41], v[162:165], v[188:191], v[38:41]
	v_mfma_f32_16x16x32_bf16 v[34:37], v[170:173], v[188:191], v[34:37]
	v_mfma_f32_16x16x32_bf16 v[30:33], v[162:165], v[200:203], v[30:33]
	v_mfma_f32_16x16x32_bf16 v[26:29], v[170:173], v[200:203], v[26:29]
	v_mfma_f32_16x16x32_bf16 v[22:25], v[162:165], v[222:225], v[22:25]
	v_mfma_f32_16x16x32_bf16 v[18:21], v[170:173], v[222:225], v[18:21]
	v_mfma_f32_16x16x32_bf16 v[58:61], v[166:169], v[184:187], v[46:49]
	v_mfma_f32_16x16x32_bf16 v[62:65], v[174:177], v[184:187], v[42:45]
	v_mfma_f32_16x16x32_bf16 v[50:53], v[166:169], v[192:195], v[38:41]
	v_mfma_f32_16x16x32_bf16 v[54:57], v[174:177], v[192:195], v[34:37]
	v_mfma_f32_16x16x32_bf16 v[42:45], v[166:169], v[218:221], v[30:33]
	v_mfma_f32_16x16x32_bf16 v[46:49], v[174:177], v[218:221], v[26:29]
	v_mfma_f32_16x16x32_bf16 v[34:37], v[166:169], v[230:233], v[22:25]
	v_mfma_f32_16x16x32_bf16 v[38:41], v[174:177], v[230:233], v[18:21]
	s_setprio 0
	s_setprio 1
	v_mfma_f32_16x16x32_bf16 v[2:5], v[196:199], v[188:191], v[2:5]
	v_mfma_f32_16x16x32_bf16 v[10:13], v[196:199], v[154:157], v[10:13]
	v_mfma_f32_16x16x32_bf16 v[22:25], v[226:229], v[192:195], v[2:5]
	v_mfma_f32_16x16x32_bf16 v[2:5], v[130:133], v[200:203], v[134:137]
	v_mfma_f32_16x16x32_bf16 v[14:17], v[130:133], v[154:157], v[14:17]
	v_mfma_f32_16x16x32_bf16 v[30:33], v[226:229], v[184:187], v[10:13]
	v_mfma_f32_16x16x32_bf16 v[6:9], v[130:133], v[188:191], v[6:9]
	v_mfma_f32_16x16x32_bf16 v[10:13], v[158:161], v[218:221], v[2:5]
	v_mfma_f32_16x16x32_bf16 v[2:5], v[196:199], v[200:203], v[138:141]
	v_mfma_f32_16x16x32_bf16 v[26:29], v[158:161], v[184:187], v[14:17]
	v_mfma_f32_16x16x32_bf16 v[18:21], v[158:161], v[192:195], v[6:9]
	v_mfma_f32_16x16x32_bf16 v[14:17], v[226:229], v[218:221], v[2:5]
	v_mfma_f32_16x16x32_bf16 v[2:5], v[130:133], v[222:225], v[146:149]
	v_mfma_f32_16x16x32_bf16 v[6:9], v[196:199], v[222:225], v[150:153]
	v_mfma_f32_16x16x32_bf16 v[2:5], v[158:161], v[230:233], v[2:5]
	v_mfma_f32_16x16x32_bf16 v[6:9], v[226:229], v[230:233], v[6:9]
	s_setprio 0
	s_barrier
	s_cbranch_scc1 .LBB0_775
	s_barrier
	s_branch .LBB0_775

; #define STAGE(P, BASE, LD, br, kt) do { const bf16* _gb = BASE + ((long)(br) * (LD) + (long)(kt) * BK); \
;     _Pragma("unroll") for (int _i = 0; _i < 2; ++_i) { \
;       __builtin_amdgcn_global_load_lds((const unsigned*)(_gb + ((&LD == &lda) ? offA[_i] : offB[_i])), \
;         (unsigned*)((char*)(P) + tidx_ * 16 + _i * 8192), 16, 0, 0); } } while (0)
; #define WAIT_V(n) asm volatile("s_waitcnt vmcnt(" #n ")" ::: "memory")
; #define BAR __builtin_amdgcn_s_barrier()
; template <class Epi, int NB>
; DEV void gemm_tile_nb(const bf16* __restrict__ A, int lda, long strideA, const bf16* __restrict__ Bt, int ldb, long strideB, int K, int brow, int bcol, Epi& epi) {
;     ...
;   const int lane_off_ = (fr * 64 + fq * 16) ^ ((fr >> 3) << 5);
;   const int aoff = wr * 8192 + lane_off_, boff = 65536 + wc * 4096 + lane_off_;
;   unsigned offA[2], offB[2];
; #pragma unroll
;   for (int _i = 0; _i < 2; ++_i) { int _r, _c; stage_rc(tidx_ * 16 + _i * 8192, _r, _c); offA[_i] = (unsigned)(_r * lda + _c); offB[_i] = (unsigned)(_r * ldb + _c); }
; #pragma unroll 1
;   for (int br = 0; br < NB; ++br) {
;   STAGE(SB(0, 0), Bt, ldb, bcol, 0); STAGE(SA(0, 0), A, lda, brow, 0);
;   STAGE(SB(0, 1), Bt, ldb, bcol + HALF, 0); STAGE(SA(0, 1), A, lda, brow + HALF, 0);
;   if (wr == 1) BAR;
;   WAIT_V(4); BAR;
;   STAGE(SB(1, 0), Bt, ldb, bcol, 1); STAGE(SA(1, 0), A, lda, brow, 1); STAGE(SB(1, 1), Bt, ldb, bcol + HALF, 1);
;   WAIT_V(6); BAR;
.LBB0_823:
	v_and_b32_e32 v141, 15, v23
	s_bfe_u32 s41, s42, 0x20006
	v_bfe_u32 v140, v23, 4, 2
	v_lshlrev_b32_e32 v24, 6, v141
	v_lshlrev_b32_e32 v23, 2, v23
	v_lshl_or_b32 v24, v140, 4, v24
	v_and_b32_e32 v23, 32, v23
	s_lshl_b32 s44, s40, 13
	s_lshl_b32 s45, s41, 12
	v_add_u32_e32 v152, s13, v16
	v_bitop3_b32 v25, v24, s45, v23 bitop3:0xde
	v_bitop3_b32 v23, v24, s44, v23 bitop3:0xde
	s_mov_b64 s[38:39], 0x80
	v_readfirstlane_b32 s44, v152
	v_add_u32_e32 v153, 0x2000, v152
	v_lshl_add_u64 v[2:3], v[2:3], 0, s[38:39]
	s_mov_b32 m0, s44
	v_readfirstlane_b32 s44, v153
	v_add_u32_e32 v154, 0x8000, v145
	s_waitcnt vmcnt(4)
	s_barrier
	global_load_lds_dwordx4 v[2:3], off
	v_lshl_add_u64 v[2:3], v[4:5], 0, s[38:39]
	s_mov_b32 m0, s44
	v_readfirstlane_b32 s44, v154
	v_add_u32_e32 v155, 0xa000, v145
	global_load_lds_dwordx4 v[2:3], off
	v_lshl_add_u64 v[2:3], v[8:9], 0, s[38:39]
	s_mov_b32 m0, s44
	v_readfirstlane_b32 s44, v155
	v_add_u32_e32 v156, s14, v16
	global_load_lds_dwordx4 v[2:3], off
	v_lshl_add_u64 v[2:3], v[10:11], 0, s[38:39]
	s_mov_b32 m0, s44
	v_readfirstlane_b32 s44, v156
	v_add_u32_e32 v157, 0x2000, v156
	global_load_lds_dwordx4 v[2:3], off
	v_lshl_add_u64 v[2:3], v[12:13], 0, s[38:39]
	s_mov_b32 m0, s44
	v_readfirstlane_b32 s44, v157
	global_load_lds_dwordx4 v[2:3], off
	v_lshl_add_u64 v[2:3], v[6:7], 0, s[38:39]
	s_mov_b32 m0, s44
	v_readlane_b32 s8, v254, 63
	global_load_lds_dwordx4 v[2:3], off
	s_add_u32 s43, s8, s43
	v_lshrrev_b32_e32 v3, 1, v14
	v_mul_lo_u32 v2, v18, s10
	s_mov_b32 s39, 0xb000
	s_addc_u32 s48, 0, 0
	v_mad_u64_u32 v[2:3], s[44:45], v3, s39, v[2:3]
	v_readlane_b32 s38, v253, 31
	s_add_u32 s44, s38, s43
	v_readlane_b32 s38, v253, 32
	v_lshrrev_b32_e32 v5, 1, v15
	v_mul_lo_u32 v4, v21, s10
	s_addc_u32 s45, s38, s48
	v_mad_u64_u32 v[4:5], s[48:49], v5, s39, v[4:5]
	v_or_b32_e32 v2, v2, v17
	v_or_b32_e32 v4, v4, v20
	v_add_u32_sdwa v2, v2, sext(v19) dst_sel:DWORD dst_unused:UNUSED_PAD src0_sel:DWORD src1_sel:WORD_0
	v_mov_b32_e32 v3, v1
	v_add_u32_sdwa v4, v4, sext(v22) dst_sel:DWORD dst_unused:UNUSED_PAD src0_sel:DWORD src1_sel:WORD_0
	v_mov_b32_e32 v5, v1
	v_readlane_b32 s38, v253, 33
	s_waitcnt vmcnt(6)
	v_lshlrev_b64 v[2:3], 1, v[2:3]
	v_lshlrev_b64 v[4:5], 1, v[4:5]
	v_readlane_b32 s39, v253, 34
	v_or_b32_e32 v25, 0x10000, v25
	v_lshl_add_u64 v[132:133], s[44:45], 0, v[2:3]
	v_lshl_add_u64 v[136:137], s[38:39], 0, v[2:3]
	v_lshl_add_u64 v[138:139], s[38:39], 0, v[4:5]
	v_mov_b32_e32 v2, 0
	v_readlane_b32 s38, v253, 42
	v_lshl_add_u64 v[134:135], s[44:45], 0, v[4:5]
	s_mov_b32 s43, -2
	v_add_u32_e32 v143, 0, v25
	v_add_u32_e32 v142, 0, v23
	v_mov_b32_e32 v3, v2
	v_mov_b32_e32 v4, v2
	v_mov_b32_e32 v5, v2
	v_mov_b32_e32 v6, v2
	v_mov_b32_e32 v7, v2
	v_mov_b32_e32 v8, v2
	v_mov_b32_e32 v9, v2
	v_mov_b32_e32 v10, v2
	v_mov_b32_e32 v11, v2
	v_mov_b32_e32 v12, v2
	v_mov_b32_e32 v13, v2
	v_mov_b32_e32 v14, v2
	v_mov_b32_e32 v15, v2
	v_mov_b32_e32 v16, v2
	v_mov_b32_e32 v17, v2
	v_mov_b32_e32 v18, v2
	v_mov_b32_e32 v19, v2
	v_mov_b32_e32 v20, v2
	v_mov_b32_e32 v21, v2
	v_mov_b32_e32 v22, v2
	v_mov_b32_e32 v23, v2
	v_mov_b32_e32 v24, v2
	v_mov_b32_e32 v25, v2
	v_mov_b32_e32 v26, v2
	v_mov_b32_e32 v27, v2
	s_waitcnt vmcnt(0)
	v_mov_b32_e32 v28, v2
	v_mov_b32_e32 v29, v2
	v_mov_b32_e32 v30, v2
	v_mov_b32_e32 v31, v2
	v_mov_b32_e32 v32, v2
	v_mov_b32_e32 v33, v2
	v_mov_b32_e32 v34, v2
	v_mov_b32_e32 v35, v2
	v_mov_b32_e32 v36, v2
	v_mov_b32_e32 v37, v2
	v_mov_b32_e32 v38, v2
	v_mov_b32_e32 v39, v2
	v_mov_b32_e32 v40, v2
	v_mov_b32_e32 v41, v2
	v_mov_b32_e32 v42, v2
	v_mov_b32_e32 v43, v2
	v_mov_b32_e32 v44, v2
	v_mov_b32_e32 v45, v2
	v_mov_b32_e32 v46, v2
	v_mov_b32_e32 v47, v2
	v_mov_b32_e32 v48, v2
	v_mov_b32_e32 v49, v2
	v_mov_b32_e32 v50, v2
	v_mov_b32_e32 v51, v2
	v_mov_b32_e32 v52, v2
	v_mov_b32_e32 v53, v2
	v_mov_b32_e32 v54, v2
	v_mov_b32_e32 v55, v2
	v_mov_b32_e32 v56, v2
	v_mov_b32_e32 v57, v2
	v_mov_b32_e32 v58, v2
	v_mov_b32_e32 v59, v2
	v_mov_b32_e32 v60, v2
	v_mov_b32_e32 v61, v2
	v_mov_b32_e32 v62, v2
	v_mov_b32_e32 v63, v2
	v_mov_b32_e32 v64, v2
	v_mov_b32_e32 v65, v2
	v_mov_b32_e32 v70, v2
	v_mov_b32_e32 v71, v2
	v_mov_b32_e32 v72, v2
	v_mov_b32_e32 v73, v2
	v_mov_b32_e32 v86, v2
	v_mov_b32_e32 v87, v2
	v_mov_b32_e32 v88, v2
	v_mov_b32_e32 v89, v2
	v_mov_b32_e32 v90, v2
	v_mov_b32_e32 v91, v2
	v_mov_b32_e32 v92, v2
	v_mov_b32_e32 v93, v2
	v_mov_b32_e32 v94, v2
	v_mov_b32_e32 v95, v2
	v_mov_b32_e32 v96, v2
	v_mov_b32_e32 v97, v2
	v_mov_b32_e32 v98, v2
	v_mov_b32_e32 v99, v2
	v_mov_b32_e32 v100, v2
	v_mov_b32_e32 v101, v2
	v_mov_b32_e32 v102, v2
	v_mov_b32_e32 v103, v2
	v_mov_b32_e32 v104, v2
	v_mov_b32_e32 v105, v2
	v_mov_b32_e32 v106, v2
	v_mov_b32_e32 v107, v2
	v_mov_b32_e32 v108, v2
	v_mov_b32_e32 v109, v2
	v_mov_b32_e32 v110, v2
	v_mov_b32_e32 v111, v2
	v_mov_b32_e32 v112, v2
	v_mov_b32_e32 v113, v2
	v_mov_b32_e32 v114, v2
	v_mov_b32_e32 v115, v2
	v_mov_b32_e32 v116, v2
	v_mov_b32_e32 v117, v2
	v_mov_b32_e32 v118, v2
	v_mov_b32_e32 v119, v2
	v_mov_b32_e32 v120, v2
	v_mov_b32_e32 v121, v2
	v_mov_b32_e32 v122, v2
	v_mov_b32_e32 v123, v2
	v_mov_b32_e32 v124, v2
	v_mov_b32_e32 v125, v2
	v_mov_b32_e32 v126, v2
	v_mov_b32_e32 v127, v2
	v_mov_b32_e32 v128, v2
	v_mov_b32_e32 v129, v2
	v_mov_b32_e32 v66, v2
	v_mov_b32_e32 v67, v2
	v_mov_b32_e32 v68, v2
	v_mov_b32_e32 v69, v2
	v_mov_b32_e32 v74, v2
	v_mov_b32_e32 v75, v2
	v_mov_b32_e32 v76, v2
	v_mov_b32_e32 v77, v2
	v_mov_b32_e32 v78, v2
	v_mov_b32_e32 v79, v2
	v_mov_b32_e32 v80, v2
	v_mov_b32_e32 v81, v2
	v_mov_b32_e32 v82, v2
	v_mov_b32_e32 v83, v2
	v_mov_b32_e32 v84, v2
	v_mov_b32_e32 v85, v2
	v_readlane_b32 s39, v253, 43
	s_barrier
	ds_read_b128 v[160:163], v143
	ds_read_b128 v[164:167], v143 offset:1024
	ds_read_b128 v[168:171], v143 offset:2048
	ds_read_b128 v[172:175], v143 offset:3072
; #define STAGE(P, BASE, LD, br, kt) do { const bf16* _gb = BASE + ((long)(br) * (LD) + (long)(kt) * BK); \
;     _Pragma("unroll") for (int _i = 0; _i < 2; ++_i) { \
;       __builtin_amdgcn_global_load_lds((const unsigned*)(_gb + ((&LD == &lda) ? offA[_i] : offB[_i])), \
;         (unsigned*)((char*)(P) + tidx_ * 16 + _i * 8192), 16, 0, 0); } } while (0)
; #define LDA(dst, b, h) _Pragma("unroll") for (int m = 0; m < 4; ++m) _Pragma("unroll") for (int k = 0; k < 2; ++k) \
;     dst[m][k] = *reinterpret_cast<const bf16x8*>(smem + (((b) * 2 + (h)) * 16384 + m * 2048 + k * 1024) + aoff)
; #define LDB(dst, b, h) _Pragma("unroll") for (int n = 0; n < 2; ++n) _Pragma("unroll") for (int k = 0; k < 2; ++k) \
;     dst[n][k] = *reinterpret_cast<const bf16x8*>(smem + (((b) * 2 + (h)) * 16384 + n * 2048 + k * 1024) + boff)
; #define MMA(ai, bj, At_, Bt_) do { __builtin_amdgcn_s_setprio(1); \
;     _Pragma("unroll") for (int m = 0; m < 4; ++m) _Pragma("unroll") for (int n = 0; n < 2; ++n) _Pragma("unroll") for (int k = 0; k < 2; ++k) \
;       acc[ai][bj][m][n] = __builtin_amdgcn_mfma_f32_16x16x32_bf16(Bt_[n][k], At_[m][k], acc[ai][bj][m][n], 0, 0, 0); \
;     __builtin_amdgcn_s_setprio(0); } while (0)
; #define WAIT_L(n) asm volatile("s_waitcnt lgkmcnt(" #n ")" ::: "memory")
; #define BAR __builtin_amdgcn_s_barrier()
; #define SCHED __builtin_amdgcn_sched_barrier(0)
; template <class Epi, int NB>
; DEV void gemm_tile_nb(const bf16* __restrict__ A, int lda, long strideA, const bf16* __restrict__ Bt, int ldb, long strideB, int K, int brow, int bcol, Epi& epi) {
;     ...
;     LDB(B0, 0, 0); SCHED; LDA(At, 0, 0); STAGE(SA(1, 1), A, lda, brow + HALF, t + 1);
;     WAIT_L(8); BAR; WAIT_L(0); MMA(0, 0, At, B0); BAR; SCHED;
;     LDB(B1, 0, 1); STAGE(SB(0, 0), Bt, ldb, bcol, t + 2);
;     BAR; WAIT_L(0); MMA(0, 1, At, B1); BAR;
;     LDA(At, 0, 1); STAGE(SA(0, 0), A, lda, brow, t + 2);
;     BAR; WAIT_L(0); MMA(1, 0, At, B0); BAR; SCHED;
.LBB0_824:
	v_add_u32_e32 v158, 0xc000, v145
	v_lshl_add_u64 v[176:177], v[136:137], 0, s[38:39]
	v_readfirstlane_b32 s44, v158
	v_lshl_add_u64 v[204:205], v[176:177], 0, s[4:5]
	s_mov_b32 m0, s44
	v_add_u32_e32 v159, 0xe000, v145
	ds_read_b128 v[184:187], v142
	ds_read_b128 v[188:191], v142 offset:1024
	ds_read_b128 v[192:195], v142 offset:2048
	ds_read_b128 v[196:199], v142 offset:3072
	ds_read_b128 v[200:203], v142 offset:4096
	ds_read_b128 v[218:221], v142 offset:5120
	ds_read_b128 v[222:225], v142 offset:6144
	ds_read_b128 v[226:229], v142 offset:7168
	global_load_lds_dwordx4 v[204:205], off
	v_lshl_add_u64 v[204:205], v[138:139], 0, s[38:39]
	v_readfirstlane_b32 s44, v159
	v_lshl_add_u64 v[208:209], v[204:205], 0, s[4:5]
	s_mov_b32 m0, s44
	s_nop 0
	global_load_lds_dwordx4 v[208:209], off
	s_waitcnt lgkmcnt(8)
	s_barrier
	s_waitcnt lgkmcnt(0)
	s_setprio 1
	s_waitcnt lgkmcnt(0)
	v_mfma_f32_16x16x32_bf16 v[126:129], v[160:163], v[184:187], v[126:129]
	v_mfma_f32_16x16x32_bf16 v[122:125], v[168:171], v[184:187], v[122:125]
	v_mfma_f32_16x16x32_bf16 v[118:121], v[160:163], v[192:195], v[118:121]
	v_mfma_f32_16x16x32_bf16 v[114:117], v[168:171], v[192:195], v[114:117]
	v_mfma_f32_16x16x32_bf16 v[110:113], v[160:163], v[200:203], v[110:113]
	v_mfma_f32_16x16x32_bf16 v[106:109], v[168:171], v[200:203], v[106:109]
	v_mfma_f32_16x16x32_bf16 v[102:105], v[160:163], v[222:225], v[102:105]
	v_mfma_f32_16x16x32_bf16 v[98:101], v[168:171], v[222:225], v[98:101]
	v_mfma_f32_16x16x32_bf16 v[126:129], v[164:167], v[188:191], v[126:129]
	v_mfma_f32_16x16x32_bf16 v[122:125], v[172:175], v[188:191], v[122:125]
	v_mfma_f32_16x16x32_bf16 v[118:121], v[164:167], v[196:199], v[118:121]
	v_mfma_f32_16x16x32_bf16 v[114:117], v[172:175], v[196:199], v[114:117]
	v_mfma_f32_16x16x32_bf16 v[110:113], v[164:167], v[218:221], v[110:113]
	v_mfma_f32_16x16x32_bf16 v[106:109], v[172:175], v[218:221], v[106:109]
	v_mfma_f32_16x16x32_bf16 v[102:105], v[164:167], v[226:229], v[102:105]
	v_mfma_f32_16x16x32_bf16 v[98:101], v[172:175], v[226:229], v[98:101]
	s_setprio 0
	s_barrier
	v_lshl_add_u64 v[208:209], v[132:133], 0, s[38:39]
	v_readfirstlane_b32 s44, v144
	v_lshl_add_u64 v[214:215], v[208:209], 0, s[24:25]
	s_mov_b32 m0, s44
	ds_read_b128 v[230:233], v143 offset:16384
	ds_read_b128 v[234:237], v143 offset:17408
	ds_read_b128 v[238:241], v143 offset:18432
	ds_read_b128 v[242:245], v143 offset:19456
	global_load_lds_dwordx4 v[214:215], off
	v_lshl_add_u64 v[214:215], v[134:135], 0, s[38:39]
	v_readfirstlane_b32 s44, v147
	v_lshl_add_u64 v[246:247], v[214:215], 0, s[24:25]
	s_mov_b32 m0, s44
	s_nop 0
	global_load_lds_dwordx4 v[246:247], off
	s_barrier
	s_waitcnt lgkmcnt(0)
	s_setprio 1
	s_waitcnt lgkmcnt(0)
	v_mfma_f32_16x16x32_bf16 v[94:97], v[230:233], v[184:187], v[94:97]
	v_mfma_f32_16x16x32_bf16 v[90:93], v[238:241], v[184:187], v[90:93]
	v_mfma_f32_16x16x32_bf16 v[86:89], v[230:233], v[192:195], v[86:89]
	v_mfma_f32_16x16x32_bf16 v[70:73], v[238:241], v[192:195], v[70:73]
	v_mfma_f32_16x16x32_bf16 v[62:65], v[230:233], v[200:203], v[62:65]
	v_mfma_f32_16x16x32_bf16 v[58:61], v[238:241], v[200:203], v[58:61]
	v_mfma_f32_16x16x32_bf16 v[54:57], v[230:233], v[222:225], v[54:57]
	v_mfma_f32_16x16x32_bf16 v[50:53], v[238:241], v[222:225], v[50:53]
	v_mfma_f32_16x16x32_bf16 v[94:97], v[234:237], v[188:191], v[94:97]
	v_mfma_f32_16x16x32_bf16 v[90:93], v[242:245], v[188:191], v[90:93]
	v_mfma_f32_16x16x32_bf16 v[86:89], v[234:237], v[196:199], v[86:89]
	v_mfma_f32_16x16x32_bf16 v[70:73], v[242:245], v[196:199], v[70:73]
	v_mfma_f32_16x16x32_bf16 v[62:65], v[234:237], v[218:221], v[62:65]
	v_mfma_f32_16x16x32_bf16 v[58:61], v[242:245], v[218:221], v[58:61]
	v_mfma_f32_16x16x32_bf16 v[54:57], v[234:237], v[226:229], v[54:57]
	v_mfma_f32_16x16x32_bf16 v[50:53], v[242:245], v[226:229], v[50:53]
	s_setprio 0
	v_readfirstlane_b32 s44, v145
	v_lshl_add_u64 v[246:247], v[176:177], 0, s[26:27]
	s_mov_b32 m0, s44
	v_readfirstlane_b32 s44, v149
	s_barrier
	ds_read_b128 v[184:187], v142 offset:16384
	ds_read_b128 v[188:191], v142 offset:17408
	ds_read_b128 v[192:195], v142 offset:18432
	ds_read_b128 v[196:199], v142 offset:19456
	ds_read_b128 v[200:203], v142 offset:20480
	ds_read_b128 v[218:221], v142 offset:21504
	ds_read_b128 v[222:225], v142 offset:22528
	ds_read_b128 v[226:229], v142 offset:23552
	global_load_lds_dwordx4 v[246:247], off
	v_lshl_add_u64 v[246:247], v[204:205], 0, s[26:27]
	s_mov_b32 m0, s44
	s_nop 0
	global_load_lds_dwordx4 v[246:247], off
	s_waitcnt vmcnt(10)
	s_barrier
	s_waitcnt lgkmcnt(0)
	s_setprio 1
	s_waitcnt lgkmcnt(0)
	v_mfma_f32_16x16x32_bf16 v[46:49], v[160:163], v[184:187], v[46:49]
	v_mfma_f32_16x16x32_bf16 v[42:45], v[168:171], v[184:187], v[42:45]
	v_mfma_f32_16x16x32_bf16 v[38:41], v[160:163], v[192:195], v[38:41]
	v_mfma_f32_16x16x32_bf16 v[34:37], v[168:171], v[192:195], v[34:37]
	v_mfma_f32_16x16x32_bf16 v[30:33], v[160:163], v[200:203], v[30:33]
	v_mfma_f32_16x16x32_bf16 v[26:29], v[168:171], v[200:203], v[26:29]
	v_mfma_f32_16x16x32_bf16 v[22:25], v[160:163], v[222:225], v[22:25]
	v_mfma_f32_16x16x32_bf16 v[18:21], v[168:171], v[222:225], v[18:21]
	v_mfma_f32_16x16x32_bf16 v[46:49], v[164:167], v[188:191], v[46:49]
	v_mfma_f32_16x16x32_bf16 v[42:45], v[172:175], v[188:191], v[42:45]
	v_mfma_f32_16x16x32_bf16 v[38:41], v[164:167], v[196:199], v[38:41]
	v_mfma_f32_16x16x32_bf16 v[34:37], v[172:175], v[196:199], v[34:37]
	v_mfma_f32_16x16x32_bf16 v[30:33], v[164:167], v[218:221], v[30:33]
	v_mfma_f32_16x16x32_bf16 v[26:29], v[172:175], v[218:221], v[26:29]
	v_mfma_f32_16x16x32_bf16 v[22:25], v[164:167], v[226:229], v[22:25]
	v_mfma_f32_16x16x32_bf16 v[18:21], v[172:175], v[226:229], v[18:21]
	s_setprio 0
	s_barrier
; #define STAGE(P, BASE, LD, br, kt) do { const bf16* _gb = BASE + ((long)(br) * (LD) + (long)(kt) * BK); \
;     _Pragma("unroll") for (int _i = 0; _i < 2; ++_i) { \
;       __builtin_amdgcn_global_load_lds((const unsigned*)(_gb + ((&LD == &lda) ? offA[_i] : offB[_i])), \
;         (unsigned*)((char*)(P) + tidx_ * 16 + _i * 8192), 16, 0, 0); } } while (0)
; #define LDA(dst, b, h) _Pragma("unroll") for (int m = 0; m < 4; ++m) _Pragma("unroll") for (int k = 0; k < 2; ++k) \
;     dst[m][k] = *reinterpret_cast<const bf16x8*>(smem + (((b) * 2 + (h)) * 16384 + m * 2048 + k * 1024) + aoff)
; #define LDB(dst, b, h) _Pragma("unroll") for (int n = 0; n < 2; ++n) _Pragma("unroll") for (int k = 0; k < 2; ++k) \
;     dst[n][k] = *reinterpret_cast<const bf16x8*>(smem + (((b) * 2 + (h)) * 16384 + n * 2048 + k * 1024) + boff)
; #define MMA(ai, bj, At_, Bt_) do { __builtin_amdgcn_s_setprio(1); \
;     _Pragma("unroll") for (int m = 0; m < 4; ++m) _Pragma("unroll") for (int n = 0; n < 2; ++n) _Pragma("unroll") for (int k = 0; k < 2; ++k) \
;       acc[ai][bj][m][n] = __builtin_amdgcn_mfma_f32_16x16x32_bf16(Bt_[n][k], At_[m][k], acc[ai][bj][m][n], 0, 0, 0); \
;     __builtin_amdgcn_s_setprio(0); } while (0)
; #define WAIT_V(n) asm volatile("s_waitcnt vmcnt(" #n ")" ::: "memory")
; #define WAIT_L(n) asm volatile("s_waitcnt lgkmcnt(" #n ")" ::: "memory")
; #define BAR __builtin_amdgcn_s_barrier()
; #define SCHED __builtin_amdgcn_sched_barrier(0)
; template <class Epi, int NB>
; DEV void gemm_tile_nb(const bf16* __restrict__ A, int lda, long strideA, const bf16* __restrict__ Bt, int ldb, long strideB, int K, int brow, int bcol, Epi& epi) {
;     ...
;     STAGE(SB(0, 1), Bt, ldb, bcol + HALF, t + 2);
;     WAIT_V(6); BAR; MMA(1, 1, At, B1); BAR;
;     LDB(B0, 1, 0); SCHED; LDA(At, 1, 0); STAGE(SA(0, 1), A, lda, brow + HALF, t + 2);
;     WAIT_L(8); BAR; WAIT_L(0); MMA(0, 0, At, B0); BAR; SCHED;
;     LDB(B1, 1, 1); STAGE(SB(1, 0), Bt, ldb, bcol, t + 3);
;     BAR; WAIT_L(0); MMA(0, 1, At, B1); BAR;
;     LDA(At, 1, 1); STAGE(SA(1, 0), A, lda, brow, t + 3);
	v_readfirstlane_b32 s44, v146
	v_lshl_add_u64 v[160:161], v[208:209], 0, s[94:95]
	s_mov_b32 m0, s44
	v_readfirstlane_b32 s44, v150
	global_load_lds_dwordx4 v[160:161], off
	v_lshl_add_u64 v[160:161], v[214:215], 0, s[94:95]
	s_mov_b32 m0, s44
	s_nop 0
	global_load_lds_dwordx4 v[160:161], off
	ds_read_b128 v[160:163], v143 offset:32768
	ds_read_b128 v[164:167], v143 offset:33792
	ds_read_b128 v[168:171], v143 offset:34816
	ds_read_b128 v[172:175], v143 offset:35840
	s_waitcnt vmcnt(6)
	s_barrier
	s_setprio 1
	v_mfma_f32_16x16x32_bf16 v[14:17], v[230:233], v[184:187], v[14:17]
	v_mfma_f32_16x16x32_bf16 v[10:13], v[238:241], v[184:187], v[10:13]
	v_mfma_f32_16x16x32_bf16 v[6:9], v[230:233], v[192:195], v[6:9]
	v_mfma_f32_16x16x32_bf16 v[2:5], v[238:241], v[192:195], v[2:5]
	v_mfma_f32_16x16x32_bf16 v[66:69], v[230:233], v[200:203], v[66:69]
	v_mfma_f32_16x16x32_bf16 v[74:77], v[238:241], v[200:203], v[74:77]
	v_mfma_f32_16x16x32_bf16 v[78:81], v[230:233], v[222:225], v[78:81]
	v_mfma_f32_16x16x32_bf16 v[82:85], v[238:241], v[222:225], v[82:85]
	v_mfma_f32_16x16x32_bf16 v[14:17], v[234:237], v[188:191], v[14:17]
	v_mfma_f32_16x16x32_bf16 v[10:13], v[242:245], v[188:191], v[10:13]
	v_mfma_f32_16x16x32_bf16 v[6:9], v[234:237], v[196:199], v[6:9]
	v_mfma_f32_16x16x32_bf16 v[2:5], v[242:245], v[196:199], v[2:5]
	v_mfma_f32_16x16x32_bf16 v[66:69], v[234:237], v[218:221], v[66:69]
	v_mfma_f32_16x16x32_bf16 v[74:77], v[242:245], v[218:221], v[74:77]
	v_mfma_f32_16x16x32_bf16 v[78:81], v[234:237], v[226:229], v[78:81]
	v_mfma_f32_16x16x32_bf16 v[82:85], v[242:245], v[226:229], v[82:85]
	s_setprio 0
	s_barrier
	v_readfirstlane_b32 s44, v148
	v_lshl_add_u64 v[230:231], v[176:177], 0, s[2:3]
	s_mov_b32 m0, s44
	v_readfirstlane_b32 s44, v151
	ds_read_b128 v[184:187], v142 offset:32768
	ds_read_b128 v[188:191], v142 offset:33792
	ds_read_b128 v[192:195], v142 offset:34816
	ds_read_b128 v[196:199], v142 offset:35840
	ds_read_b128 v[200:203], v142 offset:36864
	ds_read_b128 v[218:221], v142 offset:37888
	ds_read_b128 v[222:225], v142 offset:38912
	ds_read_b128 v[226:229], v142 offset:39936
	global_load_lds_dwordx4 v[230:231], off
	v_lshl_add_u64 v[230:231], v[204:205], 0, s[2:3]
	s_mov_b32 m0, s44
	s_nop 0
	global_load_lds_dwordx4 v[230:231], off
	s_waitcnt lgkmcnt(8)
	s_barrier
	s_waitcnt lgkmcnt(0)
	s_setprio 1
	s_waitcnt lgkmcnt(0)
	v_mfma_f32_16x16x32_bf16 v[126:129], v[160:163], v[184:187], v[126:129]
	v_mfma_f32_16x16x32_bf16 v[122:125], v[168:171], v[184:187], v[122:125]
	v_mfma_f32_16x16x32_bf16 v[118:121], v[160:163], v[192:195], v[118:121]
	v_mfma_f32_16x16x32_bf16 v[114:117], v[168:171], v[192:195], v[114:117]
	v_mfma_f32_16x16x32_bf16 v[110:113], v[160:163], v[200:203], v[110:113]
	v_mfma_f32_16x16x32_bf16 v[106:109], v[168:171], v[200:203], v[106:109]
	v_mfma_f32_16x16x32_bf16 v[102:105], v[160:163], v[222:225], v[102:105]
	v_mfma_f32_16x16x32_bf16 v[98:101], v[168:171], v[222:225], v[98:101]
	v_mfma_f32_16x16x32_bf16 v[126:129], v[164:167], v[188:191], v[126:129]
	v_mfma_f32_16x16x32_bf16 v[122:125], v[172:175], v[188:191], v[122:125]
	v_mfma_f32_16x16x32_bf16 v[118:121], v[164:167], v[196:199], v[118:121]
	v_mfma_f32_16x16x32_bf16 v[114:117], v[172:175], v[196:199], v[114:117]
	v_mfma_f32_16x16x32_bf16 v[110:113], v[164:167], v[218:221], v[110:113]
	v_mfma_f32_16x16x32_bf16 v[106:109], v[172:175], v[218:221], v[106:109]
	v_mfma_f32_16x16x32_bf16 v[102:105], v[164:167], v[226:229], v[102:105]
	v_mfma_f32_16x16x32_bf16 v[98:101], v[172:175], v[226:229], v[98:101]
	s_setprio 0
	s_barrier
	v_readfirstlane_b32 s44, v152
	v_lshl_add_u64 v[246:247], v[208:209], 0, s[46:47]
	s_mov_b32 m0, s44
	v_readfirstlane_b32 s44, v153
	ds_read_b128 v[230:233], v143 offset:49152
	ds_read_b128 v[234:237], v143 offset:50176
	ds_read_b128 v[238:241], v143 offset:51200
	ds_read_b128 v[242:245], v143 offset:52224
	global_load_lds_dwordx4 v[246:247], off
	v_lshl_add_u64 v[246:247], v[214:215], 0, s[46:47]
	s_mov_b32 m0, s44
	s_nop 0
	global_load_lds_dwordx4 v[246:247], off
	s_barrier
	s_waitcnt lgkmcnt(0)
	s_setprio 1
	s_waitcnt lgkmcnt(0)
	v_mfma_f32_16x16x32_bf16 v[94:97], v[230:233], v[184:187], v[94:97]
	v_mfma_f32_16x16x32_bf16 v[90:93], v[238:241], v[184:187], v[90:93]
	v_mfma_f32_16x16x32_bf16 v[86:89], v[230:233], v[192:195], v[86:89]
	v_mfma_f32_16x16x32_bf16 v[70:73], v[238:241], v[192:195], v[70:73]
	v_mfma_f32_16x16x32_bf16 v[62:65], v[230:233], v[200:203], v[62:65]
	v_mfma_f32_16x16x32_bf16 v[58:61], v[238:241], v[200:203], v[58:61]
	v_mfma_f32_16x16x32_bf16 v[54:57], v[230:233], v[222:225], v[54:57]
	v_mfma_f32_16x16x32_bf16 v[50:53], v[238:241], v[222:225], v[50:53]
	v_mfma_f32_16x16x32_bf16 v[94:97], v[234:237], v[188:191], v[94:97]
	v_mfma_f32_16x16x32_bf16 v[90:93], v[242:245], v[188:191], v[90:93]
	v_mfma_f32_16x16x32_bf16 v[86:89], v[234:237], v[196:199], v[86:89]
	v_mfma_f32_16x16x32_bf16 v[70:73], v[242:245], v[196:199], v[70:73]
	v_mfma_f32_16x16x32_bf16 v[62:65], v[234:237], v[218:221], v[62:65]
	v_mfma_f32_16x16x32_bf16 v[58:61], v[242:245], v[218:221], v[58:61]
	v_mfma_f32_16x16x32_bf16 v[54:57], v[234:237], v[226:229], v[54:57]
	v_mfma_f32_16x16x32_bf16 v[50:53], v[242:245], v[226:229], v[50:53]
	s_setprio 0
	v_readfirstlane_b32 s44, v154
	v_lshl_add_u64 v[176:177], v[176:177], 0, s[76:77]
	s_mov_b32 m0, s44
	v_readfirstlane_b32 s44, v155
	s_barrier
	ds_read_b128 v[184:187], v142 offset:49152
	ds_read_b128 v[188:191], v142 offset:50176
	ds_read_b128 v[192:195], v142 offset:51200
	ds_read_b128 v[196:199], v142 offset:52224
	ds_read_b128 v[200:203], v142 offset:53248
	ds_read_b128 v[218:221], v142 offset:54272
	ds_read_b128 v[222:225], v142 offset:55296
	ds_read_b128 v[226:229], v142 offset:56320
	global_load_lds_dwordx4 v[176:177], off
	v_lshl_add_u64 v[176:177], v[204:205], 0, s[76:77]
	s_mov_b32 m0, s44
	s_nop 0
	global_load_lds_dwordx4 v[176:177], off
	s_waitcnt vmcnt(10)
	s_barrier
; #define STAGE(P, BASE, LD, br, kt) do { const bf16* _gb = BASE + ((long)(br) * (LD) + (long)(kt) * BK); \
;     _Pragma("unroll") for (int _i = 0; _i < 2; ++_i) { \
;       __builtin_amdgcn_global_load_lds((const unsigned*)(_gb + ((&LD == &lda) ? offA[_i] : offB[_i])), \
;         (unsigned*)((char*)(P) + tidx_ * 16 + _i * 8192), 16, 0, 0); } } while (0)
; #define LDA(dst, b, h) _Pragma("unroll") for (int m = 0; m < 4; ++m) _Pragma("unroll") for (int k = 0; k < 2; ++k) \
;     dst[m][k] = *reinterpret_cast<const bf16x8*>(smem + (((b) * 2 + (h)) * 16384 + m * 2048 + k * 1024) + aoff)
; #define LDB(dst, b, h) _Pragma("unroll") for (int n = 0; n < 2; ++n) _Pragma("unroll") for (int k = 0; k < 2; ++k) \
;     dst[n][k] = *reinterpret_cast<const bf16x8*>(smem + (((b) * 2 + (h)) * 16384 + n * 2048 + k * 1024) + boff)
; #define MMA(ai, bj, At_, Bt_) do { __builtin_amdgcn_s_setprio(1); \
;     _Pragma("unroll") for (int m = 0; m < 4; ++m) _Pragma("unroll") for (int n = 0; n < 2; ++n) _Pragma("unroll") for (int k = 0; k < 2; ++k) \
;       acc[ai][bj][m][n] = __builtin_amdgcn_mfma_f32_16x16x32_bf16(Bt_[n][k], At_[m][k], acc[ai][bj][m][n], 0, 0, 0); \
;     __builtin_amdgcn_s_setprio(0); } while (0)
; #define WAIT_V(n) asm volatile("s_waitcnt vmcnt(" #n ")" ::: "memory")
; #define WAIT_L(n) asm volatile("s_waitcnt lgkmcnt(" #n ")" ::: "memory")
; #define BAR __builtin_amdgcn_s_barrier()
; #define SCHED __builtin_amdgcn_sched_barrier(0)
; template <class Epi, int NB>
; DEV void gemm_tile_nb(const bf16* __restrict__ A, int lda, long strideA, const bf16* __restrict__ Bt, int ldb, long strideB, int K, int brow, int bcol, Epi& epi) {
;     ...
;     BAR; WAIT_L(0); MMA(1, 0, At, B0); BAR; SCHED;
;     STAGE(SB(1, 1), Bt, ldb, bcol + HALF, t + 3);
;     WAIT_V(6); BAR; MMA(1, 1, At, B1); BAR;
;   }
;   { LDB(B0, 0, 0); LDA(At, 0, 0); STAGE(SA(1, 1), A, lda, brow + HALF, nt - 1);
;     BAR; WAIT_L(0); MMA(0, 0, At, B0); BAR;
;     LDB(B1, 0, 1); BAR; WAIT_L(0); MMA(0, 1, At, B1); BAR;
	s_waitcnt lgkmcnt(0)
	s_setprio 1
	s_waitcnt lgkmcnt(0)
	v_mfma_f32_16x16x32_bf16 v[46:49], v[160:163], v[184:187], v[46:49]
	v_mfma_f32_16x16x32_bf16 v[42:45], v[168:171], v[184:187], v[42:45]
	v_mfma_f32_16x16x32_bf16 v[38:41], v[160:163], v[192:195], v[38:41]
	v_mfma_f32_16x16x32_bf16 v[34:37], v[168:171], v[192:195], v[34:37]
	v_mfma_f32_16x16x32_bf16 v[30:33], v[160:163], v[200:203], v[30:33]
	v_mfma_f32_16x16x32_bf16 v[26:29], v[168:171], v[200:203], v[26:29]
	v_mfma_f32_16x16x32_bf16 v[22:25], v[160:163], v[222:225], v[22:25]
	v_mfma_f32_16x16x32_bf16 v[18:21], v[168:171], v[222:225], v[18:21]
	v_mfma_f32_16x16x32_bf16 v[46:49], v[164:167], v[188:191], v[46:49]
	v_mfma_f32_16x16x32_bf16 v[42:45], v[172:175], v[188:191], v[42:45]
	v_mfma_f32_16x16x32_bf16 v[38:41], v[164:167], v[196:199], v[38:41]
	v_mfma_f32_16x16x32_bf16 v[34:37], v[172:175], v[196:199], v[34:37]
	v_mfma_f32_16x16x32_bf16 v[30:33], v[164:167], v[218:221], v[30:33]
	v_mfma_f32_16x16x32_bf16 v[26:29], v[172:175], v[218:221], v[26:29]
	v_mfma_f32_16x16x32_bf16 v[22:25], v[164:167], v[226:229], v[22:25]
	v_mfma_f32_16x16x32_bf16 v[18:21], v[172:175], v[226:229], v[18:21]
	s_setprio 0
	s_barrier
	v_readfirstlane_b32 s44, v156
	v_lshl_add_u64 v[160:161], v[208:209], 0, s[78:79]
	s_mov_b32 m0, s44
	v_readfirstlane_b32 s44, v157
	global_load_lds_dwordx4 v[160:161], off
	v_lshl_add_u64 v[160:161], v[214:215], 0, s[78:79]
	s_mov_b32 m0, s44
	s_nop 0
	global_load_lds_dwordx4 v[160:161], off
	ds_read_b128 v[160:163], v143
	ds_read_b128 v[164:167], v143 offset:1024
	ds_read_b128 v[168:171], v143 offset:2048
	ds_read_b128 v[172:175], v143 offset:3072
	s_waitcnt vmcnt(6)
	s_barrier
	s_setprio 1
	v_mfma_f32_16x16x32_bf16 v[14:17], v[230:233], v[184:187], v[14:17]
	v_mfma_f32_16x16x32_bf16 v[10:13], v[238:241], v[184:187], v[10:13]
	v_mfma_f32_16x16x32_bf16 v[6:9], v[230:233], v[192:195], v[6:9]
	v_mfma_f32_16x16x32_bf16 v[2:5], v[238:241], v[192:195], v[2:5]
	v_mfma_f32_16x16x32_bf16 v[66:69], v[230:233], v[200:203], v[66:69]
	v_mfma_f32_16x16x32_bf16 v[74:77], v[238:241], v[200:203], v[74:77]
	v_mfma_f32_16x16x32_bf16 v[78:81], v[230:233], v[222:225], v[78:81]
	v_mfma_f32_16x16x32_bf16 v[82:85], v[238:241], v[222:225], v[82:85]
	v_mfma_f32_16x16x32_bf16 v[14:17], v[234:237], v[188:191], v[14:17]
	v_mfma_f32_16x16x32_bf16 v[10:13], v[242:245], v[188:191], v[10:13]
	v_mfma_f32_16x16x32_bf16 v[6:9], v[234:237], v[196:199], v[6:9]
	v_mfma_f32_16x16x32_bf16 v[2:5], v[242:245], v[196:199], v[2:5]
	v_mfma_f32_16x16x32_bf16 v[66:69], v[234:237], v[218:221], v[66:69]
	v_mfma_f32_16x16x32_bf16 v[74:77], v[242:245], v[218:221], v[74:77]
	v_mfma_f32_16x16x32_bf16 v[78:81], v[234:237], v[226:229], v[78:81]
	v_mfma_f32_16x16x32_bf16 v[82:85], v[242:245], v[226:229], v[82:85]
	s_setprio 0
	s_add_i32 s43, s43, 2
	v_lshl_add_u64 v[132:133], v[132:133], 0, s[72:73]
	v_lshl_add_u64 v[134:135], v[134:135], 0, s[72:73]
	v_lshl_add_u64 v[136:137], v[136:137], 0, s[72:73]
	s_cmp_gt_u32 s43, 17
	v_lshl_add_u64 v[138:139], v[138:139], 0, s[72:73]
	s_barrier
	s_cbranch_scc0 .LBB0_824
	v_readlane_b32 s38, v251, 21
	s_cmpk_lt_u32 s42, 0x100
	v_readlane_b32 s39, v251, 22
	v_readfirstlane_b32 s42, v158
	s_mov_b32 m0, s42
	v_lshl_add_u64 v[156:157], v[0:1], 1, s[38:39]
	v_readfirstlane_b32 s42, v159
	ds_read_b128 v[132:135], v143
	ds_read_b128 v[136:139], v143 offset:1024
	ds_read_b128 v[144:147], v143 offset:2048
	ds_read_b128 v[148:151], v143 offset:3072
	ds_read_b128 v[152:155], v142
	ds_read_b128 v[160:163], v142 offset:1024
	ds_read_b128 v[164:167], v142 offset:2048
	ds_read_b128 v[168:171], v142 offset:3072
	ds_read_b128 v[172:175], v142 offset:4096
	ds_read_b128 v[184:187], v142 offset:5120
	ds_read_b128 v[188:191], v142 offset:6144
	ds_read_b128 v[192:195], v142 offset:7168
	global_load_lds_dwordx4 v[156:157], off
	v_lshl_add_u64 v[130:131], v[130:131], 1, s[38:39]
	s_mov_b32 m0, s42
	s_nop 0
	global_load_lds_dwordx4 v[130:131], off
	s_barrier
	s_waitcnt lgkmcnt(0)
	s_setprio 1
	s_waitcnt lgkmcnt(0)
	v_mfma_f32_16x16x32_bf16 v[126:129], v[132:135], v[152:155], v[126:129]
	v_mfma_f32_16x16x32_bf16 v[118:121], v[132:135], v[164:167], v[118:121]
	v_mfma_f32_16x16x32_bf16 v[110:113], v[132:135], v[172:175], v[110:113]
	v_mfma_f32_16x16x32_bf16 v[106:109], v[144:147], v[172:175], v[106:109]
	v_mfma_f32_16x16x32_bf16 v[102:105], v[132:135], v[188:191], v[102:105]
	v_mfma_f32_16x16x32_bf16 v[98:101], v[144:147], v[188:191], v[98:101]
	v_mfma_f32_16x16x32_bf16 v[126:129], v[136:139], v[160:163], v[126:129]
	v_mfma_f32_16x16x32_bf16 v[122:125], v[144:147], v[152:155], v[122:125]
	v_mfma_f32_16x16x32_bf16 v[118:121], v[136:139], v[168:171], v[118:121]
	v_mfma_f32_16x16x32_bf16 v[114:117], v[144:147], v[164:167], v[114:117]
	v_mfma_f32_16x16x32_bf16 v[110:113], v[136:139], v[184:187], v[110:113]
	v_mfma_f32_16x16x32_bf16 v[106:109], v[148:151], v[184:187], v[106:109]
	v_mfma_f32_16x16x32_bf16 v[102:105], v[136:139], v[192:195], v[102:105]
	v_mfma_f32_16x16x32_bf16 v[98:101], v[148:151], v[192:195], v[98:101]
	v_mfma_f32_16x16x32_bf16 v[156:159], v[148:151], v[160:163], v[122:125]
	v_mfma_f32_16x16x32_bf16 v[196:199], v[148:151], v[168:171], v[114:117]
	s_setprio 0
	s_barrier
	s_nop 0
	ds_read_b128 v[114:117], v143 offset:16384
	ds_read_b128 v[122:125], v143 offset:17408
	ds_read_b128 v[200:203], v143 offset:18432
	ds_read_b128 v[218:221], v143 offset:19456
	s_barrier
; #define LDA(dst, b, h) _Pragma("unroll") for (int m = 0; m < 4; ++m) _Pragma("unroll") for (int k = 0; k < 2; ++k) \
;     dst[m][k] = *reinterpret_cast<const bf16x8*>(smem + (((b) * 2 + (h)) * 16384 + m * 2048 + k * 1024) + aoff)
; #define LDB(dst, b, h) _Pragma("unroll") for (int n = 0; n < 2; ++n) _Pragma("unroll") for (int k = 0; k < 2; ++k) \
;     dst[n][k] = *reinterpret_cast<const bf16x8*>(smem + (((b) * 2 + (h)) * 16384 + n * 2048 + k * 1024) + boff)
; #define MMA(ai, bj, At_, Bt_) do { __builtin_amdgcn_s_setprio(1); \
;     _Pragma("unroll") for (int m = 0; m < 4; ++m) _Pragma("unroll") for (int n = 0; n < 2; ++n) _Pragma("unroll") for (int k = 0; k < 2; ++k) \
;       acc[ai][bj][m][n] = __builtin_amdgcn_mfma_f32_16x16x32_bf16(Bt_[n][k], At_[m][k], acc[ai][bj][m][n], 0, 0, 0); \
;     __builtin_amdgcn_s_setprio(0); } while (0)
; #define WAIT_V(n) asm volatile("s_waitcnt vmcnt(" #n ")" ::: "memory")
; #define WAIT_L(n) asm volatile("s_waitcnt lgkmcnt(" #n ")" ::: "memory")
; #define BAR __builtin_amdgcn_s_barrier()
; template <class Epi, int NB>
; DEV void gemm_tile_nb(const bf16* __restrict__ A, int lda, long strideA, const bf16* __restrict__ Bt, int ldb, long strideB, int K, int brow, int bcol, Epi& epi) {
;     ...
;     LDB(B1, 0, 1); BAR; WAIT_L(0); MMA(0, 1, At, B1); BAR;
;     LDA(At, 0, 1); WAIT_V(4); BAR; WAIT_L(0); MMA(1, 0, At, B0); MMA(1, 1, At, B1); BAR; }
;   { LDB(B0, 1, 0); LDA(At, 1, 0); WAIT_V(2); BAR; WAIT_L(0); MMA(0, 0, At, B0); BAR;
	s_waitcnt lgkmcnt(0)
	s_setprio 1
	s_waitcnt lgkmcnt(0)
	v_mfma_f32_16x16x32_bf16 v[94:97], v[114:117], v[152:155], v[94:97]
	v_mfma_f32_16x16x32_bf16 v[90:93], v[200:203], v[152:155], v[90:93]
	v_mfma_f32_16x16x32_bf16 v[86:89], v[114:117], v[164:167], v[86:89]
	v_mfma_f32_16x16x32_bf16 v[54:57], v[114:117], v[188:191], v[54:57]
	v_mfma_f32_16x16x32_bf16 v[50:53], v[200:203], v[188:191], v[50:53]
	v_mfma_f32_16x16x32_bf16 v[94:97], v[122:125], v[160:163], v[94:97]
	v_mfma_f32_16x16x32_bf16 v[90:93], v[218:221], v[160:163], v[90:93]
	v_mfma_f32_16x16x32_bf16 v[86:89], v[122:125], v[168:171], v[86:89]
	v_mfma_f32_16x16x32_bf16 v[70:73], v[200:203], v[164:167], v[70:73]
	v_mfma_f32_16x16x32_bf16 v[62:65], v[114:117], v[172:175], v[62:65]
	v_mfma_f32_16x16x32_bf16 v[58:61], v[200:203], v[172:175], v[58:61]
	v_mfma_f32_16x16x32_bf16 v[54:57], v[122:125], v[192:195], v[54:57]
	v_mfma_f32_16x16x32_bf16 v[50:53], v[218:221], v[192:195], v[50:53]
	v_mfma_f32_16x16x32_bf16 v[152:155], v[218:221], v[168:171], v[70:73]
	v_mfma_f32_16x16x32_bf16 v[160:163], v[122:125], v[184:187], v[62:65]
	v_mfma_f32_16x16x32_bf16 v[164:167], v[218:221], v[184:187], v[58:61]
	s_setprio 0
	s_barrier
	s_nop 0
	ds_read_b128 v[58:61], v142 offset:16384
	ds_read_b128 v[62:65], v142 offset:17408
	ds_read_b128 v[70:73], v142 offset:18432
	ds_read_b128 v[168:171], v142 offset:19456
	ds_read_b128 v[172:175], v142 offset:20480
	ds_read_b128 v[184:187], v142 offset:21504
	ds_read_b128 v[188:191], v142 offset:22528
	ds_read_b128 v[192:195], v142 offset:23552
	s_waitcnt vmcnt(4)
	s_barrier
	s_waitcnt lgkmcnt(0)
	s_setprio 1
	s_waitcnt lgkmcnt(0)
	v_mfma_f32_16x16x32_bf16 v[46:49], v[132:135], v[58:61], v[46:49]
	v_mfma_f32_16x16x32_bf16 v[42:45], v[144:147], v[58:61], v[42:45]
	v_mfma_f32_16x16x32_bf16 v[38:41], v[132:135], v[70:73], v[38:41]
	v_mfma_f32_16x16x32_bf16 v[34:37], v[144:147], v[70:73], v[34:37]
	v_mfma_f32_16x16x32_bf16 v[30:33], v[132:135], v[172:175], v[30:33]
	v_mfma_f32_16x16x32_bf16 v[26:29], v[144:147], v[172:175], v[26:29]
	v_mfma_f32_16x16x32_bf16 v[22:25], v[132:135], v[188:191], v[22:25]
	v_mfma_f32_16x16x32_bf16 v[18:21], v[144:147], v[188:191], v[18:21]
	v_mfma_f32_16x16x32_bf16 v[46:49], v[136:139], v[62:65], v[46:49]
	v_mfma_f32_16x16x32_bf16 v[42:45], v[148:151], v[62:65], v[42:45]
	v_mfma_f32_16x16x32_bf16 v[38:41], v[136:139], v[168:171], v[38:41]
	v_mfma_f32_16x16x32_bf16 v[34:37], v[148:151], v[168:171], v[34:37]
	v_mfma_f32_16x16x32_bf16 v[30:33], v[136:139], v[184:187], v[30:33]
	v_mfma_f32_16x16x32_bf16 v[26:29], v[148:151], v[184:187], v[26:29]
	v_mfma_f32_16x16x32_bf16 v[22:25], v[136:139], v[192:195], v[22:25]
	v_mfma_f32_16x16x32_bf16 v[18:21], v[148:151], v[192:195], v[18:21]
	s_setprio 0
	s_setprio 1
	v_mfma_f32_16x16x32_bf16 v[2:5], v[200:203], v[70:73], v[2:5]
	v_mfma_f32_16x16x32_bf16 v[6:9], v[114:117], v[70:73], v[6:9]
	v_mfma_f32_16x16x32_bf16 v[148:151], v[218:221], v[168:171], v[2:5]
	v_mfma_f32_16x16x32_bf16 v[2:5], v[114:117], v[172:175], v[66:69]
	v_mfma_f32_16x16x32_bf16 v[144:147], v[122:125], v[168:171], v[6:9]
	v_mfma_f32_16x16x32_bf16 v[168:171], v[122:125], v[184:187], v[2:5]
	v_mfma_f32_16x16x32_bf16 v[2:5], v[200:203], v[172:175], v[74:77]
	v_mfma_f32_16x16x32_bf16 v[172:175], v[218:221], v[184:187], v[2:5]
	v_mfma_f32_16x16x32_bf16 v[2:5], v[114:117], v[188:191], v[78:81]
	v_mfma_f32_16x16x32_bf16 v[14:17], v[114:117], v[58:61], v[14:17]
	v_mfma_f32_16x16x32_bf16 v[10:13], v[200:203], v[58:61], v[10:13]
	v_mfma_f32_16x16x32_bf16 v[184:187], v[122:125], v[192:195], v[2:5]
	v_mfma_f32_16x16x32_bf16 v[2:5], v[200:203], v[188:191], v[82:85]
	v_mfma_f32_16x16x32_bf16 v[130:133], v[122:125], v[62:65], v[14:17]
	v_mfma_f32_16x16x32_bf16 v[134:137], v[218:221], v[62:65], v[10:13]
	v_mfma_f32_16x16x32_bf16 v[188:191], v[218:221], v[192:195], v[2:5]
	s_setprio 0
	s_barrier
	s_nop 0
	ds_read_b128 v[10:13], v143 offset:32768
	ds_read_b128 v[14:17], v143 offset:33792
	ds_read_b128 v[192:195], v143 offset:34816
	ds_read_b128 v[200:203], v143 offset:35840
	ds_read_b128 v[66:69], v142 offset:32768
	ds_read_b128 v[70:73], v142 offset:33792
	ds_read_b128 v[78:81], v142 offset:34816
	ds_read_b128 v[82:85], v142 offset:35840
	ds_read_b128 v[218:221], v142 offset:36864
	ds_read_b128 v[222:225], v142 offset:37888
	ds_read_b128 v[226:229], v142 offset:38912
	ds_read_b128 v[230:233], v142 offset:39936
	s_waitcnt vmcnt(2)
	s_barrier
; #define LDA(dst, b, h) _Pragma("unroll") for (int m = 0; m < 4; ++m) _Pragma("unroll") for (int k = 0; k < 2; ++k) \
;     dst[m][k] = *reinterpret_cast<const bf16x8*>(smem + (((b) * 2 + (h)) * 16384 + m * 2048 + k * 1024) + aoff)
; #define LDB(dst, b, h) _Pragma("unroll") for (int n = 0; n < 2; ++n) _Pragma("unroll") for (int k = 0; k < 2; ++k) \
;     dst[n][k] = *reinterpret_cast<const bf16x8*>(smem + (((b) * 2 + (h)) * 16384 + n * 2048 + k * 1024) + boff)
; #define MMA(ai, bj, At_, Bt_) do { __builtin_amdgcn_s_setprio(1); \
;     _Pragma("unroll") for (int m = 0; m < 4; ++m) _Pragma("unroll") for (int n = 0; n < 2; ++n) _Pragma("unroll") for (int k = 0; k < 2; ++k) \
;       acc[ai][bj][m][n] = __builtin_amdgcn_mfma_f32_16x16x32_bf16(Bt_[n][k], At_[m][k], acc[ai][bj][m][n], 0, 0, 0); \
;     __builtin_amdgcn_s_setprio(0); } while (0)
; #define WAIT_V(n) asm volatile("s_waitcnt vmcnt(" #n ")" ::: "memory")
; #define WAIT_L(n) asm volatile("s_waitcnt lgkmcnt(" #n ")" ::: "memory")
; #define BAR __builtin_amdgcn_s_barrier()
; template <class Epi, int NB>
; DEV void gemm_tile_nb(const bf16* __restrict__ A, int lda, long strideA, const bf16* __restrict__ Bt, int ldb, long strideB, int K, int brow, int bcol, Epi& epi) {
;     ...
;   { LDB(B0, 1, 0); LDA(At, 1, 0); WAIT_V(2); BAR; WAIT_L(0); MMA(0, 0, At, B0); BAR;
;     LDB(B1, 1, 1); WAIT_V(0); BAR; WAIT_L(0); MMA(0, 1, At, B1); BAR;
;     LDA(At, 1, 1); BAR; WAIT_L(0); MMA(1, 0, At, B0); MMA(1, 1, At, B1); BAR; }
;   if (wr == 0) BAR;
	s_waitcnt lgkmcnt(0)
	s_setprio 1
	s_waitcnt lgkmcnt(0)
	v_mfma_f32_16x16x32_bf16 v[2:5], v[10:13], v[66:69], v[126:129]
	v_mfma_f32_16x16x32_bf16 v[122:125], v[14:17], v[70:73], v[2:5]
	v_mfma_f32_16x16x32_bf16 v[2:5], v[192:195], v[66:69], v[156:159]
	v_mfma_f32_16x16x32_bf16 v[126:129], v[200:203], v[70:73], v[2:5]
	v_mfma_f32_16x16x32_bf16 v[2:5], v[10:13], v[78:81], v[118:121]
	v_mfma_f32_16x16x32_bf16 v[114:117], v[14:17], v[82:85], v[2:5]
	v_mfma_f32_16x16x32_bf16 v[2:5], v[192:195], v[78:81], v[196:199]
	v_mfma_f32_16x16x32_bf16 v[118:121], v[200:203], v[82:85], v[2:5]
	v_mfma_f32_16x16x32_bf16 v[2:5], v[10:13], v[218:221], v[110:113]
	v_mfma_f32_16x16x32_bf16 v[62:65], v[14:17], v[222:225], v[2:5]
	v_mfma_f32_16x16x32_bf16 v[2:5], v[192:195], v[218:221], v[106:109]
	v_mfma_f32_16x16x32_bf16 v[74:77], v[200:203], v[222:225], v[2:5]
	v_mfma_f32_16x16x32_bf16 v[2:5], v[10:13], v[226:229], v[102:105]
	v_mfma_f32_16x16x32_bf16 v[6:9], v[192:195], v[226:229], v[98:101]
	v_mfma_f32_16x16x32_bf16 v[2:5], v[14:17], v[230:233], v[2:5]
	v_mfma_f32_16x16x32_bf16 v[6:9], v[200:203], v[230:233], v[6:9]
	s_setprio 0
	s_barrier
	ds_read_b128 v[156:159], v143 offset:49152
	ds_read_b128 v[196:199], v143 offset:50176
	ds_read_b128 v[234:237], v143 offset:51200
	ds_read_b128 v[238:241], v143 offset:52224
	s_waitcnt vmcnt(0)
	s_barrier
	s_waitcnt lgkmcnt(0)
	s_setprio 1
	s_waitcnt lgkmcnt(0)
	v_mfma_f32_16x16x32_bf16 v[58:61], v[156:159], v[66:69], v[94:97]
	v_mfma_f32_16x16x32_bf16 v[66:69], v[234:237], v[66:69], v[90:93]
	v_mfma_f32_16x16x32_bf16 v[58:61], v[196:199], v[70:73], v[58:61]
	v_mfma_f32_16x16x32_bf16 v[66:69], v[238:241], v[70:73], v[66:69]
	v_mfma_f32_16x16x32_bf16 v[70:73], v[156:159], v[78:81], v[86:89]
	v_mfma_f32_16x16x32_bf16 v[78:81], v[234:237], v[78:81], v[152:155]
	v_mfma_f32_16x16x32_bf16 v[70:73], v[196:199], v[82:85], v[70:73]
	v_mfma_f32_16x16x32_bf16 v[78:81], v[238:241], v[82:85], v[78:81]
	v_mfma_f32_16x16x32_bf16 v[82:85], v[156:159], v[218:221], v[160:163]
	v_mfma_f32_16x16x32_bf16 v[86:89], v[234:237], v[218:221], v[164:167]
	v_mfma_f32_16x16x32_bf16 v[54:57], v[156:159], v[226:229], v[54:57]
	v_mfma_f32_16x16x32_bf16 v[50:53], v[234:237], v[226:229], v[50:53]
	v_mfma_f32_16x16x32_bf16 v[82:85], v[196:199], v[222:225], v[82:85]
	v_mfma_f32_16x16x32_bf16 v[86:89], v[238:241], v[222:225], v[86:89]
	v_mfma_f32_16x16x32_bf16 v[90:93], v[196:199], v[230:233], v[54:57]
	v_mfma_f32_16x16x32_bf16 v[98:101], v[238:241], v[230:233], v[50:53]
	s_setprio 0
	s_barrier
	s_nop 1
	ds_read_b128 v[50:53], v142 offset:49152
	ds_read_b128 v[152:155], v142 offset:50176
	ds_read_b128 v[160:163], v142 offset:51200
	ds_read_b128 v[164:167], v142 offset:52224
	ds_read_b128 v[218:221], v142 offset:53248
	ds_read_b128 v[222:225], v142 offset:54272
	ds_read_b128 v[226:229], v142 offset:55296
	ds_read_b128 v[230:233], v142 offset:56320
	s_barrier
	s_waitcnt lgkmcnt(0)
	s_setprio 1
	s_waitcnt lgkmcnt(0)
	v_mfma_f32_16x16x32_bf16 v[46:49], v[10:13], v[50:53], v[46:49]
	v_mfma_f32_16x16x32_bf16 v[38:41], v[10:13], v[160:163], v[38:41]
	v_mfma_f32_16x16x32_bf16 v[30:33], v[10:13], v[218:221], v[30:33]
	v_mfma_f32_16x16x32_bf16 v[10:13], v[10:13], v[226:229], v[22:25]
	v_mfma_f32_16x16x32_bf16 v[106:109], v[14:17], v[152:155], v[46:49]
	v_mfma_f32_16x16x32_bf16 v[42:45], v[192:195], v[50:53], v[42:45]
	v_mfma_f32_16x16x32_bf16 v[94:97], v[14:17], v[164:167], v[38:41]
	v_mfma_f32_16x16x32_bf16 v[34:37], v[192:195], v[160:163], v[34:37]
	v_mfma_f32_16x16x32_bf16 v[46:49], v[14:17], v[222:225], v[30:33]
	v_mfma_f32_16x16x32_bf16 v[26:29], v[192:195], v[218:221], v[26:29]
	v_mfma_f32_16x16x32_bf16 v[10:13], v[14:17], v[230:233], v[10:13]
	v_mfma_f32_16x16x32_bf16 v[14:17], v[192:195], v[226:229], v[18:21]
	v_mfma_f32_16x16x32_bf16 v[110:113], v[200:203], v[152:155], v[42:45]
	v_mfma_f32_16x16x32_bf16 v[102:105], v[200:203], v[164:167], v[34:37]
	v_mfma_f32_16x16x32_bf16 v[54:57], v[200:203], v[222:225], v[26:29]
	v_mfma_f32_16x16x32_bf16 v[14:17], v[200:203], v[230:233], v[14:17]
	s_setprio 0
	s_setprio 1
	v_mfma_f32_16x16x32_bf16 v[18:21], v[156:159], v[50:53], v[130:133]
	v_mfma_f32_16x16x32_bf16 v[22:25], v[234:237], v[50:53], v[134:137]
	v_mfma_f32_16x16x32_bf16 v[26:29], v[156:159], v[160:163], v[144:147]
	v_mfma_f32_16x16x32_bf16 v[30:33], v[234:237], v[160:163], v[148:151]
	v_mfma_f32_16x16x32_bf16 v[34:37], v[156:159], v[218:221], v[168:171]
	v_mfma_f32_16x16x32_bf16 v[38:41], v[234:237], v[218:221], v[172:175]
	v_mfma_f32_16x16x32_bf16 v[42:45], v[156:159], v[226:229], v[184:187]
	v_mfma_f32_16x16x32_bf16 v[50:53], v[234:237], v[226:229], v[188:191]
	v_mfma_f32_16x16x32_bf16 v[18:21], v[196:199], v[152:155], v[18:21]
	v_mfma_f32_16x16x32_bf16 v[22:25], v[238:241], v[152:155], v[22:25]
	v_mfma_f32_16x16x32_bf16 v[26:29], v[196:199], v[164:167], v[26:29]
	v_mfma_f32_16x16x32_bf16 v[30:33], v[238:241], v[164:167], v[30:33]
	v_mfma_f32_16x16x32_bf16 v[34:37], v[196:199], v[222:225], v[34:37]
	v_mfma_f32_16x16x32_bf16 v[38:41], v[238:241], v[222:225], v[38:41]
	v_mfma_f32_16x16x32_bf16 v[42:45], v[196:199], v[230:233], v[42:45]
	v_mfma_f32_16x16x32_bf16 v[50:53], v[238:241], v[230:233], v[50:53]
	s_setprio 0
	s_barrier
	s_cbranch_scc0 .LBB0_827
	s_barrier

; #define STAGE(P, BASE, LD, br, kt) do { const bf16* _gb = BASE + ((long)(br) * (LD) + (long)(kt) * BK); \
;     _Pragma("unroll") for (int _i = 0; _i < 2; ++_i) { \
;       __builtin_amdgcn_global_load_lds((const unsigned*)(_gb + ((&LD == &lda) ? offA[_i] : offB[_i])), \
;         (unsigned*)((char*)(P) + tidx_ * 16 + _i * 8192), 16, 0, 0); } } while (0)
; #define WAIT_V(n) asm volatile("s_waitcnt vmcnt(" #n ")" ::: "memory")
; #define BAR __builtin_amdgcn_s_barrier()
; template <class Epi, int NB>
; DEV void gemm_tile_nb(const bf16* __restrict__ A, int lda, long strideA, const bf16* __restrict__ Bt, int ldb, long strideB, int K, int brow, int bcol, Epi& epi) {
;     ...
;   const int lane_off_ = (fr * 64 + fq * 16) ^ ((fr >> 3) << 5);
;   const int aoff = wr * 8192 + lane_off_, boff = 65536 + wc * 4096 + lane_off_;
;   unsigned offA[2], offB[2];
; #pragma unroll
;   for (int _i = 0; _i < 2; ++_i) { int _r, _c; stage_rc(tidx_ * 16 + _i * 8192, _r, _c); offA[_i] = (unsigned)(_r * lda + _c); offB[_i] = (unsigned)(_r * ldb + _c); }
; #pragma unroll 1
;   for (int br = 0; br < NB; ++br) {
;   STAGE(SB(0, 0), Bt, ldb, bcol, 0); STAGE(SA(0, 0), A, lda, brow, 0);
;   STAGE(SB(0, 1), Bt, ldb, bcol + HALF, 0); STAGE(SA(0, 1), A, lda, brow + HALF, 0);
;   if (wr == 1) BAR;
;   WAIT_V(4); BAR;
;   STAGE(SB(1, 0), Bt, ldb, bcol, 1); STAGE(SA(1, 0), A, lda, brow, 1); STAGE(SB(1, 1), Bt, ldb, bcol + HALF, 1);
;   WAIT_V(6); BAR;
.LBB0_861:
	v_and_b32_e32 v141, 15, v23
	s_bfe_u32 s41, s42, 0x20006
	v_bfe_u32 v140, v23, 4, 2
	v_lshlrev_b32_e32 v24, 6, v141
	v_lshlrev_b32_e32 v23, 2, v23
	v_lshl_or_b32 v24, v140, 4, v24
	v_and_b32_e32 v23, 32, v23
	s_lshl_b32 s43, s40, 13
	s_lshl_b32 s44, s41, 12
	v_add_u32_e32 v152, s13, v15
	v_bitop3_b32 v25, v24, s44, v23 bitop3:0xde
	v_bitop3_b32 v23, v24, s43, v23 bitop3:0xde
	s_mov_b64 s[38:39], 0x80
	v_readfirstlane_b32 s43, v152
	v_add_u32_e32 v153, 0x2000, v152
	v_lshl_add_u64 v[2:3], v[2:3], 0, s[38:39]
	s_mov_b32 m0, s43
	v_readfirstlane_b32 s43, v153
	v_add_u32_e32 v154, 0x8000, v145
	s_waitcnt vmcnt(4)
	s_barrier
	global_load_lds_dwordx4 v[2:3], off
	v_lshl_add_u64 v[2:3], v[4:5], 0, s[38:39]
	s_mov_b32 m0, s43
	v_readfirstlane_b32 s43, v154
	v_add_u32_e32 v155, 0xa000, v145
	global_load_lds_dwordx4 v[2:3], off
	v_lshl_add_u64 v[2:3], v[8:9], 0, s[38:39]
	s_mov_b32 m0, s43
	v_readfirstlane_b32 s43, v155
	v_add_u32_e32 v156, s14, v15
	global_load_lds_dwordx4 v[2:3], off
	v_lshl_add_u64 v[2:3], v[10:11], 0, s[38:39]
	s_mov_b32 m0, s43
	v_readfirstlane_b32 s43, v156
	v_add_u32_e32 v157, 0x2000, v156
	global_load_lds_dwordx4 v[2:3], off
	v_lshl_add_u64 v[2:3], v[12:13], 0, s[38:39]
	s_mov_b32 m0, s43
	v_readfirstlane_b32 s43, v157
	global_load_lds_dwordx4 v[2:3], off
	v_lshl_add_u64 v[2:3], v[6:7], 0, s[38:39]
	s_mov_b32 m0, s43
	v_lshlrev_b32_e32 v4, 13, v16
	global_load_lds_dwordx4 v[2:3], off
	v_lshlrev_b32_e32 v2, 13, v14
	v_and_b32_e32 v2, 0xffffc000, v2
	v_and_b32_e32 v4, 0xffffc000, v4
	v_lshl_add_u32 v2, v17, 10, v2
	v_readlane_b32 s38, v253, 35
	v_readlane_b32 s8, v254, 63
	v_lshl_add_u32 v4, v20, 10, v4
	v_or_b32_e32 v2, v2, v18
	s_add_u32 s44, s38, s8
	v_readlane_b32 s38, v253, 36
	v_or_b32_e32 v4, v4, v21
	v_add_u32_sdwa v2, v2, sext(v19) dst_sel:DWORD dst_unused:UNUSED_PAD src0_sel:DWORD src1_sel:WORD_0
	v_mov_b32_e32 v3, v1
	s_addc_u32 s45, s38, 0
	v_add_u32_sdwa v4, v4, sext(v22) dst_sel:DWORD dst_unused:UNUSED_PAD src0_sel:DWORD src1_sel:WORD_0
	v_mov_b32_e32 v5, v1
	v_readlane_b32 s38, v253, 37
	s_waitcnt vmcnt(6)
	v_lshlrev_b64 v[2:3], 1, v[2:3]
	v_lshlrev_b64 v[4:5], 1, v[4:5]
	v_readlane_b32 s39, v253, 38
	v_or_b32_e32 v25, 0x10000, v25
	v_lshl_add_u64 v[132:133], s[44:45], 0, v[2:3]
	v_lshl_add_u64 v[136:137], s[38:39], 0, v[2:3]
	v_lshl_add_u64 v[138:139], s[38:39], 0, v[4:5]
	v_mov_b32_e32 v2, 0
	v_readlane_b32 s38, v253, 40
	v_lshl_add_u64 v[134:135], s[44:45], 0, v[4:5]
	s_mov_b32 s43, -2
	v_add_u32_e32 v143, 0, v25
	v_add_u32_e32 v142, 0, v23
	v_mov_b32_e32 v3, v2
	v_mov_b32_e32 v4, v2
	v_mov_b32_e32 v5, v2
	v_mov_b32_e32 v6, v2
	v_mov_b32_e32 v7, v2
	v_mov_b32_e32 v8, v2
	v_mov_b32_e32 v9, v2
	v_mov_b32_e32 v10, v2
	v_mov_b32_e32 v11, v2
	v_mov_b32_e32 v12, v2
	v_mov_b32_e32 v13, v2
	v_mov_b32_e32 v14, v2
	v_mov_b32_e32 v15, v2
	v_mov_b32_e32 v16, v2
	v_mov_b32_e32 v17, v2
	v_mov_b32_e32 v18, v2
	v_mov_b32_e32 v19, v2
	v_mov_b32_e32 v20, v2
	v_mov_b32_e32 v21, v2
	v_mov_b32_e32 v22, v2
	v_mov_b32_e32 v23, v2
	v_mov_b32_e32 v24, v2
	v_mov_b32_e32 v25, v2
	v_mov_b32_e32 v26, v2
	v_mov_b32_e32 v27, v2
	v_mov_b32_e32 v28, v2
	v_mov_b32_e32 v29, v2
	v_mov_b32_e32 v30, v2
	v_mov_b32_e32 v31, v2
	v_mov_b32_e32 v32, v2
	v_mov_b32_e32 v33, v2
	v_mov_b32_e32 v34, v2
	v_mov_b32_e32 v35, v2
	v_mov_b32_e32 v36, v2
	v_mov_b32_e32 v37, v2
	v_mov_b32_e32 v38, v2
	v_mov_b32_e32 v39, v2
	v_mov_b32_e32 v40, v2
	v_mov_b32_e32 v41, v2
	v_mov_b32_e32 v42, v2
	v_mov_b32_e32 v43, v2
	v_mov_b32_e32 v44, v2
	v_mov_b32_e32 v45, v2
	v_mov_b32_e32 v46, v2
	v_mov_b32_e32 v47, v2
	v_mov_b32_e32 v48, v2
	v_mov_b32_e32 v49, v2
	v_mov_b32_e32 v50, v2
	v_mov_b32_e32 v51, v2
	v_mov_b32_e32 v52, v2
	v_mov_b32_e32 v53, v2
	v_mov_b32_e32 v54, v2
	v_mov_b32_e32 v55, v2
	v_mov_b32_e32 v56, v2
	v_mov_b32_e32 v57, v2
	v_mov_b32_e32 v58, v2
	v_mov_b32_e32 v59, v2
	v_mov_b32_e32 v60, v2
	v_mov_b32_e32 v61, v2
	v_mov_b32_e32 v62, v2
	v_mov_b32_e32 v63, v2
	v_mov_b32_e32 v64, v2
	v_mov_b32_e32 v65, v2
	v_mov_b32_e32 v70, v2
	v_mov_b32_e32 v71, v2
	v_mov_b32_e32 v72, v2
	v_mov_b32_e32 v73, v2
	v_mov_b32_e32 v86, v2
	v_mov_b32_e32 v87, v2
	v_mov_b32_e32 v88, v2
	v_mov_b32_e32 v89, v2
	v_mov_b32_e32 v90, v2
	v_mov_b32_e32 v91, v2
	v_mov_b32_e32 v92, v2
	v_mov_b32_e32 v93, v2
	v_mov_b32_e32 v94, v2
	v_mov_b32_e32 v95, v2
	v_mov_b32_e32 v96, v2
	v_mov_b32_e32 v97, v2
	v_mov_b32_e32 v98, v2
	v_mov_b32_e32 v99, v2
	v_mov_b32_e32 v100, v2
	v_mov_b32_e32 v101, v2
	v_mov_b32_e32 v102, v2
	v_mov_b32_e32 v103, v2
	v_mov_b32_e32 v104, v2
	v_mov_b32_e32 v105, v2
	v_mov_b32_e32 v106, v2
	v_mov_b32_e32 v107, v2
	v_mov_b32_e32 v108, v2
	v_mov_b32_e32 v109, v2
	v_mov_b32_e32 v110, v2
	v_mov_b32_e32 v111, v2
	v_mov_b32_e32 v112, v2
	v_mov_b32_e32 v113, v2
	v_mov_b32_e32 v114, v2
	v_mov_b32_e32 v115, v2
	v_mov_b32_e32 v116, v2
	v_mov_b32_e32 v117, v2
	v_mov_b32_e32 v118, v2
	v_mov_b32_e32 v119, v2
	v_mov_b32_e32 v120, v2
	v_mov_b32_e32 v121, v2
	v_mov_b32_e32 v122, v2
	v_mov_b32_e32 v123, v2
	v_mov_b32_e32 v124, v2
	v_mov_b32_e32 v125, v2
	v_mov_b32_e32 v126, v2
	v_mov_b32_e32 v127, v2
	v_mov_b32_e32 v128, v2
	v_mov_b32_e32 v129, v2
	v_mov_b32_e32 v66, v2
	v_mov_b32_e32 v67, v2
	v_mov_b32_e32 v68, v2
	v_mov_b32_e32 v69, v2
	v_mov_b32_e32 v74, v2
	v_mov_b32_e32 v75, v2
	v_mov_b32_e32 v76, v2
	v_mov_b32_e32 v77, v2
	v_mov_b32_e32 v78, v2
	v_mov_b32_e32 v79, v2
	v_mov_b32_e32 v80, v2
	v_mov_b32_e32 v81, v2
	v_mov_b32_e32 v82, v2
	v_mov_b32_e32 v83, v2
	v_mov_b32_e32 v84, v2
	v_mov_b32_e32 v85, v2
	v_readlane_b32 s39, v253, 41
	s_mov_b64 s[48:49], 0x1e6e4080
	s_mov_b64 s[50:51], 0x2e80100
	s_mov_b64 s[56:57], 0x1e6a4100
	s_mov_b64 s[58:59], 0x2ec0100
	s_barrier
	ds_read_b128 v[160:163], v143
	ds_read_b128 v[164:167], v143 offset:1024
	ds_read_b128 v[168:171], v143 offset:2048
	ds_read_b128 v[172:175], v143 offset:3072
; #define STAGE(P, BASE, LD, br, kt) do { const bf16* _gb = BASE + ((long)(br) * (LD) + (long)(kt) * BK); \
;     _Pragma("unroll") for (int _i = 0; _i < 2; ++_i) { \
;       __builtin_amdgcn_global_load_lds((const unsigned*)(_gb + ((&LD == &lda) ? offA[_i] : offB[_i])), \
;         (unsigned*)((char*)(P) + tidx_ * 16 + _i * 8192), 16, 0, 0); } } while (0)
; #define LDA(dst, b, h) _Pragma("unroll") for (int m = 0; m < 4; ++m) _Pragma("unroll") for (int k = 0; k < 2; ++k) \
;     dst[m][k] = *reinterpret_cast<const bf16x8*>(smem + (((b) * 2 + (h)) * 16384 + m * 2048 + k * 1024) + aoff)
; #define LDB(dst, b, h) _Pragma("unroll") for (int n = 0; n < 2; ++n) _Pragma("unroll") for (int k = 0; k < 2; ++k) \
;     dst[n][k] = *reinterpret_cast<const bf16x8*>(smem + (((b) * 2 + (h)) * 16384 + n * 2048 + k * 1024) + boff)
; #define MMA(ai, bj, At_, Bt_) do { __builtin_amdgcn_s_setprio(1); \
;     _Pragma("unroll") for (int m = 0; m < 4; ++m) _Pragma("unroll") for (int n = 0; n < 2; ++n) _Pragma("unroll") for (int k = 0; k < 2; ++k) \
;       acc[ai][bj][m][n] = __builtin_amdgcn_mfma_f32_16x16x32_bf16(Bt_[n][k], At_[m][k], acc[ai][bj][m][n], 0, 0, 0); \
;     __builtin_amdgcn_s_setprio(0); } while (0)
; #define WAIT_L(n) asm volatile("s_waitcnt lgkmcnt(" #n ")" ::: "memory")
; #define BAR __builtin_amdgcn_s_barrier()
; #define SCHED __builtin_amdgcn_sched_barrier(0)
; template <class Epi, int NB>
; DEV void gemm_tile_nb(const bf16* __restrict__ A, int lda, long strideA, const bf16* __restrict__ Bt, int ldb, long strideB, int K, int brow, int bcol, Epi& epi) {
;     ...
;     LDB(B0, 0, 0); SCHED; LDA(At, 0, 0); STAGE(SA(1, 1), A, lda, brow + HALF, t + 1);
;     WAIT_L(8); BAR; WAIT_L(0); MMA(0, 0, At, B0); BAR; SCHED;
;     LDB(B1, 0, 1); STAGE(SB(0, 0), Bt, ldb, bcol, t + 2);
;     BAR; WAIT_L(0); MMA(0, 1, At, B1); BAR;
;     LDA(At, 0, 1); STAGE(SA(0, 0), A, lda, brow, t + 2);
;     BAR; WAIT_L(0); MMA(1, 0, At, B0); BAR; SCHED;
.LBB0_862:
	v_add_u32_e32 v158, 0xc000, v145
	v_lshl_add_u64 v[176:177], v[136:137], 0, s[38:39]
	v_readfirstlane_b32 s44, v158
	v_lshl_add_u64 v[204:205], v[176:177], 0, s[48:49]
	s_mov_b32 m0, s44
	v_add_u32_e32 v159, 0xe000, v145
	ds_read_b128 v[184:187], v142
	ds_read_b128 v[188:191], v142 offset:1024
	ds_read_b128 v[192:195], v142 offset:2048
	ds_read_b128 v[196:199], v142 offset:3072
	ds_read_b128 v[200:203], v142 offset:4096
	ds_read_b128 v[218:221], v142 offset:5120
	ds_read_b128 v[222:225], v142 offset:6144
	ds_read_b128 v[226:229], v142 offset:7168
	global_load_lds_dwordx4 v[204:205], off
	v_lshl_add_u64 v[204:205], v[138:139], 0, s[38:39]
	v_readfirstlane_b32 s44, v159
	v_lshl_add_u64 v[208:209], v[204:205], 0, s[48:49]
	s_mov_b32 m0, s44
	s_nop 0
	global_load_lds_dwordx4 v[208:209], off
	s_waitcnt lgkmcnt(8)
	s_barrier
	s_waitcnt lgkmcnt(0)
	s_setprio 1
	s_waitcnt lgkmcnt(0)
	v_mfma_f32_16x16x32_bf16 v[126:129], v[160:163], v[184:187], v[126:129]
	v_mfma_f32_16x16x32_bf16 v[122:125], v[168:171], v[184:187], v[122:125]
	v_mfma_f32_16x16x32_bf16 v[118:121], v[160:163], v[192:195], v[118:121]
	v_mfma_f32_16x16x32_bf16 v[114:117], v[168:171], v[192:195], v[114:117]
	v_mfma_f32_16x16x32_bf16 v[110:113], v[160:163], v[200:203], v[110:113]
	v_mfma_f32_16x16x32_bf16 v[106:109], v[168:171], v[200:203], v[106:109]
	v_mfma_f32_16x16x32_bf16 v[102:105], v[160:163], v[222:225], v[102:105]
	v_mfma_f32_16x16x32_bf16 v[98:101], v[168:171], v[222:225], v[98:101]
	v_mfma_f32_16x16x32_bf16 v[126:129], v[164:167], v[188:191], v[126:129]
	v_mfma_f32_16x16x32_bf16 v[122:125], v[172:175], v[188:191], v[122:125]
	v_mfma_f32_16x16x32_bf16 v[118:121], v[164:167], v[196:199], v[118:121]
	v_mfma_f32_16x16x32_bf16 v[114:117], v[172:175], v[196:199], v[114:117]
	v_mfma_f32_16x16x32_bf16 v[110:113], v[164:167], v[218:221], v[110:113]
	v_mfma_f32_16x16x32_bf16 v[106:109], v[172:175], v[218:221], v[106:109]
	v_mfma_f32_16x16x32_bf16 v[102:105], v[164:167], v[226:229], v[102:105]
	v_mfma_f32_16x16x32_bf16 v[98:101], v[172:175], v[226:229], v[98:101]
	s_setprio 0
	s_barrier
	v_lshl_add_u64 v[208:209], v[132:133], 0, s[38:39]
	v_readfirstlane_b32 s44, v144
	v_lshl_add_u64 v[214:215], v[208:209], 0, s[50:51]
	s_mov_b32 m0, s44
	ds_read_b128 v[230:233], v143 offset:16384
	ds_read_b128 v[234:237], v143 offset:17408
	ds_read_b128 v[238:241], v143 offset:18432
	ds_read_b128 v[242:245], v143 offset:19456
	global_load_lds_dwordx4 v[214:215], off
	v_lshl_add_u64 v[214:215], v[134:135], 0, s[38:39]
	v_readfirstlane_b32 s44, v147
	v_lshl_add_u64 v[246:247], v[214:215], 0, s[50:51]
	s_mov_b32 m0, s44
	s_nop 0
	global_load_lds_dwordx4 v[246:247], off
	s_barrier
	s_waitcnt lgkmcnt(0)
	s_setprio 1
	s_waitcnt lgkmcnt(0)
	v_mfma_f32_16x16x32_bf16 v[94:97], v[230:233], v[184:187], v[94:97]
	v_mfma_f32_16x16x32_bf16 v[90:93], v[238:241], v[184:187], v[90:93]
	v_mfma_f32_16x16x32_bf16 v[86:89], v[230:233], v[192:195], v[86:89]
	v_mfma_f32_16x16x32_bf16 v[70:73], v[238:241], v[192:195], v[70:73]
	v_mfma_f32_16x16x32_bf16 v[62:65], v[230:233], v[200:203], v[62:65]
	v_mfma_f32_16x16x32_bf16 v[58:61], v[238:241], v[200:203], v[58:61]
	v_mfma_f32_16x16x32_bf16 v[54:57], v[230:233], v[222:225], v[54:57]
	v_mfma_f32_16x16x32_bf16 v[50:53], v[238:241], v[222:225], v[50:53]
	v_mfma_f32_16x16x32_bf16 v[94:97], v[234:237], v[188:191], v[94:97]
	v_mfma_f32_16x16x32_bf16 v[90:93], v[242:245], v[188:191], v[90:93]
	v_mfma_f32_16x16x32_bf16 v[86:89], v[234:237], v[196:199], v[86:89]
	v_mfma_f32_16x16x32_bf16 v[70:73], v[242:245], v[196:199], v[70:73]
	v_mfma_f32_16x16x32_bf16 v[62:65], v[234:237], v[218:221], v[62:65]
	v_mfma_f32_16x16x32_bf16 v[58:61], v[242:245], v[218:221], v[58:61]
	v_mfma_f32_16x16x32_bf16 v[54:57], v[234:237], v[226:229], v[54:57]
	v_mfma_f32_16x16x32_bf16 v[50:53], v[242:245], v[226:229], v[50:53]
	s_setprio 0
	v_readfirstlane_b32 s44, v145
	v_lshl_add_u64 v[246:247], v[176:177], 0, s[56:57]
	s_mov_b32 m0, s44
	v_readfirstlane_b32 s44, v149
	s_barrier
	ds_read_b128 v[184:187], v142 offset:16384
	ds_read_b128 v[188:191], v142 offset:17408
	ds_read_b128 v[192:195], v142 offset:18432
	ds_read_b128 v[196:199], v142 offset:19456
	ds_read_b128 v[200:203], v142 offset:20480
	ds_read_b128 v[218:221], v142 offset:21504
	ds_read_b128 v[222:225], v142 offset:22528
	ds_read_b128 v[226:229], v142 offset:23552
	global_load_lds_dwordx4 v[246:247], off
	v_lshl_add_u64 v[246:247], v[204:205], 0, s[56:57]
	s_mov_b32 m0, s44
	s_nop 0
	global_load_lds_dwordx4 v[246:247], off
	s_waitcnt vmcnt(10)
	s_barrier
	s_waitcnt lgkmcnt(0)
	s_setprio 1
	s_waitcnt lgkmcnt(0)
	v_mfma_f32_16x16x32_bf16 v[46:49], v[160:163], v[184:187], v[46:49]
	v_mfma_f32_16x16x32_bf16 v[42:45], v[168:171], v[184:187], v[42:45]
	v_mfma_f32_16x16x32_bf16 v[38:41], v[160:163], v[192:195], v[38:41]
	v_mfma_f32_16x16x32_bf16 v[34:37], v[168:171], v[192:195], v[34:37]
	v_mfma_f32_16x16x32_bf16 v[30:33], v[160:163], v[200:203], v[30:33]
	v_mfma_f32_16x16x32_bf16 v[26:29], v[168:171], v[200:203], v[26:29]
	v_mfma_f32_16x16x32_bf16 v[22:25], v[160:163], v[222:225], v[22:25]
	v_mfma_f32_16x16x32_bf16 v[18:21], v[168:171], v[222:225], v[18:21]
	v_mfma_f32_16x16x32_bf16 v[46:49], v[164:167], v[188:191], v[46:49]
	v_mfma_f32_16x16x32_bf16 v[42:45], v[172:175], v[188:191], v[42:45]
	v_mfma_f32_16x16x32_bf16 v[38:41], v[164:167], v[196:199], v[38:41]
	v_mfma_f32_16x16x32_bf16 v[34:37], v[172:175], v[196:199], v[34:37]
	v_mfma_f32_16x16x32_bf16 v[30:33], v[164:167], v[218:221], v[30:33]
	v_mfma_f32_16x16x32_bf16 v[26:29], v[172:175], v[218:221], v[26:29]
	v_mfma_f32_16x16x32_bf16 v[22:25], v[164:167], v[226:229], v[22:25]
	v_mfma_f32_16x16x32_bf16 v[18:21], v[172:175], v[226:229], v[18:21]
	s_setprio 0
	s_barrier
; #define STAGE(P, BASE, LD, br, kt) do { const bf16* _gb = BASE + ((long)(br) * (LD) + (long)(kt) * BK); \
;     _Pragma("unroll") for (int _i = 0; _i < 2; ++_i) { \
;       __builtin_amdgcn_global_load_lds((const unsigned*)(_gb + ((&LD == &lda) ? offA[_i] : offB[_i])), \
;         (unsigned*)((char*)(P) + tidx_ * 16 + _i * 8192), 16, 0, 0); } } while (0)
; #define LDA(dst, b, h) _Pragma("unroll") for (int m = 0; m < 4; ++m) _Pragma("unroll") for (int k = 0; k < 2; ++k) \
;     dst[m][k] = *reinterpret_cast<const bf16x8*>(smem + (((b) * 2 + (h)) * 16384 + m * 2048 + k * 1024) + aoff)
; #define LDB(dst, b, h) _Pragma("unroll") for (int n = 0; n < 2; ++n) _Pragma("unroll") for (int k = 0; k < 2; ++k) \
;     dst[n][k] = *reinterpret_cast<const bf16x8*>(smem + (((b) * 2 + (h)) * 16384 + n * 2048 + k * 1024) + boff)
; #define MMA(ai, bj, At_, Bt_) do { __builtin_amdgcn_s_setprio(1); \
;     _Pragma("unroll") for (int m = 0; m < 4; ++m) _Pragma("unroll") for (int n = 0; n < 2; ++n) _Pragma("unroll") for (int k = 0; k < 2; ++k) \
;       acc[ai][bj][m][n] = __builtin_amdgcn_mfma_f32_16x16x32_bf16(Bt_[n][k], At_[m][k], acc[ai][bj][m][n], 0, 0, 0); \
;     __builtin_amdgcn_s_setprio(0); } while (0)
; #define WAIT_V(n) asm volatile("s_waitcnt vmcnt(" #n ")" ::: "memory")
; #define WAIT_L(n) asm volatile("s_waitcnt lgkmcnt(" #n ")" ::: "memory")
; #define BAR __builtin_amdgcn_s_barrier()
; #define SCHED __builtin_amdgcn_sched_barrier(0)
; template <class Epi, int NB>
; DEV void gemm_tile_nb(const bf16* __restrict__ A, int lda, long strideA, const bf16* __restrict__ Bt, int ldb, long strideB, int K, int brow, int bcol, Epi& epi) {
;     ...
;     STAGE(SB(0, 1), Bt, ldb, bcol + HALF, t + 2);
;     WAIT_V(6); BAR; MMA(1, 1, At, B1); BAR;
;     LDB(B0, 1, 0); SCHED; LDA(At, 1, 0); STAGE(SA(0, 1), A, lda, brow + HALF, t + 2);
;     WAIT_L(8); BAR; WAIT_L(0); MMA(0, 0, At, B0); BAR; SCHED;
;     LDB(B1, 1, 1); STAGE(SB(1, 0), Bt, ldb, bcol, t + 3);
;     BAR; WAIT_L(0); MMA(0, 1, At, B1); BAR;
;     LDA(At, 1, 1); STAGE(SA(1, 0), A, lda, brow, t + 3);
	v_readfirstlane_b32 s44, v146
	v_lshl_add_u64 v[160:161], v[208:209], 0, s[58:59]
	s_mov_b32 m0, s44
	v_readfirstlane_b32 s44, v150
	global_load_lds_dwordx4 v[160:161], off
	v_lshl_add_u64 v[160:161], v[214:215], 0, s[58:59]
	s_mov_b32 m0, s44
	s_nop 0
	global_load_lds_dwordx4 v[160:161], off
	ds_read_b128 v[160:163], v143 offset:32768
	ds_read_b128 v[164:167], v143 offset:33792
	ds_read_b128 v[168:171], v143 offset:34816
	ds_read_b128 v[172:175], v143 offset:35840
	s_waitcnt vmcnt(6)
	s_barrier
	s_setprio 1
	v_mfma_f32_16x16x32_bf16 v[14:17], v[230:233], v[184:187], v[14:17]
	v_mfma_f32_16x16x32_bf16 v[10:13], v[238:241], v[184:187], v[10:13]
	v_mfma_f32_16x16x32_bf16 v[6:9], v[230:233], v[192:195], v[6:9]
	v_mfma_f32_16x16x32_bf16 v[2:5], v[238:241], v[192:195], v[2:5]
	v_mfma_f32_16x16x32_bf16 v[66:69], v[230:233], v[200:203], v[66:69]
	v_mfma_f32_16x16x32_bf16 v[74:77], v[238:241], v[200:203], v[74:77]
	v_mfma_f32_16x16x32_bf16 v[78:81], v[230:233], v[222:225], v[78:81]
	v_mfma_f32_16x16x32_bf16 v[82:85], v[238:241], v[222:225], v[82:85]
	v_mfma_f32_16x16x32_bf16 v[14:17], v[234:237], v[188:191], v[14:17]
	v_mfma_f32_16x16x32_bf16 v[10:13], v[242:245], v[188:191], v[10:13]
	v_mfma_f32_16x16x32_bf16 v[6:9], v[234:237], v[196:199], v[6:9]
	v_mfma_f32_16x16x32_bf16 v[2:5], v[242:245], v[196:199], v[2:5]
	v_mfma_f32_16x16x32_bf16 v[66:69], v[234:237], v[218:221], v[66:69]
	v_mfma_f32_16x16x32_bf16 v[74:77], v[242:245], v[218:221], v[74:77]
	v_mfma_f32_16x16x32_bf16 v[78:81], v[234:237], v[226:229], v[78:81]
	v_mfma_f32_16x16x32_bf16 v[82:85], v[242:245], v[226:229], v[82:85]
	s_setprio 0
	s_barrier
	v_readfirstlane_b32 s44, v148
	v_lshl_add_u64 v[230:231], v[176:177], 0, s[16:17]
	s_mov_b32 m0, s44
	v_readfirstlane_b32 s44, v151
	ds_read_b128 v[184:187], v142 offset:32768
	ds_read_b128 v[188:191], v142 offset:33792
	ds_read_b128 v[192:195], v142 offset:34816
	ds_read_b128 v[196:199], v142 offset:35840
	ds_read_b128 v[200:203], v142 offset:36864
	ds_read_b128 v[218:221], v142 offset:37888
	ds_read_b128 v[222:225], v142 offset:38912
	ds_read_b128 v[226:229], v142 offset:39936
	global_load_lds_dwordx4 v[230:231], off
	v_lshl_add_u64 v[230:231], v[204:205], 0, s[16:17]
	s_mov_b32 m0, s44
	s_nop 0
	global_load_lds_dwordx4 v[230:231], off
	s_waitcnt lgkmcnt(8)
	s_barrier
	s_waitcnt lgkmcnt(0)
	s_setprio 1
	s_waitcnt lgkmcnt(0)
	v_mfma_f32_16x16x32_bf16 v[126:129], v[160:163], v[184:187], v[126:129]
	v_mfma_f32_16x16x32_bf16 v[122:125], v[168:171], v[184:187], v[122:125]
	v_mfma_f32_16x16x32_bf16 v[118:121], v[160:163], v[192:195], v[118:121]
	v_mfma_f32_16x16x32_bf16 v[114:117], v[168:171], v[192:195], v[114:117]
	v_mfma_f32_16x16x32_bf16 v[110:113], v[160:163], v[200:203], v[110:113]
	v_mfma_f32_16x16x32_bf16 v[106:109], v[168:171], v[200:203], v[106:109]
	v_mfma_f32_16x16x32_bf16 v[102:105], v[160:163], v[222:225], v[102:105]
	v_mfma_f32_16x16x32_bf16 v[98:101], v[168:171], v[222:225], v[98:101]
	v_mfma_f32_16x16x32_bf16 v[126:129], v[164:167], v[188:191], v[126:129]
	v_mfma_f32_16x16x32_bf16 v[122:125], v[172:175], v[188:191], v[122:125]
	v_mfma_f32_16x16x32_bf16 v[118:121], v[164:167], v[196:199], v[118:121]
	v_mfma_f32_16x16x32_bf16 v[114:117], v[172:175], v[196:199], v[114:117]
	v_mfma_f32_16x16x32_bf16 v[110:113], v[164:167], v[218:221], v[110:113]
	v_mfma_f32_16x16x32_bf16 v[106:109], v[172:175], v[218:221], v[106:109]
	v_mfma_f32_16x16x32_bf16 v[102:105], v[164:167], v[226:229], v[102:105]
	v_mfma_f32_16x16x32_bf16 v[98:101], v[172:175], v[226:229], v[98:101]
	s_setprio 0
	s_barrier
	v_readfirstlane_b32 s44, v152
	v_lshl_add_u64 v[246:247], v[208:209], 0, s[36:37]
	s_mov_b32 m0, s44
	v_readfirstlane_b32 s44, v153
	ds_read_b128 v[230:233], v143 offset:49152
	ds_read_b128 v[234:237], v143 offset:50176
	ds_read_b128 v[238:241], v143 offset:51200
	ds_read_b128 v[242:245], v143 offset:52224
	global_load_lds_dwordx4 v[246:247], off
	v_lshl_add_u64 v[246:247], v[214:215], 0, s[36:37]
	s_mov_b32 m0, s44
	s_nop 0
	global_load_lds_dwordx4 v[246:247], off
	s_barrier
	s_waitcnt lgkmcnt(0)
	s_setprio 1
	s_waitcnt lgkmcnt(0)
	v_mfma_f32_16x16x32_bf16 v[94:97], v[230:233], v[184:187], v[94:97]
	v_mfma_f32_16x16x32_bf16 v[90:93], v[238:241], v[184:187], v[90:93]
	v_mfma_f32_16x16x32_bf16 v[86:89], v[230:233], v[192:195], v[86:89]
	v_mfma_f32_16x16x32_bf16 v[70:73], v[238:241], v[192:195], v[70:73]
	v_mfma_f32_16x16x32_bf16 v[62:65], v[230:233], v[200:203], v[62:65]
	v_mfma_f32_16x16x32_bf16 v[58:61], v[238:241], v[200:203], v[58:61]
	v_mfma_f32_16x16x32_bf16 v[54:57], v[230:233], v[222:225], v[54:57]
	v_mfma_f32_16x16x32_bf16 v[50:53], v[238:241], v[222:225], v[50:53]
	v_mfma_f32_16x16x32_bf16 v[94:97], v[234:237], v[188:191], v[94:97]
	v_mfma_f32_16x16x32_bf16 v[90:93], v[242:245], v[188:191], v[90:93]
	v_mfma_f32_16x16x32_bf16 v[86:89], v[234:237], v[196:199], v[86:89]
	v_mfma_f32_16x16x32_bf16 v[70:73], v[242:245], v[196:199], v[70:73]
	v_mfma_f32_16x16x32_bf16 v[62:65], v[234:237], v[218:221], v[62:65]
	v_mfma_f32_16x16x32_bf16 v[58:61], v[242:245], v[218:221], v[58:61]
	v_mfma_f32_16x16x32_bf16 v[54:57], v[234:237], v[226:229], v[54:57]
	v_mfma_f32_16x16x32_bf16 v[50:53], v[242:245], v[226:229], v[50:53]
	s_setprio 0
	v_readfirstlane_b32 s44, v154
	v_lshl_add_u64 v[176:177], v[176:177], 0, s[18:19]
	s_mov_b32 m0, s44
	v_readfirstlane_b32 s44, v155
	s_barrier
	ds_read_b128 v[184:187], v142 offset:49152
	ds_read_b128 v[188:191], v142 offset:50176
	ds_read_b128 v[192:195], v142 offset:51200
	ds_read_b128 v[196:199], v142 offset:52224
	ds_read_b128 v[200:203], v142 offset:53248
	ds_read_b128 v[218:221], v142 offset:54272
	ds_read_b128 v[222:225], v142 offset:55296
	ds_read_b128 v[226:229], v142 offset:56320
	global_load_lds_dwordx4 v[176:177], off
	v_lshl_add_u64 v[176:177], v[204:205], 0, s[18:19]
	s_mov_b32 m0, s44
	s_nop 0
	global_load_lds_dwordx4 v[176:177], off
	s_waitcnt vmcnt(10)
	s_barrier
; #define STAGE(P, BASE, LD, br, kt) do { const bf16* _gb = BASE + ((long)(br) * (LD) + (long)(kt) * BK); \
;     _Pragma("unroll") for (int _i = 0; _i < 2; ++_i) { \
;       __builtin_amdgcn_global_load_lds((const unsigned*)(_gb + ((&LD == &lda) ? offA[_i] : offB[_i])), \
;         (unsigned*)((char*)(P) + tidx_ * 16 + _i * 8192), 16, 0, 0); } } while (0)
; #define LDA(dst, b, h) _Pragma("unroll") for (int m = 0; m < 4; ++m) _Pragma("unroll") for (int k = 0; k < 2; ++k) \
;     dst[m][k] = *reinterpret_cast<const bf16x8*>(smem + (((b) * 2 + (h)) * 16384 + m * 2048 + k * 1024) + aoff)
; #define LDB(dst, b, h) _Pragma("unroll") for (int n = 0; n < 2; ++n) _Pragma("unroll") for (int k = 0; k < 2; ++k) \
;     dst[n][k] = *reinterpret_cast<const bf16x8*>(smem + (((b) * 2 + (h)) * 16384 + n * 2048 + k * 1024) + boff)
; #define MMA(ai, bj, At_, Bt_) do { __builtin_amdgcn_s_setprio(1); \
;     _Pragma("unroll") for (int m = 0; m < 4; ++m) _Pragma("unroll") for (int n = 0; n < 2; ++n) _Pragma("unroll") for (int k = 0; k < 2; ++k) \
;       acc[ai][bj][m][n] = __builtin_amdgcn_mfma_f32_16x16x32_bf16(Bt_[n][k], At_[m][k], acc[ai][bj][m][n], 0, 0, 0); \
;     __builtin_amdgcn_s_setprio(0); } while (0)
; #define WAIT_V(n) asm volatile("s_waitcnt vmcnt(" #n ")" ::: "memory")
; #define WAIT_L(n) asm volatile("s_waitcnt lgkmcnt(" #n ")" ::: "memory")
; #define BAR __builtin_amdgcn_s_barrier()
; #define SCHED __builtin_amdgcn_sched_barrier(0)
; template <class Epi, int NB>
; DEV void gemm_tile_nb(const bf16* __restrict__ A, int lda, long strideA, const bf16* __restrict__ Bt, int ldb, long strideB, int K, int brow, int bcol, Epi& epi) {
;     ...
;     BAR; WAIT_L(0); MMA(0, 1, At, B1); BAR;
;     LDA(At, 1, 1); STAGE(SA(1, 0), A, lda, brow, t + 3);
;     BAR; WAIT_L(0); MMA(1, 0, At, B0); BAR; SCHED;
;     STAGE(SB(1, 1), Bt, ldb, bcol + HALF, t + 3);
;     WAIT_V(6); BAR; MMA(1, 1, At, B1); BAR;
;   }
;   { LDB(B0, 0, 0); LDA(At, 0, 0); STAGE(SA(1, 1), A, lda, brow + HALF, nt - 1);
;     BAR; WAIT_L(0); MMA(0, 0, At, B0); BAR;
;     LDB(B1, 0, 1); BAR; WAIT_L(0); MMA(0, 1, At, B1); BAR;
	s_waitcnt lgkmcnt(0)
	s_setprio 1
	s_waitcnt lgkmcnt(0)
	v_mfma_f32_16x16x32_bf16 v[46:49], v[160:163], v[184:187], v[46:49]
	v_mfma_f32_16x16x32_bf16 v[42:45], v[168:171], v[184:187], v[42:45]
	v_mfma_f32_16x16x32_bf16 v[38:41], v[160:163], v[192:195], v[38:41]
	v_mfma_f32_16x16x32_bf16 v[34:37], v[168:171], v[192:195], v[34:37]
	v_mfma_f32_16x16x32_bf16 v[30:33], v[160:163], v[200:203], v[30:33]
	v_mfma_f32_16x16x32_bf16 v[26:29], v[168:171], v[200:203], v[26:29]
	v_mfma_f32_16x16x32_bf16 v[22:25], v[160:163], v[222:225], v[22:25]
	v_mfma_f32_16x16x32_bf16 v[18:21], v[168:171], v[222:225], v[18:21]
	v_mfma_f32_16x16x32_bf16 v[46:49], v[164:167], v[188:191], v[46:49]
	v_mfma_f32_16x16x32_bf16 v[42:45], v[172:175], v[188:191], v[42:45]
	v_mfma_f32_16x16x32_bf16 v[38:41], v[164:167], v[196:199], v[38:41]
	v_mfma_f32_16x16x32_bf16 v[34:37], v[172:175], v[196:199], v[34:37]
	v_mfma_f32_16x16x32_bf16 v[30:33], v[164:167], v[218:221], v[30:33]
	v_mfma_f32_16x16x32_bf16 v[26:29], v[172:175], v[218:221], v[26:29]
	v_mfma_f32_16x16x32_bf16 v[22:25], v[164:167], v[226:229], v[22:25]
	v_mfma_f32_16x16x32_bf16 v[18:21], v[172:175], v[226:229], v[18:21]
	s_setprio 0
	s_barrier
	v_readfirstlane_b32 s44, v156
	v_lshl_add_u64 v[160:161], v[208:209], 0, s[22:23]
	s_mov_b32 m0, s44
	v_readfirstlane_b32 s44, v157
	global_load_lds_dwordx4 v[160:161], off
	v_lshl_add_u64 v[160:161], v[214:215], 0, s[22:23]
	s_mov_b32 m0, s44
	s_nop 0
	global_load_lds_dwordx4 v[160:161], off
	ds_read_b128 v[160:163], v143
	ds_read_b128 v[164:167], v143 offset:1024
	ds_read_b128 v[168:171], v143 offset:2048
	ds_read_b128 v[172:175], v143 offset:3072
	s_waitcnt vmcnt(6)
	s_barrier
	s_setprio 1
	v_mfma_f32_16x16x32_bf16 v[14:17], v[230:233], v[184:187], v[14:17]
	v_mfma_f32_16x16x32_bf16 v[10:13], v[238:241], v[184:187], v[10:13]
	v_mfma_f32_16x16x32_bf16 v[6:9], v[230:233], v[192:195], v[6:9]
	v_mfma_f32_16x16x32_bf16 v[2:5], v[238:241], v[192:195], v[2:5]
	v_mfma_f32_16x16x32_bf16 v[66:69], v[230:233], v[200:203], v[66:69]
	v_mfma_f32_16x16x32_bf16 v[74:77], v[238:241], v[200:203], v[74:77]
	v_mfma_f32_16x16x32_bf16 v[78:81], v[230:233], v[222:225], v[78:81]
	v_mfma_f32_16x16x32_bf16 v[82:85], v[238:241], v[222:225], v[82:85]
	v_mfma_f32_16x16x32_bf16 v[14:17], v[234:237], v[188:191], v[14:17]
	v_mfma_f32_16x16x32_bf16 v[10:13], v[242:245], v[188:191], v[10:13]
	v_mfma_f32_16x16x32_bf16 v[6:9], v[234:237], v[196:199], v[6:9]
	v_mfma_f32_16x16x32_bf16 v[2:5], v[242:245], v[196:199], v[2:5]
	v_mfma_f32_16x16x32_bf16 v[66:69], v[234:237], v[218:221], v[66:69]
	v_mfma_f32_16x16x32_bf16 v[74:77], v[242:245], v[218:221], v[74:77]
	v_mfma_f32_16x16x32_bf16 v[78:81], v[234:237], v[226:229], v[78:81]
	v_mfma_f32_16x16x32_bf16 v[82:85], v[242:245], v[226:229], v[82:85]
	s_setprio 0
	s_add_i32 s43, s43, 2
	v_lshl_add_u64 v[132:133], v[132:133], 0, s[72:73]
	v_lshl_add_u64 v[134:135], v[134:135], 0, s[72:73]
	v_lshl_add_u64 v[136:137], v[136:137], 0, s[72:73]
	s_cmp_gt_u32 s43, 3
	v_lshl_add_u64 v[138:139], v[138:139], 0, s[72:73]
	s_barrier
	s_cbranch_scc0 .LBB0_862
	v_readlane_b32 s38, v251, 34
	s_cmpk_lt_u32 s42, 0x100
	v_readlane_b32 s39, v251, 35
	v_readfirstlane_b32 s42, v158
	s_mov_b32 m0, s42
	v_lshl_add_u64 v[156:157], v[0:1], 1, s[38:39]
	v_readfirstlane_b32 s42, v159
	ds_read_b128 v[132:135], v143
	ds_read_b128 v[136:139], v143 offset:1024
	ds_read_b128 v[144:147], v143 offset:2048
	ds_read_b128 v[148:151], v143 offset:3072
	ds_read_b128 v[152:155], v142
	ds_read_b128 v[160:163], v142 offset:1024
	ds_read_b128 v[164:167], v142 offset:2048
	ds_read_b128 v[168:171], v142 offset:3072
	ds_read_b128 v[172:175], v142 offset:4096
	ds_read_b128 v[184:187], v142 offset:5120
	ds_read_b128 v[188:191], v142 offset:6144
	ds_read_b128 v[192:195], v142 offset:7168
	global_load_lds_dwordx4 v[156:157], off
	v_lshl_add_u64 v[130:131], v[130:131], 1, s[38:39]
	s_mov_b32 m0, s42
	s_nop 0
	global_load_lds_dwordx4 v[130:131], off
	s_barrier
	s_waitcnt lgkmcnt(0)
	s_setprio 1
	s_waitcnt lgkmcnt(0)
	v_mfma_f32_16x16x32_bf16 v[126:129], v[132:135], v[152:155], v[126:129]
	v_mfma_f32_16x16x32_bf16 v[118:121], v[132:135], v[164:167], v[118:121]
	v_mfma_f32_16x16x32_bf16 v[110:113], v[132:135], v[172:175], v[110:113]
	v_mfma_f32_16x16x32_bf16 v[106:109], v[144:147], v[172:175], v[106:109]
	v_mfma_f32_16x16x32_bf16 v[102:105], v[132:135], v[188:191], v[102:105]
	v_mfma_f32_16x16x32_bf16 v[98:101], v[144:147], v[188:191], v[98:101]
	v_mfma_f32_16x16x32_bf16 v[126:129], v[136:139], v[160:163], v[126:129]
	v_mfma_f32_16x16x32_bf16 v[122:125], v[144:147], v[152:155], v[122:125]
	v_mfma_f32_16x16x32_bf16 v[118:121], v[136:139], v[168:171], v[118:121]
	v_mfma_f32_16x16x32_bf16 v[114:117], v[144:147], v[164:167], v[114:117]
	v_mfma_f32_16x16x32_bf16 v[110:113], v[136:139], v[184:187], v[110:113]
	v_mfma_f32_16x16x32_bf16 v[106:109], v[148:151], v[184:187], v[106:109]
	v_mfma_f32_16x16x32_bf16 v[102:105], v[136:139], v[192:195], v[102:105]
	v_mfma_f32_16x16x32_bf16 v[98:101], v[148:151], v[192:195], v[98:101]
	v_mfma_f32_16x16x32_bf16 v[156:159], v[148:151], v[160:163], v[122:125]
	v_mfma_f32_16x16x32_bf16 v[196:199], v[148:151], v[168:171], v[114:117]
	s_setprio 0
	s_barrier
	s_nop 0
	ds_read_b128 v[114:117], v143 offset:16384
	ds_read_b128 v[122:125], v143 offset:17408
	ds_read_b128 v[200:203], v143 offset:18432
	ds_read_b128 v[218:221], v143 offset:19456
	s_barrier
; #define LDA(dst, b, h) _Pragma("unroll") for (int m = 0; m < 4; ++m) _Pragma("unroll") for (int k = 0; k < 2; ++k) \
;     dst[m][k] = *reinterpret_cast<const bf16x8*>(smem + (((b) * 2 + (h)) * 16384 + m * 2048 + k * 1024) + aoff)
; #define LDB(dst, b, h) _Pragma("unroll") for (int n = 0; n < 2; ++n) _Pragma("unroll") for (int k = 0; k < 2; ++k) \
;     dst[n][k] = *reinterpret_cast<const bf16x8*>(smem + (((b) * 2 + (h)) * 16384 + n * 2048 + k * 1024) + boff)
; #define MMA(ai, bj, At_, Bt_) do { __builtin_amdgcn_s_setprio(1); \
;     _Pragma("unroll") for (int m = 0; m < 4; ++m) _Pragma("unroll") for (int n = 0; n < 2; ++n) _Pragma("unroll") for (int k = 0; k < 2; ++k) \
;       acc[ai][bj][m][n] = __builtin_amdgcn_mfma_f32_16x16x32_bf16(Bt_[n][k], At_[m][k], acc[ai][bj][m][n], 0, 0, 0); \
;     __builtin_amdgcn_s_setprio(0); } while (0)
; #define WAIT_V(n) asm volatile("s_waitcnt vmcnt(" #n ")" ::: "memory")
; #define WAIT_L(n) asm volatile("s_waitcnt lgkmcnt(" #n ")" ::: "memory")
; #define BAR __builtin_amdgcn_s_barrier()
; template <class Epi, int NB>
; DEV void gemm_tile_nb(const bf16* __restrict__ A, int lda, long strideA, const bf16* __restrict__ Bt, int ldb, long strideB, int K, int brow, int bcol, Epi& epi) {
;     ...
;     LDB(B1, 0, 1); BAR; WAIT_L(0); MMA(0, 1, At, B1); BAR;
;     LDA(At, 0, 1); WAIT_V(4); BAR; WAIT_L(0); MMA(1, 0, At, B0); MMA(1, 1, At, B1); BAR; }
;   { LDB(B0, 1, 0); LDA(At, 1, 0); WAIT_V(2); BAR; WAIT_L(0); MMA(0, 0, At, B0); BAR;
	s_waitcnt lgkmcnt(0)
	s_setprio 1
	s_waitcnt lgkmcnt(0)
	v_mfma_f32_16x16x32_bf16 v[94:97], v[114:117], v[152:155], v[94:97]
	v_mfma_f32_16x16x32_bf16 v[90:93], v[200:203], v[152:155], v[90:93]
	v_mfma_f32_16x16x32_bf16 v[86:89], v[114:117], v[164:167], v[86:89]
	v_mfma_f32_16x16x32_bf16 v[54:57], v[114:117], v[188:191], v[54:57]
	v_mfma_f32_16x16x32_bf16 v[50:53], v[200:203], v[188:191], v[50:53]
	v_mfma_f32_16x16x32_bf16 v[94:97], v[122:125], v[160:163], v[94:97]
	v_mfma_f32_16x16x32_bf16 v[90:93], v[218:221], v[160:163], v[90:93]
	v_mfma_f32_16x16x32_bf16 v[86:89], v[122:125], v[168:171], v[86:89]
	v_mfma_f32_16x16x32_bf16 v[70:73], v[200:203], v[164:167], v[70:73]
	v_mfma_f32_16x16x32_bf16 v[62:65], v[114:117], v[172:175], v[62:65]
	v_mfma_f32_16x16x32_bf16 v[58:61], v[200:203], v[172:175], v[58:61]
	v_mfma_f32_16x16x32_bf16 v[54:57], v[122:125], v[192:195], v[54:57]
	v_mfma_f32_16x16x32_bf16 v[50:53], v[218:221], v[192:195], v[50:53]
	v_mfma_f32_16x16x32_bf16 v[152:155], v[218:221], v[168:171], v[70:73]
	v_mfma_f32_16x16x32_bf16 v[160:163], v[122:125], v[184:187], v[62:65]
	v_mfma_f32_16x16x32_bf16 v[164:167], v[218:221], v[184:187], v[58:61]
	s_setprio 0
	s_barrier
	s_nop 0
	ds_read_b128 v[58:61], v142 offset:16384
	ds_read_b128 v[62:65], v142 offset:17408
	ds_read_b128 v[70:73], v142 offset:18432
	ds_read_b128 v[168:171], v142 offset:19456
	ds_read_b128 v[172:175], v142 offset:20480
	ds_read_b128 v[184:187], v142 offset:21504
	ds_read_b128 v[188:191], v142 offset:22528
	ds_read_b128 v[192:195], v142 offset:23552
	s_waitcnt vmcnt(4)
	s_barrier
	s_waitcnt lgkmcnt(0)
	s_setprio 1
	s_waitcnt lgkmcnt(0)
	v_mfma_f32_16x16x32_bf16 v[46:49], v[132:135], v[58:61], v[46:49]
	v_mfma_f32_16x16x32_bf16 v[42:45], v[144:147], v[58:61], v[42:45]
	v_mfma_f32_16x16x32_bf16 v[38:41], v[132:135], v[70:73], v[38:41]
	v_mfma_f32_16x16x32_bf16 v[34:37], v[144:147], v[70:73], v[34:37]
	v_mfma_f32_16x16x32_bf16 v[30:33], v[132:135], v[172:175], v[30:33]
	v_mfma_f32_16x16x32_bf16 v[26:29], v[144:147], v[172:175], v[26:29]
	v_mfma_f32_16x16x32_bf16 v[22:25], v[132:135], v[188:191], v[22:25]
	v_mfma_f32_16x16x32_bf16 v[18:21], v[144:147], v[188:191], v[18:21]
	v_mfma_f32_16x16x32_bf16 v[46:49], v[136:139], v[62:65], v[46:49]
	v_mfma_f32_16x16x32_bf16 v[42:45], v[148:151], v[62:65], v[42:45]
	v_mfma_f32_16x16x32_bf16 v[38:41], v[136:139], v[168:171], v[38:41]
	v_mfma_f32_16x16x32_bf16 v[34:37], v[148:151], v[168:171], v[34:37]
	v_mfma_f32_16x16x32_bf16 v[30:33], v[136:139], v[184:187], v[30:33]
	v_mfma_f32_16x16x32_bf16 v[26:29], v[148:151], v[184:187], v[26:29]
	v_mfma_f32_16x16x32_bf16 v[22:25], v[136:139], v[192:195], v[22:25]
	v_mfma_f32_16x16x32_bf16 v[18:21], v[148:151], v[192:195], v[18:21]
	s_setprio 0
	s_setprio 1
	v_mfma_f32_16x16x32_bf16 v[2:5], v[200:203], v[70:73], v[2:5]
	v_mfma_f32_16x16x32_bf16 v[6:9], v[114:117], v[70:73], v[6:9]
	v_mfma_f32_16x16x32_bf16 v[148:151], v[218:221], v[168:171], v[2:5]
	v_mfma_f32_16x16x32_bf16 v[2:5], v[114:117], v[172:175], v[66:69]
	v_mfma_f32_16x16x32_bf16 v[144:147], v[122:125], v[168:171], v[6:9]
	v_mfma_f32_16x16x32_bf16 v[168:171], v[122:125], v[184:187], v[2:5]
	v_mfma_f32_16x16x32_bf16 v[2:5], v[200:203], v[172:175], v[74:77]
	v_mfma_f32_16x16x32_bf16 v[172:175], v[218:221], v[184:187], v[2:5]
	v_mfma_f32_16x16x32_bf16 v[2:5], v[114:117], v[188:191], v[78:81]
	v_mfma_f32_16x16x32_bf16 v[14:17], v[114:117], v[58:61], v[14:17]
	v_mfma_f32_16x16x32_bf16 v[10:13], v[200:203], v[58:61], v[10:13]
	v_mfma_f32_16x16x32_bf16 v[184:187], v[122:125], v[192:195], v[2:5]
	v_mfma_f32_16x16x32_bf16 v[2:5], v[200:203], v[188:191], v[82:85]
	v_mfma_f32_16x16x32_bf16 v[130:133], v[122:125], v[62:65], v[14:17]
	v_mfma_f32_16x16x32_bf16 v[134:137], v[218:221], v[62:65], v[10:13]
	v_mfma_f32_16x16x32_bf16 v[188:191], v[218:221], v[192:195], v[2:5]
	s_setprio 0
	s_barrier
	s_nop 0
	ds_read_b128 v[10:13], v143 offset:32768
	ds_read_b128 v[14:17], v143 offset:33792
	ds_read_b128 v[192:195], v143 offset:34816
	ds_read_b128 v[200:203], v143 offset:35840
	ds_read_b128 v[66:69], v142 offset:32768
	ds_read_b128 v[70:73], v142 offset:33792
	ds_read_b128 v[78:81], v142 offset:34816
	ds_read_b128 v[82:85], v142 offset:35840
	ds_read_b128 v[218:221], v142 offset:36864
	ds_read_b128 v[222:225], v142 offset:37888
	ds_read_b128 v[226:229], v142 offset:38912
	ds_read_b128 v[230:233], v142 offset:39936
	s_waitcnt vmcnt(2)
	s_barrier
; #define LDA(dst, b, h) _Pragma("unroll") for (int m = 0; m < 4; ++m) _Pragma("unroll") for (int k = 0; k < 2; ++k) \
;     dst[m][k] = *reinterpret_cast<const bf16x8*>(smem + (((b) * 2 + (h)) * 16384 + m * 2048 + k * 1024) + aoff)
; #define LDB(dst, b, h) _Pragma("unroll") for (int n = 0; n < 2; ++n) _Pragma("unroll") for (int k = 0; k < 2; ++k) \
;     dst[n][k] = *reinterpret_cast<const bf16x8*>(smem + (((b) * 2 + (h)) * 16384 + n * 2048 + k * 1024) + boff)
; #define MMA(ai, bj, At_, Bt_) do { __builtin_amdgcn_s_setprio(1); \
;     _Pragma("unroll") for (int m = 0; m < 4; ++m) _Pragma("unroll") for (int n = 0; n < 2; ++n) _Pragma("unroll") for (int k = 0; k < 2; ++k) \
;       acc[ai][bj][m][n] = __builtin_amdgcn_mfma_f32_16x16x32_bf16(Bt_[n][k], At_[m][k], acc[ai][bj][m][n], 0, 0, 0); \
;     __builtin_amdgcn_s_setprio(0); } while (0)
; #define WAIT_V(n) asm volatile("s_waitcnt vmcnt(" #n ")" ::: "memory")
; #define WAIT_L(n) asm volatile("s_waitcnt lgkmcnt(" #n ")" ::: "memory")
; #define BAR __builtin_amdgcn_s_barrier()
; template <class Epi, int NB>
; DEV void gemm_tile_nb(const bf16* __restrict__ A, int lda, long strideA, const bf16* __restrict__ Bt, int ldb, long strideB, int K, int brow, int bcol, Epi& epi) {
;     ...
;   { LDB(B0, 1, 0); LDA(At, 1, 0); WAIT_V(2); BAR; WAIT_L(0); MMA(0, 0, At, B0); BAR;
;     LDB(B1, 1, 1); WAIT_V(0); BAR; WAIT_L(0); MMA(0, 1, At, B1); BAR;
;     LDA(At, 1, 1); BAR; WAIT_L(0); MMA(1, 0, At, B0); MMA(1, 1, At, B1); BAR; }
;   if (wr == 0) BAR;
	s_waitcnt lgkmcnt(0)
	s_setprio 1
	s_waitcnt lgkmcnt(0)
	v_mfma_f32_16x16x32_bf16 v[2:5], v[10:13], v[66:69], v[126:129]
	v_mfma_f32_16x16x32_bf16 v[122:125], v[14:17], v[70:73], v[2:5]
	v_mfma_f32_16x16x32_bf16 v[2:5], v[192:195], v[66:69], v[156:159]
	v_mfma_f32_16x16x32_bf16 v[126:129], v[200:203], v[70:73], v[2:5]
	v_mfma_f32_16x16x32_bf16 v[2:5], v[10:13], v[78:81], v[118:121]
	v_mfma_f32_16x16x32_bf16 v[114:117], v[14:17], v[82:85], v[2:5]
	v_mfma_f32_16x16x32_bf16 v[2:5], v[192:195], v[78:81], v[196:199]
	v_mfma_f32_16x16x32_bf16 v[118:121], v[200:203], v[82:85], v[2:5]
	v_mfma_f32_16x16x32_bf16 v[2:5], v[10:13], v[218:221], v[110:113]
	v_mfma_f32_16x16x32_bf16 v[62:65], v[14:17], v[222:225], v[2:5]
	v_mfma_f32_16x16x32_bf16 v[2:5], v[192:195], v[218:221], v[106:109]
	v_mfma_f32_16x16x32_bf16 v[74:77], v[200:203], v[222:225], v[2:5]
	v_mfma_f32_16x16x32_bf16 v[2:5], v[10:13], v[226:229], v[102:105]
	v_mfma_f32_16x16x32_bf16 v[6:9], v[192:195], v[226:229], v[98:101]
	v_mfma_f32_16x16x32_bf16 v[2:5], v[14:17], v[230:233], v[2:5]
	v_mfma_f32_16x16x32_bf16 v[6:9], v[200:203], v[230:233], v[6:9]
	s_setprio 0
	s_barrier
	ds_read_b128 v[156:159], v143 offset:49152
	ds_read_b128 v[196:199], v143 offset:50176
	ds_read_b128 v[234:237], v143 offset:51200
	ds_read_b128 v[238:241], v143 offset:52224
	s_waitcnt vmcnt(0)
	s_barrier
	s_waitcnt lgkmcnt(0)
	s_setprio 1
	s_waitcnt lgkmcnt(0)
	v_mfma_f32_16x16x32_bf16 v[58:61], v[156:159], v[66:69], v[94:97]
	v_mfma_f32_16x16x32_bf16 v[66:69], v[234:237], v[66:69], v[90:93]
	v_mfma_f32_16x16x32_bf16 v[58:61], v[196:199], v[70:73], v[58:61]
	v_mfma_f32_16x16x32_bf16 v[66:69], v[238:241], v[70:73], v[66:69]
	v_mfma_f32_16x16x32_bf16 v[70:73], v[156:159], v[78:81], v[86:89]
	v_mfma_f32_16x16x32_bf16 v[78:81], v[234:237], v[78:81], v[152:155]
	v_mfma_f32_16x16x32_bf16 v[70:73], v[196:199], v[82:85], v[70:73]
	v_mfma_f32_16x16x32_bf16 v[78:81], v[238:241], v[82:85], v[78:81]
	v_mfma_f32_16x16x32_bf16 v[82:85], v[156:159], v[218:221], v[160:163]
	v_mfma_f32_16x16x32_bf16 v[86:89], v[234:237], v[218:221], v[164:167]
	v_mfma_f32_16x16x32_bf16 v[54:57], v[156:159], v[226:229], v[54:57]
	v_mfma_f32_16x16x32_bf16 v[50:53], v[234:237], v[226:229], v[50:53]
	v_mfma_f32_16x16x32_bf16 v[82:85], v[196:199], v[222:225], v[82:85]
	v_mfma_f32_16x16x32_bf16 v[86:89], v[238:241], v[222:225], v[86:89]
	v_mfma_f32_16x16x32_bf16 v[90:93], v[196:199], v[230:233], v[54:57]
	v_mfma_f32_16x16x32_bf16 v[98:101], v[238:241], v[230:233], v[50:53]
	s_setprio 0
	s_barrier
	s_nop 1
	ds_read_b128 v[50:53], v142 offset:49152
	ds_read_b128 v[152:155], v142 offset:50176
	ds_read_b128 v[160:163], v142 offset:51200
	ds_read_b128 v[164:167], v142 offset:52224
	ds_read_b128 v[218:221], v142 offset:53248
	ds_read_b128 v[222:225], v142 offset:54272
	ds_read_b128 v[226:229], v142 offset:55296
	ds_read_b128 v[230:233], v142 offset:56320
	s_barrier
	s_waitcnt lgkmcnt(0)
	s_setprio 1
	s_waitcnt lgkmcnt(0)
	v_mfma_f32_16x16x32_bf16 v[46:49], v[10:13], v[50:53], v[46:49]
	v_mfma_f32_16x16x32_bf16 v[38:41], v[10:13], v[160:163], v[38:41]
	v_mfma_f32_16x16x32_bf16 v[30:33], v[10:13], v[218:221], v[30:33]
	v_mfma_f32_16x16x32_bf16 v[10:13], v[10:13], v[226:229], v[22:25]
	v_mfma_f32_16x16x32_bf16 v[106:109], v[14:17], v[152:155], v[46:49]
	v_mfma_f32_16x16x32_bf16 v[42:45], v[192:195], v[50:53], v[42:45]
	v_mfma_f32_16x16x32_bf16 v[94:97], v[14:17], v[164:167], v[38:41]
	v_mfma_f32_16x16x32_bf16 v[34:37], v[192:195], v[160:163], v[34:37]
	v_mfma_f32_16x16x32_bf16 v[46:49], v[14:17], v[222:225], v[30:33]
	v_mfma_f32_16x16x32_bf16 v[26:29], v[192:195], v[218:221], v[26:29]
	v_mfma_f32_16x16x32_bf16 v[10:13], v[14:17], v[230:233], v[10:13]
	v_mfma_f32_16x16x32_bf16 v[14:17], v[192:195], v[226:229], v[18:21]
	v_mfma_f32_16x16x32_bf16 v[110:113], v[200:203], v[152:155], v[42:45]
	v_mfma_f32_16x16x32_bf16 v[102:105], v[200:203], v[164:167], v[34:37]
	v_mfma_f32_16x16x32_bf16 v[54:57], v[200:203], v[222:225], v[26:29]
	v_mfma_f32_16x16x32_bf16 v[14:17], v[200:203], v[230:233], v[14:17]
	s_setprio 0
	s_setprio 1
	v_mfma_f32_16x16x32_bf16 v[18:21], v[156:159], v[50:53], v[130:133]
	v_mfma_f32_16x16x32_bf16 v[22:25], v[234:237], v[50:53], v[134:137]
	v_mfma_f32_16x16x32_bf16 v[26:29], v[156:159], v[160:163], v[144:147]
	v_mfma_f32_16x16x32_bf16 v[30:33], v[234:237], v[160:163], v[148:151]
	v_mfma_f32_16x16x32_bf16 v[34:37], v[156:159], v[218:221], v[168:171]
	v_mfma_f32_16x16x32_bf16 v[38:41], v[234:237], v[218:221], v[172:175]
	v_mfma_f32_16x16x32_bf16 v[42:45], v[156:159], v[226:229], v[184:187]
	v_mfma_f32_16x16x32_bf16 v[50:53], v[234:237], v[226:229], v[188:191]
	v_mfma_f32_16x16x32_bf16 v[18:21], v[196:199], v[152:155], v[18:21]
	v_mfma_f32_16x16x32_bf16 v[22:25], v[238:241], v[152:155], v[22:25]
	v_mfma_f32_16x16x32_bf16 v[26:29], v[196:199], v[164:167], v[26:29]
	v_mfma_f32_16x16x32_bf16 v[30:33], v[238:241], v[164:167], v[30:33]
	v_mfma_f32_16x16x32_bf16 v[34:37], v[196:199], v[222:225], v[34:37]
	v_mfma_f32_16x16x32_bf16 v[38:41], v[238:241], v[222:225], v[38:41]
	v_mfma_f32_16x16x32_bf16 v[42:45], v[196:199], v[230:233], v[42:45]
	v_mfma_f32_16x16x32_bf16 v[50:53], v[238:241], v[230:233], v[50:53]
	s_setprio 0
	s_barrier
	s_cbranch_scc0 .LBB0_865
	s_barrier

; #define STAGE(P, BASE, LD, br, kt) do { const bf16* _gb = BASE + ((long)(br) * (LD) + (long)(kt) * BK); \
;     _Pragma("unroll") for (int _i = 0; _i < 2; ++_i) { \
;       __builtin_amdgcn_global_load_lds((const unsigned*)(_gb + ((&LD == &lda) ? offA[_i] : offB[_i])), \
;         (unsigned*)((char*)(P) + tidx_ * 16 + _i * 8192), 16, 0, 0); } } while (0)
; #define LDA(dst, b, h) _Pragma("unroll") for (int m = 0; m < 4; ++m) _Pragma("unroll") for (int k = 0; k < 2; ++k) \
;     dst[m][k] = *reinterpret_cast<const bf16x8*>(smem + (((b) * 2 + (h)) * 16384 + m * 2048 + k * 1024) + aoff)
; #define LDB(dst, b, h) _Pragma("unroll") for (int n = 0; n < 2; ++n) _Pragma("unroll") for (int k = 0; k < 2; ++k) \
;     dst[n][k] = *reinterpret_cast<const bf16x8*>(smem + (((b) * 2 + (h)) * 16384 + n * 2048 + k * 1024) + boff)
; #define WAIT_V(n) asm volatile("s_waitcnt vmcnt(" #n ")" ::: "memory")
; #define BAR __builtin_amdgcn_s_barrier()
; #define SCHED __builtin_amdgcn_sched_barrier(0)
; template <class Epi, int NB>
; DEV void gemm_tile_nb(const bf16* __restrict__ A, int lda, long strideA, const bf16* __restrict__ Bt, int ldb, long strideB, int K, int brow, int bcol, Epi& epi) {
;     ...
;   const int wid = __builtin_amdgcn_readfirstlane(tidx_ >> 6), lane = tidx_ & 63, wr = wid >> 2, wc = wid & 3, fr = lane & 15, fq = lane >> 4;
;   f32x4 acc[2][2][4][2] = {};
;   bf16x8 At[4][2], B0[2][2], B1[2][2];
;   const int nt = K / BK;
;   const int lane_off_ = (fr * 64 + fq * 16) ^ ((fr >> 3) << 5);
;   const int aoff = wr * 8192 + lane_off_, boff = 65536 + wc * 4096 + lane_off_;
;   unsigned offA[2], offB[2];
; #pragma unroll
;   for (int _i = 0; _i < 2; ++_i) { int _r, _c; stage_rc(tidx_ * 16 + _i * 8192, _r, _c); offA[_i] = (unsigned)(_r * lda + _c); offB[_i] = (unsigned)(_r * ldb + _c); }
; #pragma unroll 1
;   for (int br = 0; br < NB; ++br) {
;   STAGE(SB(0, 0), Bt, ldb, bcol, 0); STAGE(SA(0, 0), A, lda, brow, 0);
;   STAGE(SB(0, 1), Bt, ldb, bcol + HALF, 0); STAGE(SA(0, 1), A, lda, brow + HALF, 0);
;   if (wr == 1) BAR;
;   WAIT_V(4); BAR;
;   STAGE(SB(1, 0), Bt, ldb, bcol, 1); STAGE(SA(1, 0), A, lda, brow, 1); STAGE(SB(1, 1), Bt, ldb, bcol + HALF, 1);
;   WAIT_V(6); BAR;
;   for (int t = 0; t < nt - 2; t += 2) {
;     LDB(B0, 0, 0); SCHED; LDA(At, 0, 0); STAGE(SA(1, 1), A, lda, brow + HALF, t + 1);
.LBB0_946:
	v_and_b32_e32 v141, 15, v19
	s_bfe_u32 s54, s55, 0x20006
	v_bfe_u32 v140, v19, 4, 2
	v_lshlrev_b32_e32 v20, 6, v141
	v_lshlrev_b32_e32 v19, 2, v19
	v_lshl_or_b32 v20, v140, 4, v20
	v_and_b32_e32 v19, 32, v19
	s_lshl_b32 s56, s53, 13
	s_lshl_b32 s57, s54, 12
	v_add_u32_e32 v152, s13, v11
	v_bitop3_b32 v21, v20, s57, v19 bitop3:0xde
	v_bitop3_b32 v19, v20, s56, v19 bitop3:0xde
	s_mov_b64 s[58:59], 0x80
	v_readfirstlane_b32 s56, v152
	v_add_u32_e32 v153, 0x2000, v152
	v_lshl_add_u64 v[2:3], v[2:3], 0, s[58:59]
	s_mov_b32 m0, s56
	v_readfirstlane_b32 s56, v153
	v_add_u32_e32 v154, 0x8000, v145
	s_waitcnt vmcnt(4)
	s_barrier
	global_load_lds_dwordx4 v[2:3], off
	v_lshl_add_u64 v[2:3], v[6:7], 0, s[58:59]
	s_mov_b32 m0, s56
	v_readfirstlane_b32 s56, v154
	v_add_u32_e32 v155, 0xa000, v145
	s_add_u32 s42, s42, 0xb0080
	global_load_lds_dwordx4 v[2:3], off
	v_lshl_add_u64 v[2:3], v[8:9], 0, s[58:59]
	s_mov_b32 m0, s56
	v_readfirstlane_b32 s56, v155
	v_add_u32_e32 v156, s14, v11
	s_addc_u32 s43, s43, 0
	global_load_lds_dwordx4 v[2:3], off
	v_lshl_add_u64 v[2:3], v[4:5], 0, s[58:59]
	s_mov_b32 m0, s56
	v_readfirstlane_b32 s56, v156
	global_load_lds_dwordx4 v[2:3], off
	v_lshl_add_u64 v[2:3], v[0:1], 1, s[42:43]
	s_mov_b32 m0, s56
	v_add_u32_e32 v157, 0x2000, v156
	global_load_lds_dwordx4 v[2:3], off
	v_lshl_add_u64 v[2:3], v[130:131], 1, s[42:43]
	v_readfirstlane_b32 s42, v157
	s_mov_b32 m0, s42
	s_mov_b32 s56, 0xb000
	global_load_lds_dwordx4 v[2:3], off
	v_lshrrev_b32_e32 v3, 1, v10
	v_mul_lo_u32 v2, v13, s10
	v_mad_u64_u32 v[2:3], s[42:43], v3, s56, v[2:3]
	v_lshrrev_b32_e32 v5, 1, v15
	v_mul_lo_u32 v4, v17, s10
	v_or_b32_e32 v2, v2, v12
	v_mad_u64_u32 v[4:5], s[42:43], v5, s56, v[4:5]
	s_add_u32 s40, s49, s40
	v_add_u32_sdwa v2, v2, sext(v14) dst_sel:DWORD dst_unused:UNUSED_PAD src0_sel:DWORD src1_sel:WORD_0
	v_mov_b32_e32 v3, v1
	v_or_b32_e32 v4, v4, v16
	s_waitcnt vmcnt(6)
	s_addc_u32 s41, s50, s41
	v_lshlrev_b64 v[2:3], 1, v[2:3]
	v_add_u32_sdwa v4, v4, sext(v18) dst_sel:DWORD dst_unused:UNUSED_PAD src0_sel:DWORD src1_sel:WORD_0
	v_mov_b32_e32 v5, v1
	v_or_b32_e32 v21, 0x10000, v21
	v_lshl_add_u64 v[132:133], s[40:41], 0, v[2:3]
	v_lshlrev_b64 v[4:5], 1, v[4:5]
	v_lshl_add_u64 v[136:137], s[38:39], 0, v[2:3]
	v_mov_b32_e32 v2, 0
	v_lshl_add_u64 v[134:135], s[40:41], 0, v[4:5]
	v_lshl_add_u64 v[138:139], s[38:39], 0, v[4:5]
	s_mov_b32 s38, -2
	v_add_u32_e32 v143, 0, v21
	v_add_u32_e32 v142, 0, v19
	v_mov_b32_e32 v3, v2
	v_mov_b32_e32 v4, v2
	v_mov_b32_e32 v5, v2
	v_mov_b32_e32 v6, v2
	v_mov_b32_e32 v7, v2
	v_mov_b32_e32 v8, v2
	v_mov_b32_e32 v9, v2
	v_mov_b32_e32 v10, v2
	v_mov_b32_e32 v11, v2
	v_mov_b32_e32 v12, v2
	v_mov_b32_e32 v13, v2
	v_mov_b32_e32 v14, v2
	v_mov_b32_e32 v15, v2
	v_mov_b32_e32 v16, v2
	v_mov_b32_e32 v17, v2
	v_mov_b32_e32 v18, v2
	v_mov_b32_e32 v19, v2
	v_mov_b32_e32 v20, v2
	v_mov_b32_e32 v21, v2
	v_mov_b32_e32 v22, v2
	v_mov_b32_e32 v23, v2
	v_mov_b32_e32 v24, v2
	v_mov_b32_e32 v25, v2
	v_mov_b32_e32 v26, v2
	v_mov_b32_e32 v27, v2
	v_mov_b32_e32 v28, v2
	v_mov_b32_e32 v29, v2
	v_mov_b32_e32 v30, v2
	v_mov_b32_e32 v31, v2
	v_mov_b32_e32 v32, v2
	v_mov_b32_e32 v33, v2
	v_mov_b32_e32 v34, v2
	v_mov_b32_e32 v35, v2
	v_mov_b32_e32 v36, v2
	v_mov_b32_e32 v37, v2
	v_mov_b32_e32 v38, v2
	v_mov_b32_e32 v39, v2
	v_mov_b32_e32 v40, v2
	v_mov_b32_e32 v41, v2
	v_mov_b32_e32 v42, v2
	v_mov_b32_e32 v43, v2
	v_mov_b32_e32 v44, v2
	v_mov_b32_e32 v45, v2
	v_mov_b32_e32 v46, v2
	v_mov_b32_e32 v47, v2
	v_mov_b32_e32 v48, v2
	v_mov_b32_e32 v49, v2
	v_mov_b32_e32 v50, v2
	v_mov_b32_e32 v51, v2
	v_mov_b32_e32 v52, v2
	v_mov_b32_e32 v53, v2
	v_mov_b32_e32 v54, v2
	v_mov_b32_e32 v55, v2
	v_mov_b32_e32 v56, v2
	v_mov_b32_e32 v57, v2
	v_mov_b32_e32 v58, v2
	v_mov_b32_e32 v59, v2
	v_mov_b32_e32 v60, v2
	v_mov_b32_e32 v61, v2
	v_mov_b32_e32 v62, v2
	v_mov_b32_e32 v63, v2
	v_mov_b32_e32 v64, v2
	v_mov_b32_e32 v65, v2
	v_mov_b32_e32 v70, v2
	v_mov_b32_e32 v71, v2
	v_mov_b32_e32 v72, v2
	v_mov_b32_e32 v73, v2
	v_mov_b32_e32 v86, v2
	v_mov_b32_e32 v87, v2
	v_mov_b32_e32 v88, v2
	v_mov_b32_e32 v89, v2
	v_mov_b32_e32 v90, v2
	v_mov_b32_e32 v91, v2
	v_mov_b32_e32 v92, v2
	v_mov_b32_e32 v93, v2
	v_mov_b32_e32 v94, v2
	v_mov_b32_e32 v95, v2
	v_mov_b32_e32 v96, v2
	v_mov_b32_e32 v97, v2
	v_mov_b32_e32 v98, v2
	v_mov_b32_e32 v99, v2
	v_mov_b32_e32 v100, v2
	v_mov_b32_e32 v101, v2
	v_mov_b32_e32 v102, v2
	v_mov_b32_e32 v103, v2
	v_mov_b32_e32 v104, v2
	v_mov_b32_e32 v105, v2
	v_mov_b32_e32 v106, v2
	v_mov_b32_e32 v107, v2
	v_mov_b32_e32 v108, v2
	v_mov_b32_e32 v109, v2
	v_mov_b32_e32 v110, v2
	v_mov_b32_e32 v111, v2
	v_mov_b32_e32 v112, v2
	v_mov_b32_e32 v113, v2
	v_mov_b32_e32 v114, v2
	v_mov_b32_e32 v115, v2
	v_mov_b32_e32 v116, v2
	v_mov_b32_e32 v117, v2
	v_mov_b32_e32 v118, v2
	v_mov_b32_e32 v119, v2
	v_mov_b32_e32 v120, v2
	v_mov_b32_e32 v121, v2
	v_mov_b32_e32 v122, v2
	v_mov_b32_e32 v123, v2
	v_mov_b32_e32 v124, v2
	v_mov_b32_e32 v125, v2
	v_mov_b32_e32 v126, v2
	v_mov_b32_e32 v127, v2
	v_mov_b32_e32 v128, v2
	v_mov_b32_e32 v129, v2
	v_mov_b32_e32 v66, v2
	v_mov_b32_e32 v67, v2
	v_mov_b32_e32 v68, v2
	v_mov_b32_e32 v69, v2
	v_mov_b32_e32 v74, v2
	v_mov_b32_e32 v75, v2
	v_mov_b32_e32 v76, v2
	v_mov_b32_e32 v77, v2
	v_mov_b32_e32 v78, v2
	v_mov_b32_e32 v79, v2
	v_mov_b32_e32 v80, v2
	v_mov_b32_e32 v81, v2
	v_mov_b32_e32 v82, v2
	v_mov_b32_e32 v83, v2
	v_mov_b32_e32 v84, v2
	v_mov_b32_e32 v85, v2
	s_barrier
	ds_read_b128 v[160:163], v143
	ds_read_b128 v[164:167], v143 offset:1024
	ds_read_b128 v[168:171], v143 offset:2048
	ds_read_b128 v[172:175], v143 offset:3072
; #define STAGE(P, BASE, LD, br, kt) do { const bf16* _gb = BASE + ((long)(br) * (LD) + (long)(kt) * BK); \
;     _Pragma("unroll") for (int _i = 0; _i < 2; ++_i) { \
;       __builtin_amdgcn_global_load_lds((const unsigned*)(_gb + ((&LD == &lda) ? offA[_i] : offB[_i])), \
;         (unsigned*)((char*)(P) + tidx_ * 16 + _i * 8192), 16, 0, 0); } } while (0)
; #define LDA(dst, b, h) _Pragma("unroll") for (int m = 0; m < 4; ++m) _Pragma("unroll") for (int k = 0; k < 2; ++k) \
;     dst[m][k] = *reinterpret_cast<const bf16x8*>(smem + (((b) * 2 + (h)) * 16384 + m * 2048 + k * 1024) + aoff)
; #define LDB(dst, b, h) _Pragma("unroll") for (int n = 0; n < 2; ++n) _Pragma("unroll") for (int k = 0; k < 2; ++k) \
;     dst[n][k] = *reinterpret_cast<const bf16x8*>(smem + (((b) * 2 + (h)) * 16384 + n * 2048 + k * 1024) + boff)
; #define MMA(ai, bj, At_, Bt_) do { __builtin_amdgcn_s_setprio(1); \
;     _Pragma("unroll") for (int m = 0; m < 4; ++m) _Pragma("unroll") for (int n = 0; n < 2; ++n) _Pragma("unroll") for (int k = 0; k < 2; ++k) \
;       acc[ai][bj][m][n] = __builtin_amdgcn_mfma_f32_16x16x32_bf16(Bt_[n][k], At_[m][k], acc[ai][bj][m][n], 0, 0, 0); \
;     __builtin_amdgcn_s_setprio(0); } while (0)
; #define WAIT_L(n) asm volatile("s_waitcnt lgkmcnt(" #n ")" ::: "memory")
; #define BAR __builtin_amdgcn_s_barrier()
; #define SCHED __builtin_amdgcn_sched_barrier(0)
; template <class Epi, int NB>
; DEV void gemm_tile_nb(const bf16* __restrict__ A, int lda, long strideA, const bf16* __restrict__ Bt, int ldb, long strideB, int K, int brow, int bcol, Epi& epi) {
;     ...
;     LDB(B0, 0, 0); SCHED; LDA(At, 0, 0); STAGE(SA(1, 1), A, lda, brow + HALF, t + 1);
;     WAIT_L(8); BAR; WAIT_L(0); MMA(0, 0, At, B0); BAR; SCHED;
;     LDB(B1, 0, 1); STAGE(SB(0, 0), Bt, ldb, bcol, t + 2);
;     BAR; WAIT_L(0); MMA(0, 1, At, B1); BAR;
;     LDA(At, 0, 1); STAGE(SA(0, 0), A, lda, brow, t + 2);
;     BAR; WAIT_L(0); MMA(1, 0, At, B0); BAR; SCHED;
.LBB0_947:
	v_add_u32_e32 v158, 0xc000, v145
	v_lshl_add_u64 v[176:177], s[88:89], 0, v[136:137]
	v_readfirstlane_b32 s39, v158
	v_lshl_add_u64 v[204:205], v[176:177], 0, s[4:5]
	s_mov_b32 m0, s39
	v_add_u32_e32 v159, 0xe000, v145
	ds_read_b128 v[184:187], v142
	ds_read_b128 v[188:191], v142 offset:1024
	ds_read_b128 v[192:195], v142 offset:2048
	ds_read_b128 v[196:199], v142 offset:3072
	ds_read_b128 v[200:203], v142 offset:4096
	ds_read_b128 v[218:221], v142 offset:5120
	ds_read_b128 v[222:225], v142 offset:6144
	ds_read_b128 v[226:229], v142 offset:7168
	global_load_lds_dwordx4 v[204:205], off
	v_lshl_add_u64 v[204:205], s[88:89], 0, v[138:139]
	v_readfirstlane_b32 s39, v159
	v_lshl_add_u64 v[208:209], v[204:205], 0, s[4:5]
	s_mov_b32 m0, s39
	s_nop 0
	global_load_lds_dwordx4 v[208:209], off
	s_waitcnt lgkmcnt(8)
	s_barrier
	s_waitcnt lgkmcnt(0)
	s_setprio 1
	s_waitcnt lgkmcnt(0)
	v_mfma_f32_16x16x32_bf16 v[126:129], v[160:163], v[184:187], v[126:129]
	v_mfma_f32_16x16x32_bf16 v[122:125], v[168:171], v[184:187], v[122:125]
	v_mfma_f32_16x16x32_bf16 v[118:121], v[160:163], v[192:195], v[118:121]
	v_mfma_f32_16x16x32_bf16 v[114:117], v[168:171], v[192:195], v[114:117]
	v_mfma_f32_16x16x32_bf16 v[110:113], v[160:163], v[200:203], v[110:113]
	v_mfma_f32_16x16x32_bf16 v[106:109], v[168:171], v[200:203], v[106:109]
	v_mfma_f32_16x16x32_bf16 v[102:105], v[160:163], v[222:225], v[102:105]
	v_mfma_f32_16x16x32_bf16 v[98:101], v[168:171], v[222:225], v[98:101]
	v_mfma_f32_16x16x32_bf16 v[126:129], v[164:167], v[188:191], v[126:129]
	v_mfma_f32_16x16x32_bf16 v[122:125], v[172:175], v[188:191], v[122:125]
	v_mfma_f32_16x16x32_bf16 v[118:121], v[164:167], v[196:199], v[118:121]
	v_mfma_f32_16x16x32_bf16 v[114:117], v[172:175], v[196:199], v[114:117]
	v_mfma_f32_16x16x32_bf16 v[110:113], v[164:167], v[218:221], v[110:113]
	v_mfma_f32_16x16x32_bf16 v[106:109], v[172:175], v[218:221], v[106:109]
	v_mfma_f32_16x16x32_bf16 v[102:105], v[164:167], v[226:229], v[102:105]
	v_mfma_f32_16x16x32_bf16 v[98:101], v[172:175], v[226:229], v[98:101]
	s_setprio 0
	s_barrier
	v_lshl_add_u64 v[208:209], s[88:89], 0, v[132:133]
	v_readfirstlane_b32 s39, v144
	v_lshl_add_u64 v[214:215], v[208:209], 0, s[24:25]
	s_mov_b32 m0, s39
	ds_read_b128 v[230:233], v143 offset:16384
	ds_read_b128 v[234:237], v143 offset:17408
	ds_read_b128 v[238:241], v143 offset:18432
	ds_read_b128 v[242:245], v143 offset:19456
	global_load_lds_dwordx4 v[214:215], off
	v_lshl_add_u64 v[214:215], s[88:89], 0, v[134:135]
	v_readfirstlane_b32 s39, v147
	v_lshl_add_u64 v[246:247], v[214:215], 0, s[24:25]
	s_mov_b32 m0, s39
	s_nop 0
	global_load_lds_dwordx4 v[246:247], off
	s_barrier
	s_waitcnt lgkmcnt(0)
	s_setprio 1
	s_waitcnt lgkmcnt(0)
	v_mfma_f32_16x16x32_bf16 v[94:97], v[230:233], v[184:187], v[94:97]
	v_mfma_f32_16x16x32_bf16 v[90:93], v[238:241], v[184:187], v[90:93]
	v_mfma_f32_16x16x32_bf16 v[86:89], v[230:233], v[192:195], v[86:89]
	v_mfma_f32_16x16x32_bf16 v[70:73], v[238:241], v[192:195], v[70:73]
	v_mfma_f32_16x16x32_bf16 v[62:65], v[230:233], v[200:203], v[62:65]
	v_mfma_f32_16x16x32_bf16 v[58:61], v[238:241], v[200:203], v[58:61]
	v_mfma_f32_16x16x32_bf16 v[54:57], v[230:233], v[222:225], v[54:57]
	v_mfma_f32_16x16x32_bf16 v[50:53], v[238:241], v[222:225], v[50:53]
	v_mfma_f32_16x16x32_bf16 v[94:97], v[234:237], v[188:191], v[94:97]
	v_mfma_f32_16x16x32_bf16 v[90:93], v[242:245], v[188:191], v[90:93]
	v_mfma_f32_16x16x32_bf16 v[86:89], v[234:237], v[196:199], v[86:89]
	v_mfma_f32_16x16x32_bf16 v[70:73], v[242:245], v[196:199], v[70:73]
	v_mfma_f32_16x16x32_bf16 v[62:65], v[234:237], v[218:221], v[62:65]
	v_mfma_f32_16x16x32_bf16 v[58:61], v[242:245], v[218:221], v[58:61]
	v_mfma_f32_16x16x32_bf16 v[54:57], v[234:237], v[226:229], v[54:57]
	v_mfma_f32_16x16x32_bf16 v[50:53], v[242:245], v[226:229], v[50:53]
	s_setprio 0
	v_readfirstlane_b32 s39, v145
	v_lshl_add_u64 v[246:247], v[176:177], 0, s[26:27]
	s_mov_b32 m0, s39
	v_readfirstlane_b32 s39, v149
	s_barrier
	ds_read_b128 v[184:187], v142 offset:16384
	ds_read_b128 v[188:191], v142 offset:17408
	ds_read_b128 v[192:195], v142 offset:18432
	ds_read_b128 v[196:199], v142 offset:19456
	ds_read_b128 v[200:203], v142 offset:20480
	ds_read_b128 v[218:221], v142 offset:21504
	ds_read_b128 v[222:225], v142 offset:22528
	ds_read_b128 v[226:229], v142 offset:23552
	global_load_lds_dwordx4 v[246:247], off
	v_lshl_add_u64 v[246:247], v[204:205], 0, s[26:27]
	s_mov_b32 m0, s39
	s_nop 0
	global_load_lds_dwordx4 v[246:247], off
	s_waitcnt vmcnt(10)
	s_barrier
	s_waitcnt lgkmcnt(0)
	s_setprio 1
	s_waitcnt lgkmcnt(0)
	v_mfma_f32_16x16x32_bf16 v[46:49], v[160:163], v[184:187], v[46:49]
	v_mfma_f32_16x16x32_bf16 v[42:45], v[168:171], v[184:187], v[42:45]
	v_mfma_f32_16x16x32_bf16 v[38:41], v[160:163], v[192:195], v[38:41]
	v_mfma_f32_16x16x32_bf16 v[34:37], v[168:171], v[192:195], v[34:37]
	v_mfma_f32_16x16x32_bf16 v[30:33], v[160:163], v[200:203], v[30:33]
	v_mfma_f32_16x16x32_bf16 v[26:29], v[168:171], v[200:203], v[26:29]
	v_mfma_f32_16x16x32_bf16 v[22:25], v[160:163], v[222:225], v[22:25]
	v_mfma_f32_16x16x32_bf16 v[18:21], v[168:171], v[222:225], v[18:21]
	v_mfma_f32_16x16x32_bf16 v[46:49], v[164:167], v[188:191], v[46:49]
	v_mfma_f32_16x16x32_bf16 v[42:45], v[172:175], v[188:191], v[42:45]
	v_mfma_f32_16x16x32_bf16 v[38:41], v[164:167], v[196:199], v[38:41]
	v_mfma_f32_16x16x32_bf16 v[34:37], v[172:175], v[196:199], v[34:37]
	v_mfma_f32_16x16x32_bf16 v[30:33], v[164:167], v[218:221], v[30:33]
	v_mfma_f32_16x16x32_bf16 v[26:29], v[172:175], v[218:221], v[26:29]
	v_mfma_f32_16x16x32_bf16 v[22:25], v[164:167], v[226:229], v[22:25]
	v_mfma_f32_16x16x32_bf16 v[18:21], v[172:175], v[226:229], v[18:21]
	s_setprio 0
	s_barrier
; #define STAGE(P, BASE, LD, br, kt) do { const bf16* _gb = BASE + ((long)(br) * (LD) + (long)(kt) * BK); \
;     _Pragma("unroll") for (int _i = 0; _i < 2; ++_i) { \
;       __builtin_amdgcn_global_load_lds((const unsigned*)(_gb + ((&LD == &lda) ? offA[_i] : offB[_i])), \
;         (unsigned*)((char*)(P) + tidx_ * 16 + _i * 8192), 16, 0, 0); } } while (0)
; #define LDA(dst, b, h) _Pragma("unroll") for (int m = 0; m < 4; ++m) _Pragma("unroll") for (int k = 0; k < 2; ++k) \
;     dst[m][k] = *reinterpret_cast<const bf16x8*>(smem + (((b) * 2 + (h)) * 16384 + m * 2048 + k * 1024) + aoff)
; #define LDB(dst, b, h) _Pragma("unroll") for (int n = 0; n < 2; ++n) _Pragma("unroll") for (int k = 0; k < 2; ++k) \
;     dst[n][k] = *reinterpret_cast<const bf16x8*>(smem + (((b) * 2 + (h)) * 16384 + n * 2048 + k * 1024) + boff)
; #define MMA(ai, bj, At_, Bt_) do { __builtin_amdgcn_s_setprio(1); \
;     _Pragma("unroll") for (int m = 0; m < 4; ++m) _Pragma("unroll") for (int n = 0; n < 2; ++n) _Pragma("unroll") for (int k = 0; k < 2; ++k) \
;       acc[ai][bj][m][n] = __builtin_amdgcn_mfma_f32_16x16x32_bf16(Bt_[n][k], At_[m][k], acc[ai][bj][m][n], 0, 0, 0); \
;     __builtin_amdgcn_s_setprio(0); } while (0)
; #define WAIT_V(n) asm volatile("s_waitcnt vmcnt(" #n ")" ::: "memory")
; #define WAIT_L(n) asm volatile("s_waitcnt lgkmcnt(" #n ")" ::: "memory")
; #define BAR __builtin_amdgcn_s_barrier()
; #define SCHED __builtin_amdgcn_sched_barrier(0)
; template <class Epi, int NB>
; DEV void gemm_tile_nb(const bf16* __restrict__ A, int lda, long strideA, const bf16* __restrict__ Bt, int ldb, long strideB, int K, int brow, int bcol, Epi& epi) {
;     ...
;     STAGE(SB(0, 1), Bt, ldb, bcol + HALF, t + 2);
;     WAIT_V(6); BAR; MMA(1, 1, At, B1); BAR;
;     LDB(B0, 1, 0); SCHED; LDA(At, 1, 0); STAGE(SA(0, 1), A, lda, brow + HALF, t + 2);
;     WAIT_L(8); BAR; WAIT_L(0); MMA(0, 0, At, B0); BAR; SCHED;
;     LDB(B1, 1, 1); STAGE(SB(1, 0), Bt, ldb, bcol, t + 3);
;     BAR; WAIT_L(0); MMA(0, 1, At, B1); BAR;
;     LDA(At, 1, 1); STAGE(SA(1, 0), A, lda, brow, t + 3);
	v_readfirstlane_b32 s39, v146
	v_lshl_add_u64 v[160:161], v[208:209], 0, s[94:95]
	s_mov_b32 m0, s39
	v_readfirstlane_b32 s39, v150
	global_load_lds_dwordx4 v[160:161], off
	v_lshl_add_u64 v[160:161], v[214:215], 0, s[94:95]
	s_mov_b32 m0, s39
	s_nop 0
	global_load_lds_dwordx4 v[160:161], off
	ds_read_b128 v[160:163], v143 offset:32768
	ds_read_b128 v[164:167], v143 offset:33792
	ds_read_b128 v[168:171], v143 offset:34816
	ds_read_b128 v[172:175], v143 offset:35840
	s_waitcnt vmcnt(6)
	s_barrier
	s_setprio 1
	v_mfma_f32_16x16x32_bf16 v[14:17], v[230:233], v[184:187], v[14:17]
	v_mfma_f32_16x16x32_bf16 v[10:13], v[238:241], v[184:187], v[10:13]
	v_mfma_f32_16x16x32_bf16 v[6:9], v[230:233], v[192:195], v[6:9]
	v_mfma_f32_16x16x32_bf16 v[2:5], v[238:241], v[192:195], v[2:5]
	v_mfma_f32_16x16x32_bf16 v[66:69], v[230:233], v[200:203], v[66:69]
	v_mfma_f32_16x16x32_bf16 v[74:77], v[238:241], v[200:203], v[74:77]
	v_mfma_f32_16x16x32_bf16 v[78:81], v[230:233], v[222:225], v[78:81]
	v_mfma_f32_16x16x32_bf16 v[82:85], v[238:241], v[222:225], v[82:85]
	v_mfma_f32_16x16x32_bf16 v[14:17], v[234:237], v[188:191], v[14:17]
	v_mfma_f32_16x16x32_bf16 v[10:13], v[242:245], v[188:191], v[10:13]
	v_mfma_f32_16x16x32_bf16 v[6:9], v[234:237], v[196:199], v[6:9]
	v_mfma_f32_16x16x32_bf16 v[2:5], v[242:245], v[196:199], v[2:5]
	v_mfma_f32_16x16x32_bf16 v[66:69], v[234:237], v[218:221], v[66:69]
	v_mfma_f32_16x16x32_bf16 v[74:77], v[242:245], v[218:221], v[74:77]
	v_mfma_f32_16x16x32_bf16 v[78:81], v[234:237], v[226:229], v[78:81]
	v_mfma_f32_16x16x32_bf16 v[82:85], v[242:245], v[226:229], v[82:85]
	s_setprio 0
	s_barrier
	v_readfirstlane_b32 s39, v148
	v_lshl_add_u64 v[230:231], v[176:177], 0, s[2:3]
	s_mov_b32 m0, s39
	v_readfirstlane_b32 s39, v151
	ds_read_b128 v[184:187], v142 offset:32768
	ds_read_b128 v[188:191], v142 offset:33792
	ds_read_b128 v[192:195], v142 offset:34816
	ds_read_b128 v[196:199], v142 offset:35840
	ds_read_b128 v[200:203], v142 offset:36864
	ds_read_b128 v[218:221], v142 offset:37888
	ds_read_b128 v[222:225], v142 offset:38912
	ds_read_b128 v[226:229], v142 offset:39936
	global_load_lds_dwordx4 v[230:231], off
	v_lshl_add_u64 v[230:231], v[204:205], 0, s[2:3]
	s_mov_b32 m0, s39
	s_nop 0
	global_load_lds_dwordx4 v[230:231], off
	s_waitcnt lgkmcnt(8)
	s_barrier
	s_waitcnt lgkmcnt(0)
	s_setprio 1
	s_waitcnt lgkmcnt(0)
	v_mfma_f32_16x16x32_bf16 v[126:129], v[160:163], v[184:187], v[126:129]
	v_mfma_f32_16x16x32_bf16 v[122:125], v[168:171], v[184:187], v[122:125]
	v_mfma_f32_16x16x32_bf16 v[118:121], v[160:163], v[192:195], v[118:121]
	v_mfma_f32_16x16x32_bf16 v[114:117], v[168:171], v[192:195], v[114:117]
	v_mfma_f32_16x16x32_bf16 v[110:113], v[160:163], v[200:203], v[110:113]
	v_mfma_f32_16x16x32_bf16 v[106:109], v[168:171], v[200:203], v[106:109]
	v_mfma_f32_16x16x32_bf16 v[102:105], v[160:163], v[222:225], v[102:105]
	v_mfma_f32_16x16x32_bf16 v[98:101], v[168:171], v[222:225], v[98:101]
	v_mfma_f32_16x16x32_bf16 v[126:129], v[164:167], v[188:191], v[126:129]
	v_mfma_f32_16x16x32_bf16 v[122:125], v[172:175], v[188:191], v[122:125]
	v_mfma_f32_16x16x32_bf16 v[118:121], v[164:167], v[196:199], v[118:121]
	v_mfma_f32_16x16x32_bf16 v[114:117], v[172:175], v[196:199], v[114:117]
	v_mfma_f32_16x16x32_bf16 v[110:113], v[164:167], v[218:221], v[110:113]
	v_mfma_f32_16x16x32_bf16 v[106:109], v[172:175], v[218:221], v[106:109]
	v_mfma_f32_16x16x32_bf16 v[102:105], v[164:167], v[226:229], v[102:105]
	v_mfma_f32_16x16x32_bf16 v[98:101], v[172:175], v[226:229], v[98:101]
	s_setprio 0
	s_barrier
	v_readfirstlane_b32 s39, v152
	v_lshl_add_u64 v[246:247], v[208:209], 0, s[46:47]
	s_mov_b32 m0, s39
	v_readfirstlane_b32 s39, v153
	ds_read_b128 v[230:233], v143 offset:49152
	ds_read_b128 v[234:237], v143 offset:50176
	ds_read_b128 v[238:241], v143 offset:51200
	ds_read_b128 v[242:245], v143 offset:52224
	global_load_lds_dwordx4 v[246:247], off
	v_lshl_add_u64 v[246:247], v[214:215], 0, s[46:47]
	s_mov_b32 m0, s39
	s_nop 0
	global_load_lds_dwordx4 v[246:247], off
	s_barrier
	s_waitcnt lgkmcnt(0)
	s_setprio 1
	s_waitcnt lgkmcnt(0)
	v_mfma_f32_16x16x32_bf16 v[94:97], v[230:233], v[184:187], v[94:97]
	v_mfma_f32_16x16x32_bf16 v[90:93], v[238:241], v[184:187], v[90:93]
	v_mfma_f32_16x16x32_bf16 v[86:89], v[230:233], v[192:195], v[86:89]
	v_mfma_f32_16x16x32_bf16 v[70:73], v[238:241], v[192:195], v[70:73]
	v_mfma_f32_16x16x32_bf16 v[62:65], v[230:233], v[200:203], v[62:65]
	v_mfma_f32_16x16x32_bf16 v[58:61], v[238:241], v[200:203], v[58:61]
	v_mfma_f32_16x16x32_bf16 v[54:57], v[230:233], v[222:225], v[54:57]
	v_mfma_f32_16x16x32_bf16 v[50:53], v[238:241], v[222:225], v[50:53]
	v_mfma_f32_16x16x32_bf16 v[94:97], v[234:237], v[188:191], v[94:97]
	v_mfma_f32_16x16x32_bf16 v[90:93], v[242:245], v[188:191], v[90:93]
	v_mfma_f32_16x16x32_bf16 v[86:89], v[234:237], v[196:199], v[86:89]
	v_mfma_f32_16x16x32_bf16 v[70:73], v[242:245], v[196:199], v[70:73]
	v_mfma_f32_16x16x32_bf16 v[62:65], v[234:237], v[218:221], v[62:65]
	v_mfma_f32_16x16x32_bf16 v[58:61], v[242:245], v[218:221], v[58:61]
	v_mfma_f32_16x16x32_bf16 v[54:57], v[234:237], v[226:229], v[54:57]
	v_mfma_f32_16x16x32_bf16 v[50:53], v[242:245], v[226:229], v[50:53]
	s_setprio 0
	v_readfirstlane_b32 s39, v154
	v_lshl_add_u64 v[176:177], v[176:177], 0, s[76:77]
	s_mov_b32 m0, s39
	v_readfirstlane_b32 s39, v155
	s_barrier
	ds_read_b128 v[184:187], v142 offset:49152
	ds_read_b128 v[188:191], v142 offset:50176
	ds_read_b128 v[192:195], v142 offset:51200
	ds_read_b128 v[196:199], v142 offset:52224
	ds_read_b128 v[200:203], v142 offset:53248
	ds_read_b128 v[218:221], v142 offset:54272
	ds_read_b128 v[222:225], v142 offset:55296
	ds_read_b128 v[226:229], v142 offset:56320
	global_load_lds_dwordx4 v[176:177], off
	v_lshl_add_u64 v[176:177], v[204:205], 0, s[76:77]
	s_mov_b32 m0, s39
	s_nop 0
	global_load_lds_dwordx4 v[176:177], off
	s_waitcnt vmcnt(10)
	s_barrier
; #define STAGE(P, BASE, LD, br, kt) do { const bf16* _gb = BASE + ((long)(br) * (LD) + (long)(kt) * BK); \
;     _Pragma("unroll") for (int _i = 0; _i < 2; ++_i) { \
;       __builtin_amdgcn_global_load_lds((const unsigned*)(_gb + ((&LD == &lda) ? offA[_i] : offB[_i])), \
;         (unsigned*)((char*)(P) + tidx_ * 16 + _i * 8192), 16, 0, 0); } } while (0)
; #define LDA(dst, b, h) _Pragma("unroll") for (int m = 0; m < 4; ++m) _Pragma("unroll") for (int k = 0; k < 2; ++k) \
;     dst[m][k] = *reinterpret_cast<const bf16x8*>(smem + (((b) * 2 + (h)) * 16384 + m * 2048 + k * 1024) + aoff)
; #define LDB(dst, b, h) _Pragma("unroll") for (int n = 0; n < 2; ++n) _Pragma("unroll") for (int k = 0; k < 2; ++k) \
;     dst[n][k] = *reinterpret_cast<const bf16x8*>(smem + (((b) * 2 + (h)) * 16384 + n * 2048 + k * 1024) + boff)
; #define MMA(ai, bj, At_, Bt_) do { __builtin_amdgcn_s_setprio(1); \
;     _Pragma("unroll") for (int m = 0; m < 4; ++m) _Pragma("unroll") for (int n = 0; n < 2; ++n) _Pragma("unroll") for (int k = 0; k < 2; ++k) \
;       acc[ai][bj][m][n] = __builtin_amdgcn_mfma_f32_16x16x32_bf16(Bt_[n][k], At_[m][k], acc[ai][bj][m][n], 0, 0, 0); \
;     __builtin_amdgcn_s_setprio(0); } while (0)
; #define WAIT_V(n) asm volatile("s_waitcnt vmcnt(" #n ")" ::: "memory")
; #define WAIT_L(n) asm volatile("s_waitcnt lgkmcnt(" #n ")" ::: "memory")
; #define BAR __builtin_amdgcn_s_barrier()
; #define SCHED __builtin_amdgcn_sched_barrier(0)
; template <class Epi, int NB>
; DEV void gemm_tile_nb(const bf16* __restrict__ A, int lda, long strideA, const bf16* __restrict__ Bt, int ldb, long strideB, int K, int brow, int bcol, Epi& epi) {
;     ...
;     BAR; WAIT_L(0); MMA(1, 0, At, B0); BAR; SCHED;
;     STAGE(SB(1, 1), Bt, ldb, bcol + HALF, t + 3);
;     WAIT_V(6); BAR; MMA(1, 1, At, B1); BAR;
;   }
;   { LDB(B0, 0, 0); LDA(At, 0, 0); STAGE(SA(1, 1), A, lda, brow + HALF, nt - 1);
;     BAR; WAIT_L(0); MMA(0, 0, At, B0); BAR;
;     LDB(B1, 0, 1); BAR; WAIT_L(0); MMA(0, 1, At, B1); BAR;
	s_waitcnt lgkmcnt(0)
	s_setprio 1
	s_waitcnt lgkmcnt(0)
	v_mfma_f32_16x16x32_bf16 v[46:49], v[160:163], v[184:187], v[46:49]
	v_mfma_f32_16x16x32_bf16 v[42:45], v[168:171], v[184:187], v[42:45]
	v_mfma_f32_16x16x32_bf16 v[38:41], v[160:163], v[192:195], v[38:41]
	v_mfma_f32_16x16x32_bf16 v[34:37], v[168:171], v[192:195], v[34:37]
	v_mfma_f32_16x16x32_bf16 v[30:33], v[160:163], v[200:203], v[30:33]
	v_mfma_f32_16x16x32_bf16 v[26:29], v[168:171], v[200:203], v[26:29]
	v_mfma_f32_16x16x32_bf16 v[22:25], v[160:163], v[222:225], v[22:25]
	v_mfma_f32_16x16x32_bf16 v[18:21], v[168:171], v[222:225], v[18:21]
	v_mfma_f32_16x16x32_bf16 v[46:49], v[164:167], v[188:191], v[46:49]
	v_mfma_f32_16x16x32_bf16 v[42:45], v[172:175], v[188:191], v[42:45]
	v_mfma_f32_16x16x32_bf16 v[38:41], v[164:167], v[196:199], v[38:41]
	v_mfma_f32_16x16x32_bf16 v[34:37], v[172:175], v[196:199], v[34:37]
	v_mfma_f32_16x16x32_bf16 v[30:33], v[164:167], v[218:221], v[30:33]
	v_mfma_f32_16x16x32_bf16 v[26:29], v[172:175], v[218:221], v[26:29]
	v_mfma_f32_16x16x32_bf16 v[22:25], v[164:167], v[226:229], v[22:25]
	v_mfma_f32_16x16x32_bf16 v[18:21], v[172:175], v[226:229], v[18:21]
	s_setprio 0
	s_barrier
	v_readfirstlane_b32 s39, v156
	v_lshl_add_u64 v[160:161], v[208:209], 0, s[78:79]
	s_mov_b32 m0, s39
	v_readfirstlane_b32 s39, v157
	global_load_lds_dwordx4 v[160:161], off
	v_lshl_add_u64 v[160:161], v[214:215], 0, s[78:79]
	s_mov_b32 m0, s39
	s_nop 0
	global_load_lds_dwordx4 v[160:161], off
	ds_read_b128 v[160:163], v143
	ds_read_b128 v[164:167], v143 offset:1024
	ds_read_b128 v[168:171], v143 offset:2048
	ds_read_b128 v[172:175], v143 offset:3072
	s_waitcnt vmcnt(6)
	s_barrier
	s_setprio 1
	v_mfma_f32_16x16x32_bf16 v[14:17], v[230:233], v[184:187], v[14:17]
	v_mfma_f32_16x16x32_bf16 v[10:13], v[238:241], v[184:187], v[10:13]
	v_mfma_f32_16x16x32_bf16 v[6:9], v[230:233], v[192:195], v[6:9]
	v_mfma_f32_16x16x32_bf16 v[2:5], v[238:241], v[192:195], v[2:5]
	v_mfma_f32_16x16x32_bf16 v[66:69], v[230:233], v[200:203], v[66:69]
	v_mfma_f32_16x16x32_bf16 v[74:77], v[238:241], v[200:203], v[74:77]
	v_mfma_f32_16x16x32_bf16 v[78:81], v[230:233], v[222:225], v[78:81]
	v_mfma_f32_16x16x32_bf16 v[82:85], v[238:241], v[222:225], v[82:85]
	v_mfma_f32_16x16x32_bf16 v[14:17], v[234:237], v[188:191], v[14:17]
	v_mfma_f32_16x16x32_bf16 v[10:13], v[242:245], v[188:191], v[10:13]
	v_mfma_f32_16x16x32_bf16 v[6:9], v[234:237], v[196:199], v[6:9]
	v_mfma_f32_16x16x32_bf16 v[2:5], v[242:245], v[196:199], v[2:5]
	v_mfma_f32_16x16x32_bf16 v[66:69], v[234:237], v[218:221], v[66:69]
	v_mfma_f32_16x16x32_bf16 v[74:77], v[242:245], v[218:221], v[74:77]
	v_mfma_f32_16x16x32_bf16 v[78:81], v[234:237], v[226:229], v[78:81]
	v_mfma_f32_16x16x32_bf16 v[82:85], v[242:245], v[226:229], v[82:85]
	s_setprio 0
	s_add_i32 s38, s38, 2
	v_lshl_add_u64 v[132:133], v[132:133], 0, s[72:73]
	v_lshl_add_u64 v[134:135], v[134:135], 0, s[72:73]
	v_lshl_add_u64 v[136:137], v[136:137], 0, s[72:73]
	s_cmp_gt_u32 s38, 39
	v_lshl_add_u64 v[138:139], v[138:139], 0, s[72:73]
	s_barrier
	s_cbranch_scc0 .LBB0_947
	s_add_u32 s0, s0, 0x1580
	s_addc_u32 s1, s1, 0
	v_readfirstlane_b32 s38, v158
	v_lshl_add_u64 v[156:157], v[0:1], 1, s[0:1]
	s_mov_b32 m0, s38
	v_lshl_add_u64 v[130:131], v[130:131], 1, s[0:1]
	v_readfirstlane_b32 s0, v159
	ds_read_b128 v[132:135], v143
	ds_read_b128 v[136:139], v143 offset:1024
	ds_read_b128 v[144:147], v143 offset:2048
	ds_read_b128 v[148:151], v143 offset:3072
	ds_read_b128 v[152:155], v142
	ds_read_b128 v[160:163], v142 offset:1024
	ds_read_b128 v[164:167], v142 offset:2048
	ds_read_b128 v[168:171], v142 offset:3072
	ds_read_b128 v[172:175], v142 offset:4096
	ds_read_b128 v[184:187], v142 offset:5120
	ds_read_b128 v[188:191], v142 offset:6144
	ds_read_b128 v[192:195], v142 offset:7168
	global_load_lds_dwordx4 v[156:157], off
	s_mov_b32 m0, s0
	s_cmpk_lt_u32 s55, 0x100
	global_load_lds_dwordx4 v[130:131], off
	s_barrier
	s_waitcnt lgkmcnt(0)
	s_setprio 1
	s_waitcnt lgkmcnt(0)
	v_mfma_f32_16x16x32_bf16 v[126:129], v[132:135], v[152:155], v[126:129]
	v_mfma_f32_16x16x32_bf16 v[118:121], v[132:135], v[164:167], v[118:121]
	v_mfma_f32_16x16x32_bf16 v[110:113], v[132:135], v[172:175], v[110:113]
	v_mfma_f32_16x16x32_bf16 v[102:105], v[132:135], v[188:191], v[102:105]
	v_mfma_f32_16x16x32_bf16 v[98:101], v[144:147], v[188:191], v[98:101]
	v_mfma_f32_16x16x32_bf16 v[126:129], v[136:139], v[160:163], v[126:129]
	v_mfma_f32_16x16x32_bf16 v[122:125], v[144:147], v[152:155], v[122:125]
	v_mfma_f32_16x16x32_bf16 v[118:121], v[136:139], v[168:171], v[118:121]
	v_mfma_f32_16x16x32_bf16 v[114:117], v[144:147], v[164:167], v[114:117]
	v_mfma_f32_16x16x32_bf16 v[110:113], v[136:139], v[184:187], v[110:113]
	v_mfma_f32_16x16x32_bf16 v[106:109], v[144:147], v[172:175], v[106:109]
	v_mfma_f32_16x16x32_bf16 v[102:105], v[136:139], v[192:195], v[102:105]
	v_mfma_f32_16x16x32_bf16 v[98:101], v[148:151], v[192:195], v[98:101]
	v_mfma_f32_16x16x32_bf16 v[156:159], v[148:151], v[160:163], v[122:125]
	v_mfma_f32_16x16x32_bf16 v[196:199], v[148:151], v[168:171], v[114:117]
	v_mfma_f32_16x16x32_bf16 v[200:203], v[148:151], v[184:187], v[106:109]
	s_setprio 0
	s_barrier
	s_nop 0
	ds_read_b128 v[106:109], v143 offset:16384
	ds_read_b128 v[114:117], v143 offset:17408
	ds_read_b128 v[122:125], v143 offset:18432
	ds_read_b128 v[218:221], v143 offset:19456
	s_barrier
; #define LDA(dst, b, h) _Pragma("unroll") for (int m = 0; m < 4; ++m) _Pragma("unroll") for (int k = 0; k < 2; ++k) \
;     dst[m][k] = *reinterpret_cast<const bf16x8*>(smem + (((b) * 2 + (h)) * 16384 + m * 2048 + k * 1024) + aoff)
; #define LDB(dst, b, h) _Pragma("unroll") for (int n = 0; n < 2; ++n) _Pragma("unroll") for (int k = 0; k < 2; ++k) \
;     dst[n][k] = *reinterpret_cast<const bf16x8*>(smem + (((b) * 2 + (h)) * 16384 + n * 2048 + k * 1024) + boff)
; #define MMA(ai, bj, At_, Bt_) do { __builtin_amdgcn_s_setprio(1); \
;     _Pragma("unroll") for (int m = 0; m < 4; ++m) _Pragma("unroll") for (int n = 0; n < 2; ++n) _Pragma("unroll") for (int k = 0; k < 2; ++k) \
;       acc[ai][bj][m][n] = __builtin_amdgcn_mfma_f32_16x16x32_bf16(Bt_[n][k], At_[m][k], acc[ai][bj][m][n], 0, 0, 0); \
;     __builtin_amdgcn_s_setprio(0); } while (0)
; #define WAIT_V(n) asm volatile("s_waitcnt vmcnt(" #n ")" ::: "memory")
; #define WAIT_L(n) asm volatile("s_waitcnt lgkmcnt(" #n ")" ::: "memory")
; #define BAR __builtin_amdgcn_s_barrier()
; template <class Epi, int NB>
; DEV void gemm_tile_nb(const bf16* __restrict__ A, int lda, long strideA, const bf16* __restrict__ Bt, int ldb, long strideB, int K, int brow, int bcol, Epi& epi) {
;     ...
;     LDB(B1, 0, 1); BAR; WAIT_L(0); MMA(0, 1, At, B1); BAR;
;     LDA(At, 0, 1); WAIT_V(4); BAR; WAIT_L(0); MMA(1, 0, At, B0); MMA(1, 1, At, B1); BAR; }
;   { LDB(B0, 1, 0); LDA(At, 1, 0); WAIT_V(2); BAR; WAIT_L(0); MMA(0, 0, At, B0); BAR;
	s_waitcnt lgkmcnt(0)
	s_setprio 1
	s_waitcnt lgkmcnt(0)
	v_mfma_f32_16x16x32_bf16 v[86:89], v[106:109], v[164:167], v[86:89]
	v_mfma_f32_16x16x32_bf16 v[70:73], v[122:125], v[164:167], v[70:73]
	v_mfma_f32_16x16x32_bf16 v[62:65], v[106:109], v[172:175], v[62:65]
	v_mfma_f32_16x16x32_bf16 v[58:61], v[122:125], v[172:175], v[58:61]
	v_mfma_f32_16x16x32_bf16 v[54:57], v[106:109], v[188:191], v[54:57]
	v_mfma_f32_16x16x32_bf16 v[50:53], v[122:125], v[188:191], v[50:53]
	v_mfma_f32_16x16x32_bf16 v[94:97], v[106:109], v[152:155], v[94:97]
	v_mfma_f32_16x16x32_bf16 v[90:93], v[122:125], v[152:155], v[90:93]
	v_mfma_f32_16x16x32_bf16 v[86:89], v[114:117], v[168:171], v[86:89]
	v_mfma_f32_16x16x32_bf16 v[70:73], v[218:221], v[168:171], v[70:73]
	v_mfma_f32_16x16x32_bf16 v[62:65], v[114:117], v[184:187], v[62:65]
	v_mfma_f32_16x16x32_bf16 v[58:61], v[218:221], v[184:187], v[58:61]
	v_mfma_f32_16x16x32_bf16 v[54:57], v[114:117], v[192:195], v[54:57]
	v_mfma_f32_16x16x32_bf16 v[50:53], v[218:221], v[192:195], v[50:53]
	v_mfma_f32_16x16x32_bf16 v[222:225], v[114:117], v[160:163], v[94:97]
	v_mfma_f32_16x16x32_bf16 v[152:155], v[218:221], v[160:163], v[90:93]
	s_setprio 0
	s_barrier
	s_nop 0
	ds_read_b128 v[90:93], v142 offset:16384
	ds_read_b128 v[94:97], v142 offset:17408
	ds_read_b128 v[160:163], v142 offset:18432
	ds_read_b128 v[164:167], v142 offset:19456
	ds_read_b128 v[168:171], v142 offset:20480
	ds_read_b128 v[172:175], v142 offset:21504
	ds_read_b128 v[184:187], v142 offset:22528
	ds_read_b128 v[188:191], v142 offset:23552
	s_waitcnt vmcnt(4)
	s_barrier
	s_waitcnt lgkmcnt(0)
	s_setprio 1
	s_waitcnt lgkmcnt(0)
	v_mfma_f32_16x16x32_bf16 v[46:49], v[132:135], v[90:93], v[46:49]
	v_mfma_f32_16x16x32_bf16 v[42:45], v[144:147], v[90:93], v[42:45]
	v_mfma_f32_16x16x32_bf16 v[38:41], v[132:135], v[160:163], v[38:41]
	v_mfma_f32_16x16x32_bf16 v[34:37], v[144:147], v[160:163], v[34:37]
	v_mfma_f32_16x16x32_bf16 v[30:33], v[132:135], v[168:171], v[30:33]
	v_mfma_f32_16x16x32_bf16 v[26:29], v[144:147], v[168:171], v[26:29]
	v_mfma_f32_16x16x32_bf16 v[22:25], v[132:135], v[184:187], v[22:25]
	v_mfma_f32_16x16x32_bf16 v[18:21], v[144:147], v[184:187], v[18:21]
	v_mfma_f32_16x16x32_bf16 v[46:49], v[136:139], v[94:97], v[46:49]
	v_mfma_f32_16x16x32_bf16 v[42:45], v[148:151], v[94:97], v[42:45]
	v_mfma_f32_16x16x32_bf16 v[38:41], v[136:139], v[164:167], v[38:41]
	v_mfma_f32_16x16x32_bf16 v[34:37], v[148:151], v[164:167], v[34:37]
	v_mfma_f32_16x16x32_bf16 v[30:33], v[136:139], v[172:175], v[30:33]
	v_mfma_f32_16x16x32_bf16 v[26:29], v[148:151], v[172:175], v[26:29]
	v_mfma_f32_16x16x32_bf16 v[22:25], v[136:139], v[188:191], v[22:25]
	v_mfma_f32_16x16x32_bf16 v[18:21], v[148:151], v[188:191], v[18:21]
	s_setprio 0
	s_setprio 1
	v_mfma_f32_16x16x32_bf16 v[66:69], v[106:109], v[168:171], v[66:69]
	v_mfma_f32_16x16x32_bf16 v[130:133], v[114:117], v[172:175], v[66:69]
	v_mfma_f32_16x16x32_bf16 v[66:69], v[122:125], v[168:171], v[74:77]
	v_mfma_f32_16x16x32_bf16 v[14:17], v[106:109], v[90:93], v[14:17]
	v_mfma_f32_16x16x32_bf16 v[10:13], v[122:125], v[90:93], v[10:13]
	v_mfma_f32_16x16x32_bf16 v[6:9], v[106:109], v[160:163], v[6:9]
	v_mfma_f32_16x16x32_bf16 v[2:5], v[122:125], v[160:163], v[2:5]
	v_mfma_f32_16x16x32_bf16 v[134:137], v[218:221], v[172:175], v[66:69]
	v_mfma_f32_16x16x32_bf16 v[66:69], v[106:109], v[184:187], v[78:81]
	v_mfma_f32_16x16x32_bf16 v[14:17], v[114:117], v[94:97], v[14:17]
	v_mfma_f32_16x16x32_bf16 v[10:13], v[218:221], v[94:97], v[10:13]
	v_mfma_f32_16x16x32_bf16 v[6:9], v[114:117], v[164:167], v[6:9]
	v_mfma_f32_16x16x32_bf16 v[2:5], v[218:221], v[164:167], v[2:5]
	v_mfma_f32_16x16x32_bf16 v[144:147], v[114:117], v[188:191], v[66:69]
	v_mfma_f32_16x16x32_bf16 v[66:69], v[122:125], v[184:187], v[82:85]
	v_mfma_f32_16x16x32_bf16 v[148:151], v[218:221], v[188:191], v[66:69]
	s_setprio 0
	s_barrier
	ds_read_b128 v[160:163], v143 offset:32768
	ds_read_b128 v[164:167], v143 offset:33792
	ds_read_b128 v[168:171], v143 offset:34816
	ds_read_b128 v[172:175], v143 offset:35840
	s_nop 0
	ds_read_b128 v[66:69], v142 offset:32768
	ds_read_b128 v[74:77], v142 offset:33792
	ds_read_b128 v[78:81], v142 offset:34816
	ds_read_b128 v[184:187], v142 offset:35840
	ds_read_b128 v[188:191], v142 offset:36864
	ds_read_b128 v[192:195], v142 offset:37888
	ds_read_b128 v[218:221], v142 offset:38912
	ds_read_b128 v[226:229], v142 offset:39936
	s_waitcnt vmcnt(2)
	s_barrier
; #define LDA(dst, b, h) _Pragma("unroll") for (int m = 0; m < 4; ++m) _Pragma("unroll") for (int k = 0; k < 2; ++k) \
;     dst[m][k] = *reinterpret_cast<const bf16x8*>(smem + (((b) * 2 + (h)) * 16384 + m * 2048 + k * 1024) + aoff)
; #define LDB(dst, b, h) _Pragma("unroll") for (int n = 0; n < 2; ++n) _Pragma("unroll") for (int k = 0; k < 2; ++k) \
;     dst[n][k] = *reinterpret_cast<const bf16x8*>(smem + (((b) * 2 + (h)) * 16384 + n * 2048 + k * 1024) + boff)
; #define MMA(ai, bj, At_, Bt_) do { __builtin_amdgcn_s_setprio(1); \
;     _Pragma("unroll") for (int m = 0; m < 4; ++m) _Pragma("unroll") for (int n = 0; n < 2; ++n) _Pragma("unroll") for (int k = 0; k < 2; ++k) \
;       acc[ai][bj][m][n] = __builtin_amdgcn_mfma_f32_16x16x32_bf16(Bt_[n][k], At_[m][k], acc[ai][bj][m][n], 0, 0, 0); \
;     __builtin_amdgcn_s_setprio(0); } while (0)
; #define WAIT_V(n) asm volatile("s_waitcnt vmcnt(" #n ")" ::: "memory")
; #define WAIT_L(n) asm volatile("s_waitcnt lgkmcnt(" #n ")" ::: "memory")
; #define BAR __builtin_amdgcn_s_barrier()
; template <class Epi, int NB>
; DEV void gemm_tile_nb(const bf16* __restrict__ A, int lda, long strideA, const bf16* __restrict__ Bt, int ldb, long strideB, int K, int brow, int bcol, Epi& epi) {
;     ...
;   { LDB(B0, 1, 0); LDA(At, 1, 0); WAIT_V(2); BAR; WAIT_L(0); MMA(0, 0, At, B0); BAR;
;     LDB(B1, 1, 1); WAIT_V(0); BAR; WAIT_L(0); MMA(0, 1, At, B1); BAR;
;     LDA(At, 1, 1); BAR; WAIT_L(0); MMA(1, 0, At, B0); MMA(1, 1, At, B1); BAR; }
;   if (wr == 0) BAR;
	s_waitcnt lgkmcnt(0)
	s_setprio 1
	s_waitcnt lgkmcnt(0)
	v_mfma_f32_16x16x32_bf16 v[82:85], v[160:163], v[66:69], v[126:129]
	v_mfma_f32_16x16x32_bf16 v[122:125], v[164:167], v[74:77], v[82:85]
	v_mfma_f32_16x16x32_bf16 v[82:85], v[168:171], v[66:69], v[156:159]
	v_mfma_f32_16x16x32_bf16 v[126:129], v[172:175], v[74:77], v[82:85]
	v_mfma_f32_16x16x32_bf16 v[82:85], v[160:163], v[78:81], v[118:121]
	v_mfma_f32_16x16x32_bf16 v[114:117], v[164:167], v[184:187], v[82:85]
	v_mfma_f32_16x16x32_bf16 v[82:85], v[168:171], v[78:81], v[196:199]
	v_mfma_f32_16x16x32_bf16 v[118:121], v[172:175], v[184:187], v[82:85]
	v_mfma_f32_16x16x32_bf16 v[82:85], v[160:163], v[188:191], v[110:113]
	v_mfma_f32_16x16x32_bf16 v[106:109], v[164:167], v[192:195], v[82:85]
	v_mfma_f32_16x16x32_bf16 v[82:85], v[168:171], v[188:191], v[200:203]
	v_mfma_f32_16x16x32_bf16 v[110:113], v[172:175], v[192:195], v[82:85]
	v_mfma_f32_16x16x32_bf16 v[82:85], v[160:163], v[218:221], v[102:105]
	v_mfma_f32_16x16x32_bf16 v[90:93], v[164:167], v[226:229], v[82:85]
	v_mfma_f32_16x16x32_bf16 v[82:85], v[168:171], v[218:221], v[98:101]
	v_mfma_f32_16x16x32_bf16 v[94:97], v[172:175], v[226:229], v[82:85]
	s_setprio 0
	s_barrier
	ds_read_b128 v[156:159], v143 offset:49152
	ds_read_b128 v[196:199], v143 offset:50176
	ds_read_b128 v[200:203], v143 offset:51200
	ds_read_b128 v[230:233], v143 offset:52224
	s_waitcnt vmcnt(0)
	s_barrier
	s_waitcnt lgkmcnt(0)
	s_setprio 1
	s_waitcnt lgkmcnt(0)
	v_mfma_f32_16x16x32_bf16 v[82:85], v[156:159], v[66:69], v[222:225]
	v_mfma_f32_16x16x32_bf16 v[66:69], v[200:203], v[66:69], v[152:155]
	v_mfma_f32_16x16x32_bf16 v[102:105], v[230:233], v[74:77], v[66:69]
	v_mfma_f32_16x16x32_bf16 v[66:69], v[156:159], v[78:81], v[86:89]
	v_mfma_f32_16x16x32_bf16 v[98:101], v[196:199], v[74:77], v[82:85]
	v_mfma_f32_16x16x32_bf16 v[82:85], v[196:199], v[184:187], v[66:69]
	v_mfma_f32_16x16x32_bf16 v[66:69], v[200:203], v[78:81], v[70:73]
	v_mfma_f32_16x16x32_bf16 v[62:65], v[156:159], v[188:191], v[62:65]
	v_mfma_f32_16x16x32_bf16 v[58:61], v[200:203], v[188:191], v[58:61]
	v_mfma_f32_16x16x32_bf16 v[54:57], v[156:159], v[218:221], v[54:57]
	v_mfma_f32_16x16x32_bf16 v[50:53], v[200:203], v[218:221], v[50:53]
	v_mfma_f32_16x16x32_bf16 v[86:89], v[230:233], v[184:187], v[66:69]
	v_mfma_f32_16x16x32_bf16 v[74:77], v[196:199], v[192:195], v[62:65]
	v_mfma_f32_16x16x32_bf16 v[78:81], v[230:233], v[192:195], v[58:61]
	v_mfma_f32_16x16x32_bf16 v[66:69], v[196:199], v[226:229], v[54:57]
	v_mfma_f32_16x16x32_bf16 v[70:73], v[230:233], v[226:229], v[50:53]
	s_setprio 0
	s_barrier
	ds_read_b128 v[152:155], v142 offset:49152
	ds_read_b128 v[184:187], v142 offset:50176
	ds_read_b128 v[188:191], v142 offset:51200
	ds_read_b128 v[192:195], v142 offset:52224
	ds_read_b128 v[218:221], v142 offset:53248
	ds_read_b128 v[222:225], v142 offset:54272
	ds_read_b128 v[226:229], v142 offset:55296
	ds_read_b128 v[234:237], v142 offset:56320
	s_barrier
	s_waitcnt lgkmcnt(0)
	s_setprio 1
	s_waitcnt lgkmcnt(0)
	v_mfma_f32_16x16x32_bf16 v[46:49], v[160:163], v[152:155], v[46:49]
	v_mfma_f32_16x16x32_bf16 v[42:45], v[168:171], v[152:155], v[42:45]
	v_mfma_f32_16x16x32_bf16 v[38:41], v[160:163], v[188:191], v[38:41]
	v_mfma_f32_16x16x32_bf16 v[34:37], v[168:171], v[188:191], v[34:37]
	v_mfma_f32_16x16x32_bf16 v[30:33], v[160:163], v[218:221], v[30:33]
	v_mfma_f32_16x16x32_bf16 v[26:29], v[168:171], v[218:221], v[26:29]
	v_mfma_f32_16x16x32_bf16 v[22:25], v[160:163], v[226:229], v[22:25]
	v_mfma_f32_16x16x32_bf16 v[18:21], v[168:171], v[226:229], v[18:21]
	v_mfma_f32_16x16x32_bf16 v[58:61], v[164:167], v[184:187], v[46:49]
	v_mfma_f32_16x16x32_bf16 v[62:65], v[172:175], v[184:187], v[42:45]
	v_mfma_f32_16x16x32_bf16 v[50:53], v[164:167], v[192:195], v[38:41]
	v_mfma_f32_16x16x32_bf16 v[54:57], v[172:175], v[192:195], v[34:37]
	v_mfma_f32_16x16x32_bf16 v[42:45], v[164:167], v[222:225], v[30:33]
	v_mfma_f32_16x16x32_bf16 v[46:49], v[172:175], v[222:225], v[26:29]
	v_mfma_f32_16x16x32_bf16 v[34:37], v[164:167], v[234:237], v[22:25]
	v_mfma_f32_16x16x32_bf16 v[38:41], v[172:175], v[234:237], v[18:21]
	s_setprio 0
	s_setprio 1
	v_mfma_f32_16x16x32_bf16 v[2:5], v[200:203], v[188:191], v[2:5]
	v_mfma_f32_16x16x32_bf16 v[10:13], v[200:203], v[152:155], v[10:13]
	v_mfma_f32_16x16x32_bf16 v[22:25], v[230:233], v[192:195], v[2:5]
	v_mfma_f32_16x16x32_bf16 v[2:5], v[156:159], v[218:221], v[130:133]
	v_mfma_f32_16x16x32_bf16 v[14:17], v[156:159], v[152:155], v[14:17]
	v_mfma_f32_16x16x32_bf16 v[30:33], v[230:233], v[184:187], v[10:13]
	v_mfma_f32_16x16x32_bf16 v[6:9], v[156:159], v[188:191], v[6:9]
	v_mfma_f32_16x16x32_bf16 v[10:13], v[196:199], v[222:225], v[2:5]
	v_mfma_f32_16x16x32_bf16 v[2:5], v[200:203], v[218:221], v[134:137]
	v_mfma_f32_16x16x32_bf16 v[26:29], v[196:199], v[184:187], v[14:17]
	v_mfma_f32_16x16x32_bf16 v[18:21], v[196:199], v[192:195], v[6:9]
	v_mfma_f32_16x16x32_bf16 v[14:17], v[230:233], v[222:225], v[2:5]
	v_mfma_f32_16x16x32_bf16 v[2:5], v[156:159], v[226:229], v[144:147]
	v_mfma_f32_16x16x32_bf16 v[6:9], v[200:203], v[226:229], v[148:151]
	v_mfma_f32_16x16x32_bf16 v[2:5], v[196:199], v[234:237], v[2:5]
	v_mfma_f32_16x16x32_bf16 v[6:9], v[230:233], v[234:237], v[6:9]
	s_setprio 0
	s_barrier
	s_cbranch_scc0 .LBB0_943
	s_barrier
	s_branch .LBB0_943

; #define STAGE(P, BASE, LD, br, kt) do { const bf16* _gb = BASE + ((long)(br) * (LD) + (long)(kt) * BK); \
;     _Pragma("unroll") for (int _i = 0; _i < 2; ++_i) { \
;       __builtin_amdgcn_global_load_lds((const unsigned*)(_gb + ((&LD == &lda) ? offA[_i] : offB[_i])), \
;         (unsigned*)((char*)(P) + tidx_ * 16 + _i * 8192), 16, 0, 0); } } while (0)
; #define LDA(dst, b, h) _Pragma("unroll") for (int m = 0; m < 4; ++m) _Pragma("unroll") for (int k = 0; k < 2; ++k) \
;     dst[m][k] = *reinterpret_cast<const bf16x8*>(smem + (((b) * 2 + (h)) * 16384 + m * 2048 + k * 1024) + aoff)
; #define LDB(dst, b, h) _Pragma("unroll") for (int n = 0; n < 2; ++n) _Pragma("unroll") for (int k = 0; k < 2; ++k) \
;     dst[n][k] = *reinterpret_cast<const bf16x8*>(smem + (((b) * 2 + (h)) * 16384 + n * 2048 + k * 1024) + boff)
; #define MMA(ai, bj, At_, Bt_) do { __builtin_amdgcn_s_setprio(1); \
;     _Pragma("unroll") for (int m = 0; m < 4; ++m) _Pragma("unroll") for (int n = 0; n < 2; ++n) _Pragma("unroll") for (int k = 0; k < 2; ++k) \
;       acc[ai][bj][m][n] = __builtin_amdgcn_mfma_f32_16x16x32_bf16(Bt_[n][k], At_[m][k], acc[ai][bj][m][n], 0, 0, 0); \
;     __builtin_amdgcn_s_setprio(0); } while (0)
; #define WAIT_L(n) asm volatile("s_waitcnt lgkmcnt(" #n ")" ::: "memory")
; #define BAR __builtin_amdgcn_s_barrier()
; #define SCHED __builtin_amdgcn_sched_barrier(0)
; template <class Epi, int NB>
; DEV void gemm_tile_nb(const bf16* __restrict__ A, int lda, long strideA, const bf16* __restrict__ Bt, int ldb, long strideB, int K, int brow, int bcol, Epi& epi) {
;     ...
;     LDB(B0, 0, 0); SCHED; LDA(At, 0, 0); STAGE(SA(1, 1), A, lda, brow + HALF, t + 1);
;     WAIT_L(8); BAR; WAIT_L(0); MMA(0, 0, At, B0); BAR; SCHED;
;     LDB(B1, 0, 1); STAGE(SB(0, 0), Bt, ldb, bcol, t + 2);
;     BAR; WAIT_L(0); MMA(0, 1, At, B1); BAR;
;     LDA(At, 0, 1); STAGE(SA(0, 0), A, lda, brow, t + 2);
;     BAR; WAIT_L(0); MMA(1, 0, At, B0); BAR; SCHED;
.LBB0_960:
	v_add_u32_e32 v159, 0xc000, v146
	v_lshl_add_u64 v[246:247], v[138:139], 0, s[42:43]
	v_readfirstlane_b32 s59, v159
	v_lshl_add_u64 v[160:161], v[246:247], 0, s[80:81]
	s_mov_b32 m0, s59
	ds_read_b128 v[184:187], v0
	ds_read_b128 v[188:191], v0 offset:1024
	ds_read_b128 v[192:195], v0 offset:2048
	ds_read_b128 v[196:199], v0 offset:3072
	ds_read_b128 v[200:203], v0 offset:4096
	ds_read_b128 v[218:221], v0 offset:5120
	ds_read_b128 v[222:225], v0 offset:6144
	ds_read_b128 v[226:229], v0 offset:7168
	global_load_lds_dwordx4 v[160:161], off
	v_add_u32_e32 v160, 0xe000, v146
	v_lshl_add_u64 v[248:249], v[140:141], 0, s[42:43]
	v_readfirstlane_b32 s59, v160
	v_lshl_add_u64 v[230:231], v[248:249], 0, s[80:81]
	s_mov_b32 m0, s59
	s_nop 0
	global_load_lds_dwordx4 v[230:231], off
	s_waitcnt lgkmcnt(8)
	s_barrier
	s_waitcnt lgkmcnt(0)
	s_setprio 1
	s_waitcnt lgkmcnt(0)
	v_mfma_f32_16x16x32_bf16 v[126:129], v[162:165], v[184:187], v[126:129]
	v_mfma_f32_16x16x32_bf16 v[122:125], v[170:173], v[184:187], v[122:125]
	v_mfma_f32_16x16x32_bf16 v[118:121], v[162:165], v[192:195], v[118:121]
	v_mfma_f32_16x16x32_bf16 v[114:117], v[170:173], v[192:195], v[114:117]
	v_mfma_f32_16x16x32_bf16 v[110:113], v[162:165], v[200:203], v[110:113]
	v_mfma_f32_16x16x32_bf16 v[106:109], v[170:173], v[200:203], v[106:109]
	v_mfma_f32_16x16x32_bf16 v[102:105], v[162:165], v[222:225], v[102:105]
	v_mfma_f32_16x16x32_bf16 v[98:101], v[170:173], v[222:225], v[98:101]
	v_mfma_f32_16x16x32_bf16 v[126:129], v[166:169], v[188:191], v[126:129]
	v_mfma_f32_16x16x32_bf16 v[122:125], v[174:177], v[188:191], v[122:125]
	v_mfma_f32_16x16x32_bf16 v[118:121], v[166:169], v[196:199], v[118:121]
	v_mfma_f32_16x16x32_bf16 v[114:117], v[174:177], v[196:199], v[114:117]
	v_mfma_f32_16x16x32_bf16 v[110:113], v[166:169], v[218:221], v[110:113]
	v_mfma_f32_16x16x32_bf16 v[106:109], v[174:177], v[218:221], v[106:109]
	v_mfma_f32_16x16x32_bf16 v[102:105], v[166:169], v[226:229], v[102:105]
	v_mfma_f32_16x16x32_bf16 v[98:101], v[174:177], v[226:229], v[98:101]
	s_setprio 0
	s_barrier
	v_lshl_add_u64 v[204:205], v[134:135], 0, s[42:43]
	v_readfirstlane_b32 s59, v144
	v_lshl_add_u64 v[214:215], v[204:205], 0, s[72:73]
	s_mov_b32 m0, s59
	ds_read_b128 v[230:233], v145 offset:16384
	ds_read_b128 v[234:237], v145 offset:17408
	ds_read_b128 v[238:241], v145 offset:18432
	ds_read_b128 v[242:245], v145 offset:19456
	global_load_lds_dwordx4 v[214:215], off
	v_lshl_add_u64 v[214:215], v[136:137], 0, s[42:43]
	v_readfirstlane_b32 s59, v148
	v_lshl_add_u64 v[208:209], v[214:215], 0, s[72:73]
	s_mov_b32 m0, s59
	s_nop 0
	global_load_lds_dwordx4 v[208:209], off
	s_barrier
	s_waitcnt lgkmcnt(0)
	s_setprio 1
	s_waitcnt lgkmcnt(0)
	v_mfma_f32_16x16x32_bf16 v[94:97], v[230:233], v[184:187], v[94:97]
	v_mfma_f32_16x16x32_bf16 v[90:93], v[238:241], v[184:187], v[90:93]
	v_mfma_f32_16x16x32_bf16 v[86:89], v[230:233], v[192:195], v[86:89]
	v_mfma_f32_16x16x32_bf16 v[70:73], v[238:241], v[192:195], v[70:73]
	v_mfma_f32_16x16x32_bf16 v[62:65], v[230:233], v[200:203], v[62:65]
	v_mfma_f32_16x16x32_bf16 v[58:61], v[238:241], v[200:203], v[58:61]
	v_mfma_f32_16x16x32_bf16 v[54:57], v[230:233], v[222:225], v[54:57]
	v_mfma_f32_16x16x32_bf16 v[50:53], v[238:241], v[222:225], v[50:53]
	v_mfma_f32_16x16x32_bf16 v[94:97], v[234:237], v[188:191], v[94:97]
	v_mfma_f32_16x16x32_bf16 v[90:93], v[242:245], v[188:191], v[90:93]
	v_mfma_f32_16x16x32_bf16 v[86:89], v[234:237], v[196:199], v[86:89]
	v_mfma_f32_16x16x32_bf16 v[70:73], v[242:245], v[196:199], v[70:73]
	v_mfma_f32_16x16x32_bf16 v[62:65], v[234:237], v[218:221], v[62:65]
	v_mfma_f32_16x16x32_bf16 v[58:61], v[242:245], v[218:221], v[58:61]
	v_mfma_f32_16x16x32_bf16 v[54:57], v[234:237], v[226:229], v[54:57]
	v_mfma_f32_16x16x32_bf16 v[50:53], v[242:245], v[226:229], v[50:53]
	s_setprio 0
	v_readfirstlane_b32 s59, v146
	v_lshl_add_u64 v[208:209], v[246:247], 0, s[72:73]
	s_mov_b32 m0, s59
	v_readfirstlane_b32 s59, v150
	s_barrier
	ds_read_b128 v[184:187], v0 offset:16384
	ds_read_b128 v[188:191], v0 offset:17408
	ds_read_b128 v[192:195], v0 offset:18432
	ds_read_b128 v[196:199], v0 offset:19456
	ds_read_b128 v[200:203], v0 offset:20480
	ds_read_b128 v[218:221], v0 offset:21504
	ds_read_b128 v[222:225], v0 offset:22528
	ds_read_b128 v[226:229], v0 offset:23552
	global_load_lds_dwordx4 v[208:209], off
	v_lshl_add_u64 v[208:209], v[248:249], 0, s[72:73]
	s_mov_b32 m0, s59
	s_nop 0
	global_load_lds_dwordx4 v[208:209], off
	s_waitcnt vmcnt(10)
	s_barrier
	s_waitcnt lgkmcnt(0)
	s_setprio 1
	s_waitcnt lgkmcnt(0)
	v_mfma_f32_16x16x32_bf16 v[46:49], v[162:165], v[184:187], v[46:49]
	v_mfma_f32_16x16x32_bf16 v[42:45], v[170:173], v[184:187], v[42:45]
	v_mfma_f32_16x16x32_bf16 v[38:41], v[162:165], v[192:195], v[38:41]
	v_mfma_f32_16x16x32_bf16 v[34:37], v[170:173], v[192:195], v[34:37]
	v_mfma_f32_16x16x32_bf16 v[30:33], v[162:165], v[200:203], v[30:33]
	v_mfma_f32_16x16x32_bf16 v[26:29], v[170:173], v[200:203], v[26:29]
	v_mfma_f32_16x16x32_bf16 v[22:25], v[162:165], v[222:225], v[22:25]
	v_mfma_f32_16x16x32_bf16 v[18:21], v[170:173], v[222:225], v[18:21]
	v_mfma_f32_16x16x32_bf16 v[46:49], v[166:169], v[188:191], v[46:49]
	v_mfma_f32_16x16x32_bf16 v[42:45], v[174:177], v[188:191], v[42:45]
	v_mfma_f32_16x16x32_bf16 v[38:41], v[166:169], v[196:199], v[38:41]
	v_mfma_f32_16x16x32_bf16 v[34:37], v[174:177], v[196:199], v[34:37]
	v_mfma_f32_16x16x32_bf16 v[30:33], v[166:169], v[218:221], v[30:33]
	v_mfma_f32_16x16x32_bf16 v[26:29], v[174:177], v[218:221], v[26:29]
	v_mfma_f32_16x16x32_bf16 v[22:25], v[166:169], v[226:229], v[22:25]
	v_mfma_f32_16x16x32_bf16 v[18:21], v[174:177], v[226:229], v[18:21]
	s_setprio 0
	s_barrier
; #define STAGE(P, BASE, LD, br, kt) do { const bf16* _gb = BASE + ((long)(br) * (LD) + (long)(kt) * BK); \
;     _Pragma("unroll") for (int _i = 0; _i < 2; ++_i) { \
;       __builtin_amdgcn_global_load_lds((const unsigned*)(_gb + ((&LD == &lda) ? offA[_i] : offB[_i])), \
;         (unsigned*)((char*)(P) + tidx_ * 16 + _i * 8192), 16, 0, 0); } } while (0)
; #define LDA(dst, b, h) _Pragma("unroll") for (int m = 0; m < 4; ++m) _Pragma("unroll") for (int k = 0; k < 2; ++k) \
;     dst[m][k] = *reinterpret_cast<const bf16x8*>(smem + (((b) * 2 + (h)) * 16384 + m * 2048 + k * 1024) + aoff)
; #define LDB(dst, b, h) _Pragma("unroll") for (int n = 0; n < 2; ++n) _Pragma("unroll") for (int k = 0; k < 2; ++k) \
;     dst[n][k] = *reinterpret_cast<const bf16x8*>(smem + (((b) * 2 + (h)) * 16384 + n * 2048 + k * 1024) + boff)
; #define MMA(ai, bj, At_, Bt_) do { __builtin_amdgcn_s_setprio(1); \
;     _Pragma("unroll") for (int m = 0; m < 4; ++m) _Pragma("unroll") for (int n = 0; n < 2; ++n) _Pragma("unroll") for (int k = 0; k < 2; ++k) \
;       acc[ai][bj][m][n] = __builtin_amdgcn_mfma_f32_16x16x32_bf16(Bt_[n][k], At_[m][k], acc[ai][bj][m][n], 0, 0, 0); \
;     __builtin_amdgcn_s_setprio(0); } while (0)
; #define WAIT_V(n) asm volatile("s_waitcnt vmcnt(" #n ")" ::: "memory")
; #define WAIT_L(n) asm volatile("s_waitcnt lgkmcnt(" #n ")" ::: "memory")
; #define BAR __builtin_amdgcn_s_barrier()
; #define SCHED __builtin_amdgcn_sched_barrier(0)
; template <class Epi, int NB>
; DEV void gemm_tile_nb(const bf16* __restrict__ A, int lda, long strideA, const bf16* __restrict__ Bt, int ldb, long strideB, int K, int brow, int bcol, Epi& epi) {
;     ...
;     STAGE(SB(0, 1), Bt, ldb, bcol + HALF, t + 2);
;     WAIT_V(6); BAR; MMA(1, 1, At, B1); BAR;
;     LDB(B0, 1, 0); SCHED; LDA(At, 1, 0); STAGE(SA(0, 1), A, lda, brow + HALF, t + 2);
;     WAIT_L(8); BAR; WAIT_L(0); MMA(0, 0, At, B0); BAR; SCHED;
;     LDB(B1, 1, 1); STAGE(SB(1, 0), Bt, ldb, bcol, t + 3);
;     BAR; WAIT_L(0); MMA(0, 1, At, B1); BAR;
;     LDA(At, 1, 1); STAGE(SA(1, 0), A, lda, brow, t + 3);
	v_readfirstlane_b32 s59, v147
	v_lshl_add_u64 v[162:163], v[204:205], 0, s[82:83]
	s_mov_b32 m0, s59
	v_readfirstlane_b32 s59, v151
	global_load_lds_dwordx4 v[162:163], off
	v_lshl_add_u64 v[162:163], v[214:215], 0, s[82:83]
	s_mov_b32 m0, s59
	s_nop 0
	global_load_lds_dwordx4 v[162:163], off
	ds_read_b128 v[162:165], v145 offset:32768
	ds_read_b128 v[166:169], v145 offset:33792
	ds_read_b128 v[170:173], v145 offset:34816
	ds_read_b128 v[174:177], v145 offset:35840
	s_waitcnt vmcnt(6)
	s_barrier
	s_setprio 1
	v_mfma_f32_16x16x32_bf16 v[14:17], v[230:233], v[184:187], v[14:17]
	v_mfma_f32_16x16x32_bf16 v[10:13], v[238:241], v[184:187], v[10:13]
	v_mfma_f32_16x16x32_bf16 v[6:9], v[230:233], v[192:195], v[6:9]
	v_mfma_f32_16x16x32_bf16 v[2:5], v[238:241], v[192:195], v[2:5]
	v_mfma_f32_16x16x32_bf16 v[66:69], v[230:233], v[200:203], v[66:69]
	v_mfma_f32_16x16x32_bf16 v[74:77], v[238:241], v[200:203], v[74:77]
	v_mfma_f32_16x16x32_bf16 v[78:81], v[230:233], v[222:225], v[78:81]
	v_mfma_f32_16x16x32_bf16 v[82:85], v[238:241], v[222:225], v[82:85]
	v_mfma_f32_16x16x32_bf16 v[14:17], v[234:237], v[188:191], v[14:17]
	v_mfma_f32_16x16x32_bf16 v[10:13], v[242:245], v[188:191], v[10:13]
	v_mfma_f32_16x16x32_bf16 v[6:9], v[234:237], v[196:199], v[6:9]
	v_mfma_f32_16x16x32_bf16 v[2:5], v[242:245], v[196:199], v[2:5]
	v_mfma_f32_16x16x32_bf16 v[66:69], v[234:237], v[218:221], v[66:69]
	v_mfma_f32_16x16x32_bf16 v[74:77], v[242:245], v[218:221], v[74:77]
	v_mfma_f32_16x16x32_bf16 v[78:81], v[234:237], v[226:229], v[78:81]
	v_mfma_f32_16x16x32_bf16 v[82:85], v[242:245], v[226:229], v[82:85]
	s_setprio 0
	s_barrier
	v_readfirstlane_b32 s59, v149
	v_lshl_add_u64 v[208:209], v[246:247], 0, s[82:83]
	s_mov_b32 m0, s59
	v_readfirstlane_b32 s59, v152
	ds_read_b128 v[184:187], v0 offset:32768
	ds_read_b128 v[188:191], v0 offset:33792
	ds_read_b128 v[192:195], v0 offset:34816
	ds_read_b128 v[196:199], v0 offset:35840
	ds_read_b128 v[200:203], v0 offset:36864
	ds_read_b128 v[218:221], v0 offset:37888
	ds_read_b128 v[222:225], v0 offset:38912
	ds_read_b128 v[226:229], v0 offset:39936
	global_load_lds_dwordx4 v[208:209], off
	v_lshl_add_u64 v[208:209], v[248:249], 0, s[82:83]
	s_mov_b32 m0, s59
	s_nop 0
	global_load_lds_dwordx4 v[208:209], off
	s_waitcnt lgkmcnt(8)
	s_barrier
	s_waitcnt lgkmcnt(0)
	s_setprio 1
	s_waitcnt lgkmcnt(0)
	v_mfma_f32_16x16x32_bf16 v[126:129], v[162:165], v[184:187], v[126:129]
	v_mfma_f32_16x16x32_bf16 v[122:125], v[170:173], v[184:187], v[122:125]
	v_mfma_f32_16x16x32_bf16 v[118:121], v[162:165], v[192:195], v[118:121]
	v_mfma_f32_16x16x32_bf16 v[114:117], v[170:173], v[192:195], v[114:117]
	v_mfma_f32_16x16x32_bf16 v[110:113], v[162:165], v[200:203], v[110:113]
	v_mfma_f32_16x16x32_bf16 v[106:109], v[170:173], v[200:203], v[106:109]
	v_mfma_f32_16x16x32_bf16 v[102:105], v[162:165], v[222:225], v[102:105]
	v_mfma_f32_16x16x32_bf16 v[98:101], v[170:173], v[222:225], v[98:101]
	v_mfma_f32_16x16x32_bf16 v[126:129], v[166:169], v[188:191], v[126:129]
	v_mfma_f32_16x16x32_bf16 v[122:125], v[174:177], v[188:191], v[122:125]
	v_mfma_f32_16x16x32_bf16 v[118:121], v[166:169], v[196:199], v[118:121]
	v_mfma_f32_16x16x32_bf16 v[114:117], v[174:177], v[196:199], v[114:117]
	v_mfma_f32_16x16x32_bf16 v[110:113], v[166:169], v[218:221], v[110:113]
	v_mfma_f32_16x16x32_bf16 v[106:109], v[174:177], v[218:221], v[106:109]
	v_mfma_f32_16x16x32_bf16 v[102:105], v[166:169], v[226:229], v[102:105]
	v_mfma_f32_16x16x32_bf16 v[98:101], v[174:177], v[226:229], v[98:101]
	s_setprio 0
	s_barrier
	v_readfirstlane_b32 s59, v153
	v_lshl_add_u64 v[208:209], v[204:205], 0, s[84:85]
	s_mov_b32 m0, s59
	v_readfirstlane_b32 s59, v154
	ds_read_b128 v[230:233], v145 offset:49152
	ds_read_b128 v[234:237], v145 offset:50176
	ds_read_b128 v[238:241], v145 offset:51200
	ds_read_b128 v[242:245], v145 offset:52224
	global_load_lds_dwordx4 v[208:209], off
	v_lshl_add_u64 v[208:209], v[214:215], 0, s[84:85]
	s_mov_b32 m0, s59
	s_nop 0
	global_load_lds_dwordx4 v[208:209], off
	s_barrier
	s_waitcnt lgkmcnt(0)
	s_setprio 1
	s_waitcnt lgkmcnt(0)
	v_mfma_f32_16x16x32_bf16 v[94:97], v[230:233], v[184:187], v[94:97]
	v_mfma_f32_16x16x32_bf16 v[90:93], v[238:241], v[184:187], v[90:93]
	v_mfma_f32_16x16x32_bf16 v[86:89], v[230:233], v[192:195], v[86:89]
	v_mfma_f32_16x16x32_bf16 v[70:73], v[238:241], v[192:195], v[70:73]
	v_mfma_f32_16x16x32_bf16 v[62:65], v[230:233], v[200:203], v[62:65]
	v_mfma_f32_16x16x32_bf16 v[58:61], v[238:241], v[200:203], v[58:61]
	v_mfma_f32_16x16x32_bf16 v[54:57], v[230:233], v[222:225], v[54:57]
	v_mfma_f32_16x16x32_bf16 v[50:53], v[238:241], v[222:225], v[50:53]
	v_mfma_f32_16x16x32_bf16 v[94:97], v[234:237], v[188:191], v[94:97]
	v_mfma_f32_16x16x32_bf16 v[90:93], v[242:245], v[188:191], v[90:93]
	v_mfma_f32_16x16x32_bf16 v[86:89], v[234:237], v[196:199], v[86:89]
	v_mfma_f32_16x16x32_bf16 v[70:73], v[242:245], v[196:199], v[70:73]
	v_mfma_f32_16x16x32_bf16 v[62:65], v[234:237], v[218:221], v[62:65]
	v_mfma_f32_16x16x32_bf16 v[58:61], v[242:245], v[218:221], v[58:61]
	v_mfma_f32_16x16x32_bf16 v[54:57], v[234:237], v[226:229], v[54:57]
	v_mfma_f32_16x16x32_bf16 v[50:53], v[242:245], v[226:229], v[50:53]
	s_setprio 0
	v_readfirstlane_b32 s59, v155
	v_lshl_add_u64 v[208:209], v[246:247], 0, s[84:85]
	s_mov_b32 m0, s59
	v_readfirstlane_b32 s59, v156
	s_barrier
	ds_read_b128 v[184:187], v0 offset:49152
	ds_read_b128 v[188:191], v0 offset:50176
	ds_read_b128 v[192:195], v0 offset:51200
	ds_read_b128 v[196:199], v0 offset:52224
	ds_read_b128 v[200:203], v0 offset:53248
	ds_read_b128 v[218:221], v0 offset:54272
	ds_read_b128 v[222:225], v0 offset:55296
	ds_read_b128 v[226:229], v0 offset:56320
	global_load_lds_dwordx4 v[208:209], off
	v_lshl_add_u64 v[208:209], v[248:249], 0, s[84:85]
	s_mov_b32 m0, s59
	s_nop 0
	global_load_lds_dwordx4 v[208:209], off
	s_waitcnt vmcnt(10)
	s_barrier
; #define STAGE(P, BASE, LD, br, kt) do { const bf16* _gb = BASE + ((long)(br) * (LD) + (long)(kt) * BK); \
;     _Pragma("unroll") for (int _i = 0; _i < 2; ++_i) { \
;       __builtin_amdgcn_global_load_lds((const unsigned*)(_gb + ((&LD == &lda) ? offA[_i] : offB[_i])), \
;         (unsigned*)((char*)(P) + tidx_ * 16 + _i * 8192), 16, 0, 0); } } while (0)
; #define LDA(dst, b, h) _Pragma("unroll") for (int m = 0; m < 4; ++m) _Pragma("unroll") for (int k = 0; k < 2; ++k) \
;     dst[m][k] = *reinterpret_cast<const bf16x8*>(smem + (((b) * 2 + (h)) * 16384 + m * 2048 + k * 1024) + aoff)
; #define LDB(dst, b, h) _Pragma("unroll") for (int n = 0; n < 2; ++n) _Pragma("unroll") for (int k = 0; k < 2; ++k) \
;     dst[n][k] = *reinterpret_cast<const bf16x8*>(smem + (((b) * 2 + (h)) * 16384 + n * 2048 + k * 1024) + boff)
; #define MMA(ai, bj, At_, Bt_) do { __builtin_amdgcn_s_setprio(1); \
;     _Pragma("unroll") for (int m = 0; m < 4; ++m) _Pragma("unroll") for (int n = 0; n < 2; ++n) _Pragma("unroll") for (int k = 0; k < 2; ++k) \
;       acc[ai][bj][m][n] = __builtin_amdgcn_mfma_f32_16x16x32_bf16(Bt_[n][k], At_[m][k], acc[ai][bj][m][n], 0, 0, 0); \
;     __builtin_amdgcn_s_setprio(0); } while (0)
; #define WAIT_V(n) asm volatile("s_waitcnt vmcnt(" #n ")" ::: "memory")
; #define WAIT_L(n) asm volatile("s_waitcnt lgkmcnt(" #n ")" ::: "memory")
; #define BAR __builtin_amdgcn_s_barrier()
; #define SCHED __builtin_amdgcn_sched_barrier(0)
; template <class Epi, int NB>
; DEV void gemm_tile_nb(const bf16* __restrict__ A, int lda, long strideA, const bf16* __restrict__ Bt, int ldb, long strideB, int K, int brow, int bcol, Epi& epi) {
;     ...
;     BAR; WAIT_L(0); MMA(1, 0, At, B0); BAR; SCHED;
;     STAGE(SB(1, 1), Bt, ldb, bcol + HALF, t + 3);
;     WAIT_V(6); BAR; MMA(1, 1, At, B1); BAR;
;   }
;   { LDB(B0, 0, 0); LDA(At, 0, 0); STAGE(SA(1, 1), A, lda, brow + HALF, nt - 1);
;     BAR; WAIT_L(0); MMA(0, 0, At, B0); BAR;
;     LDB(B1, 0, 1); BAR; WAIT_L(0); MMA(0, 1, At, B1); BAR;
	s_waitcnt lgkmcnt(0)
	s_setprio 1
	s_waitcnt lgkmcnt(0)
	v_mfma_f32_16x16x32_bf16 v[46:49], v[162:165], v[184:187], v[46:49]
	v_mfma_f32_16x16x32_bf16 v[42:45], v[170:173], v[184:187], v[42:45]
	v_mfma_f32_16x16x32_bf16 v[38:41], v[162:165], v[192:195], v[38:41]
	v_mfma_f32_16x16x32_bf16 v[34:37], v[170:173], v[192:195], v[34:37]
	v_mfma_f32_16x16x32_bf16 v[30:33], v[162:165], v[200:203], v[30:33]
	v_mfma_f32_16x16x32_bf16 v[26:29], v[170:173], v[200:203], v[26:29]
	v_mfma_f32_16x16x32_bf16 v[22:25], v[162:165], v[222:225], v[22:25]
	v_mfma_f32_16x16x32_bf16 v[18:21], v[170:173], v[222:225], v[18:21]
	v_mfma_f32_16x16x32_bf16 v[46:49], v[166:169], v[188:191], v[46:49]
	v_mfma_f32_16x16x32_bf16 v[42:45], v[174:177], v[188:191], v[42:45]
	v_mfma_f32_16x16x32_bf16 v[38:41], v[166:169], v[196:199], v[38:41]
	v_mfma_f32_16x16x32_bf16 v[34:37], v[174:177], v[196:199], v[34:37]
	v_mfma_f32_16x16x32_bf16 v[30:33], v[166:169], v[218:221], v[30:33]
	v_mfma_f32_16x16x32_bf16 v[26:29], v[174:177], v[218:221], v[26:29]
	v_mfma_f32_16x16x32_bf16 v[22:25], v[166:169], v[226:229], v[22:25]
	v_mfma_f32_16x16x32_bf16 v[18:21], v[174:177], v[226:229], v[18:21]
	s_setprio 0
	s_barrier
	v_readfirstlane_b32 s59, v157
	v_lshl_add_u64 v[162:163], v[204:205], 0, s[86:87]
	s_mov_b32 m0, s59
	v_readfirstlane_b32 s59, v158
	global_load_lds_dwordx4 v[162:163], off
	v_lshl_add_u64 v[162:163], v[214:215], 0, s[86:87]
	s_mov_b32 m0, s59
	s_nop 0
	global_load_lds_dwordx4 v[162:163], off
	ds_read_b128 v[162:165], v145
	ds_read_b128 v[166:169], v145 offset:1024
	ds_read_b128 v[170:173], v145 offset:2048
	ds_read_b128 v[174:177], v145 offset:3072
	s_waitcnt vmcnt(6)
	s_barrier
	s_setprio 1
	v_mfma_f32_16x16x32_bf16 v[14:17], v[230:233], v[184:187], v[14:17]
	v_mfma_f32_16x16x32_bf16 v[10:13], v[238:241], v[184:187], v[10:13]
	v_mfma_f32_16x16x32_bf16 v[6:9], v[230:233], v[192:195], v[6:9]
	v_mfma_f32_16x16x32_bf16 v[2:5], v[238:241], v[192:195], v[2:5]
	v_mfma_f32_16x16x32_bf16 v[66:69], v[230:233], v[200:203], v[66:69]
	v_mfma_f32_16x16x32_bf16 v[74:77], v[238:241], v[200:203], v[74:77]
	v_mfma_f32_16x16x32_bf16 v[78:81], v[230:233], v[222:225], v[78:81]
	v_mfma_f32_16x16x32_bf16 v[82:85], v[238:241], v[222:225], v[82:85]
	v_mfma_f32_16x16x32_bf16 v[14:17], v[234:237], v[188:191], v[14:17]
	v_mfma_f32_16x16x32_bf16 v[10:13], v[242:245], v[188:191], v[10:13]
	v_mfma_f32_16x16x32_bf16 v[6:9], v[234:237], v[196:199], v[6:9]
	v_mfma_f32_16x16x32_bf16 v[2:5], v[242:245], v[196:199], v[2:5]
	v_mfma_f32_16x16x32_bf16 v[66:69], v[234:237], v[218:221], v[66:69]
	v_mfma_f32_16x16x32_bf16 v[74:77], v[242:245], v[218:221], v[74:77]
	v_mfma_f32_16x16x32_bf16 v[78:81], v[234:237], v[226:229], v[78:81]
	v_mfma_f32_16x16x32_bf16 v[82:85], v[242:245], v[226:229], v[82:85]
	s_setprio 0
	s_add_i32 s58, s58, 2
	s_add_u32 s42, s42, 0x100
	s_addc_u32 s43, s43, 0
	s_cmp_lt_u32 s58, 12
	s_barrier
	s_cbranch_scc1 .LBB0_960
	s_mov_b64 s[58:59], 0x780
	v_readfirstlane_b32 s42, v159
	v_lshl_add_u64 v[132:133], v[132:133], 0, s[58:59]
	s_mov_b32 m0, s42
	v_readfirstlane_b32 s42, v160
	ds_read_b128 v[134:137], v145
	ds_read_b128 v[138:141], v145 offset:1024
	ds_read_b128 v[146:149], v145 offset:2048
	ds_read_b128 v[150:153], v145 offset:3072
	ds_read_b128 v[154:157], v0
	ds_read_b128 v[162:165], v0 offset:1024
	ds_read_b128 v[166:169], v0 offset:2048
	ds_read_b128 v[170:173], v0 offset:3072
	ds_read_b128 v[174:177], v0 offset:4096
	ds_read_b128 v[184:187], v0 offset:5120
	ds_read_b128 v[188:191], v0 offset:6144
	ds_read_b128 v[192:195], v0 offset:7168
	global_load_lds_dwordx4 v[132:133], off
	v_lshl_add_u64 v[130:131], v[130:131], 0, s[58:59]
	s_mov_b32 m0, s42
	s_cmpk_gt_u32 s57, 0xff
	global_load_lds_dwordx4 v[130:131], off
	s_barrier
	s_waitcnt lgkmcnt(0)
	s_setprio 1
	s_waitcnt lgkmcnt(0)
	v_mfma_f32_16x16x32_bf16 v[126:129], v[134:137], v[154:157], v[126:129]
	v_mfma_f32_16x16x32_bf16 v[118:121], v[134:137], v[166:169], v[118:121]
	v_mfma_f32_16x16x32_bf16 v[110:113], v[134:137], v[174:177], v[110:113]
	v_mfma_f32_16x16x32_bf16 v[102:105], v[134:137], v[188:191], v[102:105]
	v_mfma_f32_16x16x32_bf16 v[126:129], v[138:141], v[162:165], v[126:129]
	v_mfma_f32_16x16x32_bf16 v[122:125], v[146:149], v[154:157], v[122:125]
	v_mfma_f32_16x16x32_bf16 v[118:121], v[138:141], v[170:173], v[118:121]
	v_mfma_f32_16x16x32_bf16 v[114:117], v[146:149], v[166:169], v[114:117]
	v_mfma_f32_16x16x32_bf16 v[110:113], v[138:141], v[184:187], v[110:113]
	v_mfma_f32_16x16x32_bf16 v[106:109], v[146:149], v[174:177], v[106:109]
	v_mfma_f32_16x16x32_bf16 v[102:105], v[138:141], v[192:195], v[102:105]
	v_mfma_f32_16x16x32_bf16 v[98:101], v[146:149], v[188:191], v[98:101]
	v_mfma_f32_16x16x32_bf16 v[130:133], v[150:153], v[162:165], v[122:125]
	v_mfma_f32_16x16x32_bf16 v[158:161], v[150:153], v[170:173], v[114:117]
	v_mfma_f32_16x16x32_bf16 v[196:199], v[150:153], v[184:187], v[106:109]
	v_mfma_f32_16x16x32_bf16 v[200:203], v[150:153], v[192:195], v[98:101]
	s_setprio 0
	s_barrier
	s_nop 1
	ds_read_b128 v[98:101], v145 offset:16384
	ds_read_b128 v[106:109], v145 offset:17408
	ds_read_b128 v[114:117], v145 offset:18432
	ds_read_b128 v[122:125], v145 offset:19456
	s_barrier
; #define LDA(dst, b, h) _Pragma("unroll") for (int m = 0; m < 4; ++m) _Pragma("unroll") for (int k = 0; k < 2; ++k) \
;     dst[m][k] = *reinterpret_cast<const bf16x8*>(smem + (((b) * 2 + (h)) * 16384 + m * 2048 + k * 1024) + aoff)
; #define LDB(dst, b, h) _Pragma("unroll") for (int n = 0; n < 2; ++n) _Pragma("unroll") for (int k = 0; k < 2; ++k) \
;     dst[n][k] = *reinterpret_cast<const bf16x8*>(smem + (((b) * 2 + (h)) * 16384 + n * 2048 + k * 1024) + boff)
; #define MMA(ai, bj, At_, Bt_) do { __builtin_amdgcn_s_setprio(1); \
;     _Pragma("unroll") for (int m = 0; m < 4; ++m) _Pragma("unroll") for (int n = 0; n < 2; ++n) _Pragma("unroll") for (int k = 0; k < 2; ++k) \
;       acc[ai][bj][m][n] = __builtin_amdgcn_mfma_f32_16x16x32_bf16(Bt_[n][k], At_[m][k], acc[ai][bj][m][n], 0, 0, 0); \
;     __builtin_amdgcn_s_setprio(0); } while (0)
; #define WAIT_V(n) asm volatile("s_waitcnt vmcnt(" #n ")" ::: "memory")
; #define WAIT_L(n) asm volatile("s_waitcnt lgkmcnt(" #n ")" ::: "memory")
; #define BAR __builtin_amdgcn_s_barrier()
; template <class Epi, int NB>
; DEV void gemm_tile_nb(const bf16* __restrict__ A, int lda, long strideA, const bf16* __restrict__ Bt, int ldb, long strideB, int K, int brow, int bcol, Epi& epi) {
;     ...
;     LDB(B1, 0, 1); BAR; WAIT_L(0); MMA(0, 1, At, B1); BAR;
;     LDA(At, 0, 1); WAIT_V(4); BAR; WAIT_L(0); MMA(1, 0, At, B0); MMA(1, 1, At, B1); BAR; }
;   { LDB(B0, 1, 0); LDA(At, 1, 0); WAIT_V(2); BAR; WAIT_L(0); MMA(0, 0, At, B0); BAR;
	s_waitcnt lgkmcnt(0)
	s_setprio 1
	s_waitcnt lgkmcnt(0)
	v_mfma_f32_16x16x32_bf16 v[94:97], v[98:101], v[154:157], v[94:97]
	v_mfma_f32_16x16x32_bf16 v[86:89], v[98:101], v[166:169], v[86:89]
	v_mfma_f32_16x16x32_bf16 v[70:73], v[114:117], v[166:169], v[70:73]
	v_mfma_f32_16x16x32_bf16 v[62:65], v[98:101], v[174:177], v[62:65]
	v_mfma_f32_16x16x32_bf16 v[58:61], v[114:117], v[174:177], v[58:61]
	v_mfma_f32_16x16x32_bf16 v[54:57], v[98:101], v[188:191], v[54:57]
	v_mfma_f32_16x16x32_bf16 v[50:53], v[114:117], v[188:191], v[50:53]
	v_mfma_f32_16x16x32_bf16 v[94:97], v[106:109], v[162:165], v[94:97]
	v_mfma_f32_16x16x32_bf16 v[90:93], v[114:117], v[154:157], v[90:93]
	v_mfma_f32_16x16x32_bf16 v[86:89], v[106:109], v[170:173], v[86:89]
	v_mfma_f32_16x16x32_bf16 v[70:73], v[122:125], v[170:173], v[70:73]
	v_mfma_f32_16x16x32_bf16 v[62:65], v[106:109], v[184:187], v[62:65]
	v_mfma_f32_16x16x32_bf16 v[58:61], v[122:125], v[184:187], v[58:61]
	v_mfma_f32_16x16x32_bf16 v[54:57], v[106:109], v[192:195], v[54:57]
	v_mfma_f32_16x16x32_bf16 v[50:53], v[122:125], v[192:195], v[50:53]
	v_mfma_f32_16x16x32_bf16 v[154:157], v[122:125], v[162:165], v[90:93]
	s_setprio 0
	s_barrier
	s_nop 0
	ds_read_b128 v[90:93], v0 offset:16384
	ds_read_b128 v[162:165], v0 offset:17408
	ds_read_b128 v[166:169], v0 offset:18432
	ds_read_b128 v[170:173], v0 offset:19456
	ds_read_b128 v[174:177], v0 offset:20480
	ds_read_b128 v[184:187], v0 offset:21504
	ds_read_b128 v[188:191], v0 offset:22528
	ds_read_b128 v[192:195], v0 offset:23552
	s_waitcnt vmcnt(4)
	s_barrier
	s_waitcnt lgkmcnt(0)
	s_setprio 1
	s_waitcnt lgkmcnt(0)
	v_mfma_f32_16x16x32_bf16 v[46:49], v[134:137], v[90:93], v[46:49]
	v_mfma_f32_16x16x32_bf16 v[42:45], v[146:149], v[90:93], v[42:45]
	v_mfma_f32_16x16x32_bf16 v[38:41], v[134:137], v[166:169], v[38:41]
	v_mfma_f32_16x16x32_bf16 v[34:37], v[146:149], v[166:169], v[34:37]
	v_mfma_f32_16x16x32_bf16 v[30:33], v[134:137], v[174:177], v[30:33]
	v_mfma_f32_16x16x32_bf16 v[22:25], v[134:137], v[188:191], v[22:25]
	v_mfma_f32_16x16x32_bf16 v[46:49], v[138:141], v[162:165], v[46:49]
	v_mfma_f32_16x16x32_bf16 v[42:45], v[150:153], v[162:165], v[42:45]
	v_mfma_f32_16x16x32_bf16 v[38:41], v[138:141], v[170:173], v[38:41]
	v_mfma_f32_16x16x32_bf16 v[34:37], v[150:153], v[170:173], v[34:37]
	v_mfma_f32_16x16x32_bf16 v[30:33], v[138:141], v[184:187], v[30:33]
	v_mfma_f32_16x16x32_bf16 v[26:29], v[146:149], v[174:177], v[26:29]
	v_mfma_f32_16x16x32_bf16 v[22:25], v[138:141], v[192:195], v[22:25]
	v_mfma_f32_16x16x32_bf16 v[18:21], v[146:149], v[188:191], v[18:21]
	v_mfma_f32_16x16x32_bf16 v[218:221], v[150:153], v[184:187], v[26:29]
	v_mfma_f32_16x16x32_bf16 v[134:137], v[150:153], v[192:195], v[18:21]
	s_setprio 0
	s_setprio 1
	v_mfma_f32_16x16x32_bf16 v[2:5], v[114:117], v[166:169], v[2:5]
	v_mfma_f32_16x16x32_bf16 v[146:149], v[122:125], v[170:173], v[2:5]
	v_mfma_f32_16x16x32_bf16 v[2:5], v[98:101], v[174:177], v[66:69]
	v_mfma_f32_16x16x32_bf16 v[14:17], v[98:101], v[90:93], v[14:17]
	v_mfma_f32_16x16x32_bf16 v[10:13], v[114:117], v[90:93], v[10:13]
	v_mfma_f32_16x16x32_bf16 v[150:153], v[106:109], v[184:187], v[2:5]
	v_mfma_f32_16x16x32_bf16 v[2:5], v[114:117], v[174:177], v[74:77]
	v_mfma_f32_16x16x32_bf16 v[14:17], v[106:109], v[162:165], v[14:17]
	v_mfma_f32_16x16x32_bf16 v[138:141], v[122:125], v[162:165], v[10:13]
	v_mfma_f32_16x16x32_bf16 v[6:9], v[98:101], v[166:169], v[6:9]
	v_mfma_f32_16x16x32_bf16 v[162:165], v[122:125], v[184:187], v[2:5]
	v_mfma_f32_16x16x32_bf16 v[2:5], v[98:101], v[188:191], v[78:81]
	v_mfma_f32_16x16x32_bf16 v[6:9], v[106:109], v[170:173], v[6:9]
	v_mfma_f32_16x16x32_bf16 v[166:169], v[106:109], v[192:195], v[2:5]
	v_mfma_f32_16x16x32_bf16 v[2:5], v[114:117], v[188:191], v[82:85]
	v_mfma_f32_16x16x32_bf16 v[170:173], v[122:125], v[192:195], v[2:5]
	s_setprio 0
	s_barrier
	s_nop 4
	ds_read_b128 v[2:5], v145 offset:32768
	ds_read_b128 v[10:13], v145 offset:33792
	ds_read_b128 v[174:177], v145 offset:34816
	ds_read_b128 v[184:187], v145 offset:35840
	ds_read_b128 v[18:21], v0 offset:32768
	ds_read_b128 v[26:29], v0 offset:33792
	ds_read_b128 v[78:81], v0 offset:34816
	ds_read_b128 v[188:191], v0 offset:35840
	ds_read_b128 v[192:195], v0 offset:36864
	ds_read_b128 v[222:225], v0 offset:37888
	ds_read_b128 v[226:229], v0 offset:38912
	ds_read_b128 v[230:233], v0 offset:39936
	s_waitcnt vmcnt(2)
	s_barrier
; #define LDA(dst, b, h) _Pragma("unroll") for (int m = 0; m < 4; ++m) _Pragma("unroll") for (int k = 0; k < 2; ++k) \
;     dst[m][k] = *reinterpret_cast<const bf16x8*>(smem + (((b) * 2 + (h)) * 16384 + m * 2048 + k * 1024) + aoff)
; #define LDB(dst, b, h) _Pragma("unroll") for (int n = 0; n < 2; ++n) _Pragma("unroll") for (int k = 0; k < 2; ++k) \
;     dst[n][k] = *reinterpret_cast<const bf16x8*>(smem + (((b) * 2 + (h)) * 16384 + n * 2048 + k * 1024) + boff)
; #define MMA(ai, bj, At_, Bt_) do { __builtin_amdgcn_s_setprio(1); \
;     _Pragma("unroll") for (int m = 0; m < 4; ++m) _Pragma("unroll") for (int n = 0; n < 2; ++n) _Pragma("unroll") for (int k = 0; k < 2; ++k) \
;       acc[ai][bj][m][n] = __builtin_amdgcn_mfma_f32_16x16x32_bf16(Bt_[n][k], At_[m][k], acc[ai][bj][m][n], 0, 0, 0); \
;     __builtin_amdgcn_s_setprio(0); } while (0)
; #define WAIT_V(n) asm volatile("s_waitcnt vmcnt(" #n ")" ::: "memory")
; #define WAIT_L(n) asm volatile("s_waitcnt lgkmcnt(" #n ")" ::: "memory")
; #define BAR __builtin_amdgcn_s_barrier()
; template <class Epi, int NB>
; DEV void gemm_tile_nb(const bf16* __restrict__ A, int lda, long strideA, const bf16* __restrict__ Bt, int ldb, long strideB, int K, int brow, int bcol, Epi& epi) {
;     ...
;   { LDB(B0, 1, 0); LDA(At, 1, 0); WAIT_V(2); BAR; WAIT_L(0); MMA(0, 0, At, B0); BAR;
;     LDB(B1, 1, 1); WAIT_V(0); BAR; WAIT_L(0); MMA(0, 1, At, B1); BAR;
;     LDA(At, 1, 1); BAR; WAIT_L(0); MMA(1, 0, At, B0); MMA(1, 1, At, B1); BAR; }
;   if (wr == 0) BAR;
	s_waitcnt lgkmcnt(0)
	s_setprio 1
	s_waitcnt lgkmcnt(0)
	v_mfma_f32_16x16x32_bf16 v[66:69], v[2:5], v[18:21], v[126:129]
	v_mfma_f32_16x16x32_bf16 v[122:125], v[10:13], v[26:29], v[66:69]
	v_mfma_f32_16x16x32_bf16 v[66:69], v[174:177], v[18:21], v[130:133]
	v_mfma_f32_16x16x32_bf16 v[114:117], v[184:187], v[26:29], v[66:69]
	v_mfma_f32_16x16x32_bf16 v[66:69], v[2:5], v[78:81], v[118:121]
	v_mfma_f32_16x16x32_bf16 v[106:109], v[10:13], v[188:191], v[66:69]
	v_mfma_f32_16x16x32_bf16 v[66:69], v[174:177], v[78:81], v[158:161]
	v_mfma_f32_16x16x32_bf16 v[98:101], v[184:187], v[188:191], v[66:69]
	v_mfma_f32_16x16x32_bf16 v[66:69], v[2:5], v[192:195], v[110:113]
	v_mfma_f32_16x16x32_bf16 v[90:93], v[10:13], v[222:225], v[66:69]
	v_mfma_f32_16x16x32_bf16 v[66:69], v[174:177], v[192:195], v[196:199]
	v_mfma_f32_16x16x32_bf16 v[82:85], v[184:187], v[222:225], v[66:69]
	v_mfma_f32_16x16x32_bf16 v[66:69], v[2:5], v[226:229], v[102:105]
	v_mfma_f32_16x16x32_bf16 v[74:77], v[10:13], v[230:233], v[66:69]
	v_mfma_f32_16x16x32_bf16 v[66:69], v[174:177], v[226:229], v[200:203]
	v_mfma_f32_16x16x32_bf16 v[66:69], v[184:187], v[230:233], v[66:69]
	s_setprio 0
	s_barrier
	ds_read_b128 v[130:133], v145 offset:49152
	ds_read_b128 v[158:161], v145 offset:50176
	ds_read_b128 v[196:199], v145 offset:51200
	ds_read_b128 v[200:203], v145 offset:52224
	s_waitcnt vmcnt(0)
	s_barrier
	s_waitcnt lgkmcnt(0)
	s_setprio 1
	s_waitcnt lgkmcnt(0)
	v_mfma_f32_16x16x32_bf16 v[94:97], v[130:133], v[18:21], v[94:97]
	v_mfma_f32_16x16x32_bf16 v[18:21], v[196:199], v[18:21], v[154:157]
	v_mfma_f32_16x16x32_bf16 v[118:121], v[200:203], v[26:29], v[18:21]
	v_mfma_f32_16x16x32_bf16 v[18:21], v[130:133], v[78:81], v[86:89]
	v_mfma_f32_16x16x32_bf16 v[110:113], v[158:161], v[188:191], v[18:21]
	v_mfma_f32_16x16x32_bf16 v[18:21], v[196:199], v[78:81], v[70:73]
	v_mfma_f32_16x16x32_bf16 v[102:105], v[200:203], v[188:191], v[18:21]
	v_mfma_f32_16x16x32_bf16 v[18:21], v[130:133], v[192:195], v[62:65]
	v_mfma_f32_16x16x32_bf16 v[126:129], v[158:161], v[26:29], v[94:97]
	v_mfma_f32_16x16x32_bf16 v[94:97], v[158:161], v[222:225], v[18:21]
	v_mfma_f32_16x16x32_bf16 v[18:21], v[196:199], v[192:195], v[58:61]
	v_mfma_f32_16x16x32_bf16 v[86:89], v[200:203], v[222:225], v[18:21]
	v_mfma_f32_16x16x32_bf16 v[18:21], v[130:133], v[226:229], v[54:57]
	v_mfma_f32_16x16x32_bf16 v[78:81], v[158:161], v[230:233], v[18:21]
	v_mfma_f32_16x16x32_bf16 v[18:21], v[196:199], v[226:229], v[50:53]
	v_mfma_f32_16x16x32_bf16 v[70:73], v[200:203], v[230:233], v[18:21]
	s_setprio 0
	s_barrier
	ds_read_b128 v[54:57], v0 offset:49152
	ds_read_b128 v[154:157], v0 offset:50176
	ds_read_b128 v[188:191], v0 offset:51200
	ds_read_b128 v[192:195], v0 offset:52224
	ds_read_b128 v[222:225], v0 offset:53248
	ds_read_b128 v[226:229], v0 offset:54272
	ds_read_b128 v[230:233], v0 offset:55296
	ds_read_b128 v[234:237], v0 offset:56320
	s_barrier
	s_waitcnt lgkmcnt(0)
	s_setprio 1
	s_waitcnt lgkmcnt(0)
	v_mfma_f32_16x16x32_bf16 v[18:21], v[2:5], v[54:57], v[46:49]
	v_mfma_f32_16x16x32_bf16 v[58:61], v[10:13], v[154:157], v[18:21]
	v_mfma_f32_16x16x32_bf16 v[18:21], v[174:177], v[54:57], v[42:45]
	v_mfma_f32_16x16x32_bf16 v[50:53], v[184:187], v[154:157], v[18:21]
	v_mfma_f32_16x16x32_bf16 v[18:21], v[2:5], v[188:191], v[38:41]
	v_mfma_f32_16x16x32_bf16 v[42:45], v[10:13], v[192:195], v[18:21]
	v_mfma_f32_16x16x32_bf16 v[18:21], v[174:177], v[188:191], v[34:37]
	v_mfma_f32_16x16x32_bf16 v[34:37], v[184:187], v[192:195], v[18:21]
	v_mfma_f32_16x16x32_bf16 v[18:21], v[2:5], v[222:225], v[30:33]
	v_mfma_f32_16x16x32_bf16 v[2:5], v[2:5], v[230:233], v[22:25]
	v_mfma_f32_16x16x32_bf16 v[26:29], v[10:13], v[226:229], v[18:21]
	v_mfma_f32_16x16x32_bf16 v[18:21], v[174:177], v[222:225], v[218:221]
	v_mfma_f32_16x16x32_bf16 v[10:13], v[10:13], v[234:237], v[2:5]
	v_mfma_f32_16x16x32_bf16 v[2:5], v[174:177], v[230:233], v[134:137]
	v_mfma_f32_16x16x32_bf16 v[18:21], v[184:187], v[226:229], v[18:21]
	v_mfma_f32_16x16x32_bf16 v[2:5], v[184:187], v[234:237], v[2:5]
	s_setprio 0
	s_setprio 1
	v_mfma_f32_16x16x32_bf16 v[6:9], v[130:133], v[188:191], v[6:9]
	v_mfma_f32_16x16x32_bf16 v[46:49], v[158:161], v[192:195], v[6:9]
	v_mfma_f32_16x16x32_bf16 v[6:9], v[196:199], v[188:191], v[146:149]
	v_mfma_f32_16x16x32_bf16 v[38:41], v[200:203], v[192:195], v[6:9]
	v_mfma_f32_16x16x32_bf16 v[6:9], v[130:133], v[222:225], v[150:153]
	v_mfma_f32_16x16x32_bf16 v[14:17], v[130:133], v[54:57], v[14:17]
	v_mfma_f32_16x16x32_bf16 v[30:33], v[158:161], v[226:229], v[6:9]
	v_mfma_f32_16x16x32_bf16 v[6:9], v[196:199], v[222:225], v[162:165]
	v_mfma_f32_16x16x32_bf16 v[62:65], v[158:161], v[154:157], v[14:17]
	v_mfma_f32_16x16x32_bf16 v[14:17], v[196:199], v[54:57], v[138:141]
	v_mfma_f32_16x16x32_bf16 v[22:25], v[200:203], v[226:229], v[6:9]
	v_mfma_f32_16x16x32_bf16 v[6:9], v[130:133], v[230:233], v[166:169]
	v_mfma_f32_16x16x32_bf16 v[54:57], v[200:203], v[154:157], v[14:17]
	v_mfma_f32_16x16x32_bf16 v[14:17], v[158:161], v[234:237], v[6:9]
	v_mfma_f32_16x16x32_bf16 v[6:9], v[196:199], v[230:233], v[170:173]
	v_mfma_f32_16x16x32_bf16 v[6:9], v[200:203], v[234:237], v[6:9]
	s_setprio 0
	s_barrier
	s_cbranch_scc1 .LBB0_956
	s_barrier
	s_branch .LBB0_956
